# v11 + GEMM k-loops rotated: taken back-edge moved from the head of phase 1 to the end of the phase-8 load section
# speedup vs baseline: 1.0204x; 1.0041x over previous
; #define PG8_MMA(ai, bj, At, Bt) do { __builtin_amdgcn_s_setprio(1); _Pragma("unroll") for (int m = 0; m < 4; ++m) _Pragma("unroll") for (int n = 0; n < 2; ++n) _Pragma("unroll") for (int k = 0; k < 2; ++k) \
;         acc[ai][bj][m][n] = __builtin_amdgcn_mfma_f32_16x16x32_bf16(Bt[n][k], At[m][k], acc[ai][bj][m][n], 0, 0, 0); __builtin_amdgcn_s_setprio(0); } while (0)
; #define PG8_WAIT_V(n) asm volatile("s_waitcnt vmcnt(" #n ")" ::: "memory")
; #define PG8_BAR __builtin_amdgcn_s_barrier()
; template <class Epi>
; __device__ __forceinline__ void gemm_phase(LAS unsigned char* lds, const Gemm g, const StaticOrder& S, const Epi& E, int wv) {
;     ...
;         const bool has_next = S.next(ui + 1, nxt);
;         const char* nA = has_next ? (const char*)g.A + (size_t)nxt.pm * tstepA + ((g.adiag & 1) ? (size_t)(nxt.pn >> 1) * K * 2 : 0) + kbeg : cA;
;         const char* nB = has_next ? (const char*)g.Bt + (size_t)nxt.pn * tstepB + kbeg : cB;
;     ...
;             PG8_WAIT_V(6); PG8_BAR; PG8_MMA(1, 1, At, B1); PG8_BAR;
;         }
;         E(acc, cur, wr, wc, fr, fq);
;         if (!has_next) break;
; #pragma unroll
;         for (int a = 0; a < 2; ++a)
; #pragma unroll
;             for (int b = 0; b < 2; ++b)
; #pragma unroll
;                 for (int m = 0; m < 4; ++m)
; #pragma unroll
;                     for (int n = 0; n < 2; ++n) acc[a][b][m][n] = (f32x4){0.f, 0.f, 0.f, 0.f};
.LBB0_207:
	s_ashr_i32 s63, s62, 31
	s_lshl_b64 s[30:31], s[62:63], 20
	v_cmp_lt_i64_e32 vcc, s[64:65], v[148:149]
	s_add_u32 s64, s5, s30
	s_addc_u32 s65, s6, s31
	s_and_b64 s[30:31], vcc, exec
	s_cselect_b32 s21, s65, s71
	s_cselect_b32 s30, s64, s70
	s_ashr_i32 s61, s60, 31
	s_lshl_b64 s[34:35], s[60:61], 20
	s_add_u32 s66, s7, s34
	s_addc_u32 s67, s8, s35
	s_and_b64 s[34:35], vcc, exec
	s_cselect_b32 s31, s67, s73
	s_cselect_b32 s33, s66, s72
	s_add_u32 s70, s70, 0x80080
	s_addc_u32 s71, s71, 0
	s_add_u32 s34, s72, 0x100
	v_mov_b32_e32 v0, 0
	s_addc_u32 s35, s73, 0
	s_mov_b32 s38, -2
	v_mov_b32_e32 v1, v0
	v_mov_b32_e32 v2, v0
	v_mov_b32_e32 v3, v0
	v_mov_b32_e32 v4, v0
	v_mov_b32_e32 v5, v0
	v_mov_b32_e32 v6, v0
	v_mov_b32_e32 v7, v0
	v_mov_b32_e32 v16, v0
	v_mov_b32_e32 v17, v0
	v_mov_b32_e32 v18, v0
	v_mov_b32_e32 v19, v0
	v_mov_b32_e32 v20, v0
	v_mov_b32_e32 v21, v0
	v_mov_b32_e32 v22, v0
	v_mov_b32_e32 v23, v0
	v_mov_b32_e32 v32, v0
	v_mov_b32_e32 v33, v0
	v_mov_b32_e32 v34, v0
	v_mov_b32_e32 v35, v0
	v_mov_b32_e32 v36, v0
	v_mov_b32_e32 v37, v0
	v_mov_b32_e32 v38, v0
	v_mov_b32_e32 v39, v0
	v_mov_b32_e32 v48, v0
	v_mov_b32_e32 v49, v0
	v_mov_b32_e32 v50, v0
	v_mov_b32_e32 v51, v0
	v_mov_b32_e32 v52, v0
	v_mov_b32_e32 v53, v0
	v_mov_b32_e32 v54, v0
	v_mov_b32_e32 v55, v0
	v_mov_b32_e32 v8, v0
	v_mov_b32_e32 v9, v0
	v_mov_b32_e32 v10, v0
	v_mov_b32_e32 v11, v0
	v_mov_b32_e32 v12, v0
	v_mov_b32_e32 v13, v0
	v_mov_b32_e32 v14, v0
	v_mov_b32_e32 v15, v0
	v_mov_b32_e32 v24, v0
	v_mov_b32_e32 v25, v0
	v_mov_b32_e32 v26, v0
	v_mov_b32_e32 v27, v0
	v_mov_b32_e32 v28, v0
	v_mov_b32_e32 v29, v0
	v_mov_b32_e32 v30, v0
	v_mov_b32_e32 v31, v0
	v_mov_b32_e32 v40, v0
	v_mov_b32_e32 v41, v0
	v_mov_b32_e32 v42, v0
	v_mov_b32_e32 v43, v0
	v_mov_b32_e32 v44, v0
	v_mov_b32_e32 v45, v0
	v_mov_b32_e32 v46, v0
	v_mov_b32_e32 v47, v0
	v_mov_b32_e32 v56, v0
	v_mov_b32_e32 v57, v0
	v_mov_b32_e32 v58, v0
	v_mov_b32_e32 v59, v0
	v_mov_b32_e32 v60, v0
	v_mov_b32_e32 v61, v0
	v_mov_b32_e32 v62, v0
	v_mov_b32_e32 v63, v0
	v_mov_b32_e32 v64, v0
	v_mov_b32_e32 v65, v0
	v_mov_b32_e32 v66, v0
	v_mov_b32_e32 v67, v0
	v_mov_b32_e32 v68, v0
	v_mov_b32_e32 v69, v0
	v_mov_b32_e32 v70, v0
	v_mov_b32_e32 v71, v0
	v_mov_b32_e32 v80, v0
	v_mov_b32_e32 v81, v0
	v_mov_b32_e32 v82, v0
	v_mov_b32_e32 v83, v0
	v_mov_b32_e32 v84, v0
	v_mov_b32_e32 v85, v0
	v_mov_b32_e32 v86, v0
	v_mov_b32_e32 v87, v0
	v_mov_b32_e32 v96, v0
	v_mov_b32_e32 v97, v0
	v_mov_b32_e32 v98, v0
	v_mov_b32_e32 v99, v0
	v_mov_b32_e32 v100, v0
	v_mov_b32_e32 v101, v0
	v_mov_b32_e32 v102, v0
	v_mov_b32_e32 v103, v0
	v_mov_b32_e32 v112, v0
	v_mov_b32_e32 v113, v0
	v_mov_b32_e32 v114, v0
	v_mov_b32_e32 v115, v0
	v_mov_b32_e32 v116, v0
	v_mov_b32_e32 v117, v0
	v_mov_b32_e32 v118, v0
	v_mov_b32_e32 v119, v0
	v_mov_b32_e32 v72, v0
	v_mov_b32_e32 v73, v0
	v_mov_b32_e32 v74, v0
	v_mov_b32_e32 v75, v0
	v_mov_b32_e32 v76, v0
	v_mov_b32_e32 v77, v0
	v_mov_b32_e32 v78, v0
	v_mov_b32_e32 v79, v0
	v_mov_b32_e32 v88, v0
	v_mov_b32_e32 v89, v0
	v_mov_b32_e32 v90, v0
	v_mov_b32_e32 v91, v0
	v_mov_b32_e32 v92, v0
	v_mov_b32_e32 v93, v0
	v_mov_b32_e32 v94, v0
	v_mov_b32_e32 v95, v0
	v_mov_b32_e32 v104, v0
	v_mov_b32_e32 v105, v0
	v_mov_b32_e32 v106, v0
	v_mov_b32_e32 v107, v0
	v_mov_b32_e32 v108, v0
	v_mov_b32_e32 v109, v0
	v_mov_b32_e32 v110, v0
	v_mov_b32_e32 v111, v0
	v_mov_b32_e32 v120, v0
	v_mov_b32_e32 v121, v0
	v_mov_b32_e32 v122, v0
	v_mov_b32_e32 v123, v0
	v_mov_b32_e32 v124, v0
	v_mov_b32_e32 v125, v0
	v_mov_b32_e32 v126, v0
	v_mov_b32_e32 v127, v0
	ds_read_b128 v[128:131], v190
	ds_read_b128 v[132:135], v190 offset:1024
	ds_read_b128 v[152:155], v190 offset:2048
	ds_read_b128 v[156:159], v190 offset:3072
	s_branch .Lrot_in_208
.LBB0_208:
	s_barrier
	v_mfma_f32_16x16x32_bf16 v[52:55], v[210:213], v[160:163], v[52:55]
	v_mfma_f32_16x16x32_bf16 v[48:51], v[218:221], v[160:163], v[48:51]
	v_mfma_f32_16x16x32_bf16 v[36:39], v[210:213], v[168:171], v[36:39]
	v_mfma_f32_16x16x32_bf16 v[32:35], v[218:221], v[168:171], v[32:35]
	v_mfma_f32_16x16x32_bf16 v[20:23], v[210:213], v[176:179], v[20:23]
	v_mfma_f32_16x16x32_bf16 v[16:19], v[218:221], v[176:179], v[16:19]
	v_mfma_f32_16x16x32_bf16 v[4:7], v[210:213], v[202:205], v[4:7]
	v_mfma_f32_16x16x32_bf16 v[0:3], v[218:221], v[202:205], v[0:3]
	v_mfma_f32_16x16x32_bf16 v[52:55], v[214:217], v[164:167], v[52:55]
	v_mfma_f32_16x16x32_bf16 v[48:51], v[222:225], v[164:167], v[48:51]
	v_mfma_f32_16x16x32_bf16 v[36:39], v[214:217], v[172:175], v[36:39]
	v_mfma_f32_16x16x32_bf16 v[32:35], v[222:225], v[172:175], v[32:35]
	v_mfma_f32_16x16x32_bf16 v[20:23], v[214:217], v[198:201], v[20:23]
	v_mfma_f32_16x16x32_bf16 v[16:19], v[222:225], v[198:201], v[16:19]
	v_mfma_f32_16x16x32_bf16 v[4:7], v[214:217], v[206:209], v[4:7]
	v_mfma_f32_16x16x32_bf16 v[0:3], v[222:225], v[206:209], v[0:3]
	s_waitcnt lgkmcnt(0)
	s_add_i32 s38, s38, 2
	s_add_u32 s70, s70, 0x100
	s_addc_u32 s71, s71, 0
	s_add_u32 s34, s34, 0x100
	s_addc_u32 s35, s35, 0
	s_cmp_gt_u32 s38, 29
	s_barrier
	s_cbranch_scc1 .Lrot_out_208
; #define PG8_STAGE(bufoff, gbase, voff) do { _Pragma("unroll") for (int _i = 0; _i < 2; ++_i) \
;         __builtin_amdgcn_global_load_lds((const unsigned*)((const char*)(gbase) + (voff)[_i]), (LAS unsigned*)(lds + (bufoff) + ldsw + _i * 8192), 16, 0, 0); } while (0)
; #define PG8_LDA(dst, b, h) do { _Pragma("unroll") for (int m = 0; m < 4; ++m) _Pragma("unroll") for (int k = 0; k < 2; ++k) dst[m][k] = *(const LAS bf16x8*)(lds + PG8_SA(b, h) + aoff + m * 2048 + k * 1024); } while (0)
; #define PG8_LDB(dst, b, h) do { _Pragma("unroll") for (int n = 0; n < 2; ++n) _Pragma("unroll") for (int k = 0; k < 2; ++k) dst[n][k] = *(const LAS bf16x8*)(lds + PG8_SB(b, h) + boff + n * 2048 + k * 1024); } while (0)
; #define PG8_WAIT_V(n) asm volatile("s_waitcnt vmcnt(" #n ")" ::: "memory")
; #define PG8_WAIT_L(n) asm volatile("s_waitcnt lgkmcnt(" #n ")" ::: "memory")
; #define PG8_BAR __builtin_amdgcn_s_barrier()
; #define PG8_SCHED __builtin_amdgcn_sched_barrier(0)
; template <class Epi>
; __device__ __forceinline__ void gemm_phase(LAS unsigned char* lds, const Gemm g, const StaticOrder& S, const Epi& E, int wv) {
;     ...
;         for (int t = 0; t < nt; t += 2) {
;             const bool last = (t == nt - 2);
;             const char* a1 = cA + (ptrdiff_t)(t + 1) * kstep;
;             const char* a2 = last ? nA : cA + (ptrdiff_t)(t + 2) * kstep; const char* b2 = last ? nB : cB + (ptrdiff_t)(t + 2) * kstep;
;             const char* a3 = a2 + kstep; const char* b3 = b2 + kstep;
;             PG8_LDB(B0, 0, 0); PG8_SCHED; PG8_LDA(At, 0, 0); PG8_STAGE(PG8_SA(1, 1), a1 + hstepA, voffA);
;             PG8_WAIT_L(8); PG8_BAR; PG8_WAIT_L(0); PG8_MMA(0, 0, At, B0); PG8_BAR; PG8_SCHED;
;             PG8_LDB(B1, 0, 1); PG8_STAGE(PG8_SB(0, 0), b2, voffB);
;             PG8_BAR; PG8_WAIT_L(0); PG8_MMA(0, 1, At, B1); PG8_BAR;
;             PG8_LDA(At, 0, 1); PG8_STAGE(PG8_SA(0, 0), a2, voffA);
;             PG8_BAR; PG8_WAIT_L(0); PG8_MMA(1, 0, At, B0); PG8_BAR; PG8_SCHED;
;             PG8_STAGE(PG8_SB(0, 1), b2 + hstepB, voffB);
;             PG8_WAIT_V(6); PG8_BAR; PG8_MMA(1, 1, At, B1); PG8_BAR;
;             PG8_LDB(B0, 1, 0); PG8_SCHED; PG8_LDA(At, 1, 0); PG8_STAGE(PG8_SA(0, 1), a2 + hstepA, voffA);
;             PG8_WAIT_L(8); PG8_BAR; PG8_WAIT_L(0); PG8_MMA(0, 0, At, B0); PG8_BAR; PG8_SCHED;
.Lrot_in_208:
	s_add_u32 s39, s70, 0xfff80080
	s_addc_u32 s40, s71, -1
	s_cmp_eq_u32 s38, 28
	s_cselect_b32 s75, s21, s40
	s_cselect_b32 s74, s30, s39
	s_cselect_b32 s73, s31, s35
	s_cselect_b32 s72, s33, s34
	s_add_i32 m0, s10, 0xc000
	ds_read_b128 v[160:163], v191
	ds_read_b128 v[164:167], v191 offset:1024
	ds_read_b128 v[168:171], v191 offset:2048
	ds_read_b128 v[172:175], v191 offset:3072
	ds_read_b128 v[176:179], v191 offset:4096
	ds_read_b128 v[198:201], v191 offset:5120
	ds_read_b128 v[202:205], v191 offset:6144
	ds_read_b128 v[206:209], v191 offset:7168
	global_load_lds_dwordx4 v144, s[70:71]
	s_add_i32 m0, s10, 0xe000
	s_nop 0
	global_load_lds_dwordx4 v146, s[70:71]
	s_waitcnt lgkmcnt(8)
	s_barrier
	s_waitcnt lgkmcnt(0)
	s_waitcnt lgkmcnt(0)
	v_mfma_f32_16x16x32_bf16 v[124:127], v[128:131], v[160:163], v[124:127]
	v_mfma_f32_16x16x32_bf16 v[120:123], v[152:155], v[160:163], v[120:123]
	v_mfma_f32_16x16x32_bf16 v[108:111], v[128:131], v[168:171], v[108:111]
	v_mfma_f32_16x16x32_bf16 v[104:107], v[152:155], v[168:171], v[104:107]
	v_mfma_f32_16x16x32_bf16 v[92:95], v[128:131], v[176:179], v[92:95]
	v_mfma_f32_16x16x32_bf16 v[88:91], v[152:155], v[176:179], v[88:91]
	v_mfma_f32_16x16x32_bf16 v[76:79], v[128:131], v[202:205], v[76:79]
	v_mfma_f32_16x16x32_bf16 v[72:75], v[152:155], v[202:205], v[72:75]
	v_mfma_f32_16x16x32_bf16 v[124:127], v[132:135], v[164:167], v[124:127]
	v_mfma_f32_16x16x32_bf16 v[120:123], v[156:159], v[164:167], v[120:123]
	v_mfma_f32_16x16x32_bf16 v[108:111], v[132:135], v[172:175], v[108:111]
	v_mfma_f32_16x16x32_bf16 v[104:107], v[156:159], v[172:175], v[104:107]
	v_mfma_f32_16x16x32_bf16 v[92:95], v[132:135], v[198:201], v[92:95]
	v_mfma_f32_16x16x32_bf16 v[88:91], v[156:159], v[198:201], v[88:91]
	v_mfma_f32_16x16x32_bf16 v[76:79], v[132:135], v[206:209], v[76:79]
	v_mfma_f32_16x16x32_bf16 v[72:75], v[156:159], v[206:209], v[72:75]
	s_barrier
	s_add_i32 s39, s23, s9
	s_add_u32 s98, s72, s58
	s_addc_u32 s99, s73, s59
	s_mov_b32 m0, s39
	ds_read_b128 v[210:213], v192
	ds_read_b128 v[214:217], v192 offset:1024
	ds_read_b128 v[218:221], v192 offset:2048
	ds_read_b128 v[222:225], v192 offset:3072
	global_load_lds_dwordx4 v138, s[72:73]
	s_add_i32 m0, s39, 0x2000
	s_nop 0
	global_load_lds_dwordx4 v142, s[72:73]
	s_barrier
	s_waitcnt lgkmcnt(0)
	s_waitcnt lgkmcnt(0)
	v_mfma_f32_16x16x32_bf16 v[116:119], v[210:213], v[160:163], v[116:119]
	v_mfma_f32_16x16x32_bf16 v[112:115], v[218:221], v[160:163], v[112:115]
	v_mfma_f32_16x16x32_bf16 v[100:103], v[210:213], v[168:171], v[100:103]
	v_mfma_f32_16x16x32_bf16 v[96:99], v[218:221], v[168:171], v[96:99]
	v_mfma_f32_16x16x32_bf16 v[84:87], v[210:213], v[176:179], v[84:87]
	v_mfma_f32_16x16x32_bf16 v[80:83], v[218:221], v[176:179], v[80:83]
	v_mfma_f32_16x16x32_bf16 v[68:71], v[210:213], v[202:205], v[68:71]
	v_mfma_f32_16x16x32_bf16 v[64:67], v[218:221], v[202:205], v[64:67]
	v_mfma_f32_16x16x32_bf16 v[116:119], v[214:217], v[164:167], v[116:119]
	v_mfma_f32_16x16x32_bf16 v[112:115], v[222:225], v[164:167], v[112:115]
	v_mfma_f32_16x16x32_bf16 v[100:103], v[214:217], v[172:175], v[100:103]
	v_mfma_f32_16x16x32_bf16 v[96:99], v[222:225], v[172:175], v[96:99]
	v_mfma_f32_16x16x32_bf16 v[84:87], v[214:217], v[198:201], v[84:87]
	v_mfma_f32_16x16x32_bf16 v[80:83], v[222:225], v[198:201], v[80:83]
	v_mfma_f32_16x16x32_bf16 v[68:71], v[214:217], v[206:209], v[68:71]
	v_mfma_f32_16x16x32_bf16 v[64:67], v[222:225], v[206:209], v[64:67]
	s_mov_b32 m0, s10
	s_add_u32 s100, s74, s58
	s_addc_u32 s101, s75, s59
	s_barrier
	ds_read_b128 v[160:163], v191 offset:16384
	ds_read_b128 v[164:167], v191 offset:17408
	ds_read_b128 v[168:171], v191 offset:18432
	ds_read_b128 v[172:175], v191 offset:19456
	ds_read_b128 v[176:179], v191 offset:20480
	ds_read_b128 v[198:201], v191 offset:21504
	ds_read_b128 v[202:205], v191 offset:22528
	ds_read_b128 v[206:209], v191 offset:23552
	global_load_lds_dwordx4 v136, s[74:75]
	s_mov_b32 m0, s11
	s_nop 0
	global_load_lds_dwordx4 v140, s[74:75]
	s_waitcnt vmcnt(10)
	s_barrier
	s_waitcnt lgkmcnt(0)
	s_waitcnt lgkmcnt(0)
	v_mfma_f32_16x16x32_bf16 v[60:63], v[128:131], v[160:163], v[60:63]
	v_mfma_f32_16x16x32_bf16 v[56:59], v[152:155], v[160:163], v[56:59]
	v_mfma_f32_16x16x32_bf16 v[44:47], v[128:131], v[168:171], v[44:47]
	v_mfma_f32_16x16x32_bf16 v[40:43], v[152:155], v[168:171], v[40:43]
	v_mfma_f32_16x16x32_bf16 v[28:31], v[128:131], v[176:179], v[28:31]
	v_mfma_f32_16x16x32_bf16 v[24:27], v[152:155], v[176:179], v[24:27]
	v_mfma_f32_16x16x32_bf16 v[12:15], v[128:131], v[202:205], v[12:15]
	v_mfma_f32_16x16x32_bf16 v[8:11], v[152:155], v[202:205], v[8:11]
	v_mfma_f32_16x16x32_bf16 v[60:63], v[132:135], v[164:167], v[60:63]
	v_mfma_f32_16x16x32_bf16 v[56:59], v[156:159], v[164:167], v[56:59]
	v_mfma_f32_16x16x32_bf16 v[44:47], v[132:135], v[172:175], v[44:47]
	v_mfma_f32_16x16x32_bf16 v[40:43], v[156:159], v[172:175], v[40:43]
	v_mfma_f32_16x16x32_bf16 v[28:31], v[132:135], v[198:201], v[28:31]
	v_mfma_f32_16x16x32_bf16 v[24:27], v[156:159], v[198:201], v[24:27]
	v_mfma_f32_16x16x32_bf16 v[12:15], v[132:135], v[206:209], v[12:15]
	v_mfma_f32_16x16x32_bf16 v[8:11], v[156:159], v[206:209], v[8:11]
	s_barrier
	s_add_u32 s40, s72, 0x80000
	s_addc_u32 s41, s73, 0
	s_add_i32 s39, s24, s9
	s_mov_b32 m0, s39
	s_nop 0
	global_load_lds_dwordx4 v138, s[40:41]
	s_add_i32 m0, s39, 0x2000
	s_nop 0
	global_load_lds_dwordx4 v142, s[40:41]
	s_add_i32 s39, 0, 0x18000
	v_add_u32_e32 v156, s39, v184
	ds_read_b128 v[128:131], v156
	ds_read_b128 v[132:135], v156 offset:1024
	ds_read_b128 v[152:155], v156 offset:2048
	ds_read_b128 v[156:159], v156 offset:3072
	s_waitcnt vmcnt(6)
	s_barrier
; #define PG8_STAGE(bufoff, gbase, voff) do { _Pragma("unroll") for (int _i = 0; _i < 2; ++_i) \
;         __builtin_amdgcn_global_load_lds((const unsigned*)((const char*)(gbase) + (voff)[_i]), (LAS unsigned*)(lds + (bufoff) + ldsw + _i * 8192), 16, 0, 0); } while (0)
; #define PG8_LDA(dst, b, h) do { _Pragma("unroll") for (int m = 0; m < 4; ++m) _Pragma("unroll") for (int k = 0; k < 2; ++k) dst[m][k] = *(const LAS bf16x8*)(lds + PG8_SA(b, h) + aoff + m * 2048 + k * 1024); } while (0)
; #define PG8_LDB(dst, b, h) do { _Pragma("unroll") for (int n = 0; n < 2; ++n) _Pragma("unroll") for (int k = 0; k < 2; ++k) dst[n][k] = *(const LAS bf16x8*)(lds + PG8_SB(b, h) + boff + n * 2048 + k * 1024); } while (0)
; #define PG8_MMA(ai, bj, At, Bt) do { __builtin_amdgcn_s_setprio(1); _Pragma("unroll") for (int m = 0; m < 4; ++m) _Pragma("unroll") for (int n = 0; n < 2; ++n) _Pragma("unroll") for (int k = 0; k < 2; ++k) \
;         acc[ai][bj][m][n] = __builtin_amdgcn_mfma_f32_16x16x32_bf16(Bt[n][k], At[m][k], acc[ai][bj][m][n], 0, 0, 0); __builtin_amdgcn_s_setprio(0); } while (0)
; #define PG8_WAIT_V(n) asm volatile("s_waitcnt vmcnt(" #n ")" ::: "memory")
; #define PG8_WAIT_L(n) asm volatile("s_waitcnt lgkmcnt(" #n ")" ::: "memory")
; #define PG8_BAR __builtin_amdgcn_s_barrier()
; #define PG8_SCHED __builtin_amdgcn_sched_barrier(0)
; template <class Epi>
; __device__ __forceinline__ void gemm_phase(LAS unsigned char* lds, const Gemm g, const StaticOrder& S, const Epi& E, int wv) {
;     ...
;             PG8_WAIT_L(8); PG8_BAR; PG8_WAIT_L(0); PG8_MMA(0, 0, At, B0); PG8_BAR; PG8_SCHED;
;             PG8_LDB(B1, 1, 1); PG8_STAGE(PG8_SB(1, 0), b3, voffB);
;             PG8_BAR; PG8_WAIT_L(0); PG8_MMA(0, 1, At, B1); PG8_BAR;
;             PG8_LDA(At, 1, 1); PG8_STAGE(PG8_SA(1, 0), a3, voffA);
;             PG8_BAR; PG8_WAIT_L(0); PG8_MMA(1, 0, At, B0); PG8_BAR; PG8_SCHED;
;             PG8_STAGE(PG8_SB(1, 1), b3 + hstepB, voffB);
;             PG8_WAIT_V(6); PG8_BAR; PG8_MMA(1, 1, At, B1); PG8_BAR;
	v_mfma_f32_16x16x32_bf16 v[52:55], v[210:213], v[160:163], v[52:55]
	v_mfma_f32_16x16x32_bf16 v[48:51], v[218:221], v[160:163], v[48:51]
	v_mfma_f32_16x16x32_bf16 v[36:39], v[210:213], v[168:171], v[36:39]
	v_mfma_f32_16x16x32_bf16 v[32:35], v[218:221], v[168:171], v[32:35]
	v_mfma_f32_16x16x32_bf16 v[20:23], v[210:213], v[176:179], v[20:23]
	v_mfma_f32_16x16x32_bf16 v[16:19], v[218:221], v[176:179], v[16:19]
	v_mfma_f32_16x16x32_bf16 v[4:7], v[210:213], v[202:205], v[4:7]
	v_mfma_f32_16x16x32_bf16 v[0:3], v[218:221], v[202:205], v[0:3]
	v_mfma_f32_16x16x32_bf16 v[52:55], v[214:217], v[164:167], v[52:55]
	v_mfma_f32_16x16x32_bf16 v[48:51], v[222:225], v[164:167], v[48:51]
	v_mfma_f32_16x16x32_bf16 v[36:39], v[214:217], v[172:175], v[36:39]
	v_mfma_f32_16x16x32_bf16 v[32:35], v[222:225], v[172:175], v[32:35]
	v_mfma_f32_16x16x32_bf16 v[20:23], v[214:217], v[198:201], v[20:23]
	v_mfma_f32_16x16x32_bf16 v[16:19], v[222:225], v[198:201], v[16:19]
	v_mfma_f32_16x16x32_bf16 v[4:7], v[214:217], v[206:209], v[4:7]
	v_mfma_f32_16x16x32_bf16 v[0:3], v[222:225], v[206:209], v[0:3]
	s_waitcnt lgkmcnt(0)
	s_barrier
	s_add_u32 s40, s74, 0x80000
	s_addc_u32 s41, s75, 0
	s_mov_b32 m0, s12
	ds_read_b128 v[160:163], v191 offset:32768
	ds_read_b128 v[164:167], v191 offset:33792
	ds_read_b128 v[168:171], v191 offset:34816
	ds_read_b128 v[172:175], v191 offset:35840
	ds_read_b128 v[176:179], v191 offset:36864
	ds_read_b128 v[198:201], v191 offset:37888
	ds_read_b128 v[202:205], v191 offset:38912
	ds_read_b128 v[206:209], v191 offset:39936
	global_load_lds_dwordx4 v136, s[40:41]
	s_mov_b32 m0, s13
	s_nop 0
	global_load_lds_dwordx4 v140, s[40:41]
	s_waitcnt lgkmcnt(8)
	s_barrier
	s_waitcnt lgkmcnt(0)
	s_waitcnt lgkmcnt(0)
	v_mfma_f32_16x16x32_bf16 v[124:127], v[128:131], v[160:163], v[124:127]
	v_mfma_f32_16x16x32_bf16 v[120:123], v[152:155], v[160:163], v[120:123]
	v_mfma_f32_16x16x32_bf16 v[108:111], v[128:131], v[168:171], v[108:111]
	v_mfma_f32_16x16x32_bf16 v[104:107], v[152:155], v[168:171], v[104:107]
	v_mfma_f32_16x16x32_bf16 v[92:95], v[128:131], v[176:179], v[92:95]
	v_mfma_f32_16x16x32_bf16 v[88:91], v[152:155], v[176:179], v[88:91]
	v_mfma_f32_16x16x32_bf16 v[76:79], v[128:131], v[202:205], v[76:79]
	v_mfma_f32_16x16x32_bf16 v[72:75], v[152:155], v[202:205], v[72:75]
	v_mfma_f32_16x16x32_bf16 v[124:127], v[132:135], v[164:167], v[124:127]
	v_mfma_f32_16x16x32_bf16 v[120:123], v[156:159], v[164:167], v[120:123]
	v_mfma_f32_16x16x32_bf16 v[108:111], v[132:135], v[172:175], v[108:111]
	v_mfma_f32_16x16x32_bf16 v[104:107], v[156:159], v[172:175], v[104:107]
	v_mfma_f32_16x16x32_bf16 v[92:95], v[132:135], v[198:201], v[92:95]
	v_mfma_f32_16x16x32_bf16 v[88:91], v[156:159], v[198:201], v[88:91]
	v_mfma_f32_16x16x32_bf16 v[76:79], v[132:135], v[206:209], v[76:79]
	v_mfma_f32_16x16x32_bf16 v[72:75], v[156:159], v[206:209], v[72:75]
	s_barrier
	s_add_i32 s42, 0, 0x1c000
	s_add_i32 s39, s39, s9
	v_add_u32_e32 v197, s42, v184
	s_mov_b32 m0, s39
	ds_read_b128 v[210:213], v197
	ds_read_b128 v[214:217], v197 offset:1024
	ds_read_b128 v[218:221], v197 offset:2048
	ds_read_b128 v[222:225], v197 offset:3072
	global_load_lds_dwordx4 v138, s[98:99]
	s_add_i32 m0, s39, 0x2000
	s_nop 0
	global_load_lds_dwordx4 v142, s[98:99]
	s_barrier
	s_waitcnt lgkmcnt(0)
	s_waitcnt lgkmcnt(0)
	v_mfma_f32_16x16x32_bf16 v[116:119], v[210:213], v[160:163], v[116:119]
	v_mfma_f32_16x16x32_bf16 v[112:115], v[218:221], v[160:163], v[112:115]
	v_mfma_f32_16x16x32_bf16 v[100:103], v[210:213], v[168:171], v[100:103]
	v_mfma_f32_16x16x32_bf16 v[96:99], v[218:221], v[168:171], v[96:99]
	v_mfma_f32_16x16x32_bf16 v[84:87], v[210:213], v[176:179], v[84:87]
	v_mfma_f32_16x16x32_bf16 v[80:83], v[218:221], v[176:179], v[80:83]
	v_mfma_f32_16x16x32_bf16 v[68:71], v[210:213], v[202:205], v[68:71]
	v_mfma_f32_16x16x32_bf16 v[64:67], v[218:221], v[202:205], v[64:67]
	v_mfma_f32_16x16x32_bf16 v[116:119], v[214:217], v[164:167], v[116:119]
	v_mfma_f32_16x16x32_bf16 v[112:115], v[222:225], v[164:167], v[112:115]
	v_mfma_f32_16x16x32_bf16 v[100:103], v[214:217], v[172:175], v[100:103]
	v_mfma_f32_16x16x32_bf16 v[96:99], v[222:225], v[172:175], v[96:99]
	v_mfma_f32_16x16x32_bf16 v[84:87], v[214:217], v[198:201], v[84:87]
	v_mfma_f32_16x16x32_bf16 v[80:83], v[222:225], v[198:201], v[80:83]
	v_mfma_f32_16x16x32_bf16 v[68:71], v[214:217], v[206:209], v[68:71]
	v_mfma_f32_16x16x32_bf16 v[64:67], v[222:225], v[206:209], v[64:67]
	s_mov_b32 m0, s15
	s_barrier
	ds_read_b128 v[160:163], v191 offset:49152
	ds_read_b128 v[164:167], v191 offset:50176
	ds_read_b128 v[168:171], v191 offset:51200
	ds_read_b128 v[172:175], v191 offset:52224
	ds_read_b128 v[176:179], v191 offset:53248
	ds_read_b128 v[198:201], v191 offset:54272
	ds_read_b128 v[202:205], v191 offset:55296
	ds_read_b128 v[206:209], v191 offset:56320
	global_load_lds_dwordx4 v136, s[100:101]
	s_mov_b32 m0, s22
	s_nop 0
	global_load_lds_dwordx4 v140, s[100:101]
	s_waitcnt vmcnt(10)
	s_barrier
	s_waitcnt lgkmcnt(0)
	s_waitcnt lgkmcnt(0)
	v_mfma_f32_16x16x32_bf16 v[60:63], v[128:131], v[160:163], v[60:63]
	v_mfma_f32_16x16x32_bf16 v[56:59], v[152:155], v[160:163], v[56:59]
	v_mfma_f32_16x16x32_bf16 v[44:47], v[128:131], v[168:171], v[44:47]
	v_mfma_f32_16x16x32_bf16 v[40:43], v[152:155], v[168:171], v[40:43]
	v_mfma_f32_16x16x32_bf16 v[28:31], v[128:131], v[176:179], v[28:31]
	v_mfma_f32_16x16x32_bf16 v[24:27], v[152:155], v[176:179], v[24:27]
	v_mfma_f32_16x16x32_bf16 v[12:15], v[128:131], v[202:205], v[12:15]
	v_mfma_f32_16x16x32_bf16 v[8:11], v[152:155], v[202:205], v[8:11]
	v_mfma_f32_16x16x32_bf16 v[60:63], v[132:135], v[164:167], v[60:63]
	v_mfma_f32_16x16x32_bf16 v[56:59], v[156:159], v[164:167], v[56:59]
	v_mfma_f32_16x16x32_bf16 v[44:47], v[132:135], v[172:175], v[44:47]
	v_mfma_f32_16x16x32_bf16 v[40:43], v[156:159], v[172:175], v[40:43]
	v_mfma_f32_16x16x32_bf16 v[28:31], v[132:135], v[198:201], v[28:31]
	v_mfma_f32_16x16x32_bf16 v[24:27], v[156:159], v[198:201], v[24:27]
	v_mfma_f32_16x16x32_bf16 v[12:15], v[132:135], v[206:209], v[12:15]
	v_mfma_f32_16x16x32_bf16 v[8:11], v[156:159], v[206:209], v[8:11]
	s_barrier
	s_add_u32 s40, s72, 0x80080
	s_addc_u32 s41, s73, 0
	s_add_i32 s39, s42, s9
	s_mov_b32 m0, s39
	s_nop 0
	global_load_lds_dwordx4 v138, s[40:41]
	s_add_i32 m0, s39, 0x2000
	s_nop 0
	global_load_lds_dwordx4 v142, s[40:41]
	ds_read_b128 v[128:131], v190
	ds_read_b128 v[132:135], v190 offset:1024
	ds_read_b128 v[152:155], v190 offset:2048
	ds_read_b128 v[156:159], v190 offset:3072
	s_waitcnt vmcnt(6)
	s_branch .LBB0_208
; __device__ __forceinline__ float ss_fix(float raw) { return (float)__float_as_uint(raw) * (1.0f / 256.0f); }
;     __device__ __forceinline__ void operator()(const f32x4 (&acc)[2][2][4][2], const Unit& u, int wr, int wc, int fr, int fq) const {
;         const int row0 = u.pm * BM + wr * 64 + fr, col0 = u.pn * BM + wc * 32 + 8 * fq;
;         const bool isq = u.pn < 8;
;         const float* gp = (isq ? gq : gk) + wc * 32 + 8 * fq;
;         const float qs = isq ? 0.08838834764831845f * LOG2E : 1.0f;
;         const f32x4 g0 = *(const f32x4*)gp * qs, g1 = *(const f32x4*)(gp + 4) * qs;
;         float rsv[8];
; #pragma unroll
;         for (int it = 0; it < 8; ++it) rsv[it] = __builtin_amdgcn_rsqf(ss_fix(ss[row0 + (it >> 2) * HALF + (it & 3) * 16]) * (1.0f / DM) + EPS);
; #pragma unroll
;         for (int it = 0; it < 8; ++it) { const int ai = it >> 2, m = it & 3; const float rs = rsv[it];
; #pragma unroll
;             for (int bj = 0; bj < 2; ++bj) { const f32x4 v0 = acc[ai][bj][m][0] * rs, v1 = acc[ai][bj][m][1] * rs;
;                 float sq = (v0[0] * v0[0] + v0[1] * v0[1]) + (v0[2] * v0[2] + v0[3] * v0[3]) + (v1[0] * v1[0] + v1[1] * v1[1]) + (v1[2] * v1[2] + v1[3] * v1[3]);
;                 sq += __shfl_xor(sq, 16); sq += __shfl_xor(sq, 32);
;                 if (fq == 0) P[((ai * HALF + wr * 64 + m * 16 + fr) * 2 + bj) * 4 + wc] = sq; } }
.Lrot_out_208:
	v_lshl_add_u32 v168, s20, 8, v183
	v_ashrrev_i32_e32 v169, 31, v168
	v_lshl_add_u64 v[128:129], v[168:169], 2, s[50:51]
	global_load_dword v159, v[128:129], off
	s_cmp_lt_i32 s68, 8
	s_cselect_b64 vcc, -1, 0
	global_load_dword v158, v[128:129], off offset:64
	global_load_dword v157, v[128:129], off offset:128
	global_load_dword v156, v[128:129], off offset:192
	global_load_dword v155, v[128:129], off offset:512
	global_load_dword v154, v[128:129], off offset:576
	global_load_dword v153, v[128:129], off offset:640
	global_load_dword v152, v[128:129], off offset:704
	s_and_b64 s[20:21], vcc, exec
	s_cselect_b32 s20, s52, s54
	s_cselect_b32 s21, s53, s55
	s_add_u32 s20, s20, s25
	s_addc_u32 s21, s21, 0
	global_load_dwordx4 v[128:131], v193, s[20:21] offset:16
	global_load_dwordx4 v[132:135], v193, s[20:21]
	v_and_b32_e32 v161, 64, v195
	v_xor_b32_e32 v160, 16, v195
	v_add_u32_e32 v167, 64, v161
	v_cmp_lt_i32_e64 s[20:21], v160, v167
	s_waitcnt vmcnt(0)
	v_cvt_f32_u32_e32 v159, v159
	v_mul_f32_e32 v159, 0x3b800000, v159
	v_fmamk_f32 v159, v159, 0x3a000000, v194
	v_rsq_f32_e32 v166, v159
	v_cndmask_b32_e64 v159, v195, v160, s[20:21]
	v_lshlrev_b32_e32 v170, 2, v159
	v_pk_mul_f32 v[160:161], v[126:127], v[166:167] op_sel_hi:[1,0]
	v_pk_mul_f32 v[162:163], v[124:125], v[166:167] op_sel_hi:[1,0]
	v_pk_mul_f32 v[172:173], v[120:121], v[166:167] op_sel_hi:[1,0]
	v_mul_f32_e32 v159, v163, v163
	v_mul_f32_e32 v161, v161, v161
	v_pk_mul_f32 v[164:165], v[122:123], v[166:167] op_sel_hi:[1,0]
	v_mul_f32_e32 v163, v173, v173
	v_fmac_f32_e32 v159, v162, v162
	v_fmac_f32_e32 v161, v160, v160
	v_mul_f32_e32 v165, v165, v165
	v_fmac_f32_e32 v163, v172, v172
	v_add_f32_e32 v159, v159, v161
	v_add_f32_e32 v159, v163, v159
	v_fmac_f32_e32 v165, v164, v164
	v_add_f32_e32 v159, v165, v159
	ds_bpermute_b32 v160, v170, v159
	v_xor_b32_e32 v161, 32, v195
	v_cmp_lt_i32_e64 s[20:21], v161, v167
	s_waitcnt lgkmcnt(0)
	v_add_f32_e32 v159, v159, v160
	v_cndmask_b32_e64 v161, v195, v161, s[20:21]
	v_lshlrev_b32_e32 v171, 2, v161
	ds_bpermute_b32 v160, v171, v159
	s_and_saveexec_b64 s[20:21], s[16:17]
	s_cbranch_execz .LBB0_211
	s_waitcnt lgkmcnt(0)
	v_add_f32_e32 v159, v159, v160
	ds_write_b32 v186, v159

; #define PG8_BAR __builtin_amdgcn_s_barrier()
; template <class Epi>
; __device__ __forceinline__ void gemm_phase(LAS unsigned char* lds, const Gemm g, const StaticOrder& S, const Epi& E, int wv) {
;     ...
;         const bool has_next = S.next(ui + 1, nxt);
;         const char* nA = has_next ? (const char*)g.A + (size_t)nxt.pm * tstepA + ((g.adiag & 1) ? (size_t)(nxt.pn >> 1) * K * 2 : 0) + kbeg : cA;
;         const char* nB = has_next ? (const char*)g.Bt + (size_t)nxt.pn * tstepB + kbeg : cB;
;         for (int t = 0; t < nt; t += 2) {
;             const bool last = (t == nt - 2);
;             const char* a1 = cA + (ptrdiff_t)(t + 1) * kstep;
;             const char* a2 = last ? nA : cA + (ptrdiff_t)(t + 2) * kstep; const char* b2 = last ? nB : cB + (ptrdiff_t)(t + 2) * kstep;
;             const char* a3 = a2 + kstep; const char* b3 = b2 + kstep;
;             PG8_LDB(B0, 0, 0); PG8_SCHED; PG8_LDA(At, 0, 0); PG8_STAGE(PG8_SA(1, 1), a1 + hstepA, voffA);
;             PG8_WAIT_L(8); PG8_BAR; PG8_WAIT_L(0); PG8_MMA(0, 0, At, B0); PG8_BAR; PG8_SCHED;
;             PG8_LDB(B1, 0, 1); PG8_STAGE(PG8_SB(0, 0), b2, voffB);
;             PG8_BAR; PG8_WAIT_L(0); PG8_MMA(0, 1, At, B1); PG8_BAR;
;             PG8_LDA(At, 0, 1); PG8_STAGE(PG8_SA(0, 0), a2, voffA);
;             PG8_BAR; PG8_WAIT_L(0); PG8_MMA(1, 0, At, B0); PG8_BAR; PG8_SCHED;
;             PG8_STAGE(PG8_SB(0, 1), b2 + hstepB, voffB);
;             PG8_WAIT_V(6); PG8_BAR; PG8_MMA(1, 1, At, B1); PG8_BAR;
;             PG8_LDB(B0, 1, 0); PG8_SCHED; PG8_LDA(At, 1, 0); PG8_STAGE(PG8_SA(0, 1), a2 + hstepA, voffA);
;             PG8_WAIT_L(8); PG8_BAR; PG8_WAIT_L(0); PG8_MMA(0, 0, At, B0); PG8_BAR; PG8_SCHED;
;             PG8_LDB(B1, 1, 1); PG8_STAGE(PG8_SB(1, 0), b3, voffB);
;             PG8_BAR; PG8_WAIT_L(0); PG8_MMA(0, 1, At, B1); PG8_BAR;
;             PG8_LDA(At, 1, 1); PG8_STAGE(PG8_SA(1, 0), a3, voffA);
;             PG8_BAR; PG8_WAIT_L(0); PG8_MMA(1, 0, At, B0); PG8_BAR; PG8_SCHED;
;             PG8_STAGE(PG8_SB(1, 1), b3 + hstepB, voffB);
;             PG8_WAIT_V(6); PG8_BAR; PG8_MMA(1, 1, At, B1); PG8_BAR;
;         }
;         E(acc, cur, wr, wc, fr, fq);
;         if (!has_next) break;
; #pragma unroll
;         for (int a = 0; a < 2; ++a)
; #pragma unroll
;             for (int b = 0; b < 2; ++b)
; #pragma unroll
;                 for (int m = 0; m < 4; ++m)
; #pragma unroll
.LBB0_258:
	s_ashr_i32 s59, s58, 31
	s_lshl_b64 s[34:35], s[58:59], 20
	v_cmp_lt_i64_e32 vcc, s[60:61], v[142:143]
	s_add_u32 s60, s5, s34
	s_addc_u32 s61, s6, s35
	s_and_b64 s[34:35], vcc, exec
	s_cselect_b32 s34, s61, s67
	s_cselect_b32 s35, s60, s66
	s_ashr_i32 s57, s56, 31
	s_lshl_b64 s[38:39], s[56:57], 20
	s_add_u32 s62, s7, s38
	s_addc_u32 s63, s8, s39
	s_and_b64 s[38:39], vcc, exec
	s_cselect_b32 s38, s63, s69
	s_cselect_b32 s39, s62, s68
	s_add_u32 s66, s66, 0x80080
	s_addc_u32 s67, s67, 0
	s_add_u32 s40, s68, 0x100
	v_mov_b32_e32 v0, 0
	s_addc_u32 s41, s69, 0
	s_mov_b32 s42, -2
	v_mov_b32_e32 v1, v0
	v_mov_b32_e32 v2, v0
	v_mov_b32_e32 v3, v0
	v_mov_b32_e32 v4, v0
	v_mov_b32_e32 v5, v0
	v_mov_b32_e32 v6, v0
	v_mov_b32_e32 v7, v0
	v_mov_b32_e32 v8, v0
	v_mov_b32_e32 v9, v0
	v_mov_b32_e32 v10, v0
	v_mov_b32_e32 v11, v0
	v_mov_b32_e32 v16, v0
	v_mov_b32_e32 v17, v0
	v_mov_b32_e32 v18, v0
	v_mov_b32_e32 v19, v0
	v_mov_b32_e32 v24, v0
	v_mov_b32_e32 v25, v0
	v_mov_b32_e32 v26, v0
	v_mov_b32_e32 v27, v0
	v_mov_b32_e32 v32, v0
	v_mov_b32_e32 v33, v0
	v_mov_b32_e32 v34, v0
	v_mov_b32_e32 v35, v0
	v_mov_b32_e32 v40, v0
	v_mov_b32_e32 v41, v0
	v_mov_b32_e32 v42, v0
	v_mov_b32_e32 v43, v0
	v_mov_b32_e32 v48, v0
	v_mov_b32_e32 v49, v0
	v_mov_b32_e32 v50, v0
	v_mov_b32_e32 v51, v0
	v_mov_b32_e32 v12, v0
	v_mov_b32_e32 v13, v0
	v_mov_b32_e32 v14, v0
	v_mov_b32_e32 v15, v0
	v_mov_b32_e32 v20, v0
	v_mov_b32_e32 v21, v0
	v_mov_b32_e32 v22, v0
	v_mov_b32_e32 v23, v0
	v_mov_b32_e32 v28, v0
	v_mov_b32_e32 v29, v0
	v_mov_b32_e32 v30, v0
	v_mov_b32_e32 v31, v0
	v_mov_b32_e32 v36, v0
	v_mov_b32_e32 v37, v0
	v_mov_b32_e32 v38, v0
	v_mov_b32_e32 v39, v0
	v_mov_b32_e32 v44, v0
	v_mov_b32_e32 v45, v0
	v_mov_b32_e32 v46, v0
	v_mov_b32_e32 v47, v0
	v_mov_b32_e32 v52, v0
	v_mov_b32_e32 v53, v0
	v_mov_b32_e32 v54, v0
	v_mov_b32_e32 v55, v0
	v_mov_b32_e32 v56, v0
	v_mov_b32_e32 v57, v0
	v_mov_b32_e32 v58, v0
	v_mov_b32_e32 v59, v0
	v_mov_b32_e32 v60, v0
	v_mov_b32_e32 v61, v0
	v_mov_b32_e32 v62, v0
	v_mov_b32_e32 v63, v0
	v_mov_b32_e32 v64, v0
	v_mov_b32_e32 v65, v0
	v_mov_b32_e32 v66, v0
	v_mov_b32_e32 v67, v0
	v_mov_b32_e32 v68, v0
	v_mov_b32_e32 v69, v0
	v_mov_b32_e32 v70, v0
	v_mov_b32_e32 v71, v0
	v_mov_b32_e32 v76, v0
	v_mov_b32_e32 v77, v0
	v_mov_b32_e32 v78, v0
	v_mov_b32_e32 v79, v0
	v_mov_b32_e32 v84, v0
	v_mov_b32_e32 v85, v0
	v_mov_b32_e32 v86, v0
	v_mov_b32_e32 v87, v0
	v_mov_b32_e32 v92, v0
	v_mov_b32_e32 v93, v0
	v_mov_b32_e32 v94, v0
	v_mov_b32_e32 v95, v0
	v_mov_b32_e32 v100, v0
	v_mov_b32_e32 v101, v0
	v_mov_b32_e32 v102, v0
	v_mov_b32_e32 v103, v0
	v_mov_b32_e32 v108, v0
	v_mov_b32_e32 v109, v0
	v_mov_b32_e32 v110, v0
	v_mov_b32_e32 v111, v0
	v_mov_b32_e32 v116, v0
	v_mov_b32_e32 v117, v0
	v_mov_b32_e32 v118, v0
	v_mov_b32_e32 v119, v0
	v_mov_b32_e32 v72, v0
	v_mov_b32_e32 v73, v0
	v_mov_b32_e32 v74, v0
	v_mov_b32_e32 v75, v0
	v_mov_b32_e32 v80, v0
	v_mov_b32_e32 v81, v0
	v_mov_b32_e32 v82, v0
	v_mov_b32_e32 v83, v0
	v_mov_b32_e32 v88, v0
	v_mov_b32_e32 v89, v0
	v_mov_b32_e32 v90, v0
	v_mov_b32_e32 v91, v0
	v_mov_b32_e32 v96, v0
	v_mov_b32_e32 v97, v0
	v_mov_b32_e32 v98, v0
	v_mov_b32_e32 v99, v0
	v_mov_b32_e32 v104, v0
	v_mov_b32_e32 v105, v0
	v_mov_b32_e32 v106, v0
	v_mov_b32_e32 v107, v0
	v_mov_b32_e32 v112, v0
	v_mov_b32_e32 v113, v0
	v_mov_b32_e32 v114, v0
	v_mov_b32_e32 v115, v0
	v_mov_b32_e32 v120, v0
	v_mov_b32_e32 v121, v0
	v_mov_b32_e32 v122, v0
	v_mov_b32_e32 v123, v0
	v_mov_b32_e32 v124, v0
	v_mov_b32_e32 v125, v0
	v_mov_b32_e32 v126, v0
	v_mov_b32_e32 v127, v0
	ds_read_b128 v[146:149], v167
	ds_read_b128 v[150:153], v167 offset:1024
	ds_read_b128 v[154:157], v167 offset:2048
	ds_read_b128 v[158:161], v167 offset:3072
	s_branch .Lrot_in_259
.LBB0_259:
	s_barrier
	v_mfma_f32_16x16x32_bf16 v[48:51], v[208:211], v[172:175], v[48:51]
	v_mfma_f32_16x16x32_bf16 v[40:43], v[216:219], v[172:175], v[40:43]
	v_mfma_f32_16x16x32_bf16 v[32:35], v[208:211], v[184:187], v[32:35]
	v_mfma_f32_16x16x32_bf16 v[24:27], v[216:219], v[184:187], v[24:27]
	v_mfma_f32_16x16x32_bf16 v[16:19], v[208:211], v[192:195], v[16:19]
	v_mfma_f32_16x16x32_bf16 v[8:11], v[216:219], v[192:195], v[8:11]
	v_mfma_f32_16x16x32_bf16 v[4:7], v[208:211], v[200:203], v[4:7]
	v_mfma_f32_16x16x32_bf16 v[0:3], v[216:219], v[200:203], v[0:3]
	v_mfma_f32_16x16x32_bf16 v[48:51], v[212:215], v[176:179], v[48:51]
	v_mfma_f32_16x16x32_bf16 v[40:43], v[220:223], v[176:179], v[40:43]
	v_mfma_f32_16x16x32_bf16 v[32:35], v[212:215], v[188:191], v[32:35]
	v_mfma_f32_16x16x32_bf16 v[24:27], v[220:223], v[188:191], v[24:27]
	v_mfma_f32_16x16x32_bf16 v[16:19], v[212:215], v[196:199], v[16:19]
	v_mfma_f32_16x16x32_bf16 v[8:11], v[220:223], v[196:199], v[8:11]
	v_mfma_f32_16x16x32_bf16 v[4:7], v[212:215], v[204:207], v[4:7]
	v_mfma_f32_16x16x32_bf16 v[0:3], v[220:223], v[204:207], v[0:3]
	s_waitcnt lgkmcnt(0)
	s_add_i32 s42, s42, 2
	s_add_u32 s66, s66, 0x100
	s_addc_u32 s67, s67, 0
	s_add_u32 s40, s40, 0x100
	s_addc_u32 s41, s41, 0
	s_cmp_gt_u32 s42, 29
	s_barrier
	s_cbranch_scc1 .Lrot_out_259
; #define PG8_STAGE(bufoff, gbase, voff) do { _Pragma("unroll") for (int _i = 0; _i < 2; ++_i) \
;         __builtin_amdgcn_global_load_lds((const unsigned*)((const char*)(gbase) + (voff)[_i]), (LAS unsigned*)(lds + (bufoff) + ldsw + _i * 8192), 16, 0, 0); } while (0)
; #define PG8_LDA(dst, b, h) do { _Pragma("unroll") for (int m = 0; m < 4; ++m) _Pragma("unroll") for (int k = 0; k < 2; ++k) dst[m][k] = *(const LAS bf16x8*)(lds + PG8_SA(b, h) + aoff + m * 2048 + k * 1024); } while (0)
; #define PG8_LDB(dst, b, h) do { _Pragma("unroll") for (int n = 0; n < 2; ++n) _Pragma("unroll") for (int k = 0; k < 2; ++k) dst[n][k] = *(const LAS bf16x8*)(lds + PG8_SB(b, h) + boff + n * 2048 + k * 1024); } while (0)
; #define PG8_MMA(ai, bj, At, Bt) do { __builtin_amdgcn_s_setprio(1); _Pragma("unroll") for (int m = 0; m < 4; ++m) _Pragma("unroll") for (int n = 0; n < 2; ++n) _Pragma("unroll") for (int k = 0; k < 2; ++k) \
;         acc[ai][bj][m][n] = __builtin_amdgcn_mfma_f32_16x16x32_bf16(Bt[n][k], At[m][k], acc[ai][bj][m][n], 0, 0, 0); __builtin_amdgcn_s_setprio(0); } while (0)
; #define PG8_WAIT_V(n) asm volatile("s_waitcnt vmcnt(" #n ")" ::: "memory")
; #define PG8_WAIT_L(n) asm volatile("s_waitcnt lgkmcnt(" #n ")" ::: "memory")
; #define PG8_BAR __builtin_amdgcn_s_barrier()
; template <class Epi>
; __device__ __forceinline__ void gemm_phase(LAS unsigned char* lds, const Gemm g, const StaticOrder& S, const Epi& E, int wv) {
;     ...
;             const bool last = (t == nt - 2);
;             const char* a1 = cA + (ptrdiff_t)(t + 1) * kstep;
;             const char* a2 = last ? nA : cA + (ptrdiff_t)(t + 2) * kstep; const char* b2 = last ? nB : cB + (ptrdiff_t)(t + 2) * kstep;
;             const char* a3 = a2 + kstep; const char* b3 = b2 + kstep;
;             PG8_LDB(B0, 0, 0); PG8_SCHED; PG8_LDA(At, 0, 0); PG8_STAGE(PG8_SA(1, 1), a1 + hstepA, voffA);
;             PG8_WAIT_L(8); PG8_BAR; PG8_WAIT_L(0); PG8_MMA(0, 0, At, B0); PG8_BAR; PG8_SCHED;
;             PG8_LDB(B1, 0, 1); PG8_STAGE(PG8_SB(0, 0), b2, voffB);
;             PG8_BAR; PG8_WAIT_L(0); PG8_MMA(0, 1, At, B1); PG8_BAR;
;             PG8_LDA(At, 0, 1); PG8_STAGE(PG8_SA(0, 0), a2, voffA);
;             PG8_BAR; PG8_WAIT_L(0); PG8_MMA(1, 0, At, B0); PG8_BAR; PG8_SCHED;
;             PG8_STAGE(PG8_SB(0, 1), b2 + hstepB, voffB);
;             PG8_WAIT_V(6); PG8_BAR; PG8_MMA(1, 1, At, B1); PG8_BAR;
.Lrot_in_259:
	s_add_u32 s43, s66, 0xfff80080
	s_addc_u32 s44, s67, -1
	s_cmp_eq_u32 s42, 28
	s_cselect_b32 s71, s34, s44
	s_cselect_b32 s70, s35, s43
	s_cselect_b32 s69, s38, s41
	s_cselect_b32 s68, s39, s40
	s_add_i32 m0, s10, 0xc000
	ds_read_b128 v[172:175], v168
	ds_read_b128 v[176:179], v168 offset:1024
	ds_read_b128 v[184:187], v168 offset:2048
	ds_read_b128 v[188:191], v168 offset:3072
	ds_read_b128 v[192:195], v168 offset:4096
	ds_read_b128 v[196:199], v168 offset:5120
	ds_read_b128 v[200:203], v168 offset:6144
	ds_read_b128 v[204:207], v168 offset:7168
	global_load_lds_dwordx4 v138, s[66:67]
	s_add_i32 m0, s10, 0xe000
	s_nop 0
	global_load_lds_dwordx4 v140, s[66:67]
	s_waitcnt lgkmcnt(8)
	s_barrier
	s_waitcnt lgkmcnt(0)
	s_waitcnt lgkmcnt(0)
	v_mfma_f32_16x16x32_bf16 v[124:127], v[146:149], v[172:175], v[124:127]
	v_mfma_f32_16x16x32_bf16 v[120:123], v[154:157], v[172:175], v[120:123]
	v_mfma_f32_16x16x32_bf16 v[112:115], v[146:149], v[184:187], v[112:115]
	v_mfma_f32_16x16x32_bf16 v[104:107], v[154:157], v[184:187], v[104:107]
	v_mfma_f32_16x16x32_bf16 v[96:99], v[146:149], v[192:195], v[96:99]
	v_mfma_f32_16x16x32_bf16 v[88:91], v[154:157], v[192:195], v[88:91]
	v_mfma_f32_16x16x32_bf16 v[80:83], v[146:149], v[200:203], v[80:83]
	v_mfma_f32_16x16x32_bf16 v[72:75], v[154:157], v[200:203], v[72:75]
	v_mfma_f32_16x16x32_bf16 v[124:127], v[150:153], v[176:179], v[124:127]
	v_mfma_f32_16x16x32_bf16 v[120:123], v[158:161], v[176:179], v[120:123]
	v_mfma_f32_16x16x32_bf16 v[112:115], v[150:153], v[188:191], v[112:115]
	v_mfma_f32_16x16x32_bf16 v[104:107], v[158:161], v[188:191], v[104:107]
	v_mfma_f32_16x16x32_bf16 v[96:99], v[150:153], v[196:199], v[96:99]
	v_mfma_f32_16x16x32_bf16 v[88:91], v[158:161], v[196:199], v[88:91]
	v_mfma_f32_16x16x32_bf16 v[80:83], v[150:153], v[204:207], v[80:83]
	v_mfma_f32_16x16x32_bf16 v[72:75], v[158:161], v[204:207], v[72:75]
	s_barrier
	s_add_i32 s43, s23, s9
	s_add_u32 s98, s68, s20
	s_addc_u32 s99, s69, s21
	s_mov_b32 m0, s43
	ds_read_b128 v[208:211], v169
	ds_read_b128 v[212:215], v169 offset:1024
	ds_read_b128 v[216:219], v169 offset:2048
	ds_read_b128 v[220:223], v169 offset:3072
	global_load_lds_dwordx4 v130, s[68:69]
	s_add_i32 m0, s43, 0x2000
	s_nop 0
	global_load_lds_dwordx4 v134, s[68:69]
	s_barrier
	s_waitcnt lgkmcnt(0)
	s_waitcnt lgkmcnt(0)
	v_mfma_f32_16x16x32_bf16 v[116:119], v[208:211], v[172:175], v[116:119]
	v_mfma_f32_16x16x32_bf16 v[108:111], v[216:219], v[172:175], v[108:111]
	v_mfma_f32_16x16x32_bf16 v[100:103], v[208:211], v[184:187], v[100:103]
	v_mfma_f32_16x16x32_bf16 v[92:95], v[216:219], v[184:187], v[92:95]
	v_mfma_f32_16x16x32_bf16 v[84:87], v[208:211], v[192:195], v[84:87]
	v_mfma_f32_16x16x32_bf16 v[76:79], v[216:219], v[192:195], v[76:79]
	v_mfma_f32_16x16x32_bf16 v[68:71], v[208:211], v[200:203], v[68:71]
	v_mfma_f32_16x16x32_bf16 v[64:67], v[216:219], v[200:203], v[64:67]
	v_mfma_f32_16x16x32_bf16 v[116:119], v[212:215], v[176:179], v[116:119]
	v_mfma_f32_16x16x32_bf16 v[108:111], v[220:223], v[176:179], v[108:111]
	v_mfma_f32_16x16x32_bf16 v[100:103], v[212:215], v[188:191], v[100:103]
	v_mfma_f32_16x16x32_bf16 v[92:95], v[220:223], v[188:191], v[92:95]
	v_mfma_f32_16x16x32_bf16 v[84:87], v[212:215], v[196:199], v[84:87]
	v_mfma_f32_16x16x32_bf16 v[76:79], v[220:223], v[196:199], v[76:79]
	v_mfma_f32_16x16x32_bf16 v[68:71], v[212:215], v[204:207], v[68:71]
	v_mfma_f32_16x16x32_bf16 v[64:67], v[220:223], v[204:207], v[64:67]
	s_mov_b32 m0, s10
	s_add_u32 s100, s70, s20
	s_addc_u32 s101, s71, s21
	s_barrier
	ds_read_b128 v[172:175], v168 offset:16384
	ds_read_b128 v[176:179], v168 offset:17408
	ds_read_b128 v[184:187], v168 offset:18432
	ds_read_b128 v[188:191], v168 offset:19456
	ds_read_b128 v[192:195], v168 offset:20480
	ds_read_b128 v[196:199], v168 offset:21504
	ds_read_b128 v[200:203], v168 offset:22528
	ds_read_b128 v[204:207], v168 offset:23552
	global_load_lds_dwordx4 v128, s[70:71]
	s_mov_b32 m0, s11
	s_nop 0
	global_load_lds_dwordx4 v132, s[70:71]
	s_waitcnt vmcnt(10)
	s_barrier
	s_waitcnt lgkmcnt(0)
	s_waitcnt lgkmcnt(0)
	v_mfma_f32_16x16x32_bf16 v[60:63], v[146:149], v[172:175], v[60:63]
	v_mfma_f32_16x16x32_bf16 v[56:59], v[154:157], v[172:175], v[56:59]
	v_mfma_f32_16x16x32_bf16 v[52:55], v[146:149], v[184:187], v[52:55]
	v_mfma_f32_16x16x32_bf16 v[44:47], v[154:157], v[184:187], v[44:47]
	v_mfma_f32_16x16x32_bf16 v[36:39], v[146:149], v[192:195], v[36:39]
	v_mfma_f32_16x16x32_bf16 v[28:31], v[154:157], v[192:195], v[28:31]
	v_mfma_f32_16x16x32_bf16 v[20:23], v[146:149], v[200:203], v[20:23]
	v_mfma_f32_16x16x32_bf16 v[12:15], v[154:157], v[200:203], v[12:15]
	v_mfma_f32_16x16x32_bf16 v[60:63], v[150:153], v[176:179], v[60:63]
	v_mfma_f32_16x16x32_bf16 v[56:59], v[158:161], v[176:179], v[56:59]
	v_mfma_f32_16x16x32_bf16 v[52:55], v[150:153], v[188:191], v[52:55]
	v_mfma_f32_16x16x32_bf16 v[44:47], v[158:161], v[188:191], v[44:47]
	v_mfma_f32_16x16x32_bf16 v[36:39], v[150:153], v[196:199], v[36:39]
	v_mfma_f32_16x16x32_bf16 v[28:31], v[158:161], v[196:199], v[28:31]
	v_mfma_f32_16x16x32_bf16 v[20:23], v[150:153], v[204:207], v[20:23]
	v_mfma_f32_16x16x32_bf16 v[12:15], v[158:161], v[204:207], v[12:15]
	s_barrier
	s_add_u32 s44, s68, 0x80000
	s_addc_u32 s45, s69, 0
	s_add_i32 s43, s24, s9
	s_mov_b32 m0, s43
	s_nop 0
	global_load_lds_dwordx4 v130, s[44:45]
	s_add_i32 m0, s43, 0x2000
	s_nop 0
	global_load_lds_dwordx4 v134, s[44:45]
	s_add_i32 s43, 0, 0x18000
	v_add_u32_e32 v158, s43, v165
	ds_read_b128 v[146:149], v158
	ds_read_b128 v[150:153], v158 offset:1024
	ds_read_b128 v[154:157], v158 offset:2048
	ds_read_b128 v[158:161], v158 offset:3072
	s_waitcnt vmcnt(6)
	s_barrier
; #define PG8_STAGE(bufoff, gbase, voff) do { _Pragma("unroll") for (int _i = 0; _i < 2; ++_i) \
;         __builtin_amdgcn_global_load_lds((const unsigned*)((const char*)(gbase) + (voff)[_i]), (LAS unsigned*)(lds + (bufoff) + ldsw + _i * 8192), 16, 0, 0); } while (0)
; #define PG8_LDA(dst, b, h) do { _Pragma("unroll") for (int m = 0; m < 4; ++m) _Pragma("unroll") for (int k = 0; k < 2; ++k) dst[m][k] = *(const LAS bf16x8*)(lds + PG8_SA(b, h) + aoff + m * 2048 + k * 1024); } while (0)
; #define PG8_LDB(dst, b, h) do { _Pragma("unroll") for (int n = 0; n < 2; ++n) _Pragma("unroll") for (int k = 0; k < 2; ++k) dst[n][k] = *(const LAS bf16x8*)(lds + PG8_SB(b, h) + boff + n * 2048 + k * 1024); } while (0)
; #define PG8_MMA(ai, bj, At, Bt) do { __builtin_amdgcn_s_setprio(1); _Pragma("unroll") for (int m = 0; m < 4; ++m) _Pragma("unroll") for (int n = 0; n < 2; ++n) _Pragma("unroll") for (int k = 0; k < 2; ++k) \
;         acc[ai][bj][m][n] = __builtin_amdgcn_mfma_f32_16x16x32_bf16(Bt[n][k], At[m][k], acc[ai][bj][m][n], 0, 0, 0); __builtin_amdgcn_s_setprio(0); } while (0)
; #define PG8_WAIT_V(n) asm volatile("s_waitcnt vmcnt(" #n ")" ::: "memory")
; #define PG8_WAIT_L(n) asm volatile("s_waitcnt lgkmcnt(" #n ")" ::: "memory")
; #define PG8_BAR __builtin_amdgcn_s_barrier()
; #define PG8_SCHED __builtin_amdgcn_sched_barrier(0)
; template <class Epi>
; __device__ __forceinline__ void gemm_phase(LAS unsigned char* lds, const Gemm g, const StaticOrder& S, const Epi& E, int wv) {
;     ...
;             PG8_WAIT_V(6); PG8_BAR; PG8_MMA(1, 1, At, B1); PG8_BAR;
;             PG8_LDB(B0, 1, 0); PG8_SCHED; PG8_LDA(At, 1, 0); PG8_STAGE(PG8_SA(0, 1), a2 + hstepA, voffA);
;             PG8_WAIT_L(8); PG8_BAR; PG8_WAIT_L(0); PG8_MMA(0, 0, At, B0); PG8_BAR; PG8_SCHED;
;             PG8_LDB(B1, 1, 1); PG8_STAGE(PG8_SB(1, 0), b3, voffB);
;             PG8_BAR; PG8_WAIT_L(0); PG8_MMA(0, 1, At, B1); PG8_BAR;
;             PG8_LDA(At, 1, 1); PG8_STAGE(PG8_SA(1, 0), a3, voffA);
;             PG8_BAR; PG8_WAIT_L(0); PG8_MMA(1, 0, At, B0); PG8_BAR; PG8_SCHED;
;             PG8_STAGE(PG8_SB(1, 1), b3 + hstepB, voffB);
;             PG8_WAIT_V(6); PG8_BAR; PG8_MMA(1, 1, At, B1); PG8_BAR;
	v_mfma_f32_16x16x32_bf16 v[48:51], v[208:211], v[172:175], v[48:51]
	v_mfma_f32_16x16x32_bf16 v[40:43], v[216:219], v[172:175], v[40:43]
	v_mfma_f32_16x16x32_bf16 v[32:35], v[208:211], v[184:187], v[32:35]
	v_mfma_f32_16x16x32_bf16 v[24:27], v[216:219], v[184:187], v[24:27]
	v_mfma_f32_16x16x32_bf16 v[16:19], v[208:211], v[192:195], v[16:19]
	v_mfma_f32_16x16x32_bf16 v[8:11], v[216:219], v[192:195], v[8:11]
	v_mfma_f32_16x16x32_bf16 v[4:7], v[208:211], v[200:203], v[4:7]
	v_mfma_f32_16x16x32_bf16 v[0:3], v[216:219], v[200:203], v[0:3]
	v_mfma_f32_16x16x32_bf16 v[48:51], v[212:215], v[176:179], v[48:51]
	v_mfma_f32_16x16x32_bf16 v[40:43], v[220:223], v[176:179], v[40:43]
	v_mfma_f32_16x16x32_bf16 v[32:35], v[212:215], v[188:191], v[32:35]
	v_mfma_f32_16x16x32_bf16 v[24:27], v[220:223], v[188:191], v[24:27]
	v_mfma_f32_16x16x32_bf16 v[16:19], v[212:215], v[196:199], v[16:19]
	v_mfma_f32_16x16x32_bf16 v[8:11], v[220:223], v[196:199], v[8:11]
	v_mfma_f32_16x16x32_bf16 v[4:7], v[212:215], v[204:207], v[4:7]
	v_mfma_f32_16x16x32_bf16 v[0:3], v[220:223], v[204:207], v[0:3]
	s_waitcnt lgkmcnt(0)
	s_barrier
	s_add_u32 s44, s70, 0x80000
	s_addc_u32 s45, s71, 0
	s_mov_b32 m0, s12
	ds_read_b128 v[172:175], v168 offset:32768
	ds_read_b128 v[176:179], v168 offset:33792
	ds_read_b128 v[184:187], v168 offset:34816
	ds_read_b128 v[188:191], v168 offset:35840
	ds_read_b128 v[192:195], v168 offset:36864
	ds_read_b128 v[196:199], v168 offset:37888
	ds_read_b128 v[200:203], v168 offset:38912
	ds_read_b128 v[204:207], v168 offset:39936
	global_load_lds_dwordx4 v128, s[44:45]
	s_mov_b32 m0, s13
	s_nop 0
	global_load_lds_dwordx4 v132, s[44:45]
	s_waitcnt lgkmcnt(8)
	s_barrier
	s_waitcnt lgkmcnt(0)
	s_waitcnt lgkmcnt(0)
	v_mfma_f32_16x16x32_bf16 v[124:127], v[146:149], v[172:175], v[124:127]
	v_mfma_f32_16x16x32_bf16 v[120:123], v[154:157], v[172:175], v[120:123]
	v_mfma_f32_16x16x32_bf16 v[112:115], v[146:149], v[184:187], v[112:115]
	v_mfma_f32_16x16x32_bf16 v[104:107], v[154:157], v[184:187], v[104:107]
	v_mfma_f32_16x16x32_bf16 v[96:99], v[146:149], v[192:195], v[96:99]
	v_mfma_f32_16x16x32_bf16 v[88:91], v[154:157], v[192:195], v[88:91]
	v_mfma_f32_16x16x32_bf16 v[80:83], v[146:149], v[200:203], v[80:83]
	v_mfma_f32_16x16x32_bf16 v[72:75], v[154:157], v[200:203], v[72:75]
	v_mfma_f32_16x16x32_bf16 v[124:127], v[150:153], v[176:179], v[124:127]
	v_mfma_f32_16x16x32_bf16 v[120:123], v[158:161], v[176:179], v[120:123]
	v_mfma_f32_16x16x32_bf16 v[112:115], v[150:153], v[188:191], v[112:115]
	v_mfma_f32_16x16x32_bf16 v[104:107], v[158:161], v[188:191], v[104:107]
	v_mfma_f32_16x16x32_bf16 v[96:99], v[150:153], v[196:199], v[96:99]
	v_mfma_f32_16x16x32_bf16 v[88:91], v[158:161], v[196:199], v[88:91]
	v_mfma_f32_16x16x32_bf16 v[80:83], v[150:153], v[204:207], v[80:83]
	v_mfma_f32_16x16x32_bf16 v[72:75], v[158:161], v[204:207], v[72:75]
	s_barrier
	s_add_i32 s46, 0, 0x1c000
	s_add_i32 s43, s43, s9
	v_add_u32_e32 v171, s46, v165
	s_mov_b32 m0, s43
	ds_read_b128 v[208:211], v171
	ds_read_b128 v[212:215], v171 offset:1024
	ds_read_b128 v[216:219], v171 offset:2048
	ds_read_b128 v[220:223], v171 offset:3072
	global_load_lds_dwordx4 v130, s[98:99]
	s_add_i32 m0, s43, 0x2000
	s_nop 0
	global_load_lds_dwordx4 v134, s[98:99]
	s_barrier
	s_waitcnt lgkmcnt(0)
	s_waitcnt lgkmcnt(0)
	v_mfma_f32_16x16x32_bf16 v[116:119], v[208:211], v[172:175], v[116:119]
	v_mfma_f32_16x16x32_bf16 v[108:111], v[216:219], v[172:175], v[108:111]
	v_mfma_f32_16x16x32_bf16 v[100:103], v[208:211], v[184:187], v[100:103]
	v_mfma_f32_16x16x32_bf16 v[92:95], v[216:219], v[184:187], v[92:95]
	v_mfma_f32_16x16x32_bf16 v[84:87], v[208:211], v[192:195], v[84:87]
	v_mfma_f32_16x16x32_bf16 v[76:79], v[216:219], v[192:195], v[76:79]
	v_mfma_f32_16x16x32_bf16 v[68:71], v[208:211], v[200:203], v[68:71]
	v_mfma_f32_16x16x32_bf16 v[64:67], v[216:219], v[200:203], v[64:67]
	v_mfma_f32_16x16x32_bf16 v[116:119], v[212:215], v[176:179], v[116:119]
	v_mfma_f32_16x16x32_bf16 v[108:111], v[220:223], v[176:179], v[108:111]
	v_mfma_f32_16x16x32_bf16 v[100:103], v[212:215], v[188:191], v[100:103]
	v_mfma_f32_16x16x32_bf16 v[92:95], v[220:223], v[188:191], v[92:95]
	v_mfma_f32_16x16x32_bf16 v[84:87], v[212:215], v[196:199], v[84:87]
	v_mfma_f32_16x16x32_bf16 v[76:79], v[220:223], v[196:199], v[76:79]
	v_mfma_f32_16x16x32_bf16 v[68:71], v[212:215], v[204:207], v[68:71]
	v_mfma_f32_16x16x32_bf16 v[64:67], v[220:223], v[204:207], v[64:67]
	s_mov_b32 m0, s15
	s_barrier
	ds_read_b128 v[172:175], v168 offset:49152
	ds_read_b128 v[176:179], v168 offset:50176
	ds_read_b128 v[184:187], v168 offset:51200
	ds_read_b128 v[188:191], v168 offset:52224
	ds_read_b128 v[192:195], v168 offset:53248
	ds_read_b128 v[196:199], v168 offset:54272
	ds_read_b128 v[200:203], v168 offset:55296
	ds_read_b128 v[204:207], v168 offset:56320
	global_load_lds_dwordx4 v128, s[100:101]
	s_mov_b32 m0, s22
	s_nop 0
	global_load_lds_dwordx4 v132, s[100:101]
	s_waitcnt vmcnt(10)
	s_barrier
	s_waitcnt lgkmcnt(0)
	s_waitcnt lgkmcnt(0)
	v_mfma_f32_16x16x32_bf16 v[60:63], v[146:149], v[172:175], v[60:63]
	v_mfma_f32_16x16x32_bf16 v[56:59], v[154:157], v[172:175], v[56:59]
	v_mfma_f32_16x16x32_bf16 v[52:55], v[146:149], v[184:187], v[52:55]
	v_mfma_f32_16x16x32_bf16 v[44:47], v[154:157], v[184:187], v[44:47]
	v_mfma_f32_16x16x32_bf16 v[36:39], v[146:149], v[192:195], v[36:39]
	v_mfma_f32_16x16x32_bf16 v[28:31], v[154:157], v[192:195], v[28:31]
	v_mfma_f32_16x16x32_bf16 v[20:23], v[146:149], v[200:203], v[20:23]
	v_mfma_f32_16x16x32_bf16 v[12:15], v[154:157], v[200:203], v[12:15]
	v_mfma_f32_16x16x32_bf16 v[60:63], v[150:153], v[176:179], v[60:63]
	v_mfma_f32_16x16x32_bf16 v[56:59], v[158:161], v[176:179], v[56:59]
	v_mfma_f32_16x16x32_bf16 v[52:55], v[150:153], v[188:191], v[52:55]
	v_mfma_f32_16x16x32_bf16 v[44:47], v[158:161], v[188:191], v[44:47]
	v_mfma_f32_16x16x32_bf16 v[36:39], v[150:153], v[196:199], v[36:39]
	v_mfma_f32_16x16x32_bf16 v[28:31], v[158:161], v[196:199], v[28:31]
	v_mfma_f32_16x16x32_bf16 v[20:23], v[150:153], v[204:207], v[20:23]
	v_mfma_f32_16x16x32_bf16 v[12:15], v[158:161], v[204:207], v[12:15]
	s_barrier
	s_add_u32 s44, s68, 0x80080
	s_addc_u32 s45, s69, 0
	s_add_i32 s43, s46, s9
	s_mov_b32 m0, s43
	s_nop 0
	global_load_lds_dwordx4 v130, s[44:45]
	s_add_i32 m0, s43, 0x2000
	s_nop 0
	global_load_lds_dwordx4 v134, s[44:45]
	ds_read_b128 v[146:149], v167
	ds_read_b128 v[150:153], v167 offset:1024
	ds_read_b128 v[154:157], v167 offset:2048
	ds_read_b128 v[158:161], v167 offset:3072
	s_waitcnt vmcnt(6)
	s_branch .LBB0_259
;     __device__ __forceinline__ void operator()(const f32x4 (&acc)[2][2][4][2], const Unit& u, int wr, int wc, int fr, int fq) const {
;         const int row0 = u.pm * BM + wr * 64 + fr; int colt = u.pn * BM; bf16_t* base = O; int tsel = 0;
;         if (split_cols) { tsel = colt / split_cols; base += (size_t)tsel * split_stride; colt -= tsel * split_cols; }
;         const int col0 = colt + wc * 32 + 8 * fq;
;         f32x4 cs[2][2];
;         if (SM == 2) {
; #pragma unroll
;             for (int bj = 0; bj < 2; ++bj)
; #pragma unroll
;                 for (int n = 0; n < 2; ++n) { const f32x4 s = *(const f32x4*)(ss + u.pn * BM + wc * 32 + 8 * fq + bj * HALF + 4 * n);
; #pragma unroll
;                     for (int j = 0; j < 4; ++j) cs[bj][n][j] = __builtin_amdgcn_rsqf(ss_fix(s[j]) * (1.0f / DM) + EPS); }
;         }
;         float rsv[8];
; #pragma unroll
;         for (int it = 0; it < 8; ++it) rsv[it] = (SM == 1) ? ss[row0 + (it >> 2) * HALF + (it & 3) * 16] : 1.0f;
; #pragma unroll
;         for (int ai = 0; ai < 2; ++ai)
; #pragma unroll
;             for (int m = 0; m < 4; ++m) { const int row = row0 + ai * HALF + m * 16; float rs = 1.0f; if (SM == 1) rs = __builtin_amdgcn_rsqf(ss_fix(rsv[ai * 4 + m]) * (1.0f / DM) + EPS);
;                 bf16_t* rowp = base + (size_t)row * ldc + col0;
; #pragma unroll
;                 for (int bj = 0; bj < 2; ++bj) { f32x4 v0 = acc[ai][bj][m][0], v1 = acc[ai][bj][m][1];
;                     if (SM == 1) { v0 *= rs; v1 *= rs; }
;                     if (SM == 2) { v0 *= cs[bj][0]; v1 *= cs[bj][1]; }
;                     if (ACT == 1) {
; #pragma unroll
;                         for (int j = 0; j < 4; ++j) { const float a = fmaxf(v0[j], 0.f), b = fmaxf(v1[j], 0.f); v0[j] = a * a; v1[j] = b * b; } }
;                     if (ACT == 2) { if (tsel == 0) {
; #pragma unroll
;                         for (int j = 0; j < 4; ++j) { const float a = v0[j], b = v1[j];
;                             v0[j] = a * fast_sigmoid(1.5957691216057308f * (a + 0.044715f * a * a * a)); v1[j] = b * fast_sigmoid(1.5957691216057308f * (b + 0.044715f * b * b * b)); } } }
;                     u32x4 w; w.x = pk_bf16(v0[0], v0[1]); w.y = pk_bf16(v0[2], v0[3]); w.z = pk_bf16(v1[0], v1[1]); w.w = pk_bf16(v1[2], v1[3]);
;                     *(u32x4*)(rowp + bj * HALF) = w; } }
.Lrot_out_259:
	s_lshl_b32 s34, s33, 8
	s_ashr_i32 s35, s34, 31
	v_lshl_add_u64 v[146:147], s[34:35], 2, v[136:137]
	global_load_dwordx4 v[148:151], v[146:147], off
	global_load_dwordx4 v[152:155], v[146:147], off offset:16
	global_load_dwordx4 v[156:159], v[146:147], off offset:512
	global_load_dwordx4 v[160:163], v[146:147], off offset:528
	v_lshl_add_u32 v172, s64, 8, v164
	v_or_b32_e32 v146, s34, v166
	v_ashrrev_i32_e32 v173, 31, v172
	v_ashrrev_i32_e32 v147, 31, v146
	v_lshlrev_b64 v[174:175], 15, v[172:173]
	v_lshl_add_u64 v[176:177], v[146:147], 1, s[18:19]
	v_lshl_add_u64 v[146:147], v[176:177], 0, v[174:175]
	s_mov_b32 s33, 0x400000
	s_mov_b64 s[34:35], 0x400000
	s_mov_b32 s64, s58
	s_mov_b64 s[68:69], s[62:63]
	s_mov_b64 s[66:67], s[60:61]
	s_waitcnt vmcnt(0)
	v_cvt_f32_u32_e32 v148, v148
	v_cvt_f32_u32_e32 v149, v149
	v_cvt_f32_u32_e32 v150, v150
	v_cvt_f32_u32_e32 v151, v151
	v_cvt_f32_u32_e32 v152, v152
	v_cvt_f32_u32_e32 v153, v153
	v_cvt_f32_u32_e32 v154, v154
	v_cvt_f32_u32_e32 v155, v155
	v_cvt_f32_u32_e32 v156, v156
	v_cvt_f32_u32_e32 v157, v157
	v_cvt_f32_u32_e32 v158, v158
	v_cvt_f32_u32_e32 v159, v159
	v_cvt_f32_u32_e32 v160, v160
	v_cvt_f32_u32_e32 v161, v161
	v_cvt_f32_u32_e32 v162, v162
	v_cvt_f32_u32_e32 v163, v163
	v_mul_f32_e32 v148, 0x3b800000, v148
	v_mul_f32_e32 v149, 0x3b800000, v149
	v_mul_f32_e32 v150, 0x3b800000, v150
	v_mul_f32_e32 v151, 0x3b800000, v151
	v_mul_f32_e32 v152, 0x3b800000, v152
	v_mul_f32_e32 v153, 0x3b800000, v153
	v_mul_f32_e32 v154, 0x3b800000, v154
	v_mul_f32_e32 v155, 0x3b800000, v155
	v_mul_f32_e32 v156, 0x3b800000, v156
	v_mul_f32_e32 v157, 0x3b800000, v157
	v_mul_f32_e32 v158, 0x3b800000, v158
	v_mul_f32_e32 v159, 0x3b800000, v159
	v_mul_f32_e32 v160, 0x3b800000, v160
	v_mul_f32_e32 v161, 0x3b800000, v161
	v_mul_f32_e32 v162, 0x3b800000, v162
	v_mul_f32_e32 v163, 0x3b800000, v163
	v_fmamk_f32 v148, v148, 0x3a000000, v170
	v_fmamk_f32 v149, v149, 0x3a000000, v170
	v_fmamk_f32 v150, v150, 0x3a000000, v170
	v_fmamk_f32 v151, v151, 0x3a000000, v170
	v_fmamk_f32 v152, v152, 0x3a000000, v170
	v_fmamk_f32 v153, v153, 0x3a000000, v170
	v_fmamk_f32 v154, v154, 0x3a000000, v170
	v_fmamk_f32 v155, v155, 0x3a000000, v170
	v_fmamk_f32 v171, v156, 0x3a000000, v170
	v_fmamk_f32 v173, v157, 0x3a000000, v170
	v_fmamk_f32 v174, v158, 0x3a000000, v170
	v_fmamk_f32 v175, v159, 0x3a000000, v170
	v_fmamk_f32 v178, v160, 0x3a000000, v170
	v_fmamk_f32 v179, v161, 0x3a000000, v170
	v_fmamk_f32 v180, v162, 0x3a000000, v170
	v_fmamk_f32 v181, v163, 0x3a000000, v170
	v_rsq_f32_e32 v158, v148
	v_rsq_f32_e32 v159, v149
	v_rsq_f32_e32 v162, v150
	v_rsq_f32_e32 v163, v151
	v_rsq_f32_e32 v156, v152
	v_rsq_f32_e32 v157, v153
	v_rsq_f32_e32 v160, v154
	v_rsq_f32_e32 v161, v155
	v_rsq_f32_e32 v150, v171
	v_rsq_f32_e32 v151, v173
	v_rsq_f32_e32 v154, v174
	v_rsq_f32_e32 v155, v175
	v_rsq_f32_e32 v148, v178
	v_rsq_f32_e32 v149, v179
	v_rsq_f32_e32 v152, v180
	v_rsq_f32_e32 v153, v181
	v_pk_mul_f32 v[126:127], v[126:127], v[162:163]
	v_pk_mul_f32 v[124:125], v[124:125], v[158:159]
	v_pk_mul_f32 v[122:123], v[122:123], v[160:161]
	v_pk_mul_f32 v[120:121], v[120:121], v[156:157]
	v_pk_mul_f32 v[118:119], v[118:119], v[154:155]
	v_pk_mul_f32 v[116:117], v[116:117], v[150:151]
	v_pk_mul_f32 v[174:175], v[110:111], v[152:153]
	v_pk_mul_f32 v[178:179], v[108:109], v[148:149]
	v_cvt_pk_bf16_f32 v108, v124, v125
	v_cvt_pk_bf16_f32 v109, v126, v127
	v_cvt_pk_bf16_f32 v110, v120, v121
	v_cvt_pk_bf16_f32 v111, v122, v123
	v_cvt_pk_bf16_f32 v116, v116, v117
	v_cvt_pk_bf16_f32 v117, v118, v119
	v_cvt_pk_bf16_f32 v118, v178, v179
	v_cvt_pk_bf16_f32 v119, v174, v175
	global_store_dwordx4 v[146:147], v[108:111], off
	global_store_dwordx4 v[146:147], v[116:119], off offset:256
	v_pk_mul_f32 v[112:113], v[112:113], v[158:159]
	v_or_b32_e32 v108, 16, v172
	v_ashrrev_i32_e32 v109, 31, v108
	v_lshlrev_b64 v[108:109], 15, v[108:109]
	v_pk_mul_f32 v[110:111], v[114:115], v[162:163]
	v_pk_mul_f32 v[114:115], v[106:107], v[160:161]
	v_pk_mul_f32 v[106:107], v[104:105], v[156:157]
	v_lshl_add_u64 v[108:109], v[176:177], 0, v[108:109]
	v_cvt_pk_bf16_f32 v104, v112, v113
	v_cvt_pk_bf16_f32 v105, v110, v111
	v_cvt_pk_bf16_f32 v106, v106, v107
	v_cvt_pk_bf16_f32 v107, v114, v115
	global_store_dwordx4 v[108:109], v[104:107], off
	v_pk_mul_f32 v[102:103], v[102:103], v[154:155]
	v_pk_mul_f32 v[100:101], v[100:101], v[150:151]
	v_pk_mul_f32 v[104:105], v[94:95], v[152:153]
	v_pk_mul_f32 v[94:95], v[92:93], v[148:149]
	v_cvt_pk_bf16_f32 v92, v100, v101
	v_cvt_pk_bf16_f32 v93, v102, v103
	v_cvt_pk_bf16_f32 v94, v94, v95
	v_cvt_pk_bf16_f32 v95, v104, v105
	global_store_dwordx4 v[108:109], v[92:95], off offset:256
	v_pk_mul_f32 v[96:97], v[96:97], v[158:159]
	v_pk_mul_f32 v[86:87], v[86:87], v[154:155]
	v_or_b32_e32 v92, 32, v172
	v_ashrrev_i32_e32 v93, 31, v92
	v_lshlrev_b64 v[92:93], 15, v[92:93]
	v_pk_mul_f32 v[94:95], v[98:99], v[162:163]
	v_pk_mul_f32 v[98:99], v[90:91], v[160:161]
	v_pk_mul_f32 v[90:91], v[88:89], v[156:157]
; __device__ __forceinline__ float fast_sigmoid(float x) { return __builtin_amdgcn_rcpf(1.0f + __builtin_amdgcn_exp2f(-x * LOG2E)); }
; __device__ __forceinline__ float ss_fix(float raw) { return (float)__float_as_uint(raw) * (1.0f / 256.0f); }
; #define PG8_WAIT_V(n) asm volatile("s_waitcnt vmcnt(" #n ")" ::: "memory")
; template <class Epi>
; __device__ __forceinline__ void gemm_phase(LAS unsigned char* lds, const Gemm g, const StaticOrder& S, const Epi& E, int wv) {
;     ...
;         if (!has_next) break;
; #pragma unroll
;         for (int a = 0; a < 2; ++a)
; #pragma unroll
;             for (int b = 0; b < 2; ++b)
; #pragma unroll
;                 for (int m = 0; m < 4; ++m)
; #pragma unroll
;                     for (int n = 0; n < 2; ++n) acc[a][b][m][n] = (f32x4){0.f, 0.f, 0.f, 0.f};
;         cur = nxt; cA = nA; cB = nB; ++ui;
;     }
;     PG8_WAIT_V(0);
;     if (wr == 0) PG8_BAR;
;     PG8_BAR;
;     __device__ __forceinline__ void operator()(const f32x4 (&acc)[2][2][4][2], const Unit& u, int wr, int wc, int fr, int fq) const {
;     ...
;         for (int ai = 0; ai < 2; ++ai)
; #pragma unroll
;             for (int m = 0; m < 4; ++m) { const int row = row0 + ai * HALF + m * 16; float rs = 1.0f; if (SM == 1) rs = __builtin_amdgcn_rsqf(ss_fix(rsv[ai * 4 + m]) * (1.0f / DM) + EPS);
;                 bf16_t* rowp = base + (size_t)row * ldc + col0;
; #pragma unroll
;                 for (int bj = 0; bj < 2; ++bj) { f32x4 v0 = acc[ai][bj][m][0], v1 = acc[ai][bj][m][1];
;                     if (SM == 1) { v0 *= rs; v1 *= rs; }
;                     if (SM == 2) { v0 *= cs[bj][0]; v1 *= cs[bj][1]; }
;                     if (ACT == 1) {
; #pragma unroll
;                         for (int j = 0; j < 4; ++j) { const float a = fmaxf(v0[j], 0.f), b = fmaxf(v1[j], 0.f); v0[j] = a * a; v1[j] = b * b; } }
;                     if (ACT == 2) { if (tsel == 0) {
; #pragma unroll
;                         for (int j = 0; j < 4; ++j) { const float a = v0[j], b = v1[j];
;                             v0[j] = a * fast_sigmoid(1.5957691216057308f * (a + 0.044715f * a * a * a)); v1[j] = b * fast_sigmoid(1.5957691216057308f * (b + 0.044715f * b * b * b)); } } }
;                     u32x4 w; w.x = pk_bf16(v0[0], v0[1]); w.y = pk_bf16(v0[2], v0[3]); w.z = pk_bf16(v1[0], v1[1]); w.w = pk_bf16(v1[2], v1[3]);
;                     *(u32x4*)(rowp + bj * HALF) = w; } }
	v_lshl_add_u64 v[92:93], v[176:177], 0, v[92:93]
	v_cvt_pk_bf16_f32 v88, v96, v97
	v_cvt_pk_bf16_f32 v89, v94, v95
	v_cvt_pk_bf16_f32 v90, v90, v91
	v_cvt_pk_bf16_f32 v91, v98, v99
	global_store_dwordx4 v[92:93], v[88:91], off
	v_pk_mul_f32 v[84:85], v[84:85], v[150:151]
	v_pk_mul_f32 v[80:81], v[80:81], v[158:159]
	v_pk_mul_f32 v[88:89], v[78:79], v[152:153]
	v_pk_mul_f32 v[78:79], v[76:77], v[148:149]
	v_cvt_pk_bf16_f32 v76, v84, v85
	v_cvt_pk_bf16_f32 v77, v86, v87
	v_cvt_pk_bf16_f32 v78, v78, v79
	v_cvt_pk_bf16_f32 v79, v88, v89
	global_store_dwordx4 v[92:93], v[76:79], off offset:256
	v_pk_mul_f32 v[70:71], v[70:71], v[154:155]
	v_pk_mul_f32 v[68:69], v[68:69], v[150:151]
	v_or_b32_e32 v76, 48, v172
	v_ashrrev_i32_e32 v77, 31, v76
	v_lshlrev_b64 v[76:77], 15, v[76:77]
	v_pk_mul_f32 v[78:79], v[82:83], v[162:163]
	v_pk_mul_f32 v[82:83], v[74:75], v[160:161]
	v_pk_mul_f32 v[74:75], v[72:73], v[156:157]
	v_lshl_add_u64 v[76:77], v[176:177], 0, v[76:77]
	v_cvt_pk_bf16_f32 v72, v80, v81
	v_cvt_pk_bf16_f32 v73, v78, v79
	v_cvt_pk_bf16_f32 v74, v74, v75
	v_cvt_pk_bf16_f32 v75, v82, v83
	global_store_dwordx4 v[76:77], v[72:75], off
	v_pk_mul_f32 v[60:61], v[60:61], v[158:159]
	v_pk_mul_f32 v[62:63], v[62:63], v[162:163]
	v_pk_mul_f32 v[72:73], v[66:67], v[152:153]
	v_pk_mul_f32 v[66:67], v[64:65], v[148:149]
	v_cvt_pk_bf16_f32 v64, v68, v69
	v_cvt_pk_bf16_f32 v65, v70, v71
	v_cvt_pk_bf16_f32 v66, v66, v67
	v_cvt_pk_bf16_f32 v67, v72, v73
	global_store_dwordx4 v[76:77], v[64:67], off offset:256
	v_pk_mul_f32 v[50:51], v[50:51], v[154:155]
	v_pk_mul_f32 v[48:49], v[48:49], v[150:151]
	v_pk_mul_f32 v[66:67], v[58:59], v[160:161]
	v_pk_mul_f32 v[58:59], v[56:57], v[156:157]
	v_cvt_pk_bf16_f32 v56, v60, v61
	v_add_co_u32_e32 v60, vcc, s33, v146
	v_cvt_pk_bf16_f32 v57, v62, v63
	v_cvt_pk_bf16_f32 v58, v58, v59
	v_cvt_pk_bf16_f32 v59, v66, v67
	v_addc_co_u32_e32 v61, vcc, 0, v147, vcc
	global_store_dwordx4 v[60:61], v[56:59], off
	v_lshl_add_u64 v[64:65], v[146:147], 0, s[34:35]
	v_pk_mul_f32 v[44:45], v[44:45], v[156:157]
	v_pk_mul_f32 v[56:57], v[42:43], v[152:153]
	v_pk_mul_f32 v[42:43], v[40:41], v[148:149]
	v_cvt_pk_bf16_f32 v40, v48, v49
	v_cvt_pk_bf16_f32 v41, v50, v51
	v_cvt_pk_bf16_f32 v42, v42, v43
	v_cvt_pk_bf16_f32 v43, v56, v57
	global_store_dwordx4 v[64:65], v[40:43], off offset:256
	v_pk_mul_f32 v[46:47], v[46:47], v[160:161]
	v_pk_mul_f32 v[34:35], v[34:35], v[154:155]
	v_pk_mul_f32 v[42:43], v[54:55], v[162:163]
	v_pk_mul_f32 v[40:41], v[52:53], v[158:159]
	v_pk_mul_f32 v[32:33], v[32:33], v[150:151]
	v_cvt_pk_bf16_f32 v40, v40, v41
	v_cvt_pk_bf16_f32 v41, v42, v43
	v_cvt_pk_bf16_f32 v42, v44, v45
	v_add_co_u32_e32 v44, vcc, s25, v146
	v_cvt_pk_bf16_f32 v43, v46, v47
	s_nop 0
	v_addc_co_u32_e32 v45, vcc, 0, v147, vcc
	global_store_dwordx4 v[44:45], v[40:43], off
	v_lshl_add_u64 v[48:49], v[146:147], 0, s[50:51]
	v_pk_mul_f32 v[28:29], v[28:29], v[156:157]
	v_pk_mul_f32 v[40:41], v[26:27], v[152:153]
	v_pk_mul_f32 v[26:27], v[24:25], v[148:149]
	v_cvt_pk_bf16_f32 v24, v32, v33
	v_cvt_pk_bf16_f32 v25, v34, v35
	v_cvt_pk_bf16_f32 v26, v26, v27
	v_cvt_pk_bf16_f32 v27, v40, v41
	global_store_dwordx4 v[48:49], v[24:27], off offset:256
	v_pk_mul_f32 v[30:31], v[30:31], v[160:161]
	v_pk_mul_f32 v[18:19], v[18:19], v[154:155]
	v_pk_mul_f32 v[26:27], v[38:39], v[162:163]
	v_pk_mul_f32 v[24:25], v[36:37], v[158:159]
	v_pk_mul_f32 v[16:17], v[16:17], v[150:151]
	v_cvt_pk_bf16_f32 v24, v24, v25
	v_cvt_pk_bf16_f32 v25, v26, v27
	v_cvt_pk_bf16_f32 v26, v28, v29
	v_add_co_u32_e32 v28, vcc, s30, v146
	v_cvt_pk_bf16_f32 v27, v30, v31
	s_nop 0
	v_addc_co_u32_e32 v29, vcc, 0, v147, vcc
	global_store_dwordx4 v[28:29], v[24:27], off
	v_lshl_add_u64 v[32:33], v[146:147], 0, s[52:53]
	v_pk_mul_f32 v[12:13], v[12:13], v[156:157]
	v_pk_mul_f32 v[24:25], v[10:11], v[152:153]
	v_pk_mul_f32 v[10:11], v[8:9], v[148:149]
	v_cvt_pk_bf16_f32 v8, v16, v17
	v_cvt_pk_bf16_f32 v9, v18, v19
	v_cvt_pk_bf16_f32 v10, v10, v11
	v_cvt_pk_bf16_f32 v11, v24, v25
	global_store_dwordx4 v[32:33], v[8:11], off offset:256
	v_pk_mul_f32 v[14:15], v[14:15], v[160:161]
	v_pk_mul_f32 v[6:7], v[6:7], v[154:155]
	v_pk_mul_f32 v[10:11], v[22:23], v[162:163]
	v_pk_mul_f32 v[8:9], v[20:21], v[158:159]
	v_pk_mul_f32 v[4:5], v[4:5], v[150:151]
	v_cvt_pk_bf16_f32 v8, v8, v9
	v_cvt_pk_bf16_f32 v9, v10, v11
	v_cvt_pk_bf16_f32 v10, v12, v13
	v_add_co_u32_e32 v12, vcc, s31, v146
	v_cvt_pk_bf16_f32 v11, v14, v15
	s_nop 0
	v_addc_co_u32_e32 v13, vcc, 0, v147, vcc
	global_store_dwordx4 v[12:13], v[8:11], off
	v_lshl_add_u64 v[16:17], v[146:147], 0, s[54:55]
	s_and_b64 vcc, exec, s[16:17]
	v_pk_mul_f32 v[8:9], v[2:3], v[152:153]
	v_pk_mul_f32 v[2:3], v[0:1], v[148:149]
	v_cvt_pk_bf16_f32 v0, v4, v5
	v_cvt_pk_bf16_f32 v1, v6, v7
	v_cvt_pk_bf16_f32 v2, v2, v3
	v_cvt_pk_bf16_f32 v3, v8, v9
	s_mov_b32 s33, s56
	global_store_dwordx4 v[16:17], v[0:3], off offset:256
	s_cbranch_vccz .LBB0_252
	s_waitcnt vmcnt(0)
	s_cmpk_gt_u32 s4, 0xff
	s_cbranch_scc1 .LBB0_263
	s_barrier

; #define PG8_BAR __builtin_amdgcn_s_barrier()
; template <class Epi>
; __device__ __forceinline__ void gemm_phase(LAS unsigned char* lds, const Gemm g, const StaticOrder& S, const Epi& E, int wv) {
;     ...
;         const bool has_next = S.next(ui + 1, nxt);
;         const char* nA = has_next ? (const char*)g.A + (size_t)nxt.pm * tstepA + ((g.adiag & 1) ? (size_t)(nxt.pn >> 1) * K * 2 : 0) + kbeg : cA;
;         const char* nB = has_next ? (const char*)g.Bt + (size_t)nxt.pn * tstepB + kbeg : cB;
;         for (int t = 0; t < nt; t += 2) {
;             const bool last = (t == nt - 2);
;             const char* a1 = cA + (ptrdiff_t)(t + 1) * kstep;
;             const char* a2 = last ? nA : cA + (ptrdiff_t)(t + 2) * kstep; const char* b2 = last ? nB : cB + (ptrdiff_t)(t + 2) * kstep;
;             const char* a3 = a2 + kstep; const char* b3 = b2 + kstep;
;             PG8_LDB(B0, 0, 0); PG8_SCHED; PG8_LDA(At, 0, 0); PG8_STAGE(PG8_SA(1, 1), a1 + hstepA, voffA);
;             PG8_WAIT_L(8); PG8_BAR; PG8_WAIT_L(0); PG8_MMA(0, 0, At, B0); PG8_BAR; PG8_SCHED;
;             PG8_LDB(B1, 0, 1); PG8_STAGE(PG8_SB(0, 0), b2, voffB);
;             PG8_BAR; PG8_WAIT_L(0); PG8_MMA(0, 1, At, B1); PG8_BAR;
;             PG8_LDA(At, 0, 1); PG8_STAGE(PG8_SA(0, 0), a2, voffA);
;             PG8_BAR; PG8_WAIT_L(0); PG8_MMA(1, 0, At, B0); PG8_BAR; PG8_SCHED;
;             PG8_STAGE(PG8_SB(0, 1), b2 + hstepB, voffB);
;             PG8_WAIT_V(6); PG8_BAR; PG8_MMA(1, 1, At, B1); PG8_BAR;
;             PG8_LDB(B0, 1, 0); PG8_SCHED; PG8_LDA(At, 1, 0); PG8_STAGE(PG8_SA(0, 1), a2 + hstepA, voffA);
;             PG8_WAIT_L(8); PG8_BAR; PG8_WAIT_L(0); PG8_MMA(0, 0, At, B0); PG8_BAR; PG8_SCHED;
;             PG8_LDB(B1, 1, 1); PG8_STAGE(PG8_SB(1, 0), b3, voffB);
;             PG8_BAR; PG8_WAIT_L(0); PG8_MMA(0, 1, At, B1); PG8_BAR;
;             PG8_LDA(At, 1, 1); PG8_STAGE(PG8_SA(1, 0), a3, voffA);
;             PG8_BAR; PG8_WAIT_L(0); PG8_MMA(1, 0, At, B0); PG8_BAR; PG8_SCHED;
;             PG8_STAGE(PG8_SB(1, 1), b3 + hstepB, voffB);
;             PG8_WAIT_V(6); PG8_BAR; PG8_MMA(1, 1, At, B1); PG8_BAR;
;         }
;         E(acc, cur, wr, wc, fr, fq);
;         if (!has_next) break;
; #pragma unroll
;         for (int a = 0; a < 2; ++a)
; #pragma unroll
;             for (int b = 0; b < 2; ++b)
; #pragma unroll
;                 for (int m = 0; m < 4; ++m)
; #pragma unroll
.LBB0_442:
	s_ashr_i32 s61, s60, 31
	s_lshl_b64 s[34:35], s[60:61], 20
	v_cmp_lt_i64_e32 vcc, s[62:63], v[156:157]
	s_add_u32 s62, s5, s34
	s_addc_u32 s63, s6, s35
	s_and_b64 s[34:35], vcc, exec
	s_cselect_b32 s33, s63, s71
	s_cselect_b32 s34, s62, s70
	s_ashr_i32 s59, s58, 31
	s_lshl_b64 s[38:39], s[58:59], 20
	s_add_u32 s64, s7, s38
	s_addc_u32 s65, s8, s39
	s_and_b64 s[38:39], vcc, exec
	s_cselect_b32 s35, s65, s73
	s_cselect_b32 s38, s64, s72
	s_add_u32 s39, s72, 0x100
	s_addc_u32 s40, s73, 0
	s_add_u32 s70, s70, 0x80080
	v_mov_b32_e32 v0, 0
	s_addc_u32 s71, s71, 0
	s_mov_b32 s41, -2
	s_waitcnt lgkmcnt(0)
	v_mov_b32_e32 v1, v0
	v_mov_b32_e32 v2, v0
	v_mov_b32_e32 v3, v0
	v_mov_b32_e32 v4, v0
	v_mov_b32_e32 v5, v0
	v_mov_b32_e32 v6, v0
	v_mov_b32_e32 v7, v0
	v_mov_b32_e32 v16, v0
	v_mov_b32_e32 v17, v0
	v_mov_b32_e32 v18, v0
	v_mov_b32_e32 v19, v0
	v_mov_b32_e32 v20, v0
	v_mov_b32_e32 v21, v0
	v_mov_b32_e32 v22, v0
	v_mov_b32_e32 v23, v0
	v_mov_b32_e32 v32, v0
	v_mov_b32_e32 v33, v0
	v_mov_b32_e32 v34, v0
	v_mov_b32_e32 v35, v0
	v_mov_b32_e32 v36, v0
	v_mov_b32_e32 v37, v0
	v_mov_b32_e32 v38, v0
	v_mov_b32_e32 v39, v0
	v_mov_b32_e32 v48, v0
	v_mov_b32_e32 v49, v0
	v_mov_b32_e32 v50, v0
	v_mov_b32_e32 v51, v0
	v_mov_b32_e32 v52, v0
	v_mov_b32_e32 v53, v0
	v_mov_b32_e32 v54, v0
	v_mov_b32_e32 v55, v0
	v_mov_b32_e32 v8, v0
	v_mov_b32_e32 v9, v0
	v_mov_b32_e32 v10, v0
	v_mov_b32_e32 v11, v0
	v_mov_b32_e32 v12, v0
	v_mov_b32_e32 v13, v0
	v_mov_b32_e32 v14, v0
	v_mov_b32_e32 v15, v0
	v_mov_b32_e32 v24, v0
	v_mov_b32_e32 v25, v0
	v_mov_b32_e32 v26, v0
	v_mov_b32_e32 v27, v0
	v_mov_b32_e32 v28, v0
	v_mov_b32_e32 v29, v0
	v_mov_b32_e32 v30, v0
	v_mov_b32_e32 v31, v0
	v_mov_b32_e32 v40, v0
	v_mov_b32_e32 v41, v0
	v_mov_b32_e32 v42, v0
	v_mov_b32_e32 v43, v0
	v_mov_b32_e32 v44, v0
	v_mov_b32_e32 v45, v0
	v_mov_b32_e32 v46, v0
	v_mov_b32_e32 v47, v0
	v_mov_b32_e32 v56, v0
	v_mov_b32_e32 v57, v0
	v_mov_b32_e32 v58, v0
	v_mov_b32_e32 v59, v0
	v_mov_b32_e32 v60, v0
	v_mov_b32_e32 v61, v0
	v_mov_b32_e32 v62, v0
	v_mov_b32_e32 v63, v0
	v_mov_b32_e32 v64, v0
	v_mov_b32_e32 v65, v0
	v_mov_b32_e32 v66, v0
	v_mov_b32_e32 v67, v0
	v_mov_b32_e32 v68, v0
	v_mov_b32_e32 v69, v0
	v_mov_b32_e32 v70, v0
	v_mov_b32_e32 v71, v0
	v_mov_b32_e32 v80, v0
	v_mov_b32_e32 v81, v0
	v_mov_b32_e32 v82, v0
	v_mov_b32_e32 v83, v0
	v_mov_b32_e32 v84, v0
	v_mov_b32_e32 v85, v0
	v_mov_b32_e32 v86, v0
	v_mov_b32_e32 v87, v0
	v_mov_b32_e32 v96, v0
	v_mov_b32_e32 v97, v0
	v_mov_b32_e32 v98, v0
	v_mov_b32_e32 v99, v0
	v_mov_b32_e32 v100, v0
	v_mov_b32_e32 v101, v0
	v_mov_b32_e32 v102, v0
	v_mov_b32_e32 v103, v0
	v_mov_b32_e32 v112, v0
	v_mov_b32_e32 v113, v0
	v_mov_b32_e32 v114, v0
	v_mov_b32_e32 v115, v0
	v_mov_b32_e32 v116, v0
	v_mov_b32_e32 v117, v0
	v_mov_b32_e32 v118, v0
	v_mov_b32_e32 v119, v0
	v_mov_b32_e32 v72, v0
	v_mov_b32_e32 v73, v0
	v_mov_b32_e32 v74, v0
	v_mov_b32_e32 v75, v0
	v_mov_b32_e32 v76, v0
	v_mov_b32_e32 v77, v0
	v_mov_b32_e32 v78, v0
	v_mov_b32_e32 v79, v0
	v_mov_b32_e32 v88, v0
	v_mov_b32_e32 v89, v0
	v_mov_b32_e32 v90, v0
	v_mov_b32_e32 v91, v0
	v_mov_b32_e32 v92, v0
	v_mov_b32_e32 v93, v0
	v_mov_b32_e32 v94, v0
	v_mov_b32_e32 v95, v0
	v_mov_b32_e32 v104, v0
	v_mov_b32_e32 v105, v0
	v_mov_b32_e32 v106, v0
	v_mov_b32_e32 v107, v0
	v_mov_b32_e32 v108, v0
	v_mov_b32_e32 v109, v0
	v_mov_b32_e32 v110, v0
	v_mov_b32_e32 v111, v0
	v_mov_b32_e32 v120, v0
	v_mov_b32_e32 v121, v0
	v_mov_b32_e32 v122, v0
	v_mov_b32_e32 v123, v0
	v_mov_b32_e32 v124, v0
	v_mov_b32_e32 v125, v0
	v_mov_b32_e32 v126, v0
	v_mov_b32_e32 v127, v0
	ds_read_b128 v[128:131], v179
	ds_read_b128 v[132:135], v179 offset:1024
	ds_read_b128 v[136:139], v179 offset:2048
	ds_read_b128 v[140:143], v179 offset:3072
	s_branch .Lrot_in_443
.LBB0_443:
	s_barrier
	v_mfma_f32_16x16x32_bf16 v[52:55], v[198:201], v[160:163], v[52:55]
	v_mfma_f32_16x16x32_bf16 v[48:51], v[206:209], v[160:163], v[48:51]
	v_mfma_f32_16x16x32_bf16 v[36:39], v[198:201], v[168:171], v[36:39]
	v_mfma_f32_16x16x32_bf16 v[32:35], v[206:209], v[168:171], v[32:35]
	v_mfma_f32_16x16x32_bf16 v[20:23], v[198:201], v[182:185], v[20:23]
	v_mfma_f32_16x16x32_bf16 v[16:19], v[206:209], v[182:185], v[16:19]
	v_mfma_f32_16x16x32_bf16 v[4:7], v[198:201], v[190:193], v[4:7]
	v_mfma_f32_16x16x32_bf16 v[0:3], v[206:209], v[190:193], v[0:3]
	v_mfma_f32_16x16x32_bf16 v[52:55], v[202:205], v[164:167], v[52:55]
	v_mfma_f32_16x16x32_bf16 v[48:51], v[210:213], v[164:167], v[48:51]
	v_mfma_f32_16x16x32_bf16 v[36:39], v[202:205], v[172:175], v[36:39]
	v_mfma_f32_16x16x32_bf16 v[32:35], v[210:213], v[172:175], v[32:35]
	v_mfma_f32_16x16x32_bf16 v[20:23], v[202:205], v[186:189], v[20:23]
	v_mfma_f32_16x16x32_bf16 v[16:19], v[210:213], v[186:189], v[16:19]
	v_mfma_f32_16x16x32_bf16 v[4:7], v[202:205], v[194:197], v[4:7]
	v_mfma_f32_16x16x32_bf16 v[0:3], v[210:213], v[194:197], v[0:3]
	s_waitcnt lgkmcnt(0)
	s_add_i32 s41, s41, 2
	s_add_u32 s39, s39, 0x100
	s_addc_u32 s40, s40, 0
	s_add_u32 s70, s70, 0x100
	s_addc_u32 s71, s71, 0
	s_cmp_gt_u32 s41, 29
	s_barrier
	s_cbranch_scc1 .Lrot_out_443
; #define PG8_STAGE(bufoff, gbase, voff) do { _Pragma("unroll") for (int _i = 0; _i < 2; ++_i) \
;         __builtin_amdgcn_global_load_lds((const unsigned*)((const char*)(gbase) + (voff)[_i]), (LAS unsigned*)(lds + (bufoff) + ldsw + _i * 8192), 16, 0, 0); } while (0)
; #define PG8_LDA(dst, b, h) do { _Pragma("unroll") for (int m = 0; m < 4; ++m) _Pragma("unroll") for (int k = 0; k < 2; ++k) dst[m][k] = *(const LAS bf16x8*)(lds + PG8_SA(b, h) + aoff + m * 2048 + k * 1024); } while (0)
; #define PG8_LDB(dst, b, h) do { _Pragma("unroll") for (int n = 0; n < 2; ++n) _Pragma("unroll") for (int k = 0; k < 2; ++k) dst[n][k] = *(const LAS bf16x8*)(lds + PG8_SB(b, h) + boff + n * 2048 + k * 1024); } while (0)
; #define PG8_MMA(ai, bj, At, Bt) do { __builtin_amdgcn_s_setprio(1); _Pragma("unroll") for (int m = 0; m < 4; ++m) _Pragma("unroll") for (int n = 0; n < 2; ++n) _Pragma("unroll") for (int k = 0; k < 2; ++k) \
;         acc[ai][bj][m][n] = __builtin_amdgcn_mfma_f32_16x16x32_bf16(Bt[n][k], At[m][k], acc[ai][bj][m][n], 0, 0, 0); __builtin_amdgcn_s_setprio(0); } while (0)
; #define PG8_WAIT_V(n) asm volatile("s_waitcnt vmcnt(" #n ")" ::: "memory")
; #define PG8_WAIT_L(n) asm volatile("s_waitcnt lgkmcnt(" #n ")" ::: "memory")
; #define PG8_BAR __builtin_amdgcn_s_barrier()
; template <class Epi>
; __device__ __forceinline__ void gemm_phase(LAS unsigned char* lds, const Gemm g, const StaticOrder& S, const Epi& E, int wv) {
;     ...
;             const bool last = (t == nt - 2);
;             const char* a1 = cA + (ptrdiff_t)(t + 1) * kstep;
;             const char* a2 = last ? nA : cA + (ptrdiff_t)(t + 2) * kstep; const char* b2 = last ? nB : cB + (ptrdiff_t)(t + 2) * kstep;
;             const char* a3 = a2 + kstep; const char* b3 = b2 + kstep;
;             PG8_LDB(B0, 0, 0); PG8_SCHED; PG8_LDA(At, 0, 0); PG8_STAGE(PG8_SA(1, 1), a1 + hstepA, voffA);
;             PG8_WAIT_L(8); PG8_BAR; PG8_WAIT_L(0); PG8_MMA(0, 0, At, B0); PG8_BAR; PG8_SCHED;
;             PG8_LDB(B1, 0, 1); PG8_STAGE(PG8_SB(0, 0), b2, voffB);
;             PG8_BAR; PG8_WAIT_L(0); PG8_MMA(0, 1, At, B1); PG8_BAR;
;             PG8_LDA(At, 0, 1); PG8_STAGE(PG8_SA(0, 0), a2, voffA);
;             PG8_BAR; PG8_WAIT_L(0); PG8_MMA(1, 0, At, B0); PG8_BAR; PG8_SCHED;
;             PG8_STAGE(PG8_SB(0, 1), b2 + hstepB, voffB);
;             PG8_WAIT_V(6); PG8_BAR; PG8_MMA(1, 1, At, B1); PG8_BAR;
.Lrot_in_443:
	s_add_u32 s42, s70, 0xfff80080
	s_addc_u32 s43, s71, -1
	s_cmp_eq_u32 s41, 28
	s_cselect_b32 s75, s33, s43
	s_cselect_b32 s74, s34, s42
	s_cselect_b32 s73, s35, s40
	s_cselect_b32 s72, s38, s39
	s_add_i32 m0, s10, 0xc000
	ds_read_b128 v[160:163], v180
	ds_read_b128 v[164:167], v180 offset:1024
	ds_read_b128 v[168:171], v180 offset:2048
	ds_read_b128 v[172:175], v180 offset:3072
	ds_read_b128 v[182:185], v180 offset:4096
	ds_read_b128 v[186:189], v180 offset:5120
	ds_read_b128 v[190:193], v180 offset:6144
	ds_read_b128 v[194:197], v180 offset:7168
	global_load_lds_dwordx4 v154, s[70:71]
	s_add_i32 m0, s10, 0xe000
	s_nop 0
	global_load_lds_dwordx4 v152, s[70:71]
	s_waitcnt lgkmcnt(8)
	s_barrier
	s_waitcnt lgkmcnt(0)
	s_waitcnt lgkmcnt(0)
	v_mfma_f32_16x16x32_bf16 v[124:127], v[128:131], v[160:163], v[124:127]
	v_mfma_f32_16x16x32_bf16 v[120:123], v[136:139], v[160:163], v[120:123]
	v_mfma_f32_16x16x32_bf16 v[108:111], v[128:131], v[168:171], v[108:111]
	v_mfma_f32_16x16x32_bf16 v[104:107], v[136:139], v[168:171], v[104:107]
	v_mfma_f32_16x16x32_bf16 v[92:95], v[128:131], v[182:185], v[92:95]
	v_mfma_f32_16x16x32_bf16 v[88:91], v[136:139], v[182:185], v[88:91]
	v_mfma_f32_16x16x32_bf16 v[76:79], v[128:131], v[190:193], v[76:79]
	v_mfma_f32_16x16x32_bf16 v[72:75], v[136:139], v[190:193], v[72:75]
	v_mfma_f32_16x16x32_bf16 v[124:127], v[132:135], v[164:167], v[124:127]
	v_mfma_f32_16x16x32_bf16 v[120:123], v[140:143], v[164:167], v[120:123]
	v_mfma_f32_16x16x32_bf16 v[108:111], v[132:135], v[172:175], v[108:111]
	v_mfma_f32_16x16x32_bf16 v[104:107], v[140:143], v[172:175], v[104:107]
	v_mfma_f32_16x16x32_bf16 v[92:95], v[132:135], v[186:189], v[92:95]
	v_mfma_f32_16x16x32_bf16 v[88:91], v[140:143], v[186:189], v[88:91]
	v_mfma_f32_16x16x32_bf16 v[76:79], v[132:135], v[194:197], v[76:79]
	v_mfma_f32_16x16x32_bf16 v[72:75], v[140:143], v[194:197], v[72:75]
	s_barrier
	s_add_i32 s42, s23, s9
	s_add_u32 s98, s72, s54
	s_addc_u32 s99, s73, s55
	s_mov_b32 m0, s42
	ds_read_b128 v[198:201], v181
	ds_read_b128 v[202:205], v181 offset:1024
	ds_read_b128 v[206:209], v181 offset:2048
	ds_read_b128 v[210:213], v181 offset:3072
	global_load_lds_dwordx4 v146, s[72:73]
	s_add_i32 m0, s42, 0x2000
	s_nop 0
	global_load_lds_dwordx4 v150, s[72:73]
	s_barrier
	s_waitcnt lgkmcnt(0)
	s_waitcnt lgkmcnt(0)
	v_mfma_f32_16x16x32_bf16 v[116:119], v[198:201], v[160:163], v[116:119]
	v_mfma_f32_16x16x32_bf16 v[112:115], v[206:209], v[160:163], v[112:115]
	v_mfma_f32_16x16x32_bf16 v[100:103], v[198:201], v[168:171], v[100:103]
	v_mfma_f32_16x16x32_bf16 v[96:99], v[206:209], v[168:171], v[96:99]
	v_mfma_f32_16x16x32_bf16 v[84:87], v[198:201], v[182:185], v[84:87]
	v_mfma_f32_16x16x32_bf16 v[80:83], v[206:209], v[182:185], v[80:83]
	v_mfma_f32_16x16x32_bf16 v[68:71], v[198:201], v[190:193], v[68:71]
	v_mfma_f32_16x16x32_bf16 v[64:67], v[206:209], v[190:193], v[64:67]
	v_mfma_f32_16x16x32_bf16 v[116:119], v[202:205], v[164:167], v[116:119]
	v_mfma_f32_16x16x32_bf16 v[112:115], v[210:213], v[164:167], v[112:115]
	v_mfma_f32_16x16x32_bf16 v[100:103], v[202:205], v[172:175], v[100:103]
	v_mfma_f32_16x16x32_bf16 v[96:99], v[210:213], v[172:175], v[96:99]
	v_mfma_f32_16x16x32_bf16 v[84:87], v[202:205], v[186:189], v[84:87]
	v_mfma_f32_16x16x32_bf16 v[80:83], v[210:213], v[186:189], v[80:83]
	v_mfma_f32_16x16x32_bf16 v[68:71], v[202:205], v[194:197], v[68:71]
	v_mfma_f32_16x16x32_bf16 v[64:67], v[210:213], v[194:197], v[64:67]
	s_mov_b32 m0, s10
	s_add_u32 s100, s74, s54
	s_addc_u32 s101, s75, s55
	s_barrier
	ds_read_b128 v[160:163], v180 offset:16384
	ds_read_b128 v[164:167], v180 offset:17408
	ds_read_b128 v[168:171], v180 offset:18432
	ds_read_b128 v[172:175], v180 offset:19456
	ds_read_b128 v[182:185], v180 offset:20480
	ds_read_b128 v[186:189], v180 offset:21504
	ds_read_b128 v[190:193], v180 offset:22528
	ds_read_b128 v[194:197], v180 offset:23552
	global_load_lds_dwordx4 v144, s[74:75]
	s_mov_b32 m0, s11
	s_nop 0
	global_load_lds_dwordx4 v148, s[74:75]
	s_waitcnt vmcnt(10)
	s_barrier
	s_waitcnt lgkmcnt(0)
	s_waitcnt lgkmcnt(0)
	v_mfma_f32_16x16x32_bf16 v[60:63], v[128:131], v[160:163], v[60:63]
	v_mfma_f32_16x16x32_bf16 v[56:59], v[136:139], v[160:163], v[56:59]
	v_mfma_f32_16x16x32_bf16 v[44:47], v[128:131], v[168:171], v[44:47]
	v_mfma_f32_16x16x32_bf16 v[40:43], v[136:139], v[168:171], v[40:43]
	v_mfma_f32_16x16x32_bf16 v[28:31], v[128:131], v[182:185], v[28:31]
	v_mfma_f32_16x16x32_bf16 v[24:27], v[136:139], v[182:185], v[24:27]
	v_mfma_f32_16x16x32_bf16 v[12:15], v[128:131], v[190:193], v[12:15]
	v_mfma_f32_16x16x32_bf16 v[8:11], v[136:139], v[190:193], v[8:11]
	v_mfma_f32_16x16x32_bf16 v[60:63], v[132:135], v[164:167], v[60:63]
	v_mfma_f32_16x16x32_bf16 v[56:59], v[140:143], v[164:167], v[56:59]
	v_mfma_f32_16x16x32_bf16 v[44:47], v[132:135], v[172:175], v[44:47]
	v_mfma_f32_16x16x32_bf16 v[40:43], v[140:143], v[172:175], v[40:43]
	v_mfma_f32_16x16x32_bf16 v[28:31], v[132:135], v[186:189], v[28:31]
	v_mfma_f32_16x16x32_bf16 v[24:27], v[140:143], v[186:189], v[24:27]
	v_mfma_f32_16x16x32_bf16 v[12:15], v[132:135], v[194:197], v[12:15]
	v_mfma_f32_16x16x32_bf16 v[8:11], v[140:143], v[194:197], v[8:11]
	s_barrier
	s_add_u32 s42, s72, 0x80000
	s_addc_u32 s43, s73, 0
	s_add_i32 s44, s24, s9
	s_mov_b32 m0, s44
	s_nop 0
	global_load_lds_dwordx4 v146, s[42:43]
	s_add_i32 m0, s44, 0x2000
	s_nop 0
	global_load_lds_dwordx4 v150, s[42:43]
	s_add_i32 s44, 0, 0x18000
	v_add_u32_e32 v140, s44, v177
	ds_read_b128 v[128:131], v140
	ds_read_b128 v[132:135], v140 offset:1024
	ds_read_b128 v[136:139], v140 offset:2048
	ds_read_b128 v[140:143], v140 offset:3072
	s_waitcnt vmcnt(6)
	s_barrier
; #define PG8_STAGE(bufoff, gbase, voff) do { _Pragma("unroll") for (int _i = 0; _i < 2; ++_i) \
;         __builtin_amdgcn_global_load_lds((const unsigned*)((const char*)(gbase) + (voff)[_i]), (LAS unsigned*)(lds + (bufoff) + ldsw + _i * 8192), 16, 0, 0); } while (0)
; #define PG8_LDA(dst, b, h) do { _Pragma("unroll") for (int m = 0; m < 4; ++m) _Pragma("unroll") for (int k = 0; k < 2; ++k) dst[m][k] = *(const LAS bf16x8*)(lds + PG8_SA(b, h) + aoff + m * 2048 + k * 1024); } while (0)
; #define PG8_LDB(dst, b, h) do { _Pragma("unroll") for (int n = 0; n < 2; ++n) _Pragma("unroll") for (int k = 0; k < 2; ++k) dst[n][k] = *(const LAS bf16x8*)(lds + PG8_SB(b, h) + boff + n * 2048 + k * 1024); } while (0)
; #define PG8_MMA(ai, bj, At, Bt) do { __builtin_amdgcn_s_setprio(1); _Pragma("unroll") for (int m = 0; m < 4; ++m) _Pragma("unroll") for (int n = 0; n < 2; ++n) _Pragma("unroll") for (int k = 0; k < 2; ++k) \
;         acc[ai][bj][m][n] = __builtin_amdgcn_mfma_f32_16x16x32_bf16(Bt[n][k], At[m][k], acc[ai][bj][m][n], 0, 0, 0); __builtin_amdgcn_s_setprio(0); } while (0)
; #define PG8_WAIT_V(n) asm volatile("s_waitcnt vmcnt(" #n ")" ::: "memory")
; #define PG8_WAIT_L(n) asm volatile("s_waitcnt lgkmcnt(" #n ")" ::: "memory")
; #define PG8_BAR __builtin_amdgcn_s_barrier()
; #define PG8_SCHED __builtin_amdgcn_sched_barrier(0)
; template <class Epi>
; __device__ __forceinline__ void gemm_phase(LAS unsigned char* lds, const Gemm g, const StaticOrder& S, const Epi& E, int wv) {
;     ...
;             PG8_WAIT_V(6); PG8_BAR; PG8_MMA(1, 1, At, B1); PG8_BAR;
;             PG8_LDB(B0, 1, 0); PG8_SCHED; PG8_LDA(At, 1, 0); PG8_STAGE(PG8_SA(0, 1), a2 + hstepA, voffA);
;             PG8_WAIT_L(8); PG8_BAR; PG8_WAIT_L(0); PG8_MMA(0, 0, At, B0); PG8_BAR; PG8_SCHED;
;             PG8_LDB(B1, 1, 1); PG8_STAGE(PG8_SB(1, 0), b3, voffB);
;             PG8_BAR; PG8_WAIT_L(0); PG8_MMA(0, 1, At, B1); PG8_BAR;
;             PG8_LDA(At, 1, 1); PG8_STAGE(PG8_SA(1, 0), a3, voffA);
;             PG8_BAR; PG8_WAIT_L(0); PG8_MMA(1, 0, At, B0); PG8_BAR; PG8_SCHED;
;             PG8_STAGE(PG8_SB(1, 1), b3 + hstepB, voffB);
;             PG8_WAIT_V(6); PG8_BAR; PG8_MMA(1, 1, At, B1); PG8_BAR;
	v_mfma_f32_16x16x32_bf16 v[52:55], v[198:201], v[160:163], v[52:55]
	v_mfma_f32_16x16x32_bf16 v[48:51], v[206:209], v[160:163], v[48:51]
	v_mfma_f32_16x16x32_bf16 v[36:39], v[198:201], v[168:171], v[36:39]
	v_mfma_f32_16x16x32_bf16 v[32:35], v[206:209], v[168:171], v[32:35]
	v_mfma_f32_16x16x32_bf16 v[20:23], v[198:201], v[182:185], v[20:23]
	v_mfma_f32_16x16x32_bf16 v[16:19], v[206:209], v[182:185], v[16:19]
	v_mfma_f32_16x16x32_bf16 v[4:7], v[198:201], v[190:193], v[4:7]
	v_mfma_f32_16x16x32_bf16 v[0:3], v[206:209], v[190:193], v[0:3]
	v_mfma_f32_16x16x32_bf16 v[52:55], v[202:205], v[164:167], v[52:55]
	v_mfma_f32_16x16x32_bf16 v[48:51], v[210:213], v[164:167], v[48:51]
	v_mfma_f32_16x16x32_bf16 v[36:39], v[202:205], v[172:175], v[36:39]
	v_mfma_f32_16x16x32_bf16 v[32:35], v[210:213], v[172:175], v[32:35]
	v_mfma_f32_16x16x32_bf16 v[20:23], v[202:205], v[186:189], v[20:23]
	v_mfma_f32_16x16x32_bf16 v[16:19], v[210:213], v[186:189], v[16:19]
	v_mfma_f32_16x16x32_bf16 v[4:7], v[202:205], v[194:197], v[4:7]
	v_mfma_f32_16x16x32_bf16 v[0:3], v[210:213], v[194:197], v[0:3]
	s_waitcnt lgkmcnt(0)
	s_barrier
	s_add_u32 s42, s74, 0x80000
	s_addc_u32 s43, s75, 0
	s_mov_b32 m0, s12
	ds_read_b128 v[160:163], v180 offset:32768
	ds_read_b128 v[164:167], v180 offset:33792
	ds_read_b128 v[168:171], v180 offset:34816
	ds_read_b128 v[172:175], v180 offset:35840
	ds_read_b128 v[182:185], v180 offset:36864
	ds_read_b128 v[186:189], v180 offset:37888
	ds_read_b128 v[190:193], v180 offset:38912
	ds_read_b128 v[194:197], v180 offset:39936
	global_load_lds_dwordx4 v144, s[42:43]
	s_mov_b32 m0, s13
	s_nop 0
	global_load_lds_dwordx4 v148, s[42:43]
	s_waitcnt lgkmcnt(8)
	s_barrier
	s_waitcnt lgkmcnt(0)
	s_waitcnt lgkmcnt(0)
	v_mfma_f32_16x16x32_bf16 v[124:127], v[128:131], v[160:163], v[124:127]
	v_mfma_f32_16x16x32_bf16 v[120:123], v[136:139], v[160:163], v[120:123]
	v_mfma_f32_16x16x32_bf16 v[108:111], v[128:131], v[168:171], v[108:111]
	v_mfma_f32_16x16x32_bf16 v[104:107], v[136:139], v[168:171], v[104:107]
	v_mfma_f32_16x16x32_bf16 v[92:95], v[128:131], v[182:185], v[92:95]
	v_mfma_f32_16x16x32_bf16 v[88:91], v[136:139], v[182:185], v[88:91]
	v_mfma_f32_16x16x32_bf16 v[76:79], v[128:131], v[190:193], v[76:79]
	v_mfma_f32_16x16x32_bf16 v[72:75], v[136:139], v[190:193], v[72:75]
	v_mfma_f32_16x16x32_bf16 v[124:127], v[132:135], v[164:167], v[124:127]
	v_mfma_f32_16x16x32_bf16 v[120:123], v[140:143], v[164:167], v[120:123]
	v_mfma_f32_16x16x32_bf16 v[108:111], v[132:135], v[172:175], v[108:111]
	v_mfma_f32_16x16x32_bf16 v[104:107], v[140:143], v[172:175], v[104:107]
	v_mfma_f32_16x16x32_bf16 v[92:95], v[132:135], v[186:189], v[92:95]
	v_mfma_f32_16x16x32_bf16 v[88:91], v[140:143], v[186:189], v[88:91]
	v_mfma_f32_16x16x32_bf16 v[76:79], v[132:135], v[194:197], v[76:79]
	v_mfma_f32_16x16x32_bf16 v[72:75], v[140:143], v[194:197], v[72:75]
	s_barrier
	s_add_i32 s45, 0, 0x1c000
	s_add_i32 s42, s44, s9
	v_add_u32_e32 v210, s45, v177
	s_mov_b32 m0, s42
	ds_read_b128 v[198:201], v210
	ds_read_b128 v[202:205], v210 offset:1024
	ds_read_b128 v[206:209], v210 offset:2048
	ds_read_b128 v[210:213], v210 offset:3072
	global_load_lds_dwordx4 v146, s[98:99]
	s_add_i32 m0, s42, 0x2000
	s_nop 0
	global_load_lds_dwordx4 v150, s[98:99]
	s_barrier
	s_waitcnt lgkmcnt(0)
	s_waitcnt lgkmcnt(0)
	v_mfma_f32_16x16x32_bf16 v[116:119], v[198:201], v[160:163], v[116:119]
	v_mfma_f32_16x16x32_bf16 v[112:115], v[206:209], v[160:163], v[112:115]
	v_mfma_f32_16x16x32_bf16 v[100:103], v[198:201], v[168:171], v[100:103]
	v_mfma_f32_16x16x32_bf16 v[96:99], v[206:209], v[168:171], v[96:99]
	v_mfma_f32_16x16x32_bf16 v[84:87], v[198:201], v[182:185], v[84:87]
	v_mfma_f32_16x16x32_bf16 v[80:83], v[206:209], v[182:185], v[80:83]
	v_mfma_f32_16x16x32_bf16 v[68:71], v[198:201], v[190:193], v[68:71]
	v_mfma_f32_16x16x32_bf16 v[64:67], v[206:209], v[190:193], v[64:67]
	v_mfma_f32_16x16x32_bf16 v[116:119], v[202:205], v[164:167], v[116:119]
	v_mfma_f32_16x16x32_bf16 v[112:115], v[210:213], v[164:167], v[112:115]
	v_mfma_f32_16x16x32_bf16 v[100:103], v[202:205], v[172:175], v[100:103]
	v_mfma_f32_16x16x32_bf16 v[96:99], v[210:213], v[172:175], v[96:99]
	v_mfma_f32_16x16x32_bf16 v[84:87], v[202:205], v[186:189], v[84:87]
	v_mfma_f32_16x16x32_bf16 v[80:83], v[210:213], v[186:189], v[80:83]
	v_mfma_f32_16x16x32_bf16 v[68:71], v[202:205], v[194:197], v[68:71]
	v_mfma_f32_16x16x32_bf16 v[64:67], v[210:213], v[194:197], v[64:67]
	s_mov_b32 m0, s15
	s_barrier
	ds_read_b128 v[160:163], v180 offset:49152
	ds_read_b128 v[164:167], v180 offset:50176
	ds_read_b128 v[168:171], v180 offset:51200
	ds_read_b128 v[172:175], v180 offset:52224
	ds_read_b128 v[182:185], v180 offset:53248
	ds_read_b128 v[186:189], v180 offset:54272
	ds_read_b128 v[190:193], v180 offset:55296
	ds_read_b128 v[194:197], v180 offset:56320
	global_load_lds_dwordx4 v144, s[100:101]
	s_mov_b32 m0, s22
	s_nop 0
	global_load_lds_dwordx4 v148, s[100:101]
	s_waitcnt vmcnt(10)
	s_barrier
	s_waitcnt lgkmcnt(0)
	s_waitcnt lgkmcnt(0)
	v_mfma_f32_16x16x32_bf16 v[60:63], v[128:131], v[160:163], v[60:63]
	v_mfma_f32_16x16x32_bf16 v[56:59], v[136:139], v[160:163], v[56:59]
	v_mfma_f32_16x16x32_bf16 v[44:47], v[128:131], v[168:171], v[44:47]
	v_mfma_f32_16x16x32_bf16 v[40:43], v[136:139], v[168:171], v[40:43]
	v_mfma_f32_16x16x32_bf16 v[28:31], v[128:131], v[182:185], v[28:31]
	v_mfma_f32_16x16x32_bf16 v[24:27], v[136:139], v[182:185], v[24:27]
	v_mfma_f32_16x16x32_bf16 v[12:15], v[128:131], v[190:193], v[12:15]
	v_mfma_f32_16x16x32_bf16 v[8:11], v[136:139], v[190:193], v[8:11]
	v_mfma_f32_16x16x32_bf16 v[60:63], v[132:135], v[164:167], v[60:63]
	v_mfma_f32_16x16x32_bf16 v[56:59], v[140:143], v[164:167], v[56:59]
	v_mfma_f32_16x16x32_bf16 v[44:47], v[132:135], v[172:175], v[44:47]
	v_mfma_f32_16x16x32_bf16 v[40:43], v[140:143], v[172:175], v[40:43]
	v_mfma_f32_16x16x32_bf16 v[28:31], v[132:135], v[186:189], v[28:31]
	v_mfma_f32_16x16x32_bf16 v[24:27], v[140:143], v[186:189], v[24:27]
	v_mfma_f32_16x16x32_bf16 v[12:15], v[132:135], v[194:197], v[12:15]
	v_mfma_f32_16x16x32_bf16 v[8:11], v[140:143], v[194:197], v[8:11]
	s_barrier
	s_add_u32 s42, s72, 0x80080
	s_addc_u32 s43, s73, 0
	s_add_i32 s44, s45, s9
	s_mov_b32 m0, s44
	s_nop 0
	global_load_lds_dwordx4 v146, s[42:43]
	s_add_i32 m0, s44, 0x2000
	s_nop 0
	global_load_lds_dwordx4 v150, s[42:43]
	ds_read_b128 v[128:131], v179
	ds_read_b128 v[132:135], v179 offset:1024
	ds_read_b128 v[136:139], v179 offset:2048
	ds_read_b128 v[140:143], v179 offset:3072
	s_waitcnt vmcnt(6)
	s_branch .LBB0_443
;     __device__ __forceinline__ void operator()(const f32x4 (&acc)[2][2][4][2], const Unit& u, int wr, int wc, int fr, int fq) const {
;         const int row0 = u.pm * BM + wr * 64 + fr, col0 = u.pn * BM + wc * 32 + 8 * fq;
;         constexpr int RD = 3;
;         f32x4 hbuf[RD][4]; u32x4 hraw[RD][2]; u32x4 pbuf[RD][2]; float rsb[RD];
;     ...
;         RES_LOAD(0, 0); RES_LOAD(1, 1);
; #pragma unroll
;         for (int it = 0; it < 8; ++it) { const int ai = it >> 2, m = it & 3, sc = it % RD;
;             if (it + RD - 1 < 8) RES_LOAD((it + RD - 1) % RD, it + RD - 1);
;             asm volatile("" ::: "memory");
;             const int row = row0 + ai * HALF + m * 16; const size_t ro = (size_t)row * DM + col0;
;             float rs = 1.0f; if (MODE == 1) rs = __builtin_amdgcn_rsqf(ss_fix(rsb[sc]) * (1.0f / DM) + EPS);
;             float sq = 0.f;
; #pragma unroll
;             for (int bj = 0; bj < 2; ++bj) { const size_t off = ro + bj * HALF;
;                 f32x4 v0 = acc[ai][bj][m][0], v1 = acc[ai][bj][m][1];
;                 if (MODE == 1) { const u32x4 pw = pbuf[sc][bj];
;                     v0[0] = fast_sigmoid(rs * v0[0]) * bf_lo(pw.x); v0[1] = fast_sigmoid(rs * v0[1]) * bf_hi(pw.x); v0[2] = fast_sigmoid(rs * v0[2]) * bf_lo(pw.y); v0[3] = fast_sigmoid(rs * v0[3]) * bf_hi(pw.y);
;                     v1[0] = fast_sigmoid(rs * v1[0]) * bf_lo(pw.z); v1[1] = fast_sigmoid(rs * v1[1]) * bf_hi(pw.z); v1[2] = fast_sigmoid(rs * v1[2]) * bf_lo(pw.w); v1[3] = fast_sigmoid(rs * v1[3]) * bf_hi(pw.w); }
;                 f32x4 h0, h1;
;                 if (IN16) { const u32x4 hw = hraw[sc][bj]; h0 = (f32x4){bf_lo(hw.x), bf_hi(hw.x), bf_lo(hw.y), bf_hi(hw.y)}; h1 = (f32x4){bf_lo(hw.z), bf_hi(hw.z), bf_lo(hw.w), bf_hi(hw.w)}; }
;                 else { h0 = hbuf[sc][2 * bj]; h1 = hbuf[sc][2 * bj + 1]; }
;                 const f32x4 o0 = h0 + v0, o1 = h1 + v1;
;                 if (OUT32) { *(f32x4*)(hout + off) = o0; *(f32x4*)(hout + off + 4) = o1; }
;                 if (hb) { u32x4 w; w.x = pk_bf16(o0[0], o0[1]); w.y = pk_bf16(o0[2], o0[3]); w.z = pk_bf16(o1[0], o1[1]); w.w = pk_bf16(o1[2], o1[3]); *(u32x4*)(hb + off) = w; }
;                 sq += ((o0[0] * o0[0] + o0[1] * o0[1]) + (o0[2] * o0[2] + o0[3] * o0[3])) + ((o1[0] * o1[0] + o1[1] * o1[1]) + (o1[2] * o1[2] + o1[3] * o1[3])); }
.Lrot_out_443:
	v_lshl_add_u32 v170, s66, 8, v176
	v_lshl_or_b32 v160, s68, 8, v178
	v_ashrrev_i32_e32 v171, 31, v170
	v_ashrrev_i32_e32 v161, 31, v160
	v_lshlrev_b64 v[190:191], 12, v[170:171]
	v_lshl_add_u64 v[128:129], s[30:31], 0, v[190:191]
	v_lshlrev_b64 v[162:163], 1, v[160:161]
	v_lshl_add_u64 v[164:165], v[128:129], 0, v[162:163]
	global_load_dwordx4 v[182:185], v[164:165], off
	global_load_dwordx4 v[186:189], v[164:165], off offset:256
	v_or_b32_e32 v172, 16, v170
	v_or_b32_e32 v166, 32, v170
	v_ashrrev_i32_e32 v173, 31, v172
	v_ashrrev_i32_e32 v167, 31, v166
	v_lshlrev_b64 v[174:175], 12, v[172:173]
	v_lshlrev_b64 v[168:169], 12, v[166:167]
	v_lshl_add_u64 v[128:129], s[30:31], 0, v[174:175]
	v_lshl_add_u64 v[130:131], s[30:31], 0, v[168:169]
	v_lshl_add_u64 v[128:129], v[128:129], 0, v[162:163]
	v_lshl_add_u64 v[130:131], v[130:131], 0, v[162:163]
	global_load_dwordx4 v[140:143], v[128:129], off
	global_load_dwordx4 v[136:139], v[128:129], off offset:256
	global_load_dwordx4 v[132:135], v[130:131], off
	s_nop 0
	global_load_dwordx4 v[128:131], v[130:131], off offset:256
	s_waitcnt vmcnt(0)
	v_lshlrev_b32_e32 v192, 16, v182
	v_and_b32_e32 v193, 0xffff0000, v182
	v_lshlrev_b32_e32 v182, 16, v183
	v_and_b32_e32 v183, 0xffff0000, v183
	v_lshlrev_b32_e32 v194, 16, v184
	v_and_b32_e32 v195, 0xffff0000, v184
	v_lshlrev_b32_e32 v184, 16, v185
	v_and_b32_e32 v185, 0xffff0000, v185
	v_lshlrev_b32_e32 v196, 16, v186
	v_and_b32_e32 v197, 0xffff0000, v186
	v_lshlrev_b32_e32 v186, 16, v187
	v_and_b32_e32 v187, 0xffff0000, v187
	v_lshlrev_b32_e32 v198, 16, v188
	v_and_b32_e32 v199, 0xffff0000, v188
	v_lshlrev_b32_e32 v188, 16, v189
	v_and_b32_e32 v189, 0xffff0000, v189
	v_pk_add_f32 v[126:127], v[126:127], v[182:183]
	v_pk_add_f32 v[124:125], v[124:125], v[192:193]
	v_pk_add_f32 v[122:123], v[122:123], v[184:185]
	v_pk_add_f32 v[120:121], v[120:121], v[194:195]
	v_pk_add_f32 v[118:119], v[118:119], v[186:187]
	v_pk_add_f32 v[116:117], v[116:117], v[196:197]
	v_pk_add_f32 v[182:183], v[114:115], v[188:189]
	v_pk_add_f32 v[184:185], v[112:113], v[198:199]
	v_cvt_pk_bf16_f32 v112, v124, v125
	v_cvt_pk_bf16_f32 v113, v126, v127
	v_cvt_pk_bf16_f32 v114, v120, v121
	v_cvt_pk_bf16_f32 v115, v122, v123
	v_mul_f32_e32 v125, v125, v125
	v_mul_f32_e32 v127, v127, v127
	v_mul_f32_e32 v121, v121, v121
	v_mul_f32_e32 v123, v123, v123
	v_mul_f32_e32 v186, v117, v117
	v_mul_f32_e32 v187, v119, v119
	v_mul_f32_e32 v188, v185, v185
	v_mul_f32_e32 v189, v183, v183
	v_fmac_f32_e32 v125, v124, v124
	v_fmac_f32_e32 v127, v126, v126
	v_fmac_f32_e32 v121, v120, v120
	v_fmac_f32_e32 v123, v122, v122
	v_fmac_f32_e32 v186, v116, v116
	v_fmac_f32_e32 v187, v118, v118
	v_fmac_f32_e32 v188, v184, v184
	v_fmac_f32_e32 v189, v182, v182
	v_add_f32_e32 v120, v125, v127
	v_add_f32_e32 v121, v121, v123
	v_add_f32_e32 v122, v186, v187
	v_add_f32_e32 v123, v188, v189
	v_add_f32_e32 v120, v120, v121
	v_add_f32_e32 v121, v122, v123
	v_add_f32_e32 v122, v120, v121
	ds_bpermute_b32 v123, v245, v122
	v_lshl_add_u64 v[120:121], s[50:51], 0, v[190:191]
	v_lshl_add_u64 v[120:121], v[120:121], 0, v[162:163]
	global_store_dwordx4 v[120:121], v[112:115], off
	s_waitcnt lgkmcnt(0)
	s_nop 0
	v_add_f32_e32 v112, v122, v123
	ds_bpermute_b32 v113, v244, v112
	v_cvt_pk_bf16_f32 v114, v116, v117
	v_cvt_pk_bf16_f32 v115, v118, v119
	v_cvt_pk_bf16_f32 v116, v184, v185
	v_cvt_pk_bf16_f32 v117, v182, v183
	global_store_dwordx4 v[120:121], v[114:117], off offset:256
	s_and_saveexec_b64 s[66:67], s[16:17]
	s_cbranch_execz .LBB0_446
	s_waitcnt lgkmcnt(0)
	v_add_f32_e32 v112, v112, v113
	v_fma_f32 v112, v112, s25, 0.5
	v_cvt_u32_f32_e32 v114, v112
	v_lshl_add_u64 v[112:113], v[170:171], 2, s[52:53]
	global_atomic_add v[112:113], v114, off

; #define PG8_BAR __builtin_amdgcn_s_barrier()
; template <class Epi>
; __device__ __forceinline__ void gemm_phase(LAS unsigned char* lds, const Gemm g, const StaticOrder& S, const Epi& E, int wv) {
;     ...
;         const bool has_next = S.next(ui + 1, nxt);
;         const char* nA = has_next ? (const char*)g.A + (size_t)nxt.pm * tstepA + ((g.adiag & 1) ? (size_t)(nxt.pn >> 1) * K * 2 : 0) + kbeg : cA;
;         const char* nB = has_next ? (const char*)g.Bt + (size_t)nxt.pn * tstepB + kbeg : cB;
;         for (int t = 0; t < nt; t += 2) {
;             const bool last = (t == nt - 2);
;             const char* a1 = cA + (ptrdiff_t)(t + 1) * kstep;
;             const char* a2 = last ? nA : cA + (ptrdiff_t)(t + 2) * kstep; const char* b2 = last ? nB : cB + (ptrdiff_t)(t + 2) * kstep;
;             const char* a3 = a2 + kstep; const char* b3 = b2 + kstep;
;             PG8_LDB(B0, 0, 0); PG8_SCHED; PG8_LDA(At, 0, 0); PG8_STAGE(PG8_SA(1, 1), a1 + hstepA, voffA);
;             PG8_WAIT_L(8); PG8_BAR; PG8_WAIT_L(0); PG8_MMA(0, 0, At, B0); PG8_BAR; PG8_SCHED;
;             PG8_LDB(B1, 0, 1); PG8_STAGE(PG8_SB(0, 0), b2, voffB);
;             PG8_BAR; PG8_WAIT_L(0); PG8_MMA(0, 1, At, B1); PG8_BAR;
;             PG8_LDA(At, 0, 1); PG8_STAGE(PG8_SA(0, 0), a2, voffA);
;             PG8_BAR; PG8_WAIT_L(0); PG8_MMA(1, 0, At, B0); PG8_BAR; PG8_SCHED;
;             PG8_STAGE(PG8_SB(0, 1), b2 + hstepB, voffB);
;             PG8_WAIT_V(6); PG8_BAR; PG8_MMA(1, 1, At, B1); PG8_BAR;
;             PG8_LDB(B0, 1, 0); PG8_SCHED; PG8_LDA(At, 1, 0); PG8_STAGE(PG8_SA(0, 1), a2 + hstepA, voffA);
;             PG8_WAIT_L(8); PG8_BAR; PG8_WAIT_L(0); PG8_MMA(0, 0, At, B0); PG8_BAR; PG8_SCHED;
;             PG8_LDB(B1, 1, 1); PG8_STAGE(PG8_SB(1, 0), b3, voffB);
;             PG8_BAR; PG8_WAIT_L(0); PG8_MMA(0, 1, At, B1); PG8_BAR;
;             PG8_LDA(At, 1, 1); PG8_STAGE(PG8_SA(1, 0), a3, voffA);
;             PG8_BAR; PG8_WAIT_L(0); PG8_MMA(1, 0, At, B0); PG8_BAR; PG8_SCHED;
;             PG8_STAGE(PG8_SB(1, 1), b3 + hstepB, voffB);
;             PG8_WAIT_V(6); PG8_BAR; PG8_MMA(1, 1, At, B1); PG8_BAR;
;         }
;         E(acc, cur, wr, wc, fr, fq);
;         if (!has_next) break;
; #pragma unroll
;         for (int a = 0; a < 2; ++a)
; #pragma unroll
;             for (int b = 0; b < 2; ++b)
; #pragma unroll
;                 for (int m = 0; m < 4; ++m)
; #pragma unroll
.LBB0_529:
	s_ashr_i32 s59, s58, 31
	s_lshl_b64 s[38:39], s[58:59], 20
	v_cmp_lt_i64_e32 vcc, s[60:61], v[140:141]
	s_add_u32 s60, s5, s38
	s_addc_u32 s61, s6, s39
	s_and_b64 s[38:39], vcc, exec
	s_cselect_b32 s35, s61, s69
	s_cselect_b32 s38, s60, s68
	s_ashr_i32 s57, s56, 31
	s_lshl_b64 s[40:41], s[56:57], 20
	s_add_u32 s62, s7, s40
	s_addc_u32 s63, s8, s41
	s_and_b64 s[40:41], vcc, exec
	s_cselect_b32 s39, s63, s67
	s_cselect_b32 s40, s62, s66
	s_add_u32 s41, s66, 0x100
	s_addc_u32 s42, s67, 0
	s_add_u32 s66, s68, 0x80080
	v_mov_b32_e32 v0, 0
	s_addc_u32 s67, s69, 0
	s_mov_b32 s43, -2
	v_mov_b32_e32 v1, v0
	v_mov_b32_e32 v2, v0
	v_mov_b32_e32 v3, v0
	v_mov_b32_e32 v4, v0
	v_mov_b32_e32 v5, v0
	v_mov_b32_e32 v6, v0
	v_mov_b32_e32 v7, v0
	v_mov_b32_e32 v16, v0
	v_mov_b32_e32 v17, v0
	v_mov_b32_e32 v18, v0
	v_mov_b32_e32 v19, v0
	v_mov_b32_e32 v20, v0
	v_mov_b32_e32 v21, v0
	v_mov_b32_e32 v22, v0
	v_mov_b32_e32 v23, v0
	v_mov_b32_e32 v32, v0
	v_mov_b32_e32 v33, v0
	v_mov_b32_e32 v34, v0
	v_mov_b32_e32 v35, v0
	v_mov_b32_e32 v36, v0
	v_mov_b32_e32 v37, v0
	v_mov_b32_e32 v38, v0
	v_mov_b32_e32 v39, v0
	v_mov_b32_e32 v48, v0
	v_mov_b32_e32 v49, v0
	v_mov_b32_e32 v50, v0
	v_mov_b32_e32 v51, v0
	v_mov_b32_e32 v52, v0
	v_mov_b32_e32 v53, v0
	v_mov_b32_e32 v54, v0
	v_mov_b32_e32 v55, v0
	v_mov_b32_e32 v8, v0
	v_mov_b32_e32 v9, v0
	v_mov_b32_e32 v10, v0
	v_mov_b32_e32 v11, v0
	v_mov_b32_e32 v12, v0
	v_mov_b32_e32 v13, v0
	v_mov_b32_e32 v14, v0
	v_mov_b32_e32 v15, v0
	v_mov_b32_e32 v24, v0
	v_mov_b32_e32 v25, v0
	v_mov_b32_e32 v26, v0
	v_mov_b32_e32 v27, v0
	v_mov_b32_e32 v28, v0
	v_mov_b32_e32 v29, v0
	v_mov_b32_e32 v30, v0
	v_mov_b32_e32 v31, v0
	v_mov_b32_e32 v40, v0
	v_mov_b32_e32 v41, v0
	v_mov_b32_e32 v42, v0
	v_mov_b32_e32 v43, v0
	v_mov_b32_e32 v44, v0
	v_mov_b32_e32 v45, v0
	v_mov_b32_e32 v46, v0
	v_mov_b32_e32 v47, v0
	v_mov_b32_e32 v56, v0
	v_mov_b32_e32 v57, v0
	v_mov_b32_e32 v58, v0
	v_mov_b32_e32 v59, v0
	v_mov_b32_e32 v60, v0
	v_mov_b32_e32 v61, v0
	v_mov_b32_e32 v62, v0
	v_mov_b32_e32 v63, v0
	v_mov_b32_e32 v64, v0
	v_mov_b32_e32 v65, v0
	v_mov_b32_e32 v66, v0
	v_mov_b32_e32 v67, v0
	v_mov_b32_e32 v68, v0
	v_mov_b32_e32 v69, v0
	v_mov_b32_e32 v70, v0
	v_mov_b32_e32 v71, v0
	v_mov_b32_e32 v80, v0
	v_mov_b32_e32 v81, v0
	v_mov_b32_e32 v82, v0
	v_mov_b32_e32 v83, v0
	v_mov_b32_e32 v84, v0
	v_mov_b32_e32 v85, v0
	v_mov_b32_e32 v86, v0
	v_mov_b32_e32 v87, v0
	v_mov_b32_e32 v96, v0
	v_mov_b32_e32 v97, v0
	v_mov_b32_e32 v98, v0
	v_mov_b32_e32 v99, v0
	v_mov_b32_e32 v100, v0
	v_mov_b32_e32 v101, v0
	v_mov_b32_e32 v102, v0
	v_mov_b32_e32 v103, v0
	v_mov_b32_e32 v104, v0
	v_mov_b32_e32 v105, v0
	v_mov_b32_e32 v106, v0
	v_mov_b32_e32 v107, v0
	v_mov_b32_e32 v108, v0
	v_mov_b32_e32 v109, v0
	v_mov_b32_e32 v110, v0
	v_mov_b32_e32 v111, v0
	v_mov_b32_e32 v72, v0
	v_mov_b32_e32 v73, v0
	v_mov_b32_e32 v74, v0
	v_mov_b32_e32 v75, v0
	v_mov_b32_e32 v76, v0
	v_mov_b32_e32 v77, v0
	v_mov_b32_e32 v78, v0
	v_mov_b32_e32 v79, v0
	v_mov_b32_e32 v88, v0
	v_mov_b32_e32 v89, v0
	v_mov_b32_e32 v90, v0
	v_mov_b32_e32 v91, v0
	v_mov_b32_e32 v92, v0
	v_mov_b32_e32 v93, v0
	v_mov_b32_e32 v94, v0
	v_mov_b32_e32 v95, v0
	v_mov_b32_e32 v112, v0
	v_mov_b32_e32 v113, v0
	v_mov_b32_e32 v114, v0
	v_mov_b32_e32 v115, v0
	v_mov_b32_e32 v116, v0
	v_mov_b32_e32 v117, v0
	v_mov_b32_e32 v118, v0
	v_mov_b32_e32 v119, v0
	v_mov_b32_e32 v120, v0
	v_mov_b32_e32 v121, v0
	v_mov_b32_e32 v122, v0
	v_mov_b32_e32 v123, v0
	v_mov_b32_e32 v124, v0
	v_mov_b32_e32 v125, v0
	v_mov_b32_e32 v126, v0
	v_mov_b32_e32 v127, v0
	ds_read_b128 v[144:147], v153
	ds_read_b128 v[158:161], v153 offset:1024
	ds_read_b128 v[162:165], v153 offset:2048
	ds_read_b128 v[166:169], v153 offset:3072
	s_branch .Lrot_in_530
.LBB0_530:
	s_barrier
	v_mfma_f32_16x16x32_bf16 v[52:55], v[202:205], v[170:173], v[52:55]
	v_mfma_f32_16x16x32_bf16 v[48:51], v[210:213], v[170:173], v[48:51]
	v_mfma_f32_16x16x32_bf16 v[36:39], v[202:205], v[178:181], v[36:39]
	v_mfma_f32_16x16x32_bf16 v[32:35], v[210:213], v[178:181], v[32:35]
	v_mfma_f32_16x16x32_bf16 v[20:23], v[202:205], v[186:189], v[20:23]
	v_mfma_f32_16x16x32_bf16 v[16:19], v[210:213], v[186:189], v[16:19]
	v_mfma_f32_16x16x32_bf16 v[4:7], v[202:205], v[194:197], v[4:7]
	v_mfma_f32_16x16x32_bf16 v[0:3], v[210:213], v[194:197], v[0:3]
	v_mfma_f32_16x16x32_bf16 v[52:55], v[206:209], v[174:177], v[52:55]
	v_mfma_f32_16x16x32_bf16 v[48:51], v[214:217], v[174:177], v[48:51]
	v_mfma_f32_16x16x32_bf16 v[36:39], v[206:209], v[182:185], v[36:39]
	v_mfma_f32_16x16x32_bf16 v[32:35], v[214:217], v[182:185], v[32:35]
	v_mfma_f32_16x16x32_bf16 v[20:23], v[206:209], v[190:193], v[20:23]
	v_mfma_f32_16x16x32_bf16 v[16:19], v[214:217], v[190:193], v[16:19]
	v_mfma_f32_16x16x32_bf16 v[4:7], v[206:209], v[198:201], v[4:7]
	v_mfma_f32_16x16x32_bf16 v[0:3], v[214:217], v[198:201], v[0:3]
	s_waitcnt lgkmcnt(0)
	s_add_i32 s43, s43, 2
	s_add_u32 s41, s41, 0x100
	s_addc_u32 s42, s42, 0
	s_add_u32 s66, s66, 0x100
	s_addc_u32 s67, s67, 0
	s_cmp_gt_u32 s43, 29
	s_barrier
	s_cbranch_scc1 .Lrot_out_530
; #define PG8_STAGE(bufoff, gbase, voff) do { _Pragma("unroll") for (int _i = 0; _i < 2; ++_i) \
;         __builtin_amdgcn_global_load_lds((const unsigned*)((const char*)(gbase) + (voff)[_i]), (LAS unsigned*)(lds + (bufoff) + ldsw + _i * 8192), 16, 0, 0); } while (0)
; #define PG8_LDA(dst, b, h) do { _Pragma("unroll") for (int m = 0; m < 4; ++m) _Pragma("unroll") for (int k = 0; k < 2; ++k) dst[m][k] = *(const LAS bf16x8*)(lds + PG8_SA(b, h) + aoff + m * 2048 + k * 1024); } while (0)
; #define PG8_LDB(dst, b, h) do { _Pragma("unroll") for (int n = 0; n < 2; ++n) _Pragma("unroll") for (int k = 0; k < 2; ++k) dst[n][k] = *(const LAS bf16x8*)(lds + PG8_SB(b, h) + boff + n * 2048 + k * 1024); } while (0)
; #define PG8_MMA(ai, bj, At, Bt) do { __builtin_amdgcn_s_setprio(1); _Pragma("unroll") for (int m = 0; m < 4; ++m) _Pragma("unroll") for (int n = 0; n < 2; ++n) _Pragma("unroll") for (int k = 0; k < 2; ++k) \
;         acc[ai][bj][m][n] = __builtin_amdgcn_mfma_f32_16x16x32_bf16(Bt[n][k], At[m][k], acc[ai][bj][m][n], 0, 0, 0); __builtin_amdgcn_s_setprio(0); } while (0)
; #define PG8_WAIT_V(n) asm volatile("s_waitcnt vmcnt(" #n ")" ::: "memory")
; #define PG8_WAIT_L(n) asm volatile("s_waitcnt lgkmcnt(" #n ")" ::: "memory")
; #define PG8_BAR __builtin_amdgcn_s_barrier()
; template <class Epi>
; __device__ __forceinline__ void gemm_phase(LAS unsigned char* lds, const Gemm g, const StaticOrder& S, const Epi& E, int wv) {
;     ...
;             const bool last = (t == nt - 2);
;             const char* a1 = cA + (ptrdiff_t)(t + 1) * kstep;
;             const char* a2 = last ? nA : cA + (ptrdiff_t)(t + 2) * kstep; const char* b2 = last ? nB : cB + (ptrdiff_t)(t + 2) * kstep;
;             const char* a3 = a2 + kstep; const char* b3 = b2 + kstep;
;             PG8_LDB(B0, 0, 0); PG8_SCHED; PG8_LDA(At, 0, 0); PG8_STAGE(PG8_SA(1, 1), a1 + hstepA, voffA);
;             PG8_WAIT_L(8); PG8_BAR; PG8_WAIT_L(0); PG8_MMA(0, 0, At, B0); PG8_BAR; PG8_SCHED;
;             PG8_LDB(B1, 0, 1); PG8_STAGE(PG8_SB(0, 0), b2, voffB);
;             PG8_BAR; PG8_WAIT_L(0); PG8_MMA(0, 1, At, B1); PG8_BAR;
;             PG8_LDA(At, 0, 1); PG8_STAGE(PG8_SA(0, 0), a2, voffA);
;             PG8_BAR; PG8_WAIT_L(0); PG8_MMA(1, 0, At, B0); PG8_BAR; PG8_SCHED;
;             PG8_STAGE(PG8_SB(0, 1), b2 + hstepB, voffB);
;             PG8_WAIT_V(6); PG8_BAR; PG8_MMA(1, 1, At, B1); PG8_BAR;
.Lrot_in_530:
	s_add_u32 s44, s66, 0xfff80080
	s_addc_u32 s45, s67, -1
	s_cmp_eq_u32 s43, 28
	s_cselect_b32 s71, s35, s45
	s_cselect_b32 s70, s38, s44
	s_cselect_b32 s69, s39, s42
	s_cselect_b32 s68, s40, s41
	s_add_i32 m0, s10, 0xc000
	ds_read_b128 v[170:173], v154
	ds_read_b128 v[174:177], v154 offset:1024
	ds_read_b128 v[178:181], v154 offset:2048
	ds_read_b128 v[182:185], v154 offset:3072
	ds_read_b128 v[186:189], v154 offset:4096
	ds_read_b128 v[190:193], v154 offset:5120
	ds_read_b128 v[194:197], v154 offset:6144
	ds_read_b128 v[198:201], v154 offset:7168
	global_load_lds_dwordx4 v138, s[66:67]
	s_add_i32 m0, s10, 0xe000
	s_nop 0
	global_load_lds_dwordx4 v136, s[66:67]
	s_waitcnt lgkmcnt(8)
	s_barrier
	s_waitcnt lgkmcnt(0)
	s_waitcnt lgkmcnt(0)
	v_mfma_f32_16x16x32_bf16 v[124:127], v[144:147], v[170:173], v[124:127]
	v_mfma_f32_16x16x32_bf16 v[120:123], v[162:165], v[170:173], v[120:123]
	v_mfma_f32_16x16x32_bf16 v[116:119], v[144:147], v[178:181], v[116:119]
	v_mfma_f32_16x16x32_bf16 v[112:115], v[162:165], v[178:181], v[112:115]
	v_mfma_f32_16x16x32_bf16 v[92:95], v[144:147], v[186:189], v[92:95]
	v_mfma_f32_16x16x32_bf16 v[88:91], v[162:165], v[186:189], v[88:91]
	v_mfma_f32_16x16x32_bf16 v[76:79], v[144:147], v[194:197], v[76:79]
	v_mfma_f32_16x16x32_bf16 v[72:75], v[162:165], v[194:197], v[72:75]
	v_mfma_f32_16x16x32_bf16 v[124:127], v[158:161], v[174:177], v[124:127]
	v_mfma_f32_16x16x32_bf16 v[120:123], v[166:169], v[174:177], v[120:123]
	v_mfma_f32_16x16x32_bf16 v[116:119], v[158:161], v[182:185], v[116:119]
	v_mfma_f32_16x16x32_bf16 v[112:115], v[166:169], v[182:185], v[112:115]
	v_mfma_f32_16x16x32_bf16 v[92:95], v[158:161], v[190:193], v[92:95]
	v_mfma_f32_16x16x32_bf16 v[88:91], v[166:169], v[190:193], v[88:91]
	v_mfma_f32_16x16x32_bf16 v[76:79], v[158:161], v[198:201], v[76:79]
	v_mfma_f32_16x16x32_bf16 v[72:75], v[166:169], v[198:201], v[72:75]
	s_barrier
	s_add_i32 s44, s23, s9
	s_add_u32 s98, s68, s52
	s_addc_u32 s99, s69, s53
	s_mov_b32 m0, s44
	ds_read_b128 v[202:205], v155
	ds_read_b128 v[206:209], v155 offset:1024
	ds_read_b128 v[210:213], v155 offset:2048
	ds_read_b128 v[214:217], v155 offset:3072
	global_load_lds_dwordx4 v130, s[68:69]
	s_add_i32 m0, s44, 0x2000
	s_nop 0
	global_load_lds_dwordx4 v134, s[68:69]
	s_barrier
	s_waitcnt lgkmcnt(0)
	s_waitcnt lgkmcnt(0)
	v_mfma_f32_16x16x32_bf16 v[108:111], v[202:205], v[170:173], v[108:111]
	v_mfma_f32_16x16x32_bf16 v[104:107], v[210:213], v[170:173], v[104:107]
	v_mfma_f32_16x16x32_bf16 v[100:103], v[202:205], v[178:181], v[100:103]
	v_mfma_f32_16x16x32_bf16 v[96:99], v[210:213], v[178:181], v[96:99]
	v_mfma_f32_16x16x32_bf16 v[84:87], v[202:205], v[186:189], v[84:87]
	v_mfma_f32_16x16x32_bf16 v[80:83], v[210:213], v[186:189], v[80:83]
	v_mfma_f32_16x16x32_bf16 v[68:71], v[202:205], v[194:197], v[68:71]
	v_mfma_f32_16x16x32_bf16 v[64:67], v[210:213], v[194:197], v[64:67]
	v_mfma_f32_16x16x32_bf16 v[108:111], v[206:209], v[174:177], v[108:111]
	v_mfma_f32_16x16x32_bf16 v[104:107], v[214:217], v[174:177], v[104:107]
	v_mfma_f32_16x16x32_bf16 v[100:103], v[206:209], v[182:185], v[100:103]
	v_mfma_f32_16x16x32_bf16 v[96:99], v[214:217], v[182:185], v[96:99]
	v_mfma_f32_16x16x32_bf16 v[84:87], v[206:209], v[190:193], v[84:87]
	v_mfma_f32_16x16x32_bf16 v[80:83], v[214:217], v[190:193], v[80:83]
	v_mfma_f32_16x16x32_bf16 v[68:71], v[206:209], v[198:201], v[68:71]
	v_mfma_f32_16x16x32_bf16 v[64:67], v[214:217], v[198:201], v[64:67]
	s_mov_b32 m0, s10
	s_add_u32 s100, s70, s52
	s_addc_u32 s101, s71, s53
	s_barrier
	ds_read_b128 v[170:173], v154 offset:16384
	ds_read_b128 v[174:177], v154 offset:17408
	ds_read_b128 v[178:181], v154 offset:18432
	ds_read_b128 v[182:185], v154 offset:19456
	ds_read_b128 v[186:189], v154 offset:20480
	ds_read_b128 v[190:193], v154 offset:21504
	ds_read_b128 v[194:197], v154 offset:22528
	ds_read_b128 v[198:201], v154 offset:23552
	global_load_lds_dwordx4 v128, s[70:71]
	s_mov_b32 m0, s11
	s_nop 0
	global_load_lds_dwordx4 v132, s[70:71]
	s_waitcnt vmcnt(10)
	s_barrier
	s_waitcnt lgkmcnt(0)
	s_waitcnt lgkmcnt(0)
	v_mfma_f32_16x16x32_bf16 v[60:63], v[144:147], v[170:173], v[60:63]
	v_mfma_f32_16x16x32_bf16 v[56:59], v[162:165], v[170:173], v[56:59]
	v_mfma_f32_16x16x32_bf16 v[44:47], v[144:147], v[178:181], v[44:47]
	v_mfma_f32_16x16x32_bf16 v[40:43], v[162:165], v[178:181], v[40:43]
	v_mfma_f32_16x16x32_bf16 v[28:31], v[144:147], v[186:189], v[28:31]
	v_mfma_f32_16x16x32_bf16 v[24:27], v[162:165], v[186:189], v[24:27]
	v_mfma_f32_16x16x32_bf16 v[12:15], v[144:147], v[194:197], v[12:15]
	v_mfma_f32_16x16x32_bf16 v[8:11], v[162:165], v[194:197], v[8:11]
	v_mfma_f32_16x16x32_bf16 v[60:63], v[158:161], v[174:177], v[60:63]
	v_mfma_f32_16x16x32_bf16 v[56:59], v[166:169], v[174:177], v[56:59]
	v_mfma_f32_16x16x32_bf16 v[44:47], v[158:161], v[182:185], v[44:47]
	v_mfma_f32_16x16x32_bf16 v[40:43], v[166:169], v[182:185], v[40:43]
	v_mfma_f32_16x16x32_bf16 v[28:31], v[158:161], v[190:193], v[28:31]
	v_mfma_f32_16x16x32_bf16 v[24:27], v[166:169], v[190:193], v[24:27]
	v_mfma_f32_16x16x32_bf16 v[12:15], v[158:161], v[198:201], v[12:15]
	v_mfma_f32_16x16x32_bf16 v[8:11], v[166:169], v[198:201], v[8:11]
	s_barrier
	s_add_u32 s44, s68, 0x80000
	s_addc_u32 s45, s69, 0
	s_add_i32 s46, s24, s9
	s_mov_b32 m0, s46
	s_nop 0
	global_load_lds_dwordx4 v130, s[44:45]
	s_add_i32 m0, s46, 0x2000
	s_nop 0
	global_load_lds_dwordx4 v134, s[44:45]
	s_add_i32 s46, 0, 0x18000
	v_add_u32_e32 v157, s46, v151
	ds_read_b128 v[144:147], v157
	ds_read_b128 v[158:161], v157 offset:1024
	ds_read_b128 v[162:165], v157 offset:2048
	ds_read_b128 v[166:169], v157 offset:3072
	s_waitcnt vmcnt(6)
	s_barrier
; #define PG8_STAGE(bufoff, gbase, voff) do { _Pragma("unroll") for (int _i = 0; _i < 2; ++_i) \
;         __builtin_amdgcn_global_load_lds((const unsigned*)((const char*)(gbase) + (voff)[_i]), (LAS unsigned*)(lds + (bufoff) + ldsw + _i * 8192), 16, 0, 0); } while (0)
; #define PG8_LDA(dst, b, h) do { _Pragma("unroll") for (int m = 0; m < 4; ++m) _Pragma("unroll") for (int k = 0; k < 2; ++k) dst[m][k] = *(const LAS bf16x8*)(lds + PG8_SA(b, h) + aoff + m * 2048 + k * 1024); } while (0)
; #define PG8_LDB(dst, b, h) do { _Pragma("unroll") for (int n = 0; n < 2; ++n) _Pragma("unroll") for (int k = 0; k < 2; ++k) dst[n][k] = *(const LAS bf16x8*)(lds + PG8_SB(b, h) + boff + n * 2048 + k * 1024); } while (0)
; #define PG8_MMA(ai, bj, At, Bt) do { __builtin_amdgcn_s_setprio(1); _Pragma("unroll") for (int m = 0; m < 4; ++m) _Pragma("unroll") for (int n = 0; n < 2; ++n) _Pragma("unroll") for (int k = 0; k < 2; ++k) \
;         acc[ai][bj][m][n] = __builtin_amdgcn_mfma_f32_16x16x32_bf16(Bt[n][k], At[m][k], acc[ai][bj][m][n], 0, 0, 0); __builtin_amdgcn_s_setprio(0); } while (0)
; #define PG8_WAIT_V(n) asm volatile("s_waitcnt vmcnt(" #n ")" ::: "memory")
; #define PG8_WAIT_L(n) asm volatile("s_waitcnt lgkmcnt(" #n ")" ::: "memory")
; #define PG8_BAR __builtin_amdgcn_s_barrier()
; #define PG8_SCHED __builtin_amdgcn_sched_barrier(0)
; template <class Epi>
; __device__ __forceinline__ void gemm_phase(LAS unsigned char* lds, const Gemm g, const StaticOrder& S, const Epi& E, int wv) {
;     ...
;             PG8_WAIT_V(6); PG8_BAR; PG8_MMA(1, 1, At, B1); PG8_BAR;
;             PG8_LDB(B0, 1, 0); PG8_SCHED; PG8_LDA(At, 1, 0); PG8_STAGE(PG8_SA(0, 1), a2 + hstepA, voffA);
;             PG8_WAIT_L(8); PG8_BAR; PG8_WAIT_L(0); PG8_MMA(0, 0, At, B0); PG8_BAR; PG8_SCHED;
;             PG8_LDB(B1, 1, 1); PG8_STAGE(PG8_SB(1, 0), b3, voffB);
;             PG8_BAR; PG8_WAIT_L(0); PG8_MMA(0, 1, At, B1); PG8_BAR;
;             PG8_LDA(At, 1, 1); PG8_STAGE(PG8_SA(1, 0), a3, voffA);
;             PG8_BAR; PG8_WAIT_L(0); PG8_MMA(1, 0, At, B0); PG8_BAR; PG8_SCHED;
;             PG8_STAGE(PG8_SB(1, 1), b3 + hstepB, voffB);
;             PG8_WAIT_V(6); PG8_BAR; PG8_MMA(1, 1, At, B1); PG8_BAR;
	v_mfma_f32_16x16x32_bf16 v[52:55], v[202:205], v[170:173], v[52:55]
	v_mfma_f32_16x16x32_bf16 v[48:51], v[210:213], v[170:173], v[48:51]
	v_mfma_f32_16x16x32_bf16 v[36:39], v[202:205], v[178:181], v[36:39]
	v_mfma_f32_16x16x32_bf16 v[32:35], v[210:213], v[178:181], v[32:35]
	v_mfma_f32_16x16x32_bf16 v[20:23], v[202:205], v[186:189], v[20:23]
	v_mfma_f32_16x16x32_bf16 v[16:19], v[210:213], v[186:189], v[16:19]
	v_mfma_f32_16x16x32_bf16 v[4:7], v[202:205], v[194:197], v[4:7]
	v_mfma_f32_16x16x32_bf16 v[0:3], v[210:213], v[194:197], v[0:3]
	v_mfma_f32_16x16x32_bf16 v[52:55], v[206:209], v[174:177], v[52:55]
	v_mfma_f32_16x16x32_bf16 v[48:51], v[214:217], v[174:177], v[48:51]
	v_mfma_f32_16x16x32_bf16 v[36:39], v[206:209], v[182:185], v[36:39]
	v_mfma_f32_16x16x32_bf16 v[32:35], v[214:217], v[182:185], v[32:35]
	v_mfma_f32_16x16x32_bf16 v[20:23], v[206:209], v[190:193], v[20:23]
	v_mfma_f32_16x16x32_bf16 v[16:19], v[214:217], v[190:193], v[16:19]
	v_mfma_f32_16x16x32_bf16 v[4:7], v[206:209], v[198:201], v[4:7]
	v_mfma_f32_16x16x32_bf16 v[0:3], v[214:217], v[198:201], v[0:3]
	s_waitcnt lgkmcnt(0)
	s_barrier
	s_add_u32 s44, s70, 0x80000
	s_addc_u32 s45, s71, 0
	s_mov_b32 m0, s12
	ds_read_b128 v[170:173], v154 offset:32768
	ds_read_b128 v[174:177], v154 offset:33792
	ds_read_b128 v[178:181], v154 offset:34816
	ds_read_b128 v[182:185], v154 offset:35840
	ds_read_b128 v[186:189], v154 offset:36864
	ds_read_b128 v[190:193], v154 offset:37888
	ds_read_b128 v[194:197], v154 offset:38912
	ds_read_b128 v[198:201], v154 offset:39936
	global_load_lds_dwordx4 v128, s[44:45]
	s_mov_b32 m0, s13
	s_nop 0
	global_load_lds_dwordx4 v132, s[44:45]
	s_waitcnt lgkmcnt(8)
	s_barrier
	s_waitcnt lgkmcnt(0)
	s_waitcnt lgkmcnt(0)
	v_mfma_f32_16x16x32_bf16 v[124:127], v[144:147], v[170:173], v[124:127]
	v_mfma_f32_16x16x32_bf16 v[120:123], v[162:165], v[170:173], v[120:123]
	v_mfma_f32_16x16x32_bf16 v[116:119], v[144:147], v[178:181], v[116:119]
	v_mfma_f32_16x16x32_bf16 v[112:115], v[162:165], v[178:181], v[112:115]
	v_mfma_f32_16x16x32_bf16 v[92:95], v[144:147], v[186:189], v[92:95]
	v_mfma_f32_16x16x32_bf16 v[88:91], v[162:165], v[186:189], v[88:91]
	v_mfma_f32_16x16x32_bf16 v[76:79], v[144:147], v[194:197], v[76:79]
	v_mfma_f32_16x16x32_bf16 v[72:75], v[162:165], v[194:197], v[72:75]
	v_mfma_f32_16x16x32_bf16 v[124:127], v[158:161], v[174:177], v[124:127]
	v_mfma_f32_16x16x32_bf16 v[120:123], v[166:169], v[174:177], v[120:123]
	v_mfma_f32_16x16x32_bf16 v[116:119], v[158:161], v[182:185], v[116:119]
	v_mfma_f32_16x16x32_bf16 v[112:115], v[166:169], v[182:185], v[112:115]
	v_mfma_f32_16x16x32_bf16 v[92:95], v[158:161], v[190:193], v[92:95]
	v_mfma_f32_16x16x32_bf16 v[88:91], v[166:169], v[190:193], v[88:91]
	v_mfma_f32_16x16x32_bf16 v[76:79], v[158:161], v[198:201], v[76:79]
	v_mfma_f32_16x16x32_bf16 v[72:75], v[166:169], v[198:201], v[72:75]
	s_barrier
	s_add_i32 s47, 0, 0x1c000
	s_add_i32 s44, s46, s9
	v_add_u32_e32 v157, s47, v151
	s_mov_b32 m0, s44
	ds_read_b128 v[202:205], v157
	ds_read_b128 v[206:209], v157 offset:1024
	ds_read_b128 v[210:213], v157 offset:2048
	ds_read_b128 v[214:217], v157 offset:3072
	global_load_lds_dwordx4 v130, s[98:99]
	s_add_i32 m0, s44, 0x2000
	s_nop 0
	global_load_lds_dwordx4 v134, s[98:99]
	s_barrier
	s_waitcnt lgkmcnt(0)
	s_waitcnt lgkmcnt(0)
	v_mfma_f32_16x16x32_bf16 v[108:111], v[202:205], v[170:173], v[108:111]
	v_mfma_f32_16x16x32_bf16 v[104:107], v[210:213], v[170:173], v[104:107]
	v_mfma_f32_16x16x32_bf16 v[100:103], v[202:205], v[178:181], v[100:103]
	v_mfma_f32_16x16x32_bf16 v[96:99], v[210:213], v[178:181], v[96:99]
	v_mfma_f32_16x16x32_bf16 v[84:87], v[202:205], v[186:189], v[84:87]
	v_mfma_f32_16x16x32_bf16 v[80:83], v[210:213], v[186:189], v[80:83]
	v_mfma_f32_16x16x32_bf16 v[68:71], v[202:205], v[194:197], v[68:71]
	v_mfma_f32_16x16x32_bf16 v[64:67], v[210:213], v[194:197], v[64:67]
	v_mfma_f32_16x16x32_bf16 v[108:111], v[206:209], v[174:177], v[108:111]
	v_mfma_f32_16x16x32_bf16 v[104:107], v[214:217], v[174:177], v[104:107]
	v_mfma_f32_16x16x32_bf16 v[100:103], v[206:209], v[182:185], v[100:103]
	v_mfma_f32_16x16x32_bf16 v[96:99], v[214:217], v[182:185], v[96:99]
	v_mfma_f32_16x16x32_bf16 v[84:87], v[206:209], v[190:193], v[84:87]
	v_mfma_f32_16x16x32_bf16 v[80:83], v[214:217], v[190:193], v[80:83]
	v_mfma_f32_16x16x32_bf16 v[68:71], v[206:209], v[198:201], v[68:71]
	v_mfma_f32_16x16x32_bf16 v[64:67], v[214:217], v[198:201], v[64:67]
	s_mov_b32 m0, s15
	s_barrier
	ds_read_b128 v[170:173], v154 offset:49152
	ds_read_b128 v[174:177], v154 offset:50176
	ds_read_b128 v[178:181], v154 offset:51200
	ds_read_b128 v[182:185], v154 offset:52224
	ds_read_b128 v[186:189], v154 offset:53248
	ds_read_b128 v[190:193], v154 offset:54272
	ds_read_b128 v[194:197], v154 offset:55296
	ds_read_b128 v[198:201], v154 offset:56320
	global_load_lds_dwordx4 v128, s[100:101]
	s_mov_b32 m0, s22
	s_nop 0
	global_load_lds_dwordx4 v132, s[100:101]
	s_waitcnt vmcnt(10)
	s_barrier
	s_waitcnt lgkmcnt(0)
	s_waitcnt lgkmcnt(0)
	v_mfma_f32_16x16x32_bf16 v[60:63], v[144:147], v[170:173], v[60:63]
	v_mfma_f32_16x16x32_bf16 v[56:59], v[162:165], v[170:173], v[56:59]
	v_mfma_f32_16x16x32_bf16 v[44:47], v[144:147], v[178:181], v[44:47]
	v_mfma_f32_16x16x32_bf16 v[40:43], v[162:165], v[178:181], v[40:43]
	v_mfma_f32_16x16x32_bf16 v[28:31], v[144:147], v[186:189], v[28:31]
	v_mfma_f32_16x16x32_bf16 v[24:27], v[162:165], v[186:189], v[24:27]
	v_mfma_f32_16x16x32_bf16 v[12:15], v[144:147], v[194:197], v[12:15]
	v_mfma_f32_16x16x32_bf16 v[8:11], v[162:165], v[194:197], v[8:11]
	v_mfma_f32_16x16x32_bf16 v[60:63], v[158:161], v[174:177], v[60:63]
	v_mfma_f32_16x16x32_bf16 v[56:59], v[166:169], v[174:177], v[56:59]
	v_mfma_f32_16x16x32_bf16 v[44:47], v[158:161], v[182:185], v[44:47]
	v_mfma_f32_16x16x32_bf16 v[40:43], v[166:169], v[182:185], v[40:43]
	v_mfma_f32_16x16x32_bf16 v[28:31], v[158:161], v[190:193], v[28:31]
	v_mfma_f32_16x16x32_bf16 v[24:27], v[166:169], v[190:193], v[24:27]
	v_mfma_f32_16x16x32_bf16 v[12:15], v[158:161], v[198:201], v[12:15]
	v_mfma_f32_16x16x32_bf16 v[8:11], v[166:169], v[198:201], v[8:11]
	s_barrier
	s_add_u32 s44, s68, 0x80080
	s_addc_u32 s45, s69, 0
	s_add_i32 s46, s47, s9
	s_mov_b32 m0, s46
	s_nop 0
	global_load_lds_dwordx4 v130, s[44:45]
	s_add_i32 m0, s46, 0x2000
	s_nop 0
	global_load_lds_dwordx4 v134, s[44:45]
	ds_read_b128 v[144:147], v153
	ds_read_b128 v[158:161], v153 offset:1024
	ds_read_b128 v[162:165], v153 offset:2048
	ds_read_b128 v[166:169], v153 offset:3072
	s_waitcnt vmcnt(6)
	s_branch .LBB0_530
; __device__ __forceinline__ float fast_sigmoid(float x) { return __builtin_amdgcn_rcpf(1.0f + __builtin_amdgcn_exp2f(-x * LOG2E)); }
; __device__ __forceinline__ float ss_fix(float raw) { return (float)__float_as_uint(raw) * (1.0f / 256.0f); }
;     __device__ __forceinline__ const CAS char* base() const { const CAS char* ka = (const CAS char*)__builtin_amdgcn_kernarg_segment_ptr(); asm volatile("" : "+s"(ka)); return ka; }
;     __device__ __forceinline__ void operator()(const f32x4 (&acc)[2][2][4][2], const Unit& u, int wr, int wc, int fr, int fq) const {
;     ...
;         float rsv[8];
; #pragma unroll
;         for (int it = 0; it < 8; ++it) rsv[it] = (SM == 1) ? ss[row0 + (it >> 2) * HALF + (it & 3) * 16] : 1.0f;
; #pragma unroll
;         for (int ai = 0; ai < 2; ++ai)
; #pragma unroll
;             for (int m = 0; m < 4; ++m) { const int row = row0 + ai * HALF + m * 16; float rs = 1.0f; if (SM == 1) rs = __builtin_amdgcn_rsqf(ss_fix(rsv[ai * 4 + m]) * (1.0f / DM) + EPS);
;                 bf16_t* rowp = base + (size_t)row * ldc + col0;
; #pragma unroll
;                 for (int bj = 0; bj < 2; ++bj) { f32x4 v0 = acc[ai][bj][m][0], v1 = acc[ai][bj][m][1];
;                     if (SM == 1) { v0 *= rs; v1 *= rs; }
;                     if (SM == 2) { v0 *= cs[bj][0]; v1 *= cs[bj][1]; }
;                     if (ACT == 1) {
; #pragma unroll
;                         for (int j = 0; j < 4; ++j) { const float a = fmaxf(v0[j], 0.f), b = fmaxf(v1[j], 0.f); v0[j] = a * a; v1[j] = b * b; } }
;                     if (ACT == 2) { if (tsel == 0) {
; #pragma unroll
;                         for (int j = 0; j < 4; ++j) { const float a = v0[j], b = v1[j];
;                             v0[j] = a * fast_sigmoid(1.5957691216057308f * (a + 0.044715f * a * a * a)); v1[j] = b * fast_sigmoid(1.5957691216057308f * (b + 0.044715f * b * b * b)); } } }
;                     u32x4 w; w.x = pk_bf16(v0[0], v0[1]); w.y = pk_bf16(v0[2], v0[3]); w.z = pk_bf16(v1[0], v1[1]); w.w = pk_bf16(v1[2], v1[3]);
;                     *(u32x4*)(rowp + bj * HALF) = w; } }
.Lrot_out_530:
	v_lshl_add_u32 v146, s64, 8, v150
	v_ashrrev_i32_e32 v147, 31, v146
	v_lshl_add_u64 v[144:145], v[146:147], 2, s[50:51]
	global_load_dword v157, v[144:145], off
	global_load_dword v162, v[144:145], off offset:64
	v_lshlrev_b64 v[160:161], 14, v[146:147]
	global_load_dword v166, v[144:145], off offset:128
	global_load_dword v167, v[144:145], off offset:192
	global_load_dword v168, v[144:145], off offset:512
	global_load_dword v169, v[144:145], off offset:576
	global_load_dword v170, v[144:145], off offset:640
	global_load_dword v147, v[144:145], off offset:704
	v_lshl_or_b32 v148, s34, 8, v152
	v_ashrrev_i32_e32 v149, 31, v148
	v_lshl_add_u64 v[148:149], v[148:149], 1, s[18:19]
	v_lshl_add_u64 v[144:145], v[148:149], 0, v[160:161]
	v_or_b32_e32 v158, 16, v146
	v_ashrrev_i32_e32 v159, 31, v158
	v_lshlrev_b64 v[158:159], 14, v[158:159]
	v_lshl_add_u64 v[158:159], v[148:149], 0, v[158:159]
	s_mov_b64 s[34:35], 0x200000
	s_mov_b32 s64, s58
	s_mov_b64 s[66:67], s[62:63]
	s_mov_b64 s[68:69], s[60:61]
	s_waitcnt vmcnt(0)
	v_cvt_f32_u32_e32 v157, v157
	v_cvt_f32_u32_e32 v161, v162
	v_mul_f32_e32 v157, 0x3b800000, v157
	v_fmamk_f32 v157, v157, 0x3a000000, v156
	v_rsq_f32_e32 v160, v157
	v_mul_f32_e32 v157, 0x3b800000, v161
	v_fmamk_f32 v157, v157, 0x3a000000, v156
	v_rsq_f32_e32 v162, v157
	v_pk_mul_f32 v[126:127], v[126:127], v[160:161] op_sel_hi:[1,0]
	v_pk_mul_f32 v[124:125], v[124:125], v[160:161] op_sel_hi:[1,0]
	v_pk_mul_f32 v[122:123], v[122:123], v[160:161] op_sel_hi:[1,0]
	v_pk_mul_f32 v[120:121], v[120:121], v[160:161] op_sel_hi:[1,0]
	v_pk_mul_f32 v[110:111], v[110:111], v[160:161] op_sel_hi:[1,0]
	v_pk_mul_f32 v[108:109], v[108:109], v[160:161] op_sel_hi:[1,0]
	v_pk_mul_f32 v[106:107], v[106:107], v[160:161] op_sel_hi:[1,0]
	v_pk_mul_f32 v[104:105], v[104:105], v[160:161] op_sel_hi:[1,0]
	v_pk_mul_f32 v[118:119], v[118:119], v[162:163] op_sel_hi:[1,0]
	v_pk_mul_f32 v[116:117], v[116:117], v[162:163] op_sel_hi:[1,0]
	v_pk_mul_f32 v[114:115], v[114:115], v[162:163] op_sel_hi:[1,0]
	v_pk_mul_f32 v[112:113], v[112:113], v[162:163] op_sel_hi:[1,0]
	v_pk_mul_f32 v[160:161], v[102:103], v[162:163] op_sel_hi:[1,0]
	v_pk_mul_f32 v[100:101], v[100:101], v[162:163] op_sel_hi:[1,0]
	v_pk_mul_f32 v[164:165], v[98:99], v[162:163] op_sel_hi:[1,0]
	v_pk_mul_f32 v[162:163], v[96:97], v[162:163] op_sel_hi:[1,0]
	v_max_f32_e32 v96, 0, v124
	v_max_f32_e32 v98, 0, v120
	v_max_f32_e32 v97, 0, v125
	v_max_f32_e32 v99, 0, v121
	v_max_f32_e32 v102, 0, v126
	v_max_f32_e32 v120, 0, v122
	v_max_f32_e32 v103, 0, v127
	v_max_f32_e32 v121, 0, v123
	v_max_f32_e32 v108, 0, v108
	v_max_f32_e32 v109, 0, v109
	v_max_f32_e32 v110, 0, v110
	v_max_f32_e32 v111, 0, v111
	v_max_f32_e32 v104, 0, v104
	v_max_f32_e32 v105, 0, v105
	v_max_f32_e32 v106, 0, v106
	v_max_f32_e32 v107, 0, v107
	v_max_f32_e32 v116, 0, v116
	v_max_f32_e32 v112, 0, v112
	v_max_f32_e32 v117, 0, v117
	v_max_f32_e32 v113, 0, v113
	v_max_f32_e32 v118, 0, v118
	v_max_f32_e32 v114, 0, v114
	v_max_f32_e32 v119, 0, v119
	v_max_f32_e32 v115, 0, v115
	v_max_f32_e32 v122, 0, v100
	v_max_f32_e32 v123, 0, v101
	v_pk_mul_f32 v[96:97], v[96:97], v[96:97]
	v_pk_mul_f32 v[98:99], v[98:99], v[98:99]
	v_pk_mul_f32 v[100:101], v[102:103], v[102:103]
	v_pk_mul_f32 v[102:103], v[120:121], v[120:121]
	v_pk_mul_f32 v[108:109], v[108:109], v[108:109]
	v_pk_mul_f32 v[110:111], v[110:111], v[110:111]
	v_pk_mul_f32 v[104:105], v[104:105], v[104:105]
	v_pk_mul_f32 v[106:107], v[106:107], v[106:107]
	v_pk_mul_f32 v[116:117], v[116:117], v[116:117]
	v_pk_mul_f32 v[112:113], v[112:113], v[112:113]
	v_pk_mul_f32 v[118:119], v[118:119], v[118:119]
	v_pk_mul_f32 v[114:115], v[114:115], v[114:115]
	v_cvt_pk_bf16_f32 v96, v96, v97
	v_cvt_pk_bf16_f32 v97, v100, v101
	v_cvt_pk_bf16_f32 v98, v98, v99
	v_cvt_pk_bf16_f32 v99, v102, v103
	v_cvt_pk_bf16_f32 v100, v108, v109
	v_cvt_pk_bf16_f32 v101, v110, v111
	v_cvt_pk_bf16_f32 v102, v104, v105
	v_cvt_pk_bf16_f32 v103, v106, v107
	v_cvt_pk_bf16_f32 v104, v116, v117
	v_cvt_pk_bf16_f32 v105, v118, v119
	v_cvt_pk_bf16_f32 v106, v112, v113
	v_cvt_pk_bf16_f32 v107, v114, v115
	global_store_dwordx4 v[144:145], v[96:99], off
	global_store_dwordx4 v[144:145], v[100:103], off offset:256
	global_store_dwordx4 v[158:159], v[104:107], off
	v_pk_mul_f32 v[96:97], v[122:123], v[122:123]
	v_max_f32_e32 v100, 0, v160
	v_max_f32_e32 v101, 0, v161
	v_pk_mul_f32 v[100:101], v[100:101], v[100:101]
	v_cvt_pk_bf16_f32 v96, v96, v97
	v_cvt_pk_bf16_f32 v97, v100, v101
	v_cvt_f32_u32_e32 v100, v166
	v_max_f32_e32 v124, 0, v162
	v_max_f32_e32 v125, 0, v163
	v_max_f32_e32 v102, 0, v164
	v_max_f32_e32 v103, 0, v165
	v_pk_mul_f32 v[98:99], v[124:125], v[124:125]
	v_pk_mul_f32 v[102:103], v[102:103], v[102:103]
	v_cvt_pk_bf16_f32 v98, v98, v99
	v_cvt_pk_bf16_f32 v99, v102, v103
	global_store_dwordx4 v[158:159], v[96:99], off offset:256
	s_nop 1
	v_mul_f32_e32 v97, 0x3b800000, v100
	v_fmamk_f32 v97, v97, 0x3a000000, v156
	v_rsq_f32_e32 v98, v97
	v_or_b32_e32 v96, 32, v146
	v_ashrrev_i32_e32 v97, 31, v96
	v_lshlrev_b64 v[96:97], 14, v[96:97]
	v_pk_mul_f32 v[88:89], v[88:89], v[98:99] op_sel_hi:[1,0]
	v_pk_mul_f32 v[94:95], v[94:95], v[98:99] op_sel_hi:[1,0]
	v_pk_mul_f32 v[92:93], v[92:93], v[98:99] op_sel_hi:[1,0]
	v_pk_mul_f32 v[90:91], v[90:91], v[98:99] op_sel_hi:[1,0]
	v_max_f32_e32 v88, 0, v88
	v_max_f32_e32 v89, 0, v89
	v_max_f32_e32 v92, 0, v92
	v_max_f32_e32 v93, 0, v93
	v_pk_mul_f32 v[100:101], v[88:89], v[88:89]
	v_max_f32_e32 v88, 0, v94
	v_max_f32_e32 v90, 0, v90
	v_max_f32_e32 v89, 0, v95
	v_max_f32_e32 v91, 0, v91
	v_pk_mul_f32 v[92:93], v[92:93], v[92:93]
	v_pk_mul_f32 v[94:95], v[88:89], v[88:89]
; __device__ __forceinline__ float fast_sigmoid(float x) { return __builtin_amdgcn_rcpf(1.0f + __builtin_amdgcn_exp2f(-x * LOG2E)); }
; __device__ __forceinline__ float ss_fix(float raw) { return (float)__float_as_uint(raw) * (1.0f / 256.0f); }
;     __device__ __forceinline__ const CAS char* base() const { const CAS char* ka = (const CAS char*)__builtin_amdgcn_kernarg_segment_ptr(); asm volatile("" : "+s"(ka)); return ka; }
;     __device__ __forceinline__ void operator()(const f32x4 (&acc)[2][2][4][2], const Unit& u, int wr, int wc, int fr, int fq) const {
;     ...
;         for (int ai = 0; ai < 2; ++ai)
; #pragma unroll
;             for (int m = 0; m < 4; ++m) { const int row = row0 + ai * HALF + m * 16; float rs = 1.0f; if (SM == 1) rs = __builtin_amdgcn_rsqf(ss_fix(rsv[ai * 4 + m]) * (1.0f / DM) + EPS);
;                 bf16_t* rowp = base + (size_t)row * ldc + col0;
; #pragma unroll
;                 for (int bj = 0; bj < 2; ++bj) { f32x4 v0 = acc[ai][bj][m][0], v1 = acc[ai][bj][m][1];
;                     if (SM == 1) { v0 *= rs; v1 *= rs; }
;                     if (SM == 2) { v0 *= cs[bj][0]; v1 *= cs[bj][1]; }
;                     if (ACT == 1) {
; #pragma unroll
;                         for (int j = 0; j < 4; ++j) { const float a = fmaxf(v0[j], 0.f), b = fmaxf(v1[j], 0.f); v0[j] = a * a; v1[j] = b * b; } }
;                     if (ACT == 2) { if (tsel == 0) {
; #pragma unroll
;                         for (int j = 0; j < 4; ++j) { const float a = v0[j], b = v1[j];
;                             v0[j] = a * fast_sigmoid(1.5957691216057308f * (a + 0.044715f * a * a * a)); v1[j] = b * fast_sigmoid(1.5957691216057308f * (b + 0.044715f * b * b * b)); } } }
;                     u32x4 w; w.x = pk_bf16(v0[0], v0[1]); w.y = pk_bf16(v0[2], v0[3]); w.z = pk_bf16(v1[0], v1[1]); w.w = pk_bf16(v1[2], v1[3]);
;                     *(u32x4*)(rowp + bj * HALF) = w; } }
	v_pk_mul_f32 v[102:103], v[90:91], v[90:91]
	v_pk_mul_f32 v[84:85], v[84:85], v[98:99] op_sel_hi:[1,0]
	v_pk_mul_f32 v[80:81], v[80:81], v[98:99] op_sel_hi:[1,0]
	v_lshl_add_u64 v[96:97], v[148:149], 0, v[96:97]
	v_cvt_pk_bf16_f32 v88, v92, v93
	v_cvt_pk_bf16_f32 v89, v94, v95
	v_cvt_pk_bf16_f32 v90, v100, v101
	v_cvt_pk_bf16_f32 v91, v102, v103
	v_pk_mul_f32 v[86:87], v[86:87], v[98:99] op_sel_hi:[1,0]
	v_max_f32_e32 v84, 0, v84
	v_max_f32_e32 v80, 0, v80
	v_max_f32_e32 v85, 0, v85
	v_max_f32_e32 v81, 0, v81
	global_store_dwordx4 v[96:97], v[88:91], off
	v_pk_mul_f32 v[84:85], v[84:85], v[84:85]
	v_pk_mul_f32 v[82:83], v[82:83], v[98:99] op_sel_hi:[1,0]
	v_pk_mul_f32 v[88:89], v[80:81], v[80:81]
	v_max_f32_e32 v80, 0, v86
	v_max_f32_e32 v81, 0, v87
	v_pk_mul_f32 v[86:87], v[80:81], v[80:81]
	v_cvt_pk_bf16_f32 v80, v84, v85
	v_cvt_f32_u32_e32 v84, v167
	v_max_f32_e32 v82, 0, v82
	v_max_f32_e32 v83, 0, v83
	v_pk_mul_f32 v[90:91], v[82:83], v[82:83]
	v_cvt_pk_bf16_f32 v81, v86, v87
	v_cvt_pk_bf16_f32 v82, v88, v89
	v_cvt_pk_bf16_f32 v83, v90, v91
	global_store_dwordx4 v[96:97], v[80:83], off offset:256
	s_nop 1
	v_mul_f32_e32 v81, 0x3b800000, v84
	v_fmamk_f32 v81, v81, 0x3a000000, v156
	v_rsq_f32_e32 v82, v81
	v_or_b32_e32 v80, 48, v146
	v_ashrrev_i32_e32 v81, 31, v80
	v_lshlrev_b64 v[80:81], 14, v[80:81]
	v_pk_mul_f32 v[72:73], v[72:73], v[82:83] op_sel_hi:[1,0]
	v_pk_mul_f32 v[78:79], v[78:79], v[82:83] op_sel_hi:[1,0]
	v_pk_mul_f32 v[76:77], v[76:77], v[82:83] op_sel_hi:[1,0]
	v_pk_mul_f32 v[74:75], v[74:75], v[82:83] op_sel_hi:[1,0]
	v_max_f32_e32 v72, 0, v72
	v_max_f32_e32 v73, 0, v73
	v_max_f32_e32 v76, 0, v76
	v_max_f32_e32 v77, 0, v77
	v_pk_mul_f32 v[84:85], v[72:73], v[72:73]
	v_max_f32_e32 v72, 0, v78
	v_max_f32_e32 v74, 0, v74
	v_max_f32_e32 v73, 0, v79
	v_max_f32_e32 v75, 0, v75
	v_pk_mul_f32 v[76:77], v[76:77], v[76:77]
	v_pk_mul_f32 v[78:79], v[72:73], v[72:73]
	v_pk_mul_f32 v[86:87], v[74:75], v[74:75]
	v_pk_mul_f32 v[66:67], v[66:67], v[82:83] op_sel_hi:[1,0]
	v_lshl_add_u64 v[80:81], v[148:149], 0, v[80:81]
	v_cvt_pk_bf16_f32 v72, v76, v77
	v_cvt_pk_bf16_f32 v73, v78, v79
	v_cvt_pk_bf16_f32 v74, v84, v85
	v_cvt_pk_bf16_f32 v75, v86, v87
	v_max_f32_e32 v66, 0, v66
	v_max_f32_e32 v67, 0, v67
	global_store_dwordx4 v[80:81], v[72:75], off
	v_pk_mul_f32 v[68:69], v[68:69], v[82:83] op_sel_hi:[1,0]
	v_pk_mul_f32 v[64:65], v[64:65], v[82:83] op_sel_hi:[1,0]
	v_pk_mul_f32 v[74:75], v[66:67], v[66:67]
	v_cvt_f32_u32_e32 v67, v168
	v_pk_mul_f32 v[70:71], v[70:71], v[82:83] op_sel_hi:[1,0]
	v_max_f32_e32 v68, 0, v68
	v_max_f32_e32 v64, 0, v64
	v_max_f32_e32 v69, 0, v69
	v_max_f32_e32 v65, 0, v65
	v_mul_f32_e32 v67, 0x3b800000, v67
	v_pk_mul_f32 v[68:69], v[68:69], v[68:69]
	v_pk_mul_f32 v[72:73], v[64:65], v[64:65]
	v_max_f32_e32 v64, 0, v70
	v_max_f32_e32 v65, 0, v71
	v_fmamk_f32 v67, v67, 0x3a000000, v156
	v_pk_mul_f32 v[70:71], v[64:65], v[64:65]
	v_cvt_pk_bf16_f32 v64, v68, v69
	v_rsq_f32_e32 v68, v67
	v_cvt_pk_bf16_f32 v65, v70, v71
	v_cvt_pk_bf16_f32 v66, v72, v73
	v_cvt_pk_bf16_f32 v67, v74, v75
	v_pk_mul_f32 v[60:61], v[60:61], v[68:69] op_sel_hi:[1,0]
	v_pk_mul_f32 v[56:57], v[56:57], v[68:69] op_sel_hi:[1,0]
	v_pk_mul_f32 v[62:63], v[62:63], v[68:69] op_sel_hi:[1,0]
	v_pk_mul_f32 v[58:59], v[58:59], v[68:69] op_sel_hi:[1,0]
	v_max_f32_e32 v60, 0, v60
	v_max_f32_e32 v56, 0, v56
	v_max_f32_e32 v61, 0, v61
	v_max_f32_e32 v57, 0, v57
	global_store_dwordx4 v[80:81], v[64:67], off offset:256
	v_pk_mul_f32 v[60:61], v[60:61], v[60:61]
	v_max_f32_e32 v58, 0, v58
	v_lshl_add_u64 v[64:65], v[144:145], 0, s[34:35]
	v_pk_mul_f32 v[66:67], v[56:57], v[56:57]
	v_max_f32_e32 v56, 0, v62
	v_max_f32_e32 v57, 0, v63
	v_max_f32_e32 v59, 0, v59
	s_mov_b32 s34, 0x200000
	v_pk_mul_f32 v[62:63], v[56:57], v[56:57]
	v_pk_mul_f32 v[70:71], v[58:59], v[58:59]
	v_cvt_pk_bf16_f32 v56, v60, v61
	v_add_co_u32_e32 v60, vcc, s34, v144
	v_pk_mul_f32 v[50:51], v[50:51], v[68:69] op_sel_hi:[1,0]
	v_cvt_pk_bf16_f32 v57, v62, v63
	v_cvt_pk_bf16_f32 v58, v66, v67
	v_cvt_pk_bf16_f32 v59, v70, v71
	v_addc_co_u32_e32 v61, vcc, 0, v145, vcc
	v_max_f32_e32 v50, 0, v50
	v_max_f32_e32 v51, 0, v51
	global_store_dwordx4 v[60:61], v[56:59], off
	v_pk_mul_f32 v[52:53], v[52:53], v[68:69] op_sel_hi:[1,0]
	v_pk_mul_f32 v[48:49], v[48:49], v[68:69] op_sel_hi:[1,0]
	v_pk_mul_f32 v[58:59], v[50:51], v[50:51]
	v_cvt_f32_u32_e32 v51, v169
	v_pk_mul_f32 v[54:55], v[54:55], v[68:69] op_sel_hi:[1,0]
	v_max_f32_e32 v52, 0, v52
	v_max_f32_e32 v48, 0, v48
	v_max_f32_e32 v53, 0, v53
	v_max_f32_e32 v49, 0, v49
	v_mul_f32_e32 v51, 0x3b800000, v51
	v_pk_mul_f32 v[52:53], v[52:53], v[52:53]
	v_pk_mul_f32 v[56:57], v[48:49], v[48:49]
	v_max_f32_e32 v48, 0, v54
	v_max_f32_e32 v49, 0, v55
	v_fmamk_f32 v51, v51, 0x3a000000, v156
	v_pk_mul_f32 v[54:55], v[48:49], v[48:49]
	v_cvt_pk_bf16_f32 v48, v52, v53
	v_rsq_f32_e32 v52, v51
	v_cvt_pk_bf16_f32 v49, v54, v55
	v_cvt_pk_bf16_f32 v50, v56, v57
	v_cvt_pk_bf16_f32 v51, v58, v59
	v_pk_mul_f32 v[44:45], v[44:45], v[52:53] op_sel_hi:[1,0]
	v_pk_mul_f32 v[40:41], v[40:41], v[52:53] op_sel_hi:[1,0]
	s_mov_b64 s[34:35], 0x240000
	v_pk_mul_f32 v[46:47], v[46:47], v[52:53] op_sel_hi:[1,0]
	v_pk_mul_f32 v[42:43], v[42:43], v[52:53] op_sel_hi:[1,0]
	v_max_f32_e32 v44, 0, v44
	v_max_f32_e32 v40, 0, v40
	v_max_f32_e32 v45, 0, v45
	v_max_f32_e32 v41, 0, v41
; __device__ __forceinline__ float fast_sigmoid(float x) { return __builtin_amdgcn_rcpf(1.0f + __builtin_amdgcn_exp2f(-x * LOG2E)); }
; __device__ __forceinline__ float ss_fix(float raw) { return (float)__float_as_uint(raw) * (1.0f / 256.0f); }
; #define PG8_WAIT_V(n) asm volatile("s_waitcnt vmcnt(" #n ")" ::: "memory")
; template <class Epi>
; __device__ __forceinline__ void gemm_phase(LAS unsigned char* lds, const Gemm g, const StaticOrder& S, const Epi& E, int wv) {
;     ...
;         if (!has_next) break;
; #pragma unroll
;         for (int a = 0; a < 2; ++a)
; #pragma unroll
;             for (int b = 0; b < 2; ++b)
; #pragma unroll
;                 for (int m = 0; m < 4; ++m)
; #pragma unroll
;                     for (int n = 0; n < 2; ++n) acc[a][b][m][n] = (f32x4){0.f, 0.f, 0.f, 0.f};
;         cur = nxt; cA = nA; cB = nB; ++ui;
;     }
;     PG8_WAIT_V(0);
;     if (wr == 0) PG8_BAR;
;     PG8_BAR;
;     __device__ __forceinline__ void operator()(const f32x4 (&acc)[2][2][4][2], const Unit& u, int wr, int wc, int fr, int fq) const {
;     ...
;         for (int ai = 0; ai < 2; ++ai)
; #pragma unroll
;             for (int m = 0; m < 4; ++m) { const int row = row0 + ai * HALF + m * 16; float rs = 1.0f; if (SM == 1) rs = __builtin_amdgcn_rsqf(ss_fix(rsv[ai * 4 + m]) * (1.0f / DM) + EPS);
;                 bf16_t* rowp = base + (size_t)row * ldc + col0;
; #pragma unroll
;                 for (int bj = 0; bj < 2; ++bj) { f32x4 v0 = acc[ai][bj][m][0], v1 = acc[ai][bj][m][1];
;                     if (SM == 1) { v0 *= rs; v1 *= rs; }
;                     if (SM == 2) { v0 *= cs[bj][0]; v1 *= cs[bj][1]; }
;                     if (ACT == 1) {
; #pragma unroll
;                         for (int j = 0; j < 4; ++j) { const float a = fmaxf(v0[j], 0.f), b = fmaxf(v1[j], 0.f); v0[j] = a * a; v1[j] = b * b; } }
;                     if (ACT == 2) { if (tsel == 0) {
; #pragma unroll
;                         for (int j = 0; j < 4; ++j) { const float a = v0[j], b = v1[j];
;                             v0[j] = a * fast_sigmoid(1.5957691216057308f * (a + 0.044715f * a * a * a)); v1[j] = b * fast_sigmoid(1.5957691216057308f * (b + 0.044715f * b * b * b)); } } }
;                     u32x4 w; w.x = pk_bf16(v0[0], v0[1]); w.y = pk_bf16(v0[2], v0[3]); w.z = pk_bf16(v1[0], v1[1]); w.w = pk_bf16(v1[2], v1[3]);
;                     *(u32x4*)(rowp + bj * HALF) = w; } }
	global_store_dwordx4 v[64:65], v[48:51], off offset:256
	v_pk_mul_f32 v[44:45], v[44:45], v[44:45]
	v_max_f32_e32 v42, 0, v42
	v_lshl_add_u64 v[48:49], v[144:145], 0, s[34:35]
	v_pk_mul_f32 v[50:51], v[40:41], v[40:41]
	v_max_f32_e32 v40, 0, v46
	v_max_f32_e32 v41, 0, v47
	v_max_f32_e32 v43, 0, v43
	s_mov_b32 s34, 0x240000
	v_pk_mul_f32 v[46:47], v[40:41], v[40:41]
	v_pk_mul_f32 v[54:55], v[42:43], v[42:43]
	v_cvt_pk_bf16_f32 v40, v44, v45
	v_add_co_u32_e32 v44, vcc, s34, v144
	v_pk_mul_f32 v[34:35], v[34:35], v[52:53] op_sel_hi:[1,0]
	v_cvt_pk_bf16_f32 v41, v46, v47
	v_cvt_pk_bf16_f32 v42, v50, v51
	v_cvt_pk_bf16_f32 v43, v54, v55
	v_addc_co_u32_e32 v45, vcc, 0, v145, vcc
	v_max_f32_e32 v34, 0, v34
	v_max_f32_e32 v35, 0, v35
	global_store_dwordx4 v[44:45], v[40:43], off
	v_pk_mul_f32 v[36:37], v[36:37], v[52:53] op_sel_hi:[1,0]
	v_pk_mul_f32 v[32:33], v[32:33], v[52:53] op_sel_hi:[1,0]
	v_pk_mul_f32 v[42:43], v[34:35], v[34:35]
	v_cvt_f32_u32_e32 v35, v170
	v_pk_mul_f32 v[38:39], v[38:39], v[52:53] op_sel_hi:[1,0]
	v_max_f32_e32 v36, 0, v36
	v_max_f32_e32 v32, 0, v32
	v_max_f32_e32 v37, 0, v37
	v_max_f32_e32 v33, 0, v33
	v_mul_f32_e32 v35, 0x3b800000, v35
	v_pk_mul_f32 v[36:37], v[36:37], v[36:37]
	v_pk_mul_f32 v[40:41], v[32:33], v[32:33]
	v_max_f32_e32 v32, 0, v38
	v_max_f32_e32 v33, 0, v39
	v_fmamk_f32 v35, v35, 0x3a000000, v156
	v_pk_mul_f32 v[38:39], v[32:33], v[32:33]
	v_cvt_pk_bf16_f32 v32, v36, v37
	v_rsq_f32_e32 v36, v35
	v_cvt_pk_bf16_f32 v33, v38, v39
	v_cvt_pk_bf16_f32 v34, v40, v41
	v_cvt_pk_bf16_f32 v35, v42, v43
	v_pk_mul_f32 v[28:29], v[28:29], v[36:37] op_sel_hi:[1,0]
	v_pk_mul_f32 v[24:25], v[24:25], v[36:37] op_sel_hi:[1,0]
	v_pk_mul_f32 v[30:31], v[30:31], v[36:37] op_sel_hi:[1,0]
	v_pk_mul_f32 v[26:27], v[26:27], v[36:37] op_sel_hi:[1,0]
	v_max_f32_e32 v28, 0, v28
	v_max_f32_e32 v24, 0, v24
	v_max_f32_e32 v29, 0, v29
	v_max_f32_e32 v25, 0, v25
	global_store_dwordx4 v[48:49], v[32:35], off offset:256
	v_pk_mul_f32 v[28:29], v[28:29], v[28:29]
	v_max_f32_e32 v26, 0, v26
	v_pk_mul_f32 v[34:35], v[24:25], v[24:25]
	v_max_f32_e32 v24, 0, v30
	v_max_f32_e32 v25, 0, v31
	v_max_f32_e32 v27, 0, v27
	v_pk_mul_f32 v[30:31], v[24:25], v[24:25]
	v_pk_mul_f32 v[38:39], v[26:27], v[26:27]
	v_cvt_pk_bf16_f32 v24, v28, v29
	v_add_co_u32_e32 v28, vcc, s25, v144
	v_pk_mul_f32 v[18:19], v[18:19], v[36:37] op_sel_hi:[1,0]
	v_cvt_pk_bf16_f32 v25, v30, v31
	v_cvt_pk_bf16_f32 v26, v34, v35
	v_cvt_pk_bf16_f32 v27, v38, v39
	v_addc_co_u32_e32 v29, vcc, 0, v145, vcc
	v_max_f32_e32 v18, 0, v18
	v_max_f32_e32 v19, 0, v19
	global_store_dwordx4 v[28:29], v[24:27], off
	v_pk_mul_f32 v[20:21], v[20:21], v[36:37] op_sel_hi:[1,0]
	v_pk_mul_f32 v[16:17], v[16:17], v[36:37] op_sel_hi:[1,0]
	v_pk_mul_f32 v[26:27], v[18:19], v[18:19]
	v_cvt_f32_u32_e32 v19, v147
	v_pk_mul_f32 v[22:23], v[22:23], v[36:37] op_sel_hi:[1,0]
	v_max_f32_e32 v20, 0, v20
	v_max_f32_e32 v16, 0, v16
	v_max_f32_e32 v21, 0, v21
	v_max_f32_e32 v17, 0, v17
	v_mul_f32_e32 v19, 0x3b800000, v19
	v_pk_mul_f32 v[20:21], v[20:21], v[20:21]
	v_pk_mul_f32 v[24:25], v[16:17], v[16:17]
	v_max_f32_e32 v16, 0, v22
	v_max_f32_e32 v17, 0, v23
	v_fmamk_f32 v19, v19, 0x3a000000, v156
	v_pk_mul_f32 v[22:23], v[16:17], v[16:17]
	v_cvt_pk_bf16_f32 v16, v20, v21
	v_rsq_f32_e32 v20, v19
	s_mov_b64 s[34:35], 0x280000
	v_lshl_add_u64 v[32:33], v[144:145], 0, s[34:35]
	v_cvt_pk_bf16_f32 v17, v22, v23
	v_pk_mul_f32 v[12:13], v[12:13], v[20:21] op_sel_hi:[1,0]
	v_pk_mul_f32 v[8:9], v[8:9], v[20:21] op_sel_hi:[1,0]
	v_cvt_pk_bf16_f32 v18, v24, v25
	v_cvt_pk_bf16_f32 v19, v26, v27
	v_pk_mul_f32 v[14:15], v[14:15], v[20:21] op_sel_hi:[1,0]
	v_pk_mul_f32 v[10:11], v[10:11], v[20:21] op_sel_hi:[1,0]
	v_max_f32_e32 v12, 0, v12
	v_max_f32_e32 v8, 0, v8
	v_max_f32_e32 v13, 0, v13
	v_max_f32_e32 v9, 0, v9
	global_store_dwordx4 v[32:33], v[16:19], off offset:256
	v_pk_mul_f32 v[12:13], v[12:13], v[12:13]
	v_max_f32_e32 v10, 0, v10
	v_pk_mul_f32 v[18:19], v[8:9], v[8:9]
	v_max_f32_e32 v8, 0, v14
	v_max_f32_e32 v9, 0, v15
	v_max_f32_e32 v11, 0, v11
	v_pk_mul_f32 v[14:15], v[8:9], v[8:9]
	v_pk_mul_f32 v[22:23], v[10:11], v[10:11]
	v_cvt_pk_bf16_f32 v8, v12, v13
	v_add_co_u32_e32 v12, vcc, s33, v144
	v_pk_mul_f32 v[0:1], v[0:1], v[20:21] op_sel_hi:[1,0]
	v_cvt_pk_bf16_f32 v9, v14, v15
	v_cvt_pk_bf16_f32 v10, v18, v19
	v_cvt_pk_bf16_f32 v11, v22, v23
	v_addc_co_u32_e32 v13, vcc, 0, v145, vcc
	v_pk_mul_f32 v[6:7], v[6:7], v[20:21] op_sel_hi:[1,0]
	v_pk_mul_f32 v[4:5], v[4:5], v[20:21] op_sel_hi:[1,0]
	v_pk_mul_f32 v[2:3], v[2:3], v[20:21] op_sel_hi:[1,0]
	v_max_f32_e32 v0, 0, v0
	v_max_f32_e32 v1, 0, v1
	global_store_dwordx4 v[12:13], v[8:11], off
	v_max_f32_e32 v4, 0, v4
	v_max_f32_e32 v5, 0, v5
	v_pk_mul_f32 v[8:9], v[0:1], v[0:1]
	v_max_f32_e32 v0, 0, v6
	v_max_f32_e32 v2, 0, v2
	v_max_f32_e32 v1, 0, v7
	v_max_f32_e32 v3, 0, v3
	v_pk_mul_f32 v[4:5], v[4:5], v[4:5]
	v_pk_mul_f32 v[6:7], v[0:1], v[0:1]
	v_pk_mul_f32 v[10:11], v[2:3], v[2:3]
	v_lshl_add_u64 v[16:17], v[144:145], 0, s[54:55]
	v_cvt_pk_bf16_f32 v0, v4, v5
	v_cvt_pk_bf16_f32 v1, v6, v7
	v_cvt_pk_bf16_f32 v2, v8, v9
	v_cvt_pk_bf16_f32 v3, v10, v11
	s_and_b64 vcc, exec, s[16:17]
	s_mov_b32 s34, s56
	global_store_dwordx4 v[16:17], v[0:3], off offset:256
	s_cbranch_vccz .LBB0_523
	s_waitcnt vmcnt(0)
	s_cmpk_gt_u32 s4, 0xff
	s_cbranch_scc1 .LBB0_534
	s_barrier

; #define PG8_BAR __builtin_amdgcn_s_barrier()
; template <class Epi>
; __device__ __forceinline__ void gemm_phase(LAS unsigned char* lds, const Gemm g, const StaticOrder& S, const Epi& E, int wv) {
;     ...
;         const bool has_next = S.next(ui + 1, nxt);
;         const char* nA = has_next ? (const char*)g.A + (size_t)nxt.pm * tstepA + ((g.adiag & 1) ? (size_t)(nxt.pn >> 1) * K * 2 : 0) + kbeg : cA;
;         const char* nB = has_next ? (const char*)g.Bt + (size_t)nxt.pn * tstepB + kbeg : cB;
;         for (int t = 0; t < nt; t += 2) {
;             const bool last = (t == nt - 2);
;             const char* a1 = cA + (ptrdiff_t)(t + 1) * kstep;
;             const char* a2 = last ? nA : cA + (ptrdiff_t)(t + 2) * kstep; const char* b2 = last ? nB : cB + (ptrdiff_t)(t + 2) * kstep;
;             const char* a3 = a2 + kstep; const char* b3 = b2 + kstep;
;             PG8_LDB(B0, 0, 0); PG8_SCHED; PG8_LDA(At, 0, 0); PG8_STAGE(PG8_SA(1, 1), a1 + hstepA, voffA);
;             PG8_WAIT_L(8); PG8_BAR; PG8_WAIT_L(0); PG8_MMA(0, 0, At, B0); PG8_BAR; PG8_SCHED;
;             PG8_LDB(B1, 0, 1); PG8_STAGE(PG8_SB(0, 0), b2, voffB);
;             PG8_BAR; PG8_WAIT_L(0); PG8_MMA(0, 1, At, B1); PG8_BAR;
;             PG8_LDA(At, 0, 1); PG8_STAGE(PG8_SA(0, 0), a2, voffA);
;             PG8_BAR; PG8_WAIT_L(0); PG8_MMA(1, 0, At, B0); PG8_BAR; PG8_SCHED;
;             PG8_STAGE(PG8_SB(0, 1), b2 + hstepB, voffB);
;             PG8_WAIT_V(6); PG8_BAR; PG8_MMA(1, 1, At, B1); PG8_BAR;
;             PG8_LDB(B0, 1, 0); PG8_SCHED; PG8_LDA(At, 1, 0); PG8_STAGE(PG8_SA(0, 1), a2 + hstepA, voffA);
;             PG8_WAIT_L(8); PG8_BAR; PG8_WAIT_L(0); PG8_MMA(0, 0, At, B0); PG8_BAR; PG8_SCHED;
;             PG8_LDB(B1, 1, 1); PG8_STAGE(PG8_SB(1, 0), b3, voffB);
;             PG8_BAR; PG8_WAIT_L(0); PG8_MMA(0, 1, At, B1); PG8_BAR;
;             PG8_LDA(At, 1, 1); PG8_STAGE(PG8_SA(1, 0), a3, voffA);
;             PG8_BAR; PG8_WAIT_L(0); PG8_MMA(1, 0, At, B0); PG8_BAR; PG8_SCHED;
;             PG8_STAGE(PG8_SB(1, 1), b3 + hstepB, voffB);
;             PG8_WAIT_V(6); PG8_BAR; PG8_MMA(1, 1, At, B1); PG8_BAR;
;         }
;         E(acc, cur, wr, wc, fr, fq);
;         if (!has_next) break;
; #pragma unroll
;         for (int a = 0; a < 2; ++a)
; #pragma unroll
;             for (int b = 0; b < 2; ++b)
; #pragma unroll
;                 for (int m = 0; m < 4; ++m)
; #pragma unroll
.LBB0_716:
	s_ashr_i32 s65, s64, 31
	s_lshl_b64 s[34:35], s[64:65], 20
	v_cmp_lt_i64_e32 vcc, s[66:67], v[172:173]
	s_add_u32 s66, s5, s34
	s_addc_u32 s67, s6, s35
	s_and_b64 s[34:35], vcc, exec
	s_cselect_b32 s33, s67, s77
	s_cselect_b32 s34, s66, s76
	s_ashr_i32 s63, s62, 31
	s_lshl_b64 s[38:39], s[62:63], 20
	s_add_u32 s68, s7, s38
	s_addc_u32 s69, s8, s39
	s_and_b64 s[38:39], vcc, exec
	s_cselect_b32 s35, s69, s75
	s_cselect_b32 s38, s68, s74
	s_add_u32 s39, s74, 0x100
	s_addc_u32 s40, s75, 0
	s_add_u32 s74, s76, 0x80080
	v_mov_b32_e32 v0, 0
	s_addc_u32 s75, s77, 0
	s_mov_b32 s41, -2
	s_waitcnt lgkmcnt(0)
	v_mov_b32_e32 v1, v0
	v_mov_b32_e32 v2, v0
	v_mov_b32_e32 v3, v0
	v_mov_b32_e32 v4, v0
	v_mov_b32_e32 v5, v0
	v_mov_b32_e32 v6, v0
	v_mov_b32_e32 v7, v0
	v_mov_b32_e32 v16, v0
	v_mov_b32_e32 v17, v0
	v_mov_b32_e32 v18, v0
	v_mov_b32_e32 v19, v0
	v_mov_b32_e32 v20, v0
	v_mov_b32_e32 v21, v0
	v_mov_b32_e32 v22, v0
	v_mov_b32_e32 v23, v0
	v_mov_b32_e32 v32, v0
	v_mov_b32_e32 v33, v0
	v_mov_b32_e32 v34, v0
	v_mov_b32_e32 v35, v0
	v_mov_b32_e32 v36, v0
	v_mov_b32_e32 v37, v0
	v_mov_b32_e32 v38, v0
	v_mov_b32_e32 v39, v0
	v_mov_b32_e32 v48, v0
	v_mov_b32_e32 v49, v0
	v_mov_b32_e32 v50, v0
	v_mov_b32_e32 v51, v0
	v_mov_b32_e32 v52, v0
	v_mov_b32_e32 v53, v0
	v_mov_b32_e32 v54, v0
	v_mov_b32_e32 v55, v0
	v_mov_b32_e32 v8, v0
	v_mov_b32_e32 v9, v0
	v_mov_b32_e32 v10, v0
	v_mov_b32_e32 v11, v0
	v_mov_b32_e32 v12, v0
	v_mov_b32_e32 v13, v0
	v_mov_b32_e32 v14, v0
	v_mov_b32_e32 v15, v0
	v_mov_b32_e32 v24, v0
	v_mov_b32_e32 v25, v0
	v_mov_b32_e32 v26, v0
	v_mov_b32_e32 v27, v0
	v_mov_b32_e32 v28, v0
	v_mov_b32_e32 v29, v0
	v_mov_b32_e32 v30, v0
	v_mov_b32_e32 v31, v0
	v_mov_b32_e32 v40, v0
	v_mov_b32_e32 v41, v0
	v_mov_b32_e32 v42, v0
	v_mov_b32_e32 v43, v0
	v_mov_b32_e32 v44, v0
	v_mov_b32_e32 v45, v0
	v_mov_b32_e32 v46, v0
	v_mov_b32_e32 v47, v0
	v_mov_b32_e32 v56, v0
	v_mov_b32_e32 v57, v0
	v_mov_b32_e32 v58, v0
	v_mov_b32_e32 v59, v0
	v_mov_b32_e32 v60, v0
	v_mov_b32_e32 v61, v0
	v_mov_b32_e32 v62, v0
	v_mov_b32_e32 v63, v0
	v_mov_b32_e32 v64, v0
	v_mov_b32_e32 v65, v0
	v_mov_b32_e32 v66, v0
	v_mov_b32_e32 v67, v0
	v_mov_b32_e32 v68, v0
	v_mov_b32_e32 v69, v0
	v_mov_b32_e32 v70, v0
	v_mov_b32_e32 v71, v0
	v_mov_b32_e32 v80, v0
	v_mov_b32_e32 v81, v0
	v_mov_b32_e32 v82, v0
	v_mov_b32_e32 v83, v0
	v_mov_b32_e32 v84, v0
	v_mov_b32_e32 v85, v0
	v_mov_b32_e32 v86, v0
	v_mov_b32_e32 v87, v0
	v_mov_b32_e32 v96, v0
	v_mov_b32_e32 v97, v0
	v_mov_b32_e32 v98, v0
	v_mov_b32_e32 v99, v0
	v_mov_b32_e32 v100, v0
	v_mov_b32_e32 v101, v0
	v_mov_b32_e32 v102, v0
	v_mov_b32_e32 v103, v0
	v_mov_b32_e32 v112, v0
	v_mov_b32_e32 v113, v0
	v_mov_b32_e32 v114, v0
	v_mov_b32_e32 v115, v0
	v_mov_b32_e32 v116, v0
	v_mov_b32_e32 v117, v0
	v_mov_b32_e32 v118, v0
	v_mov_b32_e32 v119, v0
	v_mov_b32_e32 v72, v0
	v_mov_b32_e32 v73, v0
	v_mov_b32_e32 v74, v0
	v_mov_b32_e32 v75, v0
	v_mov_b32_e32 v76, v0
	v_mov_b32_e32 v77, v0
	v_mov_b32_e32 v78, v0
	v_mov_b32_e32 v79, v0
	v_mov_b32_e32 v88, v0
	v_mov_b32_e32 v89, v0
	v_mov_b32_e32 v90, v0
	v_mov_b32_e32 v91, v0
	v_mov_b32_e32 v92, v0
	v_mov_b32_e32 v93, v0
	v_mov_b32_e32 v94, v0
	v_mov_b32_e32 v95, v0
	v_mov_b32_e32 v104, v0
	v_mov_b32_e32 v105, v0
	v_mov_b32_e32 v106, v0
	v_mov_b32_e32 v107, v0
	v_mov_b32_e32 v108, v0
	v_mov_b32_e32 v109, v0
	v_mov_b32_e32 v110, v0
	v_mov_b32_e32 v111, v0
	v_mov_b32_e32 v120, v0
	v_mov_b32_e32 v121, v0
	v_mov_b32_e32 v122, v0
	v_mov_b32_e32 v123, v0
	v_mov_b32_e32 v124, v0
	v_mov_b32_e32 v125, v0
	v_mov_b32_e32 v126, v0
	v_mov_b32_e32 v127, v0
	ds_read_b128 v[128:131], v193
	ds_read_b128 v[132:135], v193 offset:1024
	ds_read_b128 v[136:139], v193 offset:2048
	ds_read_b128 v[140:143], v193 offset:3072
	s_branch .Lrot_in_717
.LBB0_717:
	s_barrier
	v_mfma_f32_16x16x32_bf16 v[52:55], v[202:205], v[144:147], v[52:55]
	v_mfma_f32_16x16x32_bf16 v[48:51], v[210:213], v[144:147], v[48:51]
	v_mfma_f32_16x16x32_bf16 v[36:39], v[202:205], v[152:155], v[36:39]
	v_mfma_f32_16x16x32_bf16 v[32:35], v[210:213], v[152:155], v[32:35]
	v_mfma_f32_16x16x32_bf16 v[20:23], v[202:205], v[176:179], v[20:23]
	v_mfma_f32_16x16x32_bf16 v[16:19], v[210:213], v[176:179], v[16:19]
	v_mfma_f32_16x16x32_bf16 v[4:7], v[202:205], v[184:187], v[4:7]
	v_mfma_f32_16x16x32_bf16 v[0:3], v[210:213], v[184:187], v[0:3]
	v_mfma_f32_16x16x32_bf16 v[52:55], v[206:209], v[148:151], v[52:55]
	v_mfma_f32_16x16x32_bf16 v[48:51], v[214:217], v[148:151], v[48:51]
	v_mfma_f32_16x16x32_bf16 v[36:39], v[206:209], v[156:159], v[36:39]
	v_mfma_f32_16x16x32_bf16 v[32:35], v[214:217], v[156:159], v[32:35]
	v_mfma_f32_16x16x32_bf16 v[20:23], v[206:209], v[180:183], v[20:23]
	v_mfma_f32_16x16x32_bf16 v[16:19], v[214:217], v[180:183], v[16:19]
	v_mfma_f32_16x16x32_bf16 v[4:7], v[206:209], v[198:201], v[4:7]
	v_mfma_f32_16x16x32_bf16 v[0:3], v[214:217], v[198:201], v[0:3]
	s_waitcnt lgkmcnt(0)
	s_add_i32 s41, s41, 2
	s_add_u32 s39, s39, 0x100
	s_addc_u32 s40, s40, 0
	s_add_u32 s74, s74, 0x100
	s_addc_u32 s75, s75, 0
	s_cmp_gt_u32 s41, 29
	s_barrier
	s_cbranch_scc1 .Lrot_out_717
; #define PG8_STAGE(bufoff, gbase, voff) do { _Pragma("unroll") for (int _i = 0; _i < 2; ++_i) \
;         __builtin_amdgcn_global_load_lds((const unsigned*)((const char*)(gbase) + (voff)[_i]), (LAS unsigned*)(lds + (bufoff) + ldsw + _i * 8192), 16, 0, 0); } while (0)
; #define PG8_LDA(dst, b, h) do { _Pragma("unroll") for (int m = 0; m < 4; ++m) _Pragma("unroll") for (int k = 0; k < 2; ++k) dst[m][k] = *(const LAS bf16x8*)(lds + PG8_SA(b, h) + aoff + m * 2048 + k * 1024); } while (0)
; #define PG8_LDB(dst, b, h) do { _Pragma("unroll") for (int n = 0; n < 2; ++n) _Pragma("unroll") for (int k = 0; k < 2; ++k) dst[n][k] = *(const LAS bf16x8*)(lds + PG8_SB(b, h) + boff + n * 2048 + k * 1024); } while (0)
; #define PG8_MMA(ai, bj, At, Bt) do { __builtin_amdgcn_s_setprio(1); _Pragma("unroll") for (int m = 0; m < 4; ++m) _Pragma("unroll") for (int n = 0; n < 2; ++n) _Pragma("unroll") for (int k = 0; k < 2; ++k) \
;         acc[ai][bj][m][n] = __builtin_amdgcn_mfma_f32_16x16x32_bf16(Bt[n][k], At[m][k], acc[ai][bj][m][n], 0, 0, 0); __builtin_amdgcn_s_setprio(0); } while (0)
; #define PG8_WAIT_V(n) asm volatile("s_waitcnt vmcnt(" #n ")" ::: "memory")
; #define PG8_WAIT_L(n) asm volatile("s_waitcnt lgkmcnt(" #n ")" ::: "memory")
; #define PG8_BAR __builtin_amdgcn_s_barrier()
; template <class Epi>
; __device__ __forceinline__ void gemm_phase(LAS unsigned char* lds, const Gemm g, const StaticOrder& S, const Epi& E, int wv) {
;     ...
;             const bool last = (t == nt - 2);
;             const char* a1 = cA + (ptrdiff_t)(t + 1) * kstep;
;             const char* a2 = last ? nA : cA + (ptrdiff_t)(t + 2) * kstep; const char* b2 = last ? nB : cB + (ptrdiff_t)(t + 2) * kstep;
;             const char* a3 = a2 + kstep; const char* b3 = b2 + kstep;
;             PG8_LDB(B0, 0, 0); PG8_SCHED; PG8_LDA(At, 0, 0); PG8_STAGE(PG8_SA(1, 1), a1 + hstepA, voffA);
;             PG8_WAIT_L(8); PG8_BAR; PG8_WAIT_L(0); PG8_MMA(0, 0, At, B0); PG8_BAR; PG8_SCHED;
;             PG8_LDB(B1, 0, 1); PG8_STAGE(PG8_SB(0, 0), b2, voffB);
;             PG8_BAR; PG8_WAIT_L(0); PG8_MMA(0, 1, At, B1); PG8_BAR;
;             PG8_LDA(At, 0, 1); PG8_STAGE(PG8_SA(0, 0), a2, voffA);
;             PG8_BAR; PG8_WAIT_L(0); PG8_MMA(1, 0, At, B0); PG8_BAR; PG8_SCHED;
;             PG8_STAGE(PG8_SB(0, 1), b2 + hstepB, voffB);
;             PG8_WAIT_V(6); PG8_BAR; PG8_MMA(1, 1, At, B1); PG8_BAR;
.Lrot_in_717:
	s_add_u32 s42, s74, 0xfff80080
	s_addc_u32 s43, s75, -1
	s_cmp_eq_u32 s41, 28
	s_cselect_b32 s79, s33, s43
	s_cselect_b32 s78, s34, s42
	s_cselect_b32 s77, s35, s40
	s_cselect_b32 s76, s38, s39
	s_add_i32 m0, s10, 0xc000
	ds_read_b128 v[144:147], v194
	ds_read_b128 v[148:151], v194 offset:1024
	ds_read_b128 v[152:155], v194 offset:2048
	ds_read_b128 v[156:159], v194 offset:3072
	ds_read_b128 v[176:179], v194 offset:4096
	ds_read_b128 v[180:183], v194 offset:5120
	ds_read_b128 v[184:187], v194 offset:6144
	ds_read_b128 v[198:201], v194 offset:7168
	global_load_lds_dwordx4 v170, s[74:75]
	s_add_i32 m0, s10, 0xe000
	s_nop 0
	global_load_lds_dwordx4 v168, s[74:75]
	s_waitcnt lgkmcnt(8)
	s_barrier
	s_waitcnt lgkmcnt(0)
	s_waitcnt lgkmcnt(0)
	v_mfma_f32_16x16x32_bf16 v[124:127], v[128:131], v[144:147], v[124:127]
	v_mfma_f32_16x16x32_bf16 v[120:123], v[136:139], v[144:147], v[120:123]
	v_mfma_f32_16x16x32_bf16 v[108:111], v[128:131], v[152:155], v[108:111]
	v_mfma_f32_16x16x32_bf16 v[104:107], v[136:139], v[152:155], v[104:107]
	v_mfma_f32_16x16x32_bf16 v[92:95], v[128:131], v[176:179], v[92:95]
	v_mfma_f32_16x16x32_bf16 v[88:91], v[136:139], v[176:179], v[88:91]
	v_mfma_f32_16x16x32_bf16 v[76:79], v[128:131], v[184:187], v[76:79]
	v_mfma_f32_16x16x32_bf16 v[72:75], v[136:139], v[184:187], v[72:75]
	v_mfma_f32_16x16x32_bf16 v[124:127], v[132:135], v[148:151], v[124:127]
	v_mfma_f32_16x16x32_bf16 v[120:123], v[140:143], v[148:151], v[120:123]
	v_mfma_f32_16x16x32_bf16 v[108:111], v[132:135], v[156:159], v[108:111]
	v_mfma_f32_16x16x32_bf16 v[104:107], v[140:143], v[156:159], v[104:107]
	v_mfma_f32_16x16x32_bf16 v[92:95], v[132:135], v[180:183], v[92:95]
	v_mfma_f32_16x16x32_bf16 v[88:91], v[140:143], v[180:183], v[88:91]
	v_mfma_f32_16x16x32_bf16 v[76:79], v[132:135], v[198:201], v[76:79]
	v_mfma_f32_16x16x32_bf16 v[72:75], v[140:143], v[198:201], v[72:75]
	s_barrier
	s_add_i32 s42, s23, s9
	s_add_u32 s98, s76, s60
	s_addc_u32 s99, s77, s61
	s_mov_b32 m0, s42
	ds_read_b128 v[202:205], v195
	ds_read_b128 v[206:209], v195 offset:1024
	ds_read_b128 v[210:213], v195 offset:2048
	ds_read_b128 v[214:217], v195 offset:3072
	global_load_lds_dwordx4 v162, s[76:77]
	s_add_i32 m0, s42, 0x2000
	s_nop 0
	global_load_lds_dwordx4 v166, s[76:77]
	s_barrier
	s_waitcnt lgkmcnt(0)
	s_waitcnt lgkmcnt(0)
	v_mfma_f32_16x16x32_bf16 v[116:119], v[202:205], v[144:147], v[116:119]
	v_mfma_f32_16x16x32_bf16 v[112:115], v[210:213], v[144:147], v[112:115]
	v_mfma_f32_16x16x32_bf16 v[100:103], v[202:205], v[152:155], v[100:103]
	v_mfma_f32_16x16x32_bf16 v[96:99], v[210:213], v[152:155], v[96:99]
	v_mfma_f32_16x16x32_bf16 v[84:87], v[202:205], v[176:179], v[84:87]
	v_mfma_f32_16x16x32_bf16 v[80:83], v[210:213], v[176:179], v[80:83]
	v_mfma_f32_16x16x32_bf16 v[68:71], v[202:205], v[184:187], v[68:71]
	v_mfma_f32_16x16x32_bf16 v[64:67], v[210:213], v[184:187], v[64:67]
	v_mfma_f32_16x16x32_bf16 v[116:119], v[206:209], v[148:151], v[116:119]
	v_mfma_f32_16x16x32_bf16 v[112:115], v[214:217], v[148:151], v[112:115]
	v_mfma_f32_16x16x32_bf16 v[100:103], v[206:209], v[156:159], v[100:103]
	v_mfma_f32_16x16x32_bf16 v[96:99], v[214:217], v[156:159], v[96:99]
	v_mfma_f32_16x16x32_bf16 v[84:87], v[206:209], v[180:183], v[84:87]
	v_mfma_f32_16x16x32_bf16 v[80:83], v[214:217], v[180:183], v[80:83]
	v_mfma_f32_16x16x32_bf16 v[68:71], v[206:209], v[198:201], v[68:71]
	v_mfma_f32_16x16x32_bf16 v[64:67], v[214:217], v[198:201], v[64:67]
	s_mov_b32 m0, s10
	s_add_u32 s100, s78, s60
	s_addc_u32 s101, s79, s61
	s_barrier
	ds_read_b128 v[144:147], v194 offset:16384
	ds_read_b128 v[148:151], v194 offset:17408
	ds_read_b128 v[152:155], v194 offset:18432
	ds_read_b128 v[156:159], v194 offset:19456
	ds_read_b128 v[176:179], v194 offset:20480
	ds_read_b128 v[180:183], v194 offset:21504
	ds_read_b128 v[184:187], v194 offset:22528
	ds_read_b128 v[198:201], v194 offset:23552
	global_load_lds_dwordx4 v160, s[78:79]
	s_mov_b32 m0, s11
	s_nop 0
	global_load_lds_dwordx4 v164, s[78:79]
	s_waitcnt vmcnt(10)
	s_barrier
	s_waitcnt lgkmcnt(0)
	s_waitcnt lgkmcnt(0)
	v_mfma_f32_16x16x32_bf16 v[60:63], v[128:131], v[144:147], v[60:63]
	v_mfma_f32_16x16x32_bf16 v[56:59], v[136:139], v[144:147], v[56:59]
	v_mfma_f32_16x16x32_bf16 v[44:47], v[128:131], v[152:155], v[44:47]
	v_mfma_f32_16x16x32_bf16 v[40:43], v[136:139], v[152:155], v[40:43]
	v_mfma_f32_16x16x32_bf16 v[28:31], v[128:131], v[176:179], v[28:31]
	v_mfma_f32_16x16x32_bf16 v[24:27], v[136:139], v[176:179], v[24:27]
	v_mfma_f32_16x16x32_bf16 v[12:15], v[128:131], v[184:187], v[12:15]
	v_mfma_f32_16x16x32_bf16 v[8:11], v[136:139], v[184:187], v[8:11]
	v_mfma_f32_16x16x32_bf16 v[60:63], v[132:135], v[148:151], v[60:63]
	v_mfma_f32_16x16x32_bf16 v[56:59], v[140:143], v[148:151], v[56:59]
	v_mfma_f32_16x16x32_bf16 v[44:47], v[132:135], v[156:159], v[44:47]
	v_mfma_f32_16x16x32_bf16 v[40:43], v[140:143], v[156:159], v[40:43]
	v_mfma_f32_16x16x32_bf16 v[28:31], v[132:135], v[180:183], v[28:31]
	v_mfma_f32_16x16x32_bf16 v[24:27], v[140:143], v[180:183], v[24:27]
	v_mfma_f32_16x16x32_bf16 v[12:15], v[132:135], v[198:201], v[12:15]
	v_mfma_f32_16x16x32_bf16 v[8:11], v[140:143], v[198:201], v[8:11]
	s_barrier
	s_add_u32 s42, s76, 0x80000
	s_addc_u32 s43, s77, 0
	s_add_i32 s44, s24, s9
	s_mov_b32 m0, s44
	s_nop 0
	global_load_lds_dwordx4 v162, s[42:43]
	s_add_i32 m0, s44, 0x2000
	s_nop 0
	global_load_lds_dwordx4 v166, s[42:43]
	s_add_i32 s44, 0, 0x18000
	v_add_u32_e32 v140, s44, v191
	ds_read_b128 v[128:131], v140
	ds_read_b128 v[132:135], v140 offset:1024
	ds_read_b128 v[136:139], v140 offset:2048
	ds_read_b128 v[140:143], v140 offset:3072
	s_waitcnt vmcnt(6)
	s_barrier
; #define PG8_STAGE(bufoff, gbase, voff) do { _Pragma("unroll") for (int _i = 0; _i < 2; ++_i) \
;         __builtin_amdgcn_global_load_lds((const unsigned*)((const char*)(gbase) + (voff)[_i]), (LAS unsigned*)(lds + (bufoff) + ldsw + _i * 8192), 16, 0, 0); } while (0)
; #define PG8_LDA(dst, b, h) do { _Pragma("unroll") for (int m = 0; m < 4; ++m) _Pragma("unroll") for (int k = 0; k < 2; ++k) dst[m][k] = *(const LAS bf16x8*)(lds + PG8_SA(b, h) + aoff + m * 2048 + k * 1024); } while (0)
; #define PG8_LDB(dst, b, h) do { _Pragma("unroll") for (int n = 0; n < 2; ++n) _Pragma("unroll") for (int k = 0; k < 2; ++k) dst[n][k] = *(const LAS bf16x8*)(lds + PG8_SB(b, h) + boff + n * 2048 + k * 1024); } while (0)
; #define PG8_MMA(ai, bj, At, Bt) do { __builtin_amdgcn_s_setprio(1); _Pragma("unroll") for (int m = 0; m < 4; ++m) _Pragma("unroll") for (int n = 0; n < 2; ++n) _Pragma("unroll") for (int k = 0; k < 2; ++k) \
;         acc[ai][bj][m][n] = __builtin_amdgcn_mfma_f32_16x16x32_bf16(Bt[n][k], At[m][k], acc[ai][bj][m][n], 0, 0, 0); __builtin_amdgcn_s_setprio(0); } while (0)
; #define PG8_WAIT_V(n) asm volatile("s_waitcnt vmcnt(" #n ")" ::: "memory")
; #define PG8_WAIT_L(n) asm volatile("s_waitcnt lgkmcnt(" #n ")" ::: "memory")
; #define PG8_BAR __builtin_amdgcn_s_barrier()
; #define PG8_SCHED __builtin_amdgcn_sched_barrier(0)
; template <class Epi>
; __device__ __forceinline__ void gemm_phase(LAS unsigned char* lds, const Gemm g, const StaticOrder& S, const Epi& E, int wv) {
;     ...
;             PG8_WAIT_V(6); PG8_BAR; PG8_MMA(1, 1, At, B1); PG8_BAR;
;             PG8_LDB(B0, 1, 0); PG8_SCHED; PG8_LDA(At, 1, 0); PG8_STAGE(PG8_SA(0, 1), a2 + hstepA, voffA);
;             PG8_WAIT_L(8); PG8_BAR; PG8_WAIT_L(0); PG8_MMA(0, 0, At, B0); PG8_BAR; PG8_SCHED;
;             PG8_LDB(B1, 1, 1); PG8_STAGE(PG8_SB(1, 0), b3, voffB);
;             PG8_BAR; PG8_WAIT_L(0); PG8_MMA(0, 1, At, B1); PG8_BAR;
;             PG8_LDA(At, 1, 1); PG8_STAGE(PG8_SA(1, 0), a3, voffA);
;             PG8_BAR; PG8_WAIT_L(0); PG8_MMA(1, 0, At, B0); PG8_BAR; PG8_SCHED;
;             PG8_STAGE(PG8_SB(1, 1), b3 + hstepB, voffB);
;             PG8_WAIT_V(6); PG8_BAR; PG8_MMA(1, 1, At, B1); PG8_BAR;
	v_mfma_f32_16x16x32_bf16 v[52:55], v[202:205], v[144:147], v[52:55]
	v_mfma_f32_16x16x32_bf16 v[48:51], v[210:213], v[144:147], v[48:51]
	v_mfma_f32_16x16x32_bf16 v[36:39], v[202:205], v[152:155], v[36:39]
	v_mfma_f32_16x16x32_bf16 v[32:35], v[210:213], v[152:155], v[32:35]
	v_mfma_f32_16x16x32_bf16 v[20:23], v[202:205], v[176:179], v[20:23]
	v_mfma_f32_16x16x32_bf16 v[16:19], v[210:213], v[176:179], v[16:19]
	v_mfma_f32_16x16x32_bf16 v[4:7], v[202:205], v[184:187], v[4:7]
	v_mfma_f32_16x16x32_bf16 v[0:3], v[210:213], v[184:187], v[0:3]
	v_mfma_f32_16x16x32_bf16 v[52:55], v[206:209], v[148:151], v[52:55]
	v_mfma_f32_16x16x32_bf16 v[48:51], v[214:217], v[148:151], v[48:51]
	v_mfma_f32_16x16x32_bf16 v[36:39], v[206:209], v[156:159], v[36:39]
	v_mfma_f32_16x16x32_bf16 v[32:35], v[214:217], v[156:159], v[32:35]
	v_mfma_f32_16x16x32_bf16 v[20:23], v[206:209], v[180:183], v[20:23]
	v_mfma_f32_16x16x32_bf16 v[16:19], v[214:217], v[180:183], v[16:19]
	v_mfma_f32_16x16x32_bf16 v[4:7], v[206:209], v[198:201], v[4:7]
	v_mfma_f32_16x16x32_bf16 v[0:3], v[214:217], v[198:201], v[0:3]
	s_waitcnt lgkmcnt(0)
	s_barrier
	s_add_u32 s42, s78, 0x80000
	s_addc_u32 s43, s79, 0
	s_mov_b32 m0, s12
	ds_read_b128 v[144:147], v194 offset:32768
	ds_read_b128 v[148:151], v194 offset:33792
	ds_read_b128 v[152:155], v194 offset:34816
	ds_read_b128 v[156:159], v194 offset:35840
	ds_read_b128 v[176:179], v194 offset:36864
	ds_read_b128 v[180:183], v194 offset:37888
	ds_read_b128 v[184:187], v194 offset:38912
	ds_read_b128 v[198:201], v194 offset:39936
	global_load_lds_dwordx4 v160, s[42:43]
	s_mov_b32 m0, s13
	s_nop 0
	global_load_lds_dwordx4 v164, s[42:43]
	s_waitcnt lgkmcnt(8)
	s_barrier
	s_waitcnt lgkmcnt(0)
	s_waitcnt lgkmcnt(0)
	v_mfma_f32_16x16x32_bf16 v[124:127], v[128:131], v[144:147], v[124:127]
	v_mfma_f32_16x16x32_bf16 v[120:123], v[136:139], v[144:147], v[120:123]
	v_mfma_f32_16x16x32_bf16 v[108:111], v[128:131], v[152:155], v[108:111]
	v_mfma_f32_16x16x32_bf16 v[104:107], v[136:139], v[152:155], v[104:107]
	v_mfma_f32_16x16x32_bf16 v[92:95], v[128:131], v[176:179], v[92:95]
	v_mfma_f32_16x16x32_bf16 v[88:91], v[136:139], v[176:179], v[88:91]
	v_mfma_f32_16x16x32_bf16 v[76:79], v[128:131], v[184:187], v[76:79]
	v_mfma_f32_16x16x32_bf16 v[72:75], v[136:139], v[184:187], v[72:75]
	v_mfma_f32_16x16x32_bf16 v[124:127], v[132:135], v[148:151], v[124:127]
	v_mfma_f32_16x16x32_bf16 v[120:123], v[140:143], v[148:151], v[120:123]
	v_mfma_f32_16x16x32_bf16 v[108:111], v[132:135], v[156:159], v[108:111]
	v_mfma_f32_16x16x32_bf16 v[104:107], v[140:143], v[156:159], v[104:107]
	v_mfma_f32_16x16x32_bf16 v[92:95], v[132:135], v[180:183], v[92:95]
	v_mfma_f32_16x16x32_bf16 v[88:91], v[140:143], v[180:183], v[88:91]
	v_mfma_f32_16x16x32_bf16 v[76:79], v[132:135], v[198:201], v[76:79]
	v_mfma_f32_16x16x32_bf16 v[72:75], v[140:143], v[198:201], v[72:75]
	s_barrier
	s_add_i32 s45, 0, 0x1c000
	s_add_i32 s42, s44, s9
	v_add_u32_e32 v197, s45, v191
	s_mov_b32 m0, s42
	ds_read_b128 v[202:205], v197
	ds_read_b128 v[206:209], v197 offset:1024
	ds_read_b128 v[210:213], v197 offset:2048
	ds_read_b128 v[214:217], v197 offset:3072
	global_load_lds_dwordx4 v162, s[98:99]
	s_add_i32 m0, s42, 0x2000
	s_nop 0
	global_load_lds_dwordx4 v166, s[98:99]
	s_barrier
	s_waitcnt lgkmcnt(0)
	s_waitcnt lgkmcnt(0)
	v_mfma_f32_16x16x32_bf16 v[116:119], v[202:205], v[144:147], v[116:119]
	v_mfma_f32_16x16x32_bf16 v[112:115], v[210:213], v[144:147], v[112:115]
	v_mfma_f32_16x16x32_bf16 v[100:103], v[202:205], v[152:155], v[100:103]
	v_mfma_f32_16x16x32_bf16 v[96:99], v[210:213], v[152:155], v[96:99]
	v_mfma_f32_16x16x32_bf16 v[84:87], v[202:205], v[176:179], v[84:87]
	v_mfma_f32_16x16x32_bf16 v[80:83], v[210:213], v[176:179], v[80:83]
	v_mfma_f32_16x16x32_bf16 v[68:71], v[202:205], v[184:187], v[68:71]
	v_mfma_f32_16x16x32_bf16 v[64:67], v[210:213], v[184:187], v[64:67]
	v_mfma_f32_16x16x32_bf16 v[116:119], v[206:209], v[148:151], v[116:119]
	v_mfma_f32_16x16x32_bf16 v[112:115], v[214:217], v[148:151], v[112:115]
	v_mfma_f32_16x16x32_bf16 v[100:103], v[206:209], v[156:159], v[100:103]
	v_mfma_f32_16x16x32_bf16 v[96:99], v[214:217], v[156:159], v[96:99]
	v_mfma_f32_16x16x32_bf16 v[84:87], v[206:209], v[180:183], v[84:87]
	v_mfma_f32_16x16x32_bf16 v[80:83], v[214:217], v[180:183], v[80:83]
	v_mfma_f32_16x16x32_bf16 v[68:71], v[206:209], v[198:201], v[68:71]
	v_mfma_f32_16x16x32_bf16 v[64:67], v[214:217], v[198:201], v[64:67]
	s_mov_b32 m0, s15
	s_barrier
	ds_read_b128 v[144:147], v194 offset:49152
	ds_read_b128 v[148:151], v194 offset:50176
	ds_read_b128 v[152:155], v194 offset:51200
	ds_read_b128 v[156:159], v194 offset:52224
	ds_read_b128 v[176:179], v194 offset:53248
	ds_read_b128 v[180:183], v194 offset:54272
	ds_read_b128 v[184:187], v194 offset:55296
	ds_read_b128 v[198:201], v194 offset:56320
	global_load_lds_dwordx4 v160, s[100:101]
	s_mov_b32 m0, s22
	s_nop 0
	global_load_lds_dwordx4 v164, s[100:101]
	s_waitcnt vmcnt(10)
	s_barrier
	s_waitcnt lgkmcnt(0)
	s_waitcnt lgkmcnt(0)
	v_mfma_f32_16x16x32_bf16 v[60:63], v[128:131], v[144:147], v[60:63]
	v_mfma_f32_16x16x32_bf16 v[56:59], v[136:139], v[144:147], v[56:59]
	v_mfma_f32_16x16x32_bf16 v[44:47], v[128:131], v[152:155], v[44:47]
	v_mfma_f32_16x16x32_bf16 v[40:43], v[136:139], v[152:155], v[40:43]
	v_mfma_f32_16x16x32_bf16 v[28:31], v[128:131], v[176:179], v[28:31]
	v_mfma_f32_16x16x32_bf16 v[24:27], v[136:139], v[176:179], v[24:27]
	v_mfma_f32_16x16x32_bf16 v[12:15], v[128:131], v[184:187], v[12:15]
	v_mfma_f32_16x16x32_bf16 v[8:11], v[136:139], v[184:187], v[8:11]
	v_mfma_f32_16x16x32_bf16 v[60:63], v[132:135], v[148:151], v[60:63]
	v_mfma_f32_16x16x32_bf16 v[56:59], v[140:143], v[148:151], v[56:59]
	v_mfma_f32_16x16x32_bf16 v[44:47], v[132:135], v[156:159], v[44:47]
	v_mfma_f32_16x16x32_bf16 v[40:43], v[140:143], v[156:159], v[40:43]
	v_mfma_f32_16x16x32_bf16 v[28:31], v[132:135], v[180:183], v[28:31]
	v_mfma_f32_16x16x32_bf16 v[24:27], v[140:143], v[180:183], v[24:27]
	v_mfma_f32_16x16x32_bf16 v[12:15], v[132:135], v[198:201], v[12:15]
	v_mfma_f32_16x16x32_bf16 v[8:11], v[140:143], v[198:201], v[8:11]
	s_barrier
	s_add_u32 s42, s76, 0x80080
	s_addc_u32 s43, s77, 0
	s_add_i32 s44, s45, s9
	s_mov_b32 m0, s44
	s_nop 0
	global_load_lds_dwordx4 v162, s[42:43]
	s_add_i32 m0, s44, 0x2000
	s_nop 0
	global_load_lds_dwordx4 v166, s[42:43]
	ds_read_b128 v[128:131], v193
	ds_read_b128 v[132:135], v193 offset:1024
	ds_read_b128 v[136:139], v193 offset:2048
	ds_read_b128 v[140:143], v193 offset:3072
	s_waitcnt vmcnt(6)
	s_branch .LBB0_717
;     __device__ __forceinline__ void operator()(const f32x4 (&acc)[2][2][4][2], const Unit& u, int wr, int wc, int fr, int fq) const {
;     ...
;         RES_LOAD(0, 0); RES_LOAD(1, 1);
; #pragma unroll
;         for (int it = 0; it < 8; ++it) { const int ai = it >> 2, m = it & 3, sc = it % RD;
;             if (it + RD - 1 < 8) RES_LOAD((it + RD - 1) % RD, it + RD - 1);
.Lrot_out_717:
	v_lshl_add_u32 v186, s70, 8, v190
	v_lshl_or_b32 v176, s72, 8, v192
	v_ashrrev_i32_e32 v187, 31, v186
	v_lshlrev_b64 v[128:129], 11, v[186:187]
	v_ashrrev_i32_e32 v177, 31, v176
	v_lshl_add_u64 v[128:129], v[128:129], 0, v[176:177]
	v_lshlrev_b64 v[178:179], 1, v[128:129]
	v_lshl_add_u64 v[180:181], v[186:187], 2, s[56:57]
	v_lshl_add_u64 v[128:129], s[58:59], 0, v[178:179]
	global_load_dword v199, v[180:181], off
	global_load_dwordx4 v[200:203], v[128:129], off
	v_or_b32_e32 v188, 16, v186
	v_or_b32_e32 v182, 32, v186
	v_ashrrev_i32_e32 v189, 31, v188
	v_ashrrev_i32_e32 v183, 31, v182
	v_lshl_add_u64 v[130:131], v[188:189], 2, s[56:57]
	v_lshlrev_b64 v[132:133], 11, v[182:183]
	v_lshl_add_u64 v[134:135], v[182:183], 2, s[56:57]
	global_load_dword v198, v[130:131], off
	global_load_dword v197, v[134:135], off
	v_lshl_add_u64 v[130:131], v[132:133], 0, v[176:177]
	v_lshl_add_u64 v[132:133], s[50:51], 0, v[178:179]
	global_load_dwordx4 v[204:207], v[132:133], off
	v_lshlrev_b64 v[128:129], 11, v[188:189]
	v_lshl_add_u64 v[128:129], v[128:129], 0, v[176:177]
	v_or_b32_e32 v132, 0x100, v178
	v_mov_b32_e32 v133, v179
	v_lshlrev_b64 v[128:129], 1, v[128:129]
	v_lshl_add_u64 v[134:135], s[50:51], 0, v[132:133]
	v_lshl_add_u64 v[132:133], s[58:59], 0, v[132:133]
	v_lshl_add_u64 v[136:137], s[50:51], 0, v[128:129]
	v_lshl_add_u64 v[138:139], s[58:59], 0, v[128:129]
	global_load_dwordx4 v[208:211], v[134:135], off
	global_load_dwordx4 v[212:215], v[132:133], off
	global_load_dwordx4 v[152:155], v[136:137], off
	global_load_dwordx4 v[156:159], v[138:139], off
	v_lshlrev_b64 v[130:131], 1, v[130:131]
	v_or_b32_e32 v128, 0x100, v128
	v_lshl_add_u64 v[140:141], s[50:51], 0, v[130:131]
	v_lshl_add_u64 v[142:143], s[58:59], 0, v[130:131]
	v_or_b32_e32 v130, 0x100, v130
	v_lshl_add_u64 v[132:133], s[50:51], 0, v[128:129]
	v_lshl_add_u64 v[128:129], s[58:59], 0, v[128:129]
	v_lshl_add_u64 v[134:135], s[50:51], 0, v[130:131]
	global_load_dwordx4 v[136:139], v[140:141], off
	s_nop 0
	global_load_dwordx4 v[140:143], v[142:143], off
	v_lshl_add_u64 v[216:217], s[58:59], 0, v[130:131]
	global_load_dwordx4 v[144:147], v[132:133], off
	global_load_dwordx4 v[148:151], v[128:129], off
	s_nop 0
	global_load_dwordx4 v[128:131], v[134:135], off
	s_nop 0
	global_load_dwordx4 v[132:135], v[216:217], off
	v_lshlrev_b64 v[184:185], 12, v[186:187]
	s_waitcnt vmcnt(0)
; __device__ __forceinline__ float bf_lo(unsigned w) { return __uint_as_float(w << 16); }
; __device__ __forceinline__ float bf_hi(unsigned w) { return __uint_as_float(w & 0xffff0000u); }
;     __device__ __forceinline__ void operator()(const f32x4 (&acc)[2][2][4][2], const Unit& u, int wr, int wc, int fr, int fq) const {
;     ...
;         for (int it = 0; it < 8; ++it) { const int ai = it >> 2, m = it & 3, sc = it % RD;
;             if (it + RD - 1 < 8) RES_LOAD((it + RD - 1) % RD, it + RD - 1);
;             asm volatile("" ::: "memory");
;             const int row = row0 + ai * HALF + m * 16; const size_t ro = (size_t)row * DM + col0;
;             float rs = 1.0f; if (MODE == 1) rs = __builtin_amdgcn_rsqf(ss_fix(rsb[sc]) * (1.0f / DM) + EPS);
;             float sq = 0.f;
; #pragma unroll
;             for (int bj = 0; bj < 2; ++bj) { const size_t off = ro + bj * HALF;
;                 f32x4 v0 = acc[ai][bj][m][0], v1 = acc[ai][bj][m][1];
;                 if (MODE == 1) { const u32x4 pw = pbuf[sc][bj];
;                     v0[0] = fast_sigmoid(rs * v0[0]) * bf_lo(pw.x); v0[1] = fast_sigmoid(rs * v0[1]) * bf_hi(pw.x); v0[2] = fast_sigmoid(rs * v0[2]) * bf_lo(pw.y); v0[3] = fast_sigmoid(rs * v0[3]) * bf_hi(pw.y);
;                     v1[0] = fast_sigmoid(rs * v1[0]) * bf_lo(pw.z); v1[1] = fast_sigmoid(rs * v1[1]) * bf_hi(pw.z); v1[2] = fast_sigmoid(rs * v1[2]) * bf_lo(pw.w); v1[3] = fast_sigmoid(rs * v1[3]) * bf_hi(pw.w); }
;                 f32x4 h0, h1;
;                 if (IN16) { const u32x4 hw = hraw[sc][bj]; h0 = (f32x4){bf_lo(hw.x), bf_hi(hw.x), bf_lo(hw.y), bf_hi(hw.y)}; h1 = (f32x4){bf_lo(hw.z), bf_hi(hw.z), bf_lo(hw.w), bf_hi(hw.w)}; }
;                 else { h0 = hbuf[sc][2 * bj]; h1 = hbuf[sc][2 * bj + 1]; }
;                 const f32x4 o0 = h0 + v0, o1 = h1 + v1;
;                 if (OUT32) { *(f32x4*)(hout + off) = o0; *(f32x4*)(hout + off + 4) = o1; }
;                 if (hb) { u32x4 w; w.x = pk_bf16(o0[0], o0[1]); w.y = pk_bf16(o0[2], o0[3]); w.z = pk_bf16(o1[0], o1[1]); w.w = pk_bf16(o1[2], o1[3]); *(u32x4*)(hb + off) = w; }
;                 sq += ((o0[0] * o0[0] + o0[1] * o0[1]) + (o0[2] * o0[2] + o0[3] * o0[3])) + ((o1[0] * o1[0] + o1[1] * o1[1]) + (o1[2] * o1[2] + o1[3] * o1[3])); }
;             if (ss_out) { sq += __shfl_xor(sq, 16); sq += __shfl_xor(sq, 32); if (fq == 0) atomicAdd((unsigned*)(ss_out + row), ss_enc(sq)); }
	v_cvt_f32_u32_e32 v199, v199
	v_lshlrev_b32_e32 v218, 16, v202
	v_and_b32_e32 v219, 0xffff0000, v202
	v_lshlrev_b32_e32 v216, 16, v200
	v_mul_f32_e32 v199, 0x3b800000, v199
	v_fmamk_f32 v199, v199, 0x3a000000, v196
	v_rsq_f32_e32 v199, v199
	v_and_b32_e32 v217, 0xffff0000, v200
	v_lshlrev_b32_e32 v200, 16, v201
	v_and_b32_e32 v201, 0xffff0000, v201
	v_mul_f32_e32 v124, v124, v199
	v_mul_f32_e32 v125, v125, v199
	v_mul_f32_e32 v126, v126, v199
	v_mul_f32_e32 v127, v127, v199
	v_mul_f32_e32 v120, v120, v199
	v_mul_f32_e32 v121, v121, v199
	v_mul_f32_e32 v122, v122, v199
	v_mul_f32_e32 v123, v123, v199
	v_mul_f32_e32 v124, 0xbfb8aa3b, v124
	v_mul_f32_e32 v125, 0xbfb8aa3b, v125
	v_mul_f32_e32 v126, 0xbfb8aa3b, v126
	v_mul_f32_e32 v127, 0xbfb8aa3b, v127
	v_mul_f32_e32 v120, 0xbfb8aa3b, v120
	v_mul_f32_e32 v121, 0xbfb8aa3b, v121
	v_mul_f32_e32 v122, 0xbfb8aa3b, v122
	v_mul_f32_e32 v123, 0xbfb8aa3b, v123
	v_exp_f32_e32 v124, v124
	v_exp_f32_e32 v125, v125
	v_exp_f32_e32 v126, v126
	v_exp_f32_e32 v127, v127
	v_exp_f32_e32 v120, v120
	v_exp_f32_e32 v121, v121
	v_exp_f32_e32 v122, v122
	v_exp_f32_e32 v202, v123
	v_add_f32_e32 v123, 1.0, v124
	v_add_f32_e32 v124, 1.0, v125
	v_add_f32_e32 v125, 1.0, v126
	v_add_f32_e32 v126, 1.0, v127
	v_add_f32_e32 v127, 1.0, v120
	v_add_f32_e32 v220, 1.0, v121
	v_mul_f32_e32 v116, v116, v199
	v_mul_f32_e32 v117, v117, v199
	v_mul_f32_e32 v118, v118, v199
	v_mul_f32_e32 v119, v119, v199
	v_add_f32_e32 v221, 1.0, v122
	v_rcp_f32_e32 v121, v124
	v_rcp_f32_e32 v122, v125
	v_rcp_f32_e32 v124, v127
	v_rcp_f32_e32 v125, v220
	v_add_f32_e32 v127, 1.0, v202
	v_mul_f32_e32 v116, 0xbfb8aa3b, v116
	v_mul_f32_e32 v117, 0xbfb8aa3b, v117
	v_mul_f32_e32 v118, 0xbfb8aa3b, v118
	v_mul_f32_e32 v119, 0xbfb8aa3b, v119
	v_mul_f32_e32 v112, v112, v199
	v_mul_f32_e32 v113, v113, v199
	v_rcp_f32_e32 v120, v123
	v_rcp_f32_e32 v123, v126
	v_rcp_f32_e32 v126, v221
	v_rcp_f32_e32 v127, v127
	v_exp_f32_e32 v116, v116
	v_exp_f32_e32 v117, v117
	v_exp_f32_e32 v118, v118
	v_exp_f32_e32 v119, v119
	v_mul_f32_e32 v112, 0xbfb8aa3b, v112
	v_mul_f32_e32 v113, 0xbfb8aa3b, v113
	v_mul_f32_e32 v114, v114, v199
	v_mul_f32_e32 v115, v115, v199
	v_exp_f32_e32 v112, v112
	v_exp_f32_e32 v113, v113
	v_mul_f32_e32 v114, 0xbfb8aa3b, v114
	v_mul_f32_e32 v115, 0xbfb8aa3b, v115
	v_lshlrev_b32_e32 v222, 16, v206
	v_and_b32_e32 v223, 0xffff0000, v206
	v_exp_f32_e32 v114, v114
	v_exp_f32_e32 v115, v115
	v_lshlrev_b32_e32 v202, 16, v203
	v_and_b32_e32 v203, 0xffff0000, v203
	v_lshlrev_b32_e32 v220, 16, v204
	v_and_b32_e32 v221, 0xffff0000, v204
	v_lshlrev_b32_e32 v204, 16, v205
	v_and_b32_e32 v205, 0xffff0000, v205
	v_lshlrev_b32_e32 v206, 16, v207
	v_and_b32_e32 v207, 0xffff0000, v207
	v_pk_fma_f32 v[124:125], v[124:125], v[218:219], v[222:223]
	v_pk_fma_f32 v[200:201], v[122:123], v[200:201], v[204:205]
	v_pk_fma_f32 v[204:205], v[120:121], v[216:217], v[220:221]
	v_pk_fma_f32 v[126:127], v[126:127], v[202:203], v[206:207]
	v_cvt_pk_bf16_f32 v122, v124, v125
	v_mul_f32_e32 v125, v125, v125
	v_add_f32_e32 v116, 1.0, v116
	v_add_f32_e32 v117, 1.0, v117
	v_add_f32_e32 v118, 1.0, v118
	v_add_f32_e32 v119, 1.0, v119
	v_cvt_pk_bf16_f32 v121, v200, v201
	v_mul_f32_e32 v202, v205, v205
	v_mul_f32_e32 v201, v201, v201
	v_fmac_f32_e32 v125, v124, v124
	v_mul_f32_e32 v124, v127, v127
	v_rcp_f32_e32 v116, v116
	v_rcp_f32_e32 v117, v117
	v_rcp_f32_e32 v118, v118
	v_rcp_f32_e32 v119, v119
	v_add_f32_e32 v112, 1.0, v112
	v_add_f32_e32 v113, 1.0, v113
	v_fmac_f32_e32 v202, v204, v204
	v_fmac_f32_e32 v201, v200, v200
	v_fmac_f32_e32 v124, v126, v126
	v_rcp_f32_e32 v112, v112
	v_rcp_f32_e32 v113, v113
	v_add_f32_e32 v114, 1.0, v114
	v_add_f32_e32 v115, 1.0, v115
	v_add_f32_e32 v200, v202, v201
	v_add_f32_e32 v124, v125, v124
	v_rcp_f32_e32 v114, v114
	v_rcp_f32_e32 v115, v115
	v_cvt_pk_bf16_f32 v120, v204, v205
	v_cvt_pk_bf16_f32 v123, v126, v127
	v_add_f32_e32 v216, v200, v124
	v_lshlrev_b32_e32 v124, 16, v212
	v_and_b32_e32 v125, 0xffff0000, v212
	v_lshlrev_b32_e32 v126, 16, v213
	v_and_b32_e32 v127, 0xffff0000, v213
	v_lshlrev_b32_e32 v204, 16, v208
	v_and_b32_e32 v205, 0xffff0000, v208
	v_lshlrev_b32_e32 v206, 16, v209
	v_and_b32_e32 v207, 0xffff0000, v209
	v_lshlrev_b32_e32 v200, 16, v214
	v_and_b32_e32 v201, 0xffff0000, v214
	v_lshlrev_b32_e32 v208, 16, v210
	v_and_b32_e32 v209, 0xffff0000, v210
	v_pk_fma_f32 v[118:119], v[118:119], v[126:127], v[206:207]
	v_pk_fma_f32 v[116:117], v[116:117], v[124:125], v[204:205]
	v_lshlrev_b32_e32 v202, 16, v215
	v_and_b32_e32 v203, 0xffff0000, v215
	v_lshlrev_b32_e32 v210, 16, v211
	v_and_b32_e32 v211, 0xffff0000, v211
	v_pk_fma_f32 v[126:127], v[112:113], v[200:201], v[208:209]
	v_mul_f32_e32 v112, v117, v117
	v_mul_f32_e32 v113, v119, v119
	v_pk_fma_f32 v[124:125], v[114:115], v[202:203], v[210:211]
	v_fmac_f32_e32 v112, v116, v116
	v_fmac_f32_e32 v113, v118, v118
	v_add_f32_e32 v112, v112, v113
	v_mul_f32_e32 v113, v127, v127
	v_mul_f32_e32 v114, v125, v125
	v_fmac_f32_e32 v113, v126, v126
	v_fmac_f32_e32 v114, v124, v124
	v_add_f32_e32 v113, v113, v114
	v_add_f32_e32 v112, v112, v113
	v_add_f32_e32 v115, v216, v112
	ds_bpermute_b32 v199, v245, v115
	v_lshl_add_u64 v[112:113], s[52:53], 0, v[184:185]
	v_lshl_add_u64 v[184:185], v[176:177], 1, v[112:113]
	v_cvt_pk_bf16_f32 v114, v116, v117
	v_cvt_pk_bf16_f32 v116, v126, v127
	s_waitcnt lgkmcnt(0)
	v_add_f32_e32 v112, v115, v199
	ds_bpermute_b32 v113, v244, v112
	v_cvt_pk_bf16_f32 v115, v118, v119
	v_cvt_pk_bf16_f32 v117, v124, v125
	global_store_dwordx4 v[184:185], v[120:123], off
	global_store_dwordx4 v[184:185], v[114:117], off offset:256
	s_and_saveexec_b64 s[70:71], s[16:17]
	s_cbranch_execz .LBB0_720
	s_waitcnt lgkmcnt(0)
	v_add_f32_e32 v112, v112, v113
	v_fma_f32 v112, v112, s25, 0.5
	v_cvt_u32_f32_e32 v114, v112
	v_lshl_add_u64 v[112:113], v[186:187], 2, s[54:55]
	global_atomic_add v[112:113], v114, off

; #define PG8_BAR __builtin_amdgcn_s_barrier()
; template <class Epi>
; __device__ __forceinline__ void gemm_phase(LAS unsigned char* lds, const Gemm g, const StaticOrder& S, const Epi& E, int wv) {
;     ...
;         const bool has_next = S.next(ui + 1, nxt);
;         const char* nA = has_next ? (const char*)g.A + (size_t)nxt.pm * tstepA + ((g.adiag & 1) ? (size_t)(nxt.pn >> 1) * K * 2 : 0) + kbeg : cA;
;         const char* nB = has_next ? (const char*)g.Bt + (size_t)nxt.pn * tstepB + kbeg : cB;
;         for (int t = 0; t < nt; t += 2) {
;             const bool last = (t == nt - 2);
;             const char* a1 = cA + (ptrdiff_t)(t + 1) * kstep;
;             const char* a2 = last ? nA : cA + (ptrdiff_t)(t + 2) * kstep; const char* b2 = last ? nB : cB + (ptrdiff_t)(t + 2) * kstep;
;             const char* a3 = a2 + kstep; const char* b3 = b2 + kstep;
;             PG8_LDB(B0, 0, 0); PG8_SCHED; PG8_LDA(At, 0, 0); PG8_STAGE(PG8_SA(1, 1), a1 + hstepA, voffA);
;             PG8_WAIT_L(8); PG8_BAR; PG8_WAIT_L(0); PG8_MMA(0, 0, At, B0); PG8_BAR; PG8_SCHED;
;             PG8_LDB(B1, 0, 1); PG8_STAGE(PG8_SB(0, 0), b2, voffB);
;             PG8_BAR; PG8_WAIT_L(0); PG8_MMA(0, 1, At, B1); PG8_BAR;
;             PG8_LDA(At, 0, 1); PG8_STAGE(PG8_SA(0, 0), a2, voffA);
;             PG8_BAR; PG8_WAIT_L(0); PG8_MMA(1, 0, At, B0); PG8_BAR; PG8_SCHED;
;             PG8_STAGE(PG8_SB(0, 1), b2 + hstepB, voffB);
;             PG8_WAIT_V(6); PG8_BAR; PG8_MMA(1, 1, At, B1); PG8_BAR;
;             PG8_LDB(B0, 1, 0); PG8_SCHED; PG8_LDA(At, 1, 0); PG8_STAGE(PG8_SA(0, 1), a2 + hstepA, voffA);
;             PG8_WAIT_L(8); PG8_BAR; PG8_WAIT_L(0); PG8_MMA(0, 0, At, B0); PG8_BAR; PG8_SCHED;
;             PG8_LDB(B1, 1, 1); PG8_STAGE(PG8_SB(1, 0), b3, voffB);
;             PG8_BAR; PG8_WAIT_L(0); PG8_MMA(0, 1, At, B1); PG8_BAR;
;             PG8_LDA(At, 1, 1); PG8_STAGE(PG8_SA(1, 0), a3, voffA);
;             PG8_BAR; PG8_WAIT_L(0); PG8_MMA(1, 0, At, B0); PG8_BAR; PG8_SCHED;
;             PG8_STAGE(PG8_SB(1, 1), b3 + hstepB, voffB);
;             PG8_WAIT_V(6); PG8_BAR; PG8_MMA(1, 1, At, B1); PG8_BAR;
;         }
;         E(acc, cur, wr, wc, fr, fq);
;         if (!has_next) break;
; #pragma unroll
;         for (int a = 0; a < 2; ++a)
; #pragma unroll
;             for (int b = 0; b < 2; ++b)
; #pragma unroll
;                 for (int m = 0; m < 4; ++m)
; #pragma unroll
.LBB0_957:
	s_ashr_i32 s41, s40, 31
	v_cmp_lt_i64_e32 vcc, s[42:43], v[140:141]
	s_lshl_b64 s[42:43], s[40:41], 20
	s_add_u32 s42, s5, s42
	s_addc_u32 s43, s6, s43
	s_and_b64 s[44:45], vcc, exec
	s_cselect_b32 s11, s43, s51
	s_cselect_b32 s41, s42, s50
	s_ashr_i32 s39, s38, 31
	s_lshl_b64 s[44:45], s[38:39], 20
	s_add_u32 s44, s7, s44
	s_addc_u32 s45, s22, s45
	s_and_b64 s[52:53], vcc, exec
	s_cselect_b32 s39, s45, s49
	s_cselect_b32 s47, s44, s48
	s_add_u32 s68, s48, 0x100
	s_addc_u32 s69, s49, 0
	s_add_u32 s48, s50, 0x80080
	v_mov_b32_e32 v0, 0
	s_addc_u32 s49, s51, 0
	s_mov_b32 s70, -2
	v_mov_b32_e32 v1, v0
	v_mov_b32_e32 v2, v0
	v_mov_b32_e32 v3, v0
	v_mov_b32_e32 v4, v0
	v_mov_b32_e32 v5, v0
	v_mov_b32_e32 v6, v0
	v_mov_b32_e32 v7, v0
	v_mov_b32_e32 v16, v0
	v_mov_b32_e32 v17, v0
	v_mov_b32_e32 v18, v0
	v_mov_b32_e32 v19, v0
	v_mov_b32_e32 v20, v0
	v_mov_b32_e32 v21, v0
	v_mov_b32_e32 v22, v0
	v_mov_b32_e32 v23, v0
	v_mov_b32_e32 v32, v0
	v_mov_b32_e32 v33, v0
	v_mov_b32_e32 v34, v0
	v_mov_b32_e32 v35, v0
	v_mov_b32_e32 v36, v0
	v_mov_b32_e32 v37, v0
	v_mov_b32_e32 v38, v0
	v_mov_b32_e32 v39, v0
	v_mov_b32_e32 v48, v0
	v_mov_b32_e32 v49, v0
	v_mov_b32_e32 v50, v0
	v_mov_b32_e32 v51, v0
	v_mov_b32_e32 v52, v0
	v_mov_b32_e32 v53, v0
	v_mov_b32_e32 v54, v0
	v_mov_b32_e32 v55, v0
	v_mov_b32_e32 v8, v0
	v_mov_b32_e32 v9, v0
	v_mov_b32_e32 v10, v0
	v_mov_b32_e32 v11, v0
	v_mov_b32_e32 v12, v0
	v_mov_b32_e32 v13, v0
	v_mov_b32_e32 v14, v0
	v_mov_b32_e32 v15, v0
	v_mov_b32_e32 v24, v0
	v_mov_b32_e32 v25, v0
	v_mov_b32_e32 v26, v0
	v_mov_b32_e32 v27, v0
	v_mov_b32_e32 v28, v0
	v_mov_b32_e32 v29, v0
	v_mov_b32_e32 v30, v0
	v_mov_b32_e32 v31, v0
	v_mov_b32_e32 v40, v0
	v_mov_b32_e32 v41, v0
	v_mov_b32_e32 v42, v0
	v_mov_b32_e32 v43, v0
	v_mov_b32_e32 v44, v0
	v_mov_b32_e32 v45, v0
	v_mov_b32_e32 v46, v0
	v_mov_b32_e32 v47, v0
	v_mov_b32_e32 v56, v0
	v_mov_b32_e32 v57, v0
	v_mov_b32_e32 v58, v0
	v_mov_b32_e32 v59, v0
	v_mov_b32_e32 v60, v0
	v_mov_b32_e32 v61, v0
	v_mov_b32_e32 v62, v0
	v_mov_b32_e32 v63, v0
	v_mov_b32_e32 v64, v0
	v_mov_b32_e32 v65, v0
	v_mov_b32_e32 v66, v0
	v_mov_b32_e32 v67, v0
	v_mov_b32_e32 v68, v0
	v_mov_b32_e32 v69, v0
	v_mov_b32_e32 v70, v0
	v_mov_b32_e32 v71, v0
	v_mov_b32_e32 v80, v0
	v_mov_b32_e32 v81, v0
	v_mov_b32_e32 v82, v0
	v_mov_b32_e32 v83, v0
	v_mov_b32_e32 v84, v0
	v_mov_b32_e32 v85, v0
	v_mov_b32_e32 v86, v0
	v_mov_b32_e32 v87, v0
	v_mov_b32_e32 v96, v0
	v_mov_b32_e32 v97, v0
	v_mov_b32_e32 v98, v0
	v_mov_b32_e32 v99, v0
	v_mov_b32_e32 v100, v0
	v_mov_b32_e32 v101, v0
	v_mov_b32_e32 v102, v0
	v_mov_b32_e32 v103, v0
	v_mov_b32_e32 v112, v0
	v_mov_b32_e32 v113, v0
	v_mov_b32_e32 v114, v0
	v_mov_b32_e32 v115, v0
	v_mov_b32_e32 v116, v0
	v_mov_b32_e32 v117, v0
	v_mov_b32_e32 v118, v0
	v_mov_b32_e32 v119, v0
	v_mov_b32_e32 v72, v0
	v_mov_b32_e32 v73, v0
	v_mov_b32_e32 v74, v0
	v_mov_b32_e32 v75, v0
	v_mov_b32_e32 v76, v0
	v_mov_b32_e32 v77, v0
	v_mov_b32_e32 v78, v0
	v_mov_b32_e32 v79, v0
	v_mov_b32_e32 v88, v0
	v_mov_b32_e32 v89, v0
	v_mov_b32_e32 v90, v0
	v_mov_b32_e32 v91, v0
	v_mov_b32_e32 v92, v0
	v_mov_b32_e32 v93, v0
	v_mov_b32_e32 v94, v0
	v_mov_b32_e32 v95, v0
	v_mov_b32_e32 v104, v0
	v_mov_b32_e32 v105, v0
	v_mov_b32_e32 v106, v0
	v_mov_b32_e32 v107, v0
	v_mov_b32_e32 v108, v0
	v_mov_b32_e32 v109, v0
	v_mov_b32_e32 v110, v0
	v_mov_b32_e32 v111, v0
	v_mov_b32_e32 v120, v0
	v_mov_b32_e32 v121, v0
	v_mov_b32_e32 v122, v0
	v_mov_b32_e32 v123, v0
	v_mov_b32_e32 v124, v0
	v_mov_b32_e32 v125, v0
	v_mov_b32_e32 v126, v0
	v_mov_b32_e32 v127, v0
	ds_read_b128 v[144:147], v155
	ds_read_b128 v[148:151], v155 offset:1024
	ds_read_b128 v[160:163], v155 offset:2048
	ds_read_b128 v[164:167], v155 offset:3072
	s_branch .Lrot_in_958
.LBB0_958:
	s_barrier
	v_mfma_f32_16x16x32_bf16 v[52:55], v[200:203], v[168:171], v[52:55]
	v_mfma_f32_16x16x32_bf16 v[48:51], v[208:211], v[168:171], v[48:51]
	v_mfma_f32_16x16x32_bf16 v[36:39], v[200:203], v[176:179], v[36:39]
	v_mfma_f32_16x16x32_bf16 v[32:35], v[208:211], v[176:179], v[32:35]
	v_mfma_f32_16x16x32_bf16 v[20:23], v[200:203], v[184:187], v[20:23]
	v_mfma_f32_16x16x32_bf16 v[16:19], v[208:211], v[184:187], v[16:19]
	v_mfma_f32_16x16x32_bf16 v[4:7], v[200:203], v[192:195], v[4:7]
	v_mfma_f32_16x16x32_bf16 v[0:3], v[208:211], v[192:195], v[0:3]
	v_mfma_f32_16x16x32_bf16 v[52:55], v[204:207], v[172:175], v[52:55]
	v_mfma_f32_16x16x32_bf16 v[48:51], v[212:215], v[172:175], v[48:51]
	v_mfma_f32_16x16x32_bf16 v[36:39], v[204:207], v[180:183], v[36:39]
	v_mfma_f32_16x16x32_bf16 v[32:35], v[212:215], v[180:183], v[32:35]
	v_mfma_f32_16x16x32_bf16 v[20:23], v[204:207], v[188:191], v[20:23]
	v_mfma_f32_16x16x32_bf16 v[16:19], v[212:215], v[188:191], v[16:19]
	v_mfma_f32_16x16x32_bf16 v[4:7], v[204:207], v[196:199], v[4:7]
	v_mfma_f32_16x16x32_bf16 v[0:3], v[212:215], v[196:199], v[0:3]
	s_waitcnt lgkmcnt(0)
	s_add_i32 s70, s70, 2
	s_add_u32 s68, s68, 0x100
	s_addc_u32 s69, s69, 0
	s_add_u32 s48, s48, 0x100
	s_addc_u32 s49, s49, 0
	s_cmp_gt_u32 s70, 29
	s_barrier
	s_cbranch_scc1 .Lrot_out_958
; #define PG8_STAGE(bufoff, gbase, voff) do { _Pragma("unroll") for (int _i = 0; _i < 2; ++_i) \
;         __builtin_amdgcn_global_load_lds((const unsigned*)((const char*)(gbase) + (voff)[_i]), (LAS unsigned*)(lds + (bufoff) + ldsw + _i * 8192), 16, 0, 0); } while (0)
; #define PG8_LDA(dst, b, h) do { _Pragma("unroll") for (int m = 0; m < 4; ++m) _Pragma("unroll") for (int k = 0; k < 2; ++k) dst[m][k] = *(const LAS bf16x8*)(lds + PG8_SA(b, h) + aoff + m * 2048 + k * 1024); } while (0)
; #define PG8_LDB(dst, b, h) do { _Pragma("unroll") for (int n = 0; n < 2; ++n) _Pragma("unroll") for (int k = 0; k < 2; ++k) dst[n][k] = *(const LAS bf16x8*)(lds + PG8_SB(b, h) + boff + n * 2048 + k * 1024); } while (0)
; #define PG8_MMA(ai, bj, At, Bt) do { __builtin_amdgcn_s_setprio(1); _Pragma("unroll") for (int m = 0; m < 4; ++m) _Pragma("unroll") for (int n = 0; n < 2; ++n) _Pragma("unroll") for (int k = 0; k < 2; ++k) \
;         acc[ai][bj][m][n] = __builtin_amdgcn_mfma_f32_16x16x32_bf16(Bt[n][k], At[m][k], acc[ai][bj][m][n], 0, 0, 0); __builtin_amdgcn_s_setprio(0); } while (0)
; #define PG8_WAIT_V(n) asm volatile("s_waitcnt vmcnt(" #n ")" ::: "memory")
; #define PG8_WAIT_L(n) asm volatile("s_waitcnt lgkmcnt(" #n ")" ::: "memory")
; #define PG8_BAR __builtin_amdgcn_s_barrier()
; template <class Epi>
; __device__ __forceinline__ void gemm_phase(LAS unsigned char* lds, const Gemm g, const StaticOrder& S, const Epi& E, int wv) {
;     ...
;             const bool last = (t == nt - 2);
;             const char* a1 = cA + (ptrdiff_t)(t + 1) * kstep;
;             const char* a2 = last ? nA : cA + (ptrdiff_t)(t + 2) * kstep; const char* b2 = last ? nB : cB + (ptrdiff_t)(t + 2) * kstep;
;             const char* a3 = a2 + kstep; const char* b3 = b2 + kstep;
;             PG8_LDB(B0, 0, 0); PG8_SCHED; PG8_LDA(At, 0, 0); PG8_STAGE(PG8_SA(1, 1), a1 + hstepA, voffA);
;             PG8_WAIT_L(8); PG8_BAR; PG8_WAIT_L(0); PG8_MMA(0, 0, At, B0); PG8_BAR; PG8_SCHED;
;             PG8_LDB(B1, 0, 1); PG8_STAGE(PG8_SB(0, 0), b2, voffB);
;             PG8_BAR; PG8_WAIT_L(0); PG8_MMA(0, 1, At, B1); PG8_BAR;
;             PG8_LDA(At, 0, 1); PG8_STAGE(PG8_SA(0, 0), a2, voffA);
;             PG8_BAR; PG8_WAIT_L(0); PG8_MMA(1, 0, At, B0); PG8_BAR; PG8_SCHED;
;             PG8_STAGE(PG8_SB(0, 1), b2 + hstepB, voffB);
;             PG8_WAIT_V(6); PG8_BAR; PG8_MMA(1, 1, At, B1); PG8_BAR;
.Lrot_in_958:
	s_add_u32 s50, s48, 0xfff80080
	s_addc_u32 s51, s49, -1
	s_cmp_eq_u32 s70, 28
	s_cselect_b32 s53, s11, s51
	s_cselect_b32 s52, s41, s50
	s_cselect_b32 s51, s39, s69
	s_cselect_b32 s50, s47, s68
	s_add_i32 m0, s24, 0xc000
	ds_read_b128 v[168:171], v156
	ds_read_b128 v[172:175], v156 offset:1024
	ds_read_b128 v[176:179], v156 offset:2048
	ds_read_b128 v[180:183], v156 offset:3072
	ds_read_b128 v[184:187], v156 offset:4096
	ds_read_b128 v[188:191], v156 offset:5120
	ds_read_b128 v[192:195], v156 offset:6144
	ds_read_b128 v[196:199], v156 offset:7168
	global_load_lds_dwordx4 v138, s[48:49]
	s_add_i32 m0, s24, 0xe000
	s_nop 0
	global_load_lds_dwordx4 v136, s[48:49]
	s_waitcnt lgkmcnt(8)
	s_barrier
	s_waitcnt lgkmcnt(0)
	s_waitcnt lgkmcnt(0)
	v_mfma_f32_16x16x32_bf16 v[124:127], v[144:147], v[168:171], v[124:127]
	v_mfma_f32_16x16x32_bf16 v[120:123], v[160:163], v[168:171], v[120:123]
	v_mfma_f32_16x16x32_bf16 v[108:111], v[144:147], v[176:179], v[108:111]
	v_mfma_f32_16x16x32_bf16 v[104:107], v[160:163], v[176:179], v[104:107]
	v_mfma_f32_16x16x32_bf16 v[92:95], v[144:147], v[184:187], v[92:95]
	v_mfma_f32_16x16x32_bf16 v[88:91], v[160:163], v[184:187], v[88:91]
	v_mfma_f32_16x16x32_bf16 v[76:79], v[144:147], v[192:195], v[76:79]
	v_mfma_f32_16x16x32_bf16 v[72:75], v[160:163], v[192:195], v[72:75]
	v_mfma_f32_16x16x32_bf16 v[124:127], v[148:151], v[172:175], v[124:127]
	v_mfma_f32_16x16x32_bf16 v[120:123], v[164:167], v[172:175], v[120:123]
	v_mfma_f32_16x16x32_bf16 v[108:111], v[148:151], v[180:183], v[108:111]
	v_mfma_f32_16x16x32_bf16 v[104:107], v[164:167], v[180:183], v[104:107]
	v_mfma_f32_16x16x32_bf16 v[92:95], v[148:151], v[188:191], v[92:95]
	v_mfma_f32_16x16x32_bf16 v[88:91], v[164:167], v[188:191], v[88:91]
	v_mfma_f32_16x16x32_bf16 v[76:79], v[148:151], v[196:199], v[76:79]
	v_mfma_f32_16x16x32_bf16 v[72:75], v[164:167], v[196:199], v[72:75]
	s_barrier
	s_add_i32 s71, s60, s23
	s_add_u32 s98, s50, s16
	s_addc_u32 s99, s51, s17
	s_mov_b32 m0, s71
	ds_read_b128 v[200:203], v157
	ds_read_b128 v[204:207], v157 offset:1024
	ds_read_b128 v[208:211], v157 offset:2048
	ds_read_b128 v[212:215], v157 offset:3072
	global_load_lds_dwordx4 v130, s[50:51]
	s_add_i32 m0, s71, 0x2000
	s_nop 0
	global_load_lds_dwordx4 v134, s[50:51]
	s_barrier
	s_waitcnt lgkmcnt(0)
	s_waitcnt lgkmcnt(0)
	v_mfma_f32_16x16x32_bf16 v[116:119], v[200:203], v[168:171], v[116:119]
	v_mfma_f32_16x16x32_bf16 v[112:115], v[208:211], v[168:171], v[112:115]
	v_mfma_f32_16x16x32_bf16 v[100:103], v[200:203], v[176:179], v[100:103]
	v_mfma_f32_16x16x32_bf16 v[96:99], v[208:211], v[176:179], v[96:99]
	v_mfma_f32_16x16x32_bf16 v[84:87], v[200:203], v[184:187], v[84:87]
	v_mfma_f32_16x16x32_bf16 v[80:83], v[208:211], v[184:187], v[80:83]
	v_mfma_f32_16x16x32_bf16 v[68:71], v[200:203], v[192:195], v[68:71]
	v_mfma_f32_16x16x32_bf16 v[64:67], v[208:211], v[192:195], v[64:67]
	v_mfma_f32_16x16x32_bf16 v[116:119], v[204:207], v[172:175], v[116:119]
	v_mfma_f32_16x16x32_bf16 v[112:115], v[212:215], v[172:175], v[112:115]
	v_mfma_f32_16x16x32_bf16 v[100:103], v[204:207], v[180:183], v[100:103]
	v_mfma_f32_16x16x32_bf16 v[96:99], v[212:215], v[180:183], v[96:99]
	v_mfma_f32_16x16x32_bf16 v[84:87], v[204:207], v[188:191], v[84:87]
	v_mfma_f32_16x16x32_bf16 v[80:83], v[212:215], v[188:191], v[80:83]
	v_mfma_f32_16x16x32_bf16 v[68:71], v[204:207], v[196:199], v[68:71]
	v_mfma_f32_16x16x32_bf16 v[64:67], v[212:215], v[196:199], v[64:67]
	s_mov_b32 m0, s24
	s_add_u32 s100, s52, s16
	s_addc_u32 s101, s53, s17
	s_barrier
	ds_read_b128 v[168:171], v156 offset:16384
	ds_read_b128 v[172:175], v156 offset:17408
	ds_read_b128 v[176:179], v156 offset:18432
	ds_read_b128 v[180:183], v156 offset:19456
	ds_read_b128 v[184:187], v156 offset:20480
	ds_read_b128 v[188:191], v156 offset:21504
	ds_read_b128 v[192:195], v156 offset:22528
	ds_read_b128 v[196:199], v156 offset:23552
	global_load_lds_dwordx4 v128, s[52:53]
	s_mov_b32 m0, s25
	s_nop 0
	global_load_lds_dwordx4 v132, s[52:53]
	s_waitcnt vmcnt(10)
	s_barrier
	s_waitcnt lgkmcnt(0)
	s_waitcnt lgkmcnt(0)
	v_mfma_f32_16x16x32_bf16 v[60:63], v[144:147], v[168:171], v[60:63]
	v_mfma_f32_16x16x32_bf16 v[56:59], v[160:163], v[168:171], v[56:59]
	v_mfma_f32_16x16x32_bf16 v[44:47], v[144:147], v[176:179], v[44:47]
	v_mfma_f32_16x16x32_bf16 v[40:43], v[160:163], v[176:179], v[40:43]
	v_mfma_f32_16x16x32_bf16 v[28:31], v[144:147], v[184:187], v[28:31]
	v_mfma_f32_16x16x32_bf16 v[24:27], v[160:163], v[184:187], v[24:27]
	v_mfma_f32_16x16x32_bf16 v[12:15], v[144:147], v[192:195], v[12:15]
	v_mfma_f32_16x16x32_bf16 v[8:11], v[160:163], v[192:195], v[8:11]
	v_mfma_f32_16x16x32_bf16 v[60:63], v[148:151], v[172:175], v[60:63]
	v_mfma_f32_16x16x32_bf16 v[56:59], v[164:167], v[172:175], v[56:59]
	v_mfma_f32_16x16x32_bf16 v[44:47], v[148:151], v[180:183], v[44:47]
	v_mfma_f32_16x16x32_bf16 v[40:43], v[164:167], v[180:183], v[40:43]
	v_mfma_f32_16x16x32_bf16 v[28:31], v[148:151], v[188:191], v[28:31]
	v_mfma_f32_16x16x32_bf16 v[24:27], v[164:167], v[188:191], v[24:27]
	v_mfma_f32_16x16x32_bf16 v[12:15], v[148:151], v[196:199], v[12:15]
	v_mfma_f32_16x16x32_bf16 v[8:11], v[164:167], v[196:199], v[8:11]
	s_barrier
	s_add_u32 s72, s50, 0x80000
	s_addc_u32 s73, s51, 0
	s_add_i32 s71, s61, s23
	s_mov_b32 m0, s71
	s_nop 0
	global_load_lds_dwordx4 v130, s[72:73]
	s_add_i32 m0, s71, 0x2000
	s_nop 0
	global_load_lds_dwordx4 v134, s[72:73]
	s_add_i32 s71, 0, 0x18000
	v_add_u32_e32 v159, s71, v153
	ds_read_b128 v[144:147], v159
	ds_read_b128 v[148:151], v159 offset:1024
	ds_read_b128 v[160:163], v159 offset:2048
	ds_read_b128 v[164:167], v159 offset:3072
	s_waitcnt vmcnt(6)
	s_barrier
; #define PG8_STAGE(bufoff, gbase, voff) do { _Pragma("unroll") for (int _i = 0; _i < 2; ++_i) \
;         __builtin_amdgcn_global_load_lds((const unsigned*)((const char*)(gbase) + (voff)[_i]), (LAS unsigned*)(lds + (bufoff) + ldsw + _i * 8192), 16, 0, 0); } while (0)
; #define PG8_LDA(dst, b, h) do { _Pragma("unroll") for (int m = 0; m < 4; ++m) _Pragma("unroll") for (int k = 0; k < 2; ++k) dst[m][k] = *(const LAS bf16x8*)(lds + PG8_SA(b, h) + aoff + m * 2048 + k * 1024); } while (0)
; #define PG8_LDB(dst, b, h) do { _Pragma("unroll") for (int n = 0; n < 2; ++n) _Pragma("unroll") for (int k = 0; k < 2; ++k) dst[n][k] = *(const LAS bf16x8*)(lds + PG8_SB(b, h) + boff + n * 2048 + k * 1024); } while (0)
; #define PG8_MMA(ai, bj, At, Bt) do { __builtin_amdgcn_s_setprio(1); _Pragma("unroll") for (int m = 0; m < 4; ++m) _Pragma("unroll") for (int n = 0; n < 2; ++n) _Pragma("unroll") for (int k = 0; k < 2; ++k) \
;         acc[ai][bj][m][n] = __builtin_amdgcn_mfma_f32_16x16x32_bf16(Bt[n][k], At[m][k], acc[ai][bj][m][n], 0, 0, 0); __builtin_amdgcn_s_setprio(0); } while (0)
; #define PG8_WAIT_V(n) asm volatile("s_waitcnt vmcnt(" #n ")" ::: "memory")
; #define PG8_WAIT_L(n) asm volatile("s_waitcnt lgkmcnt(" #n ")" ::: "memory")
; #define PG8_BAR __builtin_amdgcn_s_barrier()
; #define PG8_SCHED __builtin_amdgcn_sched_barrier(0)
; template <class Epi>
; __device__ __forceinline__ void gemm_phase(LAS unsigned char* lds, const Gemm g, const StaticOrder& S, const Epi& E, int wv) {
;     ...
;             PG8_WAIT_V(6); PG8_BAR; PG8_MMA(1, 1, At, B1); PG8_BAR;
;             PG8_LDB(B0, 1, 0); PG8_SCHED; PG8_LDA(At, 1, 0); PG8_STAGE(PG8_SA(0, 1), a2 + hstepA, voffA);
;             PG8_WAIT_L(8); PG8_BAR; PG8_WAIT_L(0); PG8_MMA(0, 0, At, B0); PG8_BAR; PG8_SCHED;
;             PG8_LDB(B1, 1, 1); PG8_STAGE(PG8_SB(1, 0), b3, voffB);
;             PG8_BAR; PG8_WAIT_L(0); PG8_MMA(0, 1, At, B1); PG8_BAR;
;             PG8_LDA(At, 1, 1); PG8_STAGE(PG8_SA(1, 0), a3, voffA);
;             PG8_BAR; PG8_WAIT_L(0); PG8_MMA(1, 0, At, B0); PG8_BAR; PG8_SCHED;
;             PG8_STAGE(PG8_SB(1, 1), b3 + hstepB, voffB);
;             PG8_WAIT_V(6); PG8_BAR; PG8_MMA(1, 1, At, B1); PG8_BAR;
	v_mfma_f32_16x16x32_bf16 v[52:55], v[200:203], v[168:171], v[52:55]
	v_mfma_f32_16x16x32_bf16 v[48:51], v[208:211], v[168:171], v[48:51]
	v_mfma_f32_16x16x32_bf16 v[36:39], v[200:203], v[176:179], v[36:39]
	v_mfma_f32_16x16x32_bf16 v[32:35], v[208:211], v[176:179], v[32:35]
	v_mfma_f32_16x16x32_bf16 v[20:23], v[200:203], v[184:187], v[20:23]
	v_mfma_f32_16x16x32_bf16 v[16:19], v[208:211], v[184:187], v[16:19]
	v_mfma_f32_16x16x32_bf16 v[4:7], v[200:203], v[192:195], v[4:7]
	v_mfma_f32_16x16x32_bf16 v[0:3], v[208:211], v[192:195], v[0:3]
	v_mfma_f32_16x16x32_bf16 v[52:55], v[204:207], v[172:175], v[52:55]
	v_mfma_f32_16x16x32_bf16 v[48:51], v[212:215], v[172:175], v[48:51]
	v_mfma_f32_16x16x32_bf16 v[36:39], v[204:207], v[180:183], v[36:39]
	v_mfma_f32_16x16x32_bf16 v[32:35], v[212:215], v[180:183], v[32:35]
	v_mfma_f32_16x16x32_bf16 v[20:23], v[204:207], v[188:191], v[20:23]
	v_mfma_f32_16x16x32_bf16 v[16:19], v[212:215], v[188:191], v[16:19]
	v_mfma_f32_16x16x32_bf16 v[4:7], v[204:207], v[196:199], v[4:7]
	v_mfma_f32_16x16x32_bf16 v[0:3], v[212:215], v[196:199], v[0:3]
	s_waitcnt lgkmcnt(0)
	s_barrier
	s_add_u32 s52, s52, 0x80000
	s_addc_u32 s53, s53, 0
	s_mov_b32 m0, s33
	ds_read_b128 v[168:171], v156 offset:32768
	ds_read_b128 v[172:175], v156 offset:33792
	ds_read_b128 v[176:179], v156 offset:34816
	ds_read_b128 v[180:183], v156 offset:35840
	ds_read_b128 v[184:187], v156 offset:36864
	ds_read_b128 v[188:191], v156 offset:37888
	ds_read_b128 v[192:195], v156 offset:38912
	ds_read_b128 v[196:199], v156 offset:39936
	global_load_lds_dwordx4 v128, s[52:53]
	s_mov_b32 m0, s54
	s_nop 0
	global_load_lds_dwordx4 v132, s[52:53]
	s_waitcnt lgkmcnt(8)
	s_barrier
	s_waitcnt lgkmcnt(0)
	s_waitcnt lgkmcnt(0)
	v_mfma_f32_16x16x32_bf16 v[124:127], v[144:147], v[168:171], v[124:127]
	v_mfma_f32_16x16x32_bf16 v[120:123], v[160:163], v[168:171], v[120:123]
	v_mfma_f32_16x16x32_bf16 v[108:111], v[144:147], v[176:179], v[108:111]
	v_mfma_f32_16x16x32_bf16 v[104:107], v[160:163], v[176:179], v[104:107]
	v_mfma_f32_16x16x32_bf16 v[92:95], v[144:147], v[184:187], v[92:95]
	v_mfma_f32_16x16x32_bf16 v[88:91], v[160:163], v[184:187], v[88:91]
	v_mfma_f32_16x16x32_bf16 v[76:79], v[144:147], v[192:195], v[76:79]
	v_mfma_f32_16x16x32_bf16 v[72:75], v[160:163], v[192:195], v[72:75]
	v_mfma_f32_16x16x32_bf16 v[124:127], v[148:151], v[172:175], v[124:127]
	v_mfma_f32_16x16x32_bf16 v[120:123], v[164:167], v[172:175], v[120:123]
	v_mfma_f32_16x16x32_bf16 v[108:111], v[148:151], v[180:183], v[108:111]
	v_mfma_f32_16x16x32_bf16 v[104:107], v[164:167], v[180:183], v[104:107]
	v_mfma_f32_16x16x32_bf16 v[92:95], v[148:151], v[188:191], v[92:95]
	v_mfma_f32_16x16x32_bf16 v[88:91], v[164:167], v[188:191], v[88:91]
	v_mfma_f32_16x16x32_bf16 v[76:79], v[148:151], v[196:199], v[76:79]
	v_mfma_f32_16x16x32_bf16 v[72:75], v[164:167], v[196:199], v[72:75]
	s_barrier
	s_add_i32 s52, 0, 0x1c000
	s_add_i32 s53, s71, s23
	v_add_u32_e32 v159, s52, v153
	s_mov_b32 m0, s53
	ds_read_b128 v[200:203], v159
	ds_read_b128 v[204:207], v159 offset:1024
	ds_read_b128 v[208:211], v159 offset:2048
	ds_read_b128 v[212:215], v159 offset:3072
	global_load_lds_dwordx4 v130, s[98:99]
	s_add_i32 m0, s53, 0x2000
	s_nop 0
	global_load_lds_dwordx4 v134, s[98:99]
	s_barrier
	s_waitcnt lgkmcnt(0)
	s_waitcnt lgkmcnt(0)
	v_mfma_f32_16x16x32_bf16 v[116:119], v[200:203], v[168:171], v[116:119]
	v_mfma_f32_16x16x32_bf16 v[112:115], v[208:211], v[168:171], v[112:115]
	v_mfma_f32_16x16x32_bf16 v[100:103], v[200:203], v[176:179], v[100:103]
	v_mfma_f32_16x16x32_bf16 v[96:99], v[208:211], v[176:179], v[96:99]
	v_mfma_f32_16x16x32_bf16 v[84:87], v[200:203], v[184:187], v[84:87]
	v_mfma_f32_16x16x32_bf16 v[80:83], v[208:211], v[184:187], v[80:83]
	v_mfma_f32_16x16x32_bf16 v[68:71], v[200:203], v[192:195], v[68:71]
	v_mfma_f32_16x16x32_bf16 v[64:67], v[208:211], v[192:195], v[64:67]
	v_mfma_f32_16x16x32_bf16 v[116:119], v[204:207], v[172:175], v[116:119]
	v_mfma_f32_16x16x32_bf16 v[112:115], v[212:215], v[172:175], v[112:115]
	v_mfma_f32_16x16x32_bf16 v[100:103], v[204:207], v[180:183], v[100:103]
	v_mfma_f32_16x16x32_bf16 v[96:99], v[212:215], v[180:183], v[96:99]
	v_mfma_f32_16x16x32_bf16 v[84:87], v[204:207], v[188:191], v[84:87]
	v_mfma_f32_16x16x32_bf16 v[80:83], v[212:215], v[188:191], v[80:83]
	v_mfma_f32_16x16x32_bf16 v[68:71], v[204:207], v[196:199], v[68:71]
	v_mfma_f32_16x16x32_bf16 v[64:67], v[212:215], v[196:199], v[64:67]
	s_mov_b32 m0, s58
	s_barrier
	ds_read_b128 v[168:171], v156 offset:49152
	ds_read_b128 v[172:175], v156 offset:50176
	ds_read_b128 v[176:179], v156 offset:51200
	ds_read_b128 v[180:183], v156 offset:52224
	ds_read_b128 v[184:187], v156 offset:53248
	ds_read_b128 v[188:191], v156 offset:54272
	ds_read_b128 v[192:195], v156 offset:55296
	ds_read_b128 v[196:199], v156 offset:56320
	global_load_lds_dwordx4 v128, s[100:101]
	s_mov_b32 m0, s59
	s_nop 0
	global_load_lds_dwordx4 v132, s[100:101]
	s_waitcnt vmcnt(10)
	s_barrier
	s_waitcnt lgkmcnt(0)
	s_waitcnt lgkmcnt(0)
	v_mfma_f32_16x16x32_bf16 v[60:63], v[144:147], v[168:171], v[60:63]
	v_mfma_f32_16x16x32_bf16 v[56:59], v[160:163], v[168:171], v[56:59]
	v_mfma_f32_16x16x32_bf16 v[44:47], v[144:147], v[176:179], v[44:47]
	v_mfma_f32_16x16x32_bf16 v[40:43], v[160:163], v[176:179], v[40:43]
	v_mfma_f32_16x16x32_bf16 v[28:31], v[144:147], v[184:187], v[28:31]
	v_mfma_f32_16x16x32_bf16 v[24:27], v[160:163], v[184:187], v[24:27]
	v_mfma_f32_16x16x32_bf16 v[12:15], v[144:147], v[192:195], v[12:15]
	v_mfma_f32_16x16x32_bf16 v[8:11], v[160:163], v[192:195], v[8:11]
	v_mfma_f32_16x16x32_bf16 v[60:63], v[148:151], v[172:175], v[60:63]
	v_mfma_f32_16x16x32_bf16 v[56:59], v[164:167], v[172:175], v[56:59]
	v_mfma_f32_16x16x32_bf16 v[44:47], v[148:151], v[180:183], v[44:47]
	v_mfma_f32_16x16x32_bf16 v[40:43], v[164:167], v[180:183], v[40:43]
	v_mfma_f32_16x16x32_bf16 v[28:31], v[148:151], v[188:191], v[28:31]
	v_mfma_f32_16x16x32_bf16 v[24:27], v[164:167], v[188:191], v[24:27]
	v_mfma_f32_16x16x32_bf16 v[12:15], v[148:151], v[196:199], v[12:15]
	v_mfma_f32_16x16x32_bf16 v[8:11], v[164:167], v[196:199], v[8:11]
	s_barrier
	s_add_u32 s50, s50, 0x80080
	s_addc_u32 s51, s51, 0
	s_add_i32 s52, s52, s23
	s_mov_b32 m0, s52
	s_nop 0
	global_load_lds_dwordx4 v130, s[50:51]
	s_add_i32 m0, s52, 0x2000
	s_nop 0
	global_load_lds_dwordx4 v134, s[50:51]
	ds_read_b128 v[144:147], v155
	ds_read_b128 v[148:151], v155 offset:1024
	ds_read_b128 v[160:163], v155 offset:2048
	ds_read_b128 v[164:167], v155 offset:3072
	s_waitcnt vmcnt(6)
	s_branch .LBB0_958
; __device__ __forceinline__ float fast_sigmoid(float x) { return __builtin_amdgcn_rcpf(1.0f + __builtin_amdgcn_exp2f(-x * LOG2E)); }
; __device__ __forceinline__ float ss_fix(float raw) { return (float)__float_as_uint(raw) * (1.0f / 256.0f); }
;     __device__ __forceinline__ const CAS char* base() const { const CAS char* ka = (const CAS char*)__builtin_amdgcn_kernarg_segment_ptr(); asm volatile("" : "+s"(ka)); return ka; }
;     __device__ __forceinline__ void operator()(const f32x4 (&acc)[2][2][4][2], const Unit& u, int wr, int wc, int fr, int fq) const {
;     ...
;         float rsv[8];
; #pragma unroll
;         for (int it = 0; it < 8; ++it) rsv[it] = (SM == 1) ? ss[row0 + (it >> 2) * HALF + (it & 3) * 16] : 1.0f;
; #pragma unroll
;         for (int ai = 0; ai < 2; ++ai)
; #pragma unroll
;             for (int m = 0; m < 4; ++m) { const int row = row0 + ai * HALF + m * 16; float rs = 1.0f; if (SM == 1) rs = __builtin_amdgcn_rsqf(ss_fix(rsv[ai * 4 + m]) * (1.0f / DM) + EPS);
;                 bf16_t* rowp = base + (size_t)row * ldc + col0;
; #pragma unroll
;                 for (int bj = 0; bj < 2; ++bj) { f32x4 v0 = acc[ai][bj][m][0], v1 = acc[ai][bj][m][1];
;                     if (SM == 1) { v0 *= rs; v1 *= rs; }
;                     if (SM == 2) { v0 *= cs[bj][0]; v1 *= cs[bj][1]; }
;                     if (ACT == 1) {
; #pragma unroll
;                         for (int j = 0; j < 4; ++j) { const float a = fmaxf(v0[j], 0.f), b = fmaxf(v1[j], 0.f); v0[j] = a * a; v1[j] = b * b; } }
;                     if (ACT == 2) { if (tsel == 0) {
; #pragma unroll
;                         for (int j = 0; j < 4; ++j) { const float a = v0[j], b = v1[j];
;                             v0[j] = a * fast_sigmoid(1.5957691216057308f * (a + 0.044715f * a * a * a)); v1[j] = b * fast_sigmoid(1.5957691216057308f * (b + 0.044715f * b * b * b)); } } }
;                     u32x4 w; w.x = pk_bf16(v0[0], v0[1]); w.y = pk_bf16(v0[2], v0[3]); w.z = pk_bf16(v1[0], v1[1]); w.w = pk_bf16(v1[2], v1[3]);
;                     *(u32x4*)(rowp + bj * HALF) = w; } }
.Lrot_out_958:
	v_lshl_add_u32 v144, s46, 8, v152
	v_ashrrev_i32_e32 v145, 31, v144
	v_lshl_add_u64 v[146:147], v[144:145], 2, s[14:15]
	global_load_dword v148, v[146:147], off
	global_load_dword v165, v[146:147], off offset:64
	global_load_dword v164, v[146:147], off offset:128
	global_load_dword v163, v[146:147], off offset:192
	global_load_dword v162, v[146:147], off offset:512
	global_load_dword v161, v[146:147], off offset:576
	global_load_dword v160, v[146:147], off offset:640
	global_load_dword v159, v[146:147], off offset:704
	s_add_i32 s11, s10, 7
	s_cmp_lt_u32 s11, 15
	s_cselect_b64 s[46:47], -1, 0
	s_cmp_gt_u32 s11, 14
	s_waitcnt vmcnt(0)
	v_cvt_f32_u32_e32 v146, v148
	v_mul_f32_e32 v146, 0x3b800000, v146
	v_fmamk_f32 v146, v146, 0x3a000000, v158
	v_rsq_f32_e32 v146, v146
	s_nop 0
	v_pk_mul_f32 v[126:127], v[126:127], v[146:147] op_sel_hi:[1,0]
	v_pk_mul_f32 v[124:125], v[124:125], v[146:147] op_sel_hi:[1,0]
	v_pk_mul_f32 v[148:149], v[122:123], v[146:147] op_sel_hi:[1,0]
	v_pk_mul_f32 v[150:151], v[120:121], v[146:147] op_sel_hi:[1,0]
	s_cbranch_scc1 .LBB0_961
	v_mul_f32_e32 v121, 0x3d372713, v150
	v_mul_f32_e32 v121, v150, v121
	v_mul_f32_e32 v122, 0x3d372713, v125
	v_fma_f32 v121, v150, v121, v150
	v_mul_f32_e32 v122, v125, v122
	v_mov_b32_e32 v123, v125
	v_mul_f32_e32 v121, 0x3fcc422a, v121
	v_fmac_f32_e32 v123, v123, v122
	v_mul_f32_e32 v121, 0xbfb8aa3b, v121
	v_mul_f32_e32 v122, 0x3fcc422a, v123
	v_exp_f32_e32 v121, v121
	v_mul_f32_e32 v122, 0xbfb8aa3b, v122
	v_exp_f32_e32 v123, v122
	v_mov_b32_e32 v147, v151
	v_add_f32_e32 v121, 1.0, v121
	v_rcp_f32_e32 v122, v121
	v_add_f32_e32 v121, 1.0, v123
	v_mul_f32_e32 v123, 0x3d372713, v151
	v_mul_f32_e32 v123, v151, v123
	v_fmac_f32_e32 v147, v147, v123
	v_mul_f32_e32 v123, 0x3fcc422a, v147
	v_mul_f32_e32 v147, 0x3d372713, v126
	v_mul_f32_e32 v147, v126, v147
	v_mul_f32_e32 v166, 0x3d372713, v148
	v_fma_f32 v147, v126, v147, v126
	v_mul_f32_e32 v166, v148, v166
	v_mul_f32_e32 v147, 0x3fcc422a, v147
	v_fma_f32 v166, v148, v166, v148
	v_mul_f32_e32 v147, 0xbfb8aa3b, v147
	v_mul_f32_e32 v166, 0x3fcc422a, v166
	v_exp_f32_e32 v147, v147
	v_mul_f32_e32 v166, 0xbfb8aa3b, v166
	v_exp_f32_e32 v167, v166
	v_mul_f32_e32 v120, 0x3d372713, v124
	v_add_f32_e32 v147, 1.0, v147
	v_rcp_f32_e32 v166, v147
	v_add_f32_e32 v147, 1.0, v167
	v_mul_f32_e32 v167, 0x3d372713, v127
	v_mul_f32_e32 v167, v127, v167
	v_mul_f32_e32 v168, 0x3d372713, v149
	v_mul_f32_e32 v120, v124, v120
	v_fma_f32 v167, v127, v167, v127
	v_mul_f32_e32 v168, v149, v168
	v_fma_f32 v120, v124, v120, v124
	v_mul_f32_e32 v167, 0x3fcc422a, v167
	v_fma_f32 v168, v149, v168, v149
	v_mul_f32_e32 v120, 0x3fcc422a, v120
	v_mul_f32_e32 v167, 0xbfb8aa3b, v167
	v_mul_f32_e32 v168, 0x3fcc422a, v168
	v_mul_f32_e32 v120, 0xbfb8aa3b, v120
	v_mul_f32_e32 v123, 0xbfb8aa3b, v123
	v_exp_f32_e32 v167, v167
	v_mul_f32_e32 v168, 0xbfb8aa3b, v168
	v_exp_f32_e32 v120, v120
	v_exp_f32_e32 v123, v123
	v_exp_f32_e32 v169, v168
	v_rcp_f32_e32 v168, v147
	v_add_f32_e32 v147, 1.0, v167
	v_add_f32_e32 v120, 1.0, v120
	v_add_f32_e32 v123, 1.0, v123
	v_rcp_f32_e32 v167, v147
	v_add_f32_e32 v147, 1.0, v169
	v_rcp_f32_e32 v120, v120
	v_rcp_f32_e32 v121, v121
	v_rcp_f32_e32 v169, v147
	v_rcp_f32_e32 v123, v123
	v_pk_mul_f32 v[126:127], v[126:127], v[166:167]
	v_pk_mul_f32 v[124:125], v[124:125], v[120:121]
	v_pk_mul_f32 v[148:149], v[148:149], v[168:169]
	v_pk_mul_f32 v[150:151], v[150:151], v[122:123]

; #define PG8_BAR __builtin_amdgcn_s_barrier()
; template <class Epi>
; __device__ __forceinline__ void gemm_phase(LAS unsigned char* lds, const Gemm g, const StaticOrder& S, const Epi& E, int wv) {
;     ...
;         const bool has_next = S.next(ui + 1, nxt);
;         const char* nA = has_next ? (const char*)g.A + (size_t)nxt.pm * tstepA + ((g.adiag & 1) ? (size_t)(nxt.pn >> 1) * K * 2 : 0) + kbeg : cA;
;         const char* nB = has_next ? (const char*)g.Bt + (size_t)nxt.pn * tstepB + kbeg : cB;
;         for (int t = 0; t < nt; t += 2) {
;             const bool last = (t == nt - 2);
;             const char* a1 = cA + (ptrdiff_t)(t + 1) * kstep;
;             const char* a2 = last ? nA : cA + (ptrdiff_t)(t + 2) * kstep; const char* b2 = last ? nB : cB + (ptrdiff_t)(t + 2) * kstep;
;             const char* a3 = a2 + kstep; const char* b3 = b2 + kstep;
;             PG8_LDB(B0, 0, 0); PG8_SCHED; PG8_LDA(At, 0, 0); PG8_STAGE(PG8_SA(1, 1), a1 + hstepA, voffA);
;             PG8_WAIT_L(8); PG8_BAR; PG8_WAIT_L(0); PG8_MMA(0, 0, At, B0); PG8_BAR; PG8_SCHED;
;             PG8_LDB(B1, 0, 1); PG8_STAGE(PG8_SB(0, 0), b2, voffB);
;             PG8_BAR; PG8_WAIT_L(0); PG8_MMA(0, 1, At, B1); PG8_BAR;
;             PG8_LDA(At, 0, 1); PG8_STAGE(PG8_SA(0, 0), a2, voffA);
;             PG8_BAR; PG8_WAIT_L(0); PG8_MMA(1, 0, At, B0); PG8_BAR; PG8_SCHED;
;             PG8_STAGE(PG8_SB(0, 1), b2 + hstepB, voffB);
;             PG8_WAIT_V(6); PG8_BAR; PG8_MMA(1, 1, At, B1); PG8_BAR;
;             PG8_LDB(B0, 1, 0); PG8_SCHED; PG8_LDA(At, 1, 0); PG8_STAGE(PG8_SA(0, 1), a2 + hstepA, voffA);
;             PG8_WAIT_L(8); PG8_BAR; PG8_WAIT_L(0); PG8_MMA(0, 0, At, B0); PG8_BAR; PG8_SCHED;
;             PG8_LDB(B1, 1, 1); PG8_STAGE(PG8_SB(1, 0), b3, voffB);
;             PG8_BAR; PG8_WAIT_L(0); PG8_MMA(0, 1, At, B1); PG8_BAR;
;             PG8_LDA(At, 1, 1); PG8_STAGE(PG8_SA(1, 0), a3, voffA);
;             PG8_BAR; PG8_WAIT_L(0); PG8_MMA(1, 0, At, B0); PG8_BAR; PG8_SCHED;
;             PG8_STAGE(PG8_SB(1, 1), b3 + hstepB, voffB);
;             PG8_WAIT_V(6); PG8_BAR; PG8_MMA(1, 1, At, B1); PG8_BAR;
;         }
;         E(acc, cur, wr, wc, fr, fq);
;         if (!has_next) break;
; #pragma unroll
;         for (int a = 0; a < 2; ++a)
; #pragma unroll
;             for (int b = 0; b < 2; ++b)
; #pragma unroll
;                 for (int m = 0; m < 4; ++m)
; #pragma unroll
.LBB0_1580:
	s_ashr_i32 s37, s36, 31
	v_cmp_lt_i64_e32 vcc, s[38:39], v[156:157]
	s_lshl_b64 s[38:39], s[36:37], 20
	s_add_u32 s38, s5, s38
	s_addc_u32 s39, s22, s39
	s_and_b64 s[40:41], vcc, exec
	s_cselect_b32 s37, s39, s47
	s_cselect_b32 s43, s38, s46
	s_ashr_i32 s35, s34, 31
	s_lshl_b64 s[40:41], s[34:35], 20
	s_add_u32 s40, s23, s40
	s_addc_u32 s41, s24, s41
	s_and_b64 s[50:51], vcc, exec
	s_cselect_b32 s35, s41, s49
	s_cselect_b32 s60, s40, s48
	s_add_u32 s61, s48, 0x100
	s_addc_u32 s62, s49, 0
	s_add_u32 s46, s46, 0x80080
	v_mov_b32_e32 v0, 0
	s_addc_u32 s47, s47, 0
	s_mov_b32 s63, -2
	s_waitcnt lgkmcnt(0)
	v_mov_b32_e32 v1, v0
	v_mov_b32_e32 v2, v0
	v_mov_b32_e32 v3, v0
	v_mov_b32_e32 v4, v0
	v_mov_b32_e32 v5, v0
	v_mov_b32_e32 v6, v0
	v_mov_b32_e32 v7, v0
	v_mov_b32_e32 v16, v0
	v_mov_b32_e32 v17, v0
	v_mov_b32_e32 v18, v0
	v_mov_b32_e32 v19, v0
	v_mov_b32_e32 v20, v0
	v_mov_b32_e32 v21, v0
	v_mov_b32_e32 v22, v0
	v_mov_b32_e32 v23, v0
	v_mov_b32_e32 v32, v0
	v_mov_b32_e32 v33, v0
	v_mov_b32_e32 v34, v0
	v_mov_b32_e32 v35, v0
	v_mov_b32_e32 v36, v0
	v_mov_b32_e32 v37, v0
	v_mov_b32_e32 v38, v0
	v_mov_b32_e32 v39, v0
	v_mov_b32_e32 v48, v0
	v_mov_b32_e32 v49, v0
	v_mov_b32_e32 v50, v0
	v_mov_b32_e32 v51, v0
	v_mov_b32_e32 v52, v0
	v_mov_b32_e32 v53, v0
	v_mov_b32_e32 v54, v0
	v_mov_b32_e32 v55, v0
	v_mov_b32_e32 v8, v0
	v_mov_b32_e32 v9, v0
	v_mov_b32_e32 v10, v0
	v_mov_b32_e32 v11, v0
	v_mov_b32_e32 v12, v0
	v_mov_b32_e32 v13, v0
	v_mov_b32_e32 v14, v0
	v_mov_b32_e32 v15, v0
	v_mov_b32_e32 v24, v0
	v_mov_b32_e32 v25, v0
	v_mov_b32_e32 v26, v0
	v_mov_b32_e32 v27, v0
	v_mov_b32_e32 v28, v0
	v_mov_b32_e32 v29, v0
	v_mov_b32_e32 v30, v0
	v_mov_b32_e32 v31, v0
	v_mov_b32_e32 v40, v0
	v_mov_b32_e32 v41, v0
	v_mov_b32_e32 v42, v0
	v_mov_b32_e32 v43, v0
	v_mov_b32_e32 v44, v0
	v_mov_b32_e32 v45, v0
	v_mov_b32_e32 v46, v0
	v_mov_b32_e32 v47, v0
	v_mov_b32_e32 v56, v0
	v_mov_b32_e32 v57, v0
	v_mov_b32_e32 v58, v0
	v_mov_b32_e32 v59, v0
	v_mov_b32_e32 v60, v0
	v_mov_b32_e32 v61, v0
	v_mov_b32_e32 v62, v0
	v_mov_b32_e32 v63, v0
	v_mov_b32_e32 v64, v0
	v_mov_b32_e32 v65, v0
	v_mov_b32_e32 v66, v0
	v_mov_b32_e32 v67, v0
	v_mov_b32_e32 v68, v0
	v_mov_b32_e32 v69, v0
	v_mov_b32_e32 v70, v0
	v_mov_b32_e32 v71, v0
	v_mov_b32_e32 v80, v0
	v_mov_b32_e32 v81, v0
	v_mov_b32_e32 v82, v0
	v_mov_b32_e32 v83, v0
	v_mov_b32_e32 v84, v0
	v_mov_b32_e32 v85, v0
	v_mov_b32_e32 v86, v0
	v_mov_b32_e32 v87, v0
	v_mov_b32_e32 v96, v0
	v_mov_b32_e32 v97, v0
	v_mov_b32_e32 v98, v0
	v_mov_b32_e32 v99, v0
	v_mov_b32_e32 v100, v0
	v_mov_b32_e32 v101, v0
	v_mov_b32_e32 v102, v0
	v_mov_b32_e32 v103, v0
	v_mov_b32_e32 v112, v0
	v_mov_b32_e32 v113, v0
	v_mov_b32_e32 v114, v0
	v_mov_b32_e32 v115, v0
	v_mov_b32_e32 v116, v0
	v_mov_b32_e32 v117, v0
	v_mov_b32_e32 v118, v0
	v_mov_b32_e32 v119, v0
	v_mov_b32_e32 v72, v0
	v_mov_b32_e32 v73, v0
	v_mov_b32_e32 v74, v0
	v_mov_b32_e32 v75, v0
	v_mov_b32_e32 v76, v0
	v_mov_b32_e32 v77, v0
	v_mov_b32_e32 v78, v0
	v_mov_b32_e32 v79, v0
	v_mov_b32_e32 v88, v0
	v_mov_b32_e32 v89, v0
	v_mov_b32_e32 v90, v0
	v_mov_b32_e32 v91, v0
	v_mov_b32_e32 v92, v0
	v_mov_b32_e32 v93, v0
	v_mov_b32_e32 v94, v0
	v_mov_b32_e32 v95, v0
	v_mov_b32_e32 v104, v0
	v_mov_b32_e32 v105, v0
	v_mov_b32_e32 v106, v0
	v_mov_b32_e32 v107, v0
	v_mov_b32_e32 v108, v0
	v_mov_b32_e32 v109, v0
	v_mov_b32_e32 v110, v0
	v_mov_b32_e32 v111, v0
	v_mov_b32_e32 v120, v0
	v_mov_b32_e32 v121, v0
	v_mov_b32_e32 v122, v0
	v_mov_b32_e32 v123, v0
	v_mov_b32_e32 v124, v0
	v_mov_b32_e32 v125, v0
	v_mov_b32_e32 v126, v0
	v_mov_b32_e32 v127, v0
	ds_read_b128 v[128:131], v179
	ds_read_b128 v[132:135], v179 offset:1024
	ds_read_b128 v[136:139], v179 offset:2048
	ds_read_b128 v[140:143], v179 offset:3072
	s_branch .Lrot_in_1581
.LBB0_1581:
	s_barrier
	v_mfma_f32_16x16x32_bf16 v[52:55], v[198:201], v[160:163], v[52:55]
	v_mfma_f32_16x16x32_bf16 v[48:51], v[206:209], v[160:163], v[48:51]
	v_mfma_f32_16x16x32_bf16 v[36:39], v[198:201], v[168:171], v[36:39]
	v_mfma_f32_16x16x32_bf16 v[32:35], v[206:209], v[168:171], v[32:35]
	v_mfma_f32_16x16x32_bf16 v[20:23], v[198:201], v[182:185], v[20:23]
	v_mfma_f32_16x16x32_bf16 v[16:19], v[206:209], v[182:185], v[16:19]
	v_mfma_f32_16x16x32_bf16 v[4:7], v[198:201], v[190:193], v[4:7]
	v_mfma_f32_16x16x32_bf16 v[0:3], v[206:209], v[190:193], v[0:3]
	v_mfma_f32_16x16x32_bf16 v[52:55], v[202:205], v[164:167], v[52:55]
	v_mfma_f32_16x16x32_bf16 v[48:51], v[210:213], v[164:167], v[48:51]
	v_mfma_f32_16x16x32_bf16 v[36:39], v[202:205], v[172:175], v[36:39]
	v_mfma_f32_16x16x32_bf16 v[32:35], v[210:213], v[172:175], v[32:35]
	v_mfma_f32_16x16x32_bf16 v[20:23], v[202:205], v[186:189], v[20:23]
	v_mfma_f32_16x16x32_bf16 v[16:19], v[210:213], v[186:189], v[16:19]
	v_mfma_f32_16x16x32_bf16 v[4:7], v[202:205], v[194:197], v[4:7]
	v_mfma_f32_16x16x32_bf16 v[0:3], v[210:213], v[194:197], v[0:3]
	s_waitcnt lgkmcnt(0)
	s_add_i32 s63, s63, 2
	s_add_u32 s61, s61, 0x100
	s_addc_u32 s62, s62, 0
	s_add_u32 s46, s46, 0x100
	s_addc_u32 s47, s47, 0
	s_cmp_gt_u32 s63, 29
	s_barrier
	s_cbranch_scc1 .Lrot_out_1581
; #define PG8_STAGE(bufoff, gbase, voff) do { _Pragma("unroll") for (int _i = 0; _i < 2; ++_i) \
;         __builtin_amdgcn_global_load_lds((const unsigned*)((const char*)(gbase) + (voff)[_i]), (LAS unsigned*)(lds + (bufoff) + ldsw + _i * 8192), 16, 0, 0); } while (0)
; #define PG8_LDA(dst, b, h) do { _Pragma("unroll") for (int m = 0; m < 4; ++m) _Pragma("unroll") for (int k = 0; k < 2; ++k) dst[m][k] = *(const LAS bf16x8*)(lds + PG8_SA(b, h) + aoff + m * 2048 + k * 1024); } while (0)
; #define PG8_LDB(dst, b, h) do { _Pragma("unroll") for (int n = 0; n < 2; ++n) _Pragma("unroll") for (int k = 0; k < 2; ++k) dst[n][k] = *(const LAS bf16x8*)(lds + PG8_SB(b, h) + boff + n * 2048 + k * 1024); } while (0)
; #define PG8_MMA(ai, bj, At, Bt) do { __builtin_amdgcn_s_setprio(1); _Pragma("unroll") for (int m = 0; m < 4; ++m) _Pragma("unroll") for (int n = 0; n < 2; ++n) _Pragma("unroll") for (int k = 0; k < 2; ++k) \
;         acc[ai][bj][m][n] = __builtin_amdgcn_mfma_f32_16x16x32_bf16(Bt[n][k], At[m][k], acc[ai][bj][m][n], 0, 0, 0); __builtin_amdgcn_s_setprio(0); } while (0)
; #define PG8_WAIT_V(n) asm volatile("s_waitcnt vmcnt(" #n ")" ::: "memory")
; #define PG8_WAIT_L(n) asm volatile("s_waitcnt lgkmcnt(" #n ")" ::: "memory")
; template <class Epi>
; __device__ __forceinline__ void gemm_phase(LAS unsigned char* lds, const Gemm g, const StaticOrder& S, const Epi& E, int wv) {
;     ...
;         for (int t = 0; t < nt; t += 2) {
;             const bool last = (t == nt - 2);
;             const char* a1 = cA + (ptrdiff_t)(t + 1) * kstep;
;             const char* a2 = last ? nA : cA + (ptrdiff_t)(t + 2) * kstep; const char* b2 = last ? nB : cB + (ptrdiff_t)(t + 2) * kstep;
;             const char* a3 = a2 + kstep; const char* b3 = b2 + kstep;
;             PG8_LDB(B0, 0, 0); PG8_SCHED; PG8_LDA(At, 0, 0); PG8_STAGE(PG8_SA(1, 1), a1 + hstepA, voffA);
;             PG8_WAIT_L(8); PG8_BAR; PG8_WAIT_L(0); PG8_MMA(0, 0, At, B0); PG8_BAR; PG8_SCHED;
;             PG8_LDB(B1, 0, 1); PG8_STAGE(PG8_SB(0, 0), b2, voffB);
;             PG8_BAR; PG8_WAIT_L(0); PG8_MMA(0, 1, At, B1); PG8_BAR;
;             PG8_LDA(At, 0, 1); PG8_STAGE(PG8_SA(0, 0), a2, voffA);
;             PG8_BAR; PG8_WAIT_L(0); PG8_MMA(1, 0, At, B0); PG8_BAR; PG8_SCHED;
;             PG8_STAGE(PG8_SB(0, 1), b2 + hstepB, voffB);
;             PG8_WAIT_V(6); PG8_BAR; PG8_MMA(1, 1, At, B1); PG8_BAR;
.Lrot_in_1581:
	s_add_u32 s48, s46, 0xfff80080
	s_addc_u32 s49, s47, -1
	s_cmp_eq_u32 s63, 28
	s_cselect_b32 s51, s37, s49
	s_cselect_b32 s50, s43, s48
	s_cselect_b32 s49, s35, s62
	s_cselect_b32 s48, s60, s61
	s_add_i32 m0, s33, 0xc000
	ds_read_b128 v[160:163], v180
	ds_read_b128 v[164:167], v180 offset:1024
	ds_read_b128 v[168:171], v180 offset:2048
	ds_read_b128 v[172:175], v180 offset:3072
	ds_read_b128 v[182:185], v180 offset:4096
	ds_read_b128 v[186:189], v180 offset:5120
	ds_read_b128 v[190:193], v180 offset:6144
	ds_read_b128 v[194:197], v180 offset:7168
	global_load_lds_dwordx4 v154, s[46:47]
	s_add_i32 m0, s33, 0xe000
	s_nop 0
	global_load_lds_dwordx4 v152, s[46:47]
	s_waitcnt lgkmcnt(8)
	s_barrier
	s_waitcnt lgkmcnt(0)
	s_waitcnt lgkmcnt(0)
	v_mfma_f32_16x16x32_bf16 v[124:127], v[128:131], v[160:163], v[124:127]
	v_mfma_f32_16x16x32_bf16 v[120:123], v[136:139], v[160:163], v[120:123]
	v_mfma_f32_16x16x32_bf16 v[108:111], v[128:131], v[168:171], v[108:111]
	v_mfma_f32_16x16x32_bf16 v[104:107], v[136:139], v[168:171], v[104:107]
	v_mfma_f32_16x16x32_bf16 v[92:95], v[128:131], v[182:185], v[92:95]
	v_mfma_f32_16x16x32_bf16 v[88:91], v[136:139], v[182:185], v[88:91]
	v_mfma_f32_16x16x32_bf16 v[76:79], v[128:131], v[190:193], v[76:79]
	v_mfma_f32_16x16x32_bf16 v[72:75], v[136:139], v[190:193], v[72:75]
	v_mfma_f32_16x16x32_bf16 v[124:127], v[132:135], v[164:167], v[124:127]
	v_mfma_f32_16x16x32_bf16 v[120:123], v[140:143], v[164:167], v[120:123]
	v_mfma_f32_16x16x32_bf16 v[108:111], v[132:135], v[172:175], v[108:111]
	v_mfma_f32_16x16x32_bf16 v[104:107], v[140:143], v[172:175], v[104:107]
	v_mfma_f32_16x16x32_bf16 v[92:95], v[132:135], v[186:189], v[92:95]
	v_mfma_f32_16x16x32_bf16 v[88:91], v[140:143], v[186:189], v[88:91]
	v_mfma_f32_16x16x32_bf16 v[76:79], v[132:135], v[194:197], v[76:79]
	v_mfma_f32_16x16x32_bf16 v[72:75], v[140:143], v[194:197], v[72:75]
	s_barrier
	s_add_i32 s64, s57, s25
	s_add_u32 s98, s48, s16
	s_addc_u32 s99, s49, s17
	s_mov_b32 m0, s64
	ds_read_b128 v[198:201], v181
	ds_read_b128 v[202:205], v181 offset:1024
	ds_read_b128 v[206:209], v181 offset:2048
	ds_read_b128 v[210:213], v181 offset:3072
	global_load_lds_dwordx4 v146, s[48:49]
	s_add_i32 m0, s64, 0x2000
	s_nop 0
	global_load_lds_dwordx4 v150, s[48:49]
	s_barrier
	s_waitcnt lgkmcnt(0)
	s_waitcnt lgkmcnt(0)
	v_mfma_f32_16x16x32_bf16 v[116:119], v[198:201], v[160:163], v[116:119]
	v_mfma_f32_16x16x32_bf16 v[112:115], v[206:209], v[160:163], v[112:115]
	v_mfma_f32_16x16x32_bf16 v[100:103], v[198:201], v[168:171], v[100:103]
	v_mfma_f32_16x16x32_bf16 v[96:99], v[206:209], v[168:171], v[96:99]
	v_mfma_f32_16x16x32_bf16 v[84:87], v[198:201], v[182:185], v[84:87]
	v_mfma_f32_16x16x32_bf16 v[80:83], v[206:209], v[182:185], v[80:83]
	v_mfma_f32_16x16x32_bf16 v[68:71], v[198:201], v[190:193], v[68:71]
	v_mfma_f32_16x16x32_bf16 v[64:67], v[206:209], v[190:193], v[64:67]
	v_mfma_f32_16x16x32_bf16 v[116:119], v[202:205], v[164:167], v[116:119]
	v_mfma_f32_16x16x32_bf16 v[112:115], v[210:213], v[164:167], v[112:115]
	v_mfma_f32_16x16x32_bf16 v[100:103], v[202:205], v[172:175], v[100:103]
	v_mfma_f32_16x16x32_bf16 v[96:99], v[210:213], v[172:175], v[96:99]
	v_mfma_f32_16x16x32_bf16 v[84:87], v[202:205], v[186:189], v[84:87]
	v_mfma_f32_16x16x32_bf16 v[80:83], v[210:213], v[186:189], v[80:83]
	v_mfma_f32_16x16x32_bf16 v[68:71], v[202:205], v[194:197], v[68:71]
	v_mfma_f32_16x16x32_bf16 v[64:67], v[210:213], v[194:197], v[64:67]
	s_mov_b32 m0, s33
	s_add_u32 s100, s50, s16
	s_addc_u32 s101, s51, s17
	s_barrier
	ds_read_b128 v[160:163], v180 offset:16384
	ds_read_b128 v[164:167], v180 offset:17408
	ds_read_b128 v[168:171], v180 offset:18432
	ds_read_b128 v[172:175], v180 offset:19456
	ds_read_b128 v[182:185], v180 offset:20480
	ds_read_b128 v[186:189], v180 offset:21504
	ds_read_b128 v[190:193], v180 offset:22528
	ds_read_b128 v[194:197], v180 offset:23552
	global_load_lds_dwordx4 v144, s[50:51]
	s_mov_b32 m0, s45
	s_nop 0
	global_load_lds_dwordx4 v148, s[50:51]
	s_waitcnt vmcnt(10)
	s_barrier
	s_waitcnt lgkmcnt(0)
	s_waitcnt lgkmcnt(0)
	v_mfma_f32_16x16x32_bf16 v[60:63], v[128:131], v[160:163], v[60:63]
	v_mfma_f32_16x16x32_bf16 v[56:59], v[136:139], v[160:163], v[56:59]
	v_mfma_f32_16x16x32_bf16 v[44:47], v[128:131], v[168:171], v[44:47]
	v_mfma_f32_16x16x32_bf16 v[40:43], v[136:139], v[168:171], v[40:43]
	v_mfma_f32_16x16x32_bf16 v[28:31], v[128:131], v[182:185], v[28:31]
	v_mfma_f32_16x16x32_bf16 v[24:27], v[136:139], v[182:185], v[24:27]
	v_mfma_f32_16x16x32_bf16 v[12:15], v[128:131], v[190:193], v[12:15]
	v_mfma_f32_16x16x32_bf16 v[8:11], v[136:139], v[190:193], v[8:11]
	v_mfma_f32_16x16x32_bf16 v[60:63], v[132:135], v[164:167], v[60:63]
	v_mfma_f32_16x16x32_bf16 v[56:59], v[140:143], v[164:167], v[56:59]
	v_mfma_f32_16x16x32_bf16 v[44:47], v[132:135], v[172:175], v[44:47]
	v_mfma_f32_16x16x32_bf16 v[40:43], v[140:143], v[172:175], v[40:43]
	v_mfma_f32_16x16x32_bf16 v[28:31], v[132:135], v[186:189], v[28:31]
	v_mfma_f32_16x16x32_bf16 v[24:27], v[140:143], v[186:189], v[24:27]
	v_mfma_f32_16x16x32_bf16 v[12:15], v[132:135], v[194:197], v[12:15]
	v_mfma_f32_16x16x32_bf16 v[8:11], v[140:143], v[194:197], v[8:11]
	s_barrier
	s_add_u32 s64, s48, 0x80000
	s_addc_u32 s65, s49, 0
	s_add_i32 s66, s58, s25
	s_mov_b32 m0, s66
	s_nop 0
	global_load_lds_dwordx4 v146, s[64:65]
	s_add_i32 m0, s66, 0x2000
	s_nop 0
	global_load_lds_dwordx4 v150, s[64:65]
	s_add_i32 s64, 0, 0x18000
	v_add_u32_e32 v140, s64, v177
	ds_read_b128 v[128:131], v140
	ds_read_b128 v[132:135], v140 offset:1024
	ds_read_b128 v[136:139], v140 offset:2048
	ds_read_b128 v[140:143], v140 offset:3072
	s_waitcnt vmcnt(6)
	s_barrier
; #define PG8_STAGE(bufoff, gbase, voff) do { _Pragma("unroll") for (int _i = 0; _i < 2; ++_i) \
;         __builtin_amdgcn_global_load_lds((const unsigned*)((const char*)(gbase) + (voff)[_i]), (LAS unsigned*)(lds + (bufoff) + ldsw + _i * 8192), 16, 0, 0); } while (0)
; #define PG8_LDA(dst, b, h) do { _Pragma("unroll") for (int m = 0; m < 4; ++m) _Pragma("unroll") for (int k = 0; k < 2; ++k) dst[m][k] = *(const LAS bf16x8*)(lds + PG8_SA(b, h) + aoff + m * 2048 + k * 1024); } while (0)
; #define PG8_LDB(dst, b, h) do { _Pragma("unroll") for (int n = 0; n < 2; ++n) _Pragma("unroll") for (int k = 0; k < 2; ++k) dst[n][k] = *(const LAS bf16x8*)(lds + PG8_SB(b, h) + boff + n * 2048 + k * 1024); } while (0)
; #define PG8_MMA(ai, bj, At, Bt) do { __builtin_amdgcn_s_setprio(1); _Pragma("unroll") for (int m = 0; m < 4; ++m) _Pragma("unroll") for (int n = 0; n < 2; ++n) _Pragma("unroll") for (int k = 0; k < 2; ++k) \
;         acc[ai][bj][m][n] = __builtin_amdgcn_mfma_f32_16x16x32_bf16(Bt[n][k], At[m][k], acc[ai][bj][m][n], 0, 0, 0); __builtin_amdgcn_s_setprio(0); } while (0)
; #define PG8_WAIT_V(n) asm volatile("s_waitcnt vmcnt(" #n ")" ::: "memory")
; #define PG8_WAIT_L(n) asm volatile("s_waitcnt lgkmcnt(" #n ")" ::: "memory")
; #define PG8_BAR __builtin_amdgcn_s_barrier()
; #define PG8_SCHED __builtin_amdgcn_sched_barrier(0)
; template <class Epi>
; __device__ __forceinline__ void gemm_phase(LAS unsigned char* lds, const Gemm g, const StaticOrder& S, const Epi& E, int wv) {
;     ...
;             PG8_WAIT_V(6); PG8_BAR; PG8_MMA(1, 1, At, B1); PG8_BAR;
;             PG8_LDB(B0, 1, 0); PG8_SCHED; PG8_LDA(At, 1, 0); PG8_STAGE(PG8_SA(0, 1), a2 + hstepA, voffA);
;             PG8_WAIT_L(8); PG8_BAR; PG8_WAIT_L(0); PG8_MMA(0, 0, At, B0); PG8_BAR; PG8_SCHED;
;             PG8_LDB(B1, 1, 1); PG8_STAGE(PG8_SB(1, 0), b3, voffB);
;             PG8_BAR; PG8_WAIT_L(0); PG8_MMA(0, 1, At, B1); PG8_BAR;
;             PG8_LDA(At, 1, 1); PG8_STAGE(PG8_SA(1, 0), a3, voffA);
;             PG8_BAR; PG8_WAIT_L(0); PG8_MMA(1, 0, At, B0); PG8_BAR; PG8_SCHED;
;             PG8_STAGE(PG8_SB(1, 1), b3 + hstepB, voffB);
;             PG8_WAIT_V(6); PG8_BAR; PG8_MMA(1, 1, At, B1); PG8_BAR;
	v_mfma_f32_16x16x32_bf16 v[52:55], v[198:201], v[160:163], v[52:55]
	v_mfma_f32_16x16x32_bf16 v[48:51], v[206:209], v[160:163], v[48:51]
	v_mfma_f32_16x16x32_bf16 v[36:39], v[198:201], v[168:171], v[36:39]
	v_mfma_f32_16x16x32_bf16 v[32:35], v[206:209], v[168:171], v[32:35]
	v_mfma_f32_16x16x32_bf16 v[20:23], v[198:201], v[182:185], v[20:23]
	v_mfma_f32_16x16x32_bf16 v[16:19], v[206:209], v[182:185], v[16:19]
	v_mfma_f32_16x16x32_bf16 v[4:7], v[198:201], v[190:193], v[4:7]
	v_mfma_f32_16x16x32_bf16 v[0:3], v[206:209], v[190:193], v[0:3]
	v_mfma_f32_16x16x32_bf16 v[52:55], v[202:205], v[164:167], v[52:55]
	v_mfma_f32_16x16x32_bf16 v[48:51], v[210:213], v[164:167], v[48:51]
	v_mfma_f32_16x16x32_bf16 v[36:39], v[202:205], v[172:175], v[36:39]
	v_mfma_f32_16x16x32_bf16 v[32:35], v[210:213], v[172:175], v[32:35]
	v_mfma_f32_16x16x32_bf16 v[20:23], v[202:205], v[186:189], v[20:23]
	v_mfma_f32_16x16x32_bf16 v[16:19], v[210:213], v[186:189], v[16:19]
	v_mfma_f32_16x16x32_bf16 v[4:7], v[202:205], v[194:197], v[4:7]
	v_mfma_f32_16x16x32_bf16 v[0:3], v[210:213], v[194:197], v[0:3]
	s_waitcnt lgkmcnt(0)
	s_barrier
	s_add_u32 s50, s50, 0x80000
	s_addc_u32 s51, s51, 0
	s_mov_b32 m0, s52
	ds_read_b128 v[160:163], v180 offset:32768
	ds_read_b128 v[164:167], v180 offset:33792
	ds_read_b128 v[168:171], v180 offset:34816
	ds_read_b128 v[172:175], v180 offset:35840
	ds_read_b128 v[182:185], v180 offset:36864
	ds_read_b128 v[186:189], v180 offset:37888
	ds_read_b128 v[190:193], v180 offset:38912
	ds_read_b128 v[194:197], v180 offset:39936
	global_load_lds_dwordx4 v144, s[50:51]
	s_mov_b32 m0, s53
	s_nop 0
	global_load_lds_dwordx4 v148, s[50:51]
	s_waitcnt lgkmcnt(8)
	s_barrier
	s_waitcnt lgkmcnt(0)
	s_waitcnt lgkmcnt(0)
	v_mfma_f32_16x16x32_bf16 v[124:127], v[128:131], v[160:163], v[124:127]
	v_mfma_f32_16x16x32_bf16 v[120:123], v[136:139], v[160:163], v[120:123]
	v_mfma_f32_16x16x32_bf16 v[108:111], v[128:131], v[168:171], v[108:111]
	v_mfma_f32_16x16x32_bf16 v[104:107], v[136:139], v[168:171], v[104:107]
	v_mfma_f32_16x16x32_bf16 v[92:95], v[128:131], v[182:185], v[92:95]
	v_mfma_f32_16x16x32_bf16 v[88:91], v[136:139], v[182:185], v[88:91]
	v_mfma_f32_16x16x32_bf16 v[76:79], v[128:131], v[190:193], v[76:79]
	v_mfma_f32_16x16x32_bf16 v[72:75], v[136:139], v[190:193], v[72:75]
	v_mfma_f32_16x16x32_bf16 v[124:127], v[132:135], v[164:167], v[124:127]
	v_mfma_f32_16x16x32_bf16 v[120:123], v[140:143], v[164:167], v[120:123]
	v_mfma_f32_16x16x32_bf16 v[108:111], v[132:135], v[172:175], v[108:111]
	v_mfma_f32_16x16x32_bf16 v[104:107], v[140:143], v[172:175], v[104:107]
	v_mfma_f32_16x16x32_bf16 v[92:95], v[132:135], v[186:189], v[92:95]
	v_mfma_f32_16x16x32_bf16 v[88:91], v[140:143], v[186:189], v[88:91]
	v_mfma_f32_16x16x32_bf16 v[76:79], v[132:135], v[194:197], v[76:79]
	v_mfma_f32_16x16x32_bf16 v[72:75], v[140:143], v[194:197], v[72:75]
	s_barrier
	s_add_i32 s50, 0, 0x1c000
	s_add_i32 s51, s64, s25
	v_add_u32_e32 v210, s50, v177
	s_mov_b32 m0, s51
	ds_read_b128 v[198:201], v210
	ds_read_b128 v[202:205], v210 offset:1024
	ds_read_b128 v[206:209], v210 offset:2048
	ds_read_b128 v[210:213], v210 offset:3072
	global_load_lds_dwordx4 v146, s[98:99]
	s_add_i32 m0, s51, 0x2000
	s_nop 0
	global_load_lds_dwordx4 v150, s[98:99]
	s_barrier
	s_waitcnt lgkmcnt(0)
	s_waitcnt lgkmcnt(0)
	v_mfma_f32_16x16x32_bf16 v[116:119], v[198:201], v[160:163], v[116:119]
	v_mfma_f32_16x16x32_bf16 v[112:115], v[206:209], v[160:163], v[112:115]
	v_mfma_f32_16x16x32_bf16 v[100:103], v[198:201], v[168:171], v[100:103]
	v_mfma_f32_16x16x32_bf16 v[96:99], v[206:209], v[168:171], v[96:99]
	v_mfma_f32_16x16x32_bf16 v[84:87], v[198:201], v[182:185], v[84:87]
	v_mfma_f32_16x16x32_bf16 v[80:83], v[206:209], v[182:185], v[80:83]
	v_mfma_f32_16x16x32_bf16 v[68:71], v[198:201], v[190:193], v[68:71]
	v_mfma_f32_16x16x32_bf16 v[64:67], v[206:209], v[190:193], v[64:67]
	v_mfma_f32_16x16x32_bf16 v[116:119], v[202:205], v[164:167], v[116:119]
	v_mfma_f32_16x16x32_bf16 v[112:115], v[210:213], v[164:167], v[112:115]
	v_mfma_f32_16x16x32_bf16 v[100:103], v[202:205], v[172:175], v[100:103]
	v_mfma_f32_16x16x32_bf16 v[96:99], v[210:213], v[172:175], v[96:99]
	v_mfma_f32_16x16x32_bf16 v[84:87], v[202:205], v[186:189], v[84:87]
	v_mfma_f32_16x16x32_bf16 v[80:83], v[210:213], v[186:189], v[80:83]
	v_mfma_f32_16x16x32_bf16 v[68:71], v[202:205], v[194:197], v[68:71]
	v_mfma_f32_16x16x32_bf16 v[64:67], v[210:213], v[194:197], v[64:67]
	s_mov_b32 m0, s55
	s_barrier
	ds_read_b128 v[160:163], v180 offset:49152
	ds_read_b128 v[164:167], v180 offset:50176
	ds_read_b128 v[168:171], v180 offset:51200
	ds_read_b128 v[172:175], v180 offset:52224
	ds_read_b128 v[182:185], v180 offset:53248
	ds_read_b128 v[186:189], v180 offset:54272
	ds_read_b128 v[190:193], v180 offset:55296
	ds_read_b128 v[194:197], v180 offset:56320
	global_load_lds_dwordx4 v144, s[100:101]
	s_mov_b32 m0, s56
	s_nop 0
	global_load_lds_dwordx4 v148, s[100:101]
	s_waitcnt vmcnt(10)
	s_barrier
	s_waitcnt lgkmcnt(0)
	s_waitcnt lgkmcnt(0)
	v_mfma_f32_16x16x32_bf16 v[60:63], v[128:131], v[160:163], v[60:63]
	v_mfma_f32_16x16x32_bf16 v[56:59], v[136:139], v[160:163], v[56:59]
	v_mfma_f32_16x16x32_bf16 v[44:47], v[128:131], v[168:171], v[44:47]
	v_mfma_f32_16x16x32_bf16 v[40:43], v[136:139], v[168:171], v[40:43]
	v_mfma_f32_16x16x32_bf16 v[28:31], v[128:131], v[182:185], v[28:31]
	v_mfma_f32_16x16x32_bf16 v[24:27], v[136:139], v[182:185], v[24:27]
	v_mfma_f32_16x16x32_bf16 v[12:15], v[128:131], v[190:193], v[12:15]
	v_mfma_f32_16x16x32_bf16 v[8:11], v[136:139], v[190:193], v[8:11]
	v_mfma_f32_16x16x32_bf16 v[60:63], v[132:135], v[164:167], v[60:63]
	v_mfma_f32_16x16x32_bf16 v[56:59], v[140:143], v[164:167], v[56:59]
	v_mfma_f32_16x16x32_bf16 v[44:47], v[132:135], v[172:175], v[44:47]
	v_mfma_f32_16x16x32_bf16 v[40:43], v[140:143], v[172:175], v[40:43]
	v_mfma_f32_16x16x32_bf16 v[28:31], v[132:135], v[186:189], v[28:31]
	v_mfma_f32_16x16x32_bf16 v[24:27], v[140:143], v[186:189], v[24:27]
	v_mfma_f32_16x16x32_bf16 v[12:15], v[132:135], v[194:197], v[12:15]
	v_mfma_f32_16x16x32_bf16 v[8:11], v[140:143], v[194:197], v[8:11]
	s_barrier
	s_add_u32 s48, s48, 0x80080
	s_addc_u32 s49, s49, 0
	s_add_i32 s50, s50, s25
	s_mov_b32 m0, s50
	s_nop 0
	global_load_lds_dwordx4 v146, s[48:49]
	s_add_i32 m0, s50, 0x2000
	s_nop 0
	global_load_lds_dwordx4 v150, s[48:49]
	ds_read_b128 v[128:131], v179
	ds_read_b128 v[132:135], v179 offset:1024
	ds_read_b128 v[136:139], v179 offset:2048
	ds_read_b128 v[140:143], v179 offset:3072
	s_waitcnt vmcnt(6)
	s_branch .LBB0_1581
;     __device__ __forceinline__ void operator()(const f32x4 (&acc)[2][2][4][2], const Unit& u, int wr, int wc, int fr, int fq) const {
;         const int row0 = u.pm * BM + wr * 64 + fr, col0 = u.pn * BM + wc * 32 + 8 * fq;
;         constexpr int RD = 3;
;         f32x4 hbuf[RD][4]; u32x4 hraw[RD][2]; u32x4 pbuf[RD][2]; float rsb[RD];
;     ...
;         RES_LOAD(0, 0); RES_LOAD(1, 1);
; #pragma unroll
;         for (int it = 0; it < 8; ++it) { const int ai = it >> 2, m = it & 3, sc = it % RD;
;             if (it + RD - 1 < 8) RES_LOAD((it + RD - 1) % RD, it + RD - 1);
;             asm volatile("" ::: "memory");
;             const int row = row0 + ai * HALF + m * 16; const size_t ro = (size_t)row * DM + col0;
;             float rs = 1.0f; if (MODE == 1) rs = __builtin_amdgcn_rsqf(ss_fix(rsb[sc]) * (1.0f / DM) + EPS);
;             float sq = 0.f;
; #pragma unroll
;             for (int bj = 0; bj < 2; ++bj) { const size_t off = ro + bj * HALF;
;                 f32x4 v0 = acc[ai][bj][m][0], v1 = acc[ai][bj][m][1];
;                 if (MODE == 1) { const u32x4 pw = pbuf[sc][bj];
;                     v0[0] = fast_sigmoid(rs * v0[0]) * bf_lo(pw.x); v0[1] = fast_sigmoid(rs * v0[1]) * bf_hi(pw.x); v0[2] = fast_sigmoid(rs * v0[2]) * bf_lo(pw.y); v0[3] = fast_sigmoid(rs * v0[3]) * bf_hi(pw.y);
;                     v1[0] = fast_sigmoid(rs * v1[0]) * bf_lo(pw.z); v1[1] = fast_sigmoid(rs * v1[1]) * bf_hi(pw.z); v1[2] = fast_sigmoid(rs * v1[2]) * bf_lo(pw.w); v1[3] = fast_sigmoid(rs * v1[3]) * bf_hi(pw.w); }
;                 f32x4 h0, h1;
;                 if (IN16) { const u32x4 hw = hraw[sc][bj]; h0 = (f32x4){bf_lo(hw.x), bf_hi(hw.x), bf_lo(hw.y), bf_hi(hw.y)}; h1 = (f32x4){bf_lo(hw.z), bf_hi(hw.z), bf_lo(hw.w), bf_hi(hw.w)}; }
;                 else { h0 = hbuf[sc][2 * bj]; h1 = hbuf[sc][2 * bj + 1]; }
;                 const f32x4 o0 = h0 + v0, o1 = h1 + v1;
;                 if (OUT32) { *(f32x4*)(hout + off) = o0; *(f32x4*)(hout + off + 4) = o1; }
;                 if (hb) { u32x4 w; w.x = pk_bf16(o0[0], o0[1]); w.y = pk_bf16(o0[2], o0[3]); w.z = pk_bf16(o1[0], o1[1]); w.w = pk_bf16(o1[2], o1[3]); *(u32x4*)(hb + off) = w; }
;                 sq += ((o0[0] * o0[0] + o0[1] * o0[1]) + (o0[2] * o0[2] + o0[3] * o0[3])) + ((o1[0] * o1[0] + o1[1] * o1[1]) + (o1[2] * o1[2] + o1[3] * o1[3])); }
.Lrot_out_1581:
	v_lshl_add_u32 v170, s42, 8, v176
	v_lshl_or_b32 v160, s44, 8, v178
	v_ashrrev_i32_e32 v171, 31, v170
	v_ashrrev_i32_e32 v161, 31, v160
	v_lshlrev_b64 v[190:191], 12, v[170:171]
	v_lshl_add_u64 v[128:129], s[10:11], 0, v[190:191]
	v_lshlrev_b64 v[162:163], 1, v[160:161]
	v_lshl_add_u64 v[164:165], v[128:129], 0, v[162:163]
	global_load_dwordx4 v[182:185], v[164:165], off
	global_load_dwordx4 v[186:189], v[164:165], off offset:256
	v_or_b32_e32 v172, 16, v170
	v_or_b32_e32 v166, 32, v170
	v_ashrrev_i32_e32 v173, 31, v172
	v_ashrrev_i32_e32 v167, 31, v166
	v_lshlrev_b64 v[174:175], 12, v[172:173]
	v_lshlrev_b64 v[168:169], 12, v[166:167]
	v_lshl_add_u64 v[128:129], s[10:11], 0, v[174:175]
	v_lshl_add_u64 v[130:131], s[10:11], 0, v[168:169]
	v_lshl_add_u64 v[128:129], v[128:129], 0, v[162:163]
	v_lshl_add_u64 v[130:131], v[130:131], 0, v[162:163]
	global_load_dwordx4 v[140:143], v[128:129], off
	global_load_dwordx4 v[136:139], v[128:129], off offset:256
	global_load_dwordx4 v[132:135], v[130:131], off
	s_nop 0
	global_load_dwordx4 v[128:131], v[130:131], off offset:256
	s_waitcnt vmcnt(0)
	v_lshlrev_b32_e32 v192, 16, v182
	v_and_b32_e32 v193, 0xffff0000, v182
	v_lshlrev_b32_e32 v182, 16, v183
	v_and_b32_e32 v183, 0xffff0000, v183
	v_lshlrev_b32_e32 v194, 16, v184
	v_and_b32_e32 v195, 0xffff0000, v184
	v_lshlrev_b32_e32 v184, 16, v185
	v_and_b32_e32 v185, 0xffff0000, v185
	v_lshlrev_b32_e32 v196, 16, v186
	v_and_b32_e32 v197, 0xffff0000, v186
	v_lshlrev_b32_e32 v186, 16, v187
	v_and_b32_e32 v187, 0xffff0000, v187
	v_lshlrev_b32_e32 v198, 16, v188
	v_and_b32_e32 v199, 0xffff0000, v188
	v_lshlrev_b32_e32 v188, 16, v189
	v_and_b32_e32 v189, 0xffff0000, v189
	v_pk_add_f32 v[126:127], v[126:127], v[182:183]
	v_pk_add_f32 v[124:125], v[124:125], v[192:193]
	v_pk_add_f32 v[122:123], v[122:123], v[184:185]
	v_pk_add_f32 v[120:121], v[120:121], v[194:195]
	v_pk_add_f32 v[118:119], v[118:119], v[186:187]
	v_pk_add_f32 v[116:117], v[116:117], v[196:197]
	v_pk_add_f32 v[182:183], v[114:115], v[188:189]
	v_pk_add_f32 v[184:185], v[112:113], v[198:199]
	v_cvt_pk_bf16_f32 v112, v124, v125
	v_cvt_pk_bf16_f32 v113, v126, v127
	v_cvt_pk_bf16_f32 v114, v120, v121
	v_cvt_pk_bf16_f32 v115, v122, v123
	v_mul_f32_e32 v125, v125, v125
	v_mul_f32_e32 v127, v127, v127
	v_mul_f32_e32 v121, v121, v121
	v_mul_f32_e32 v123, v123, v123
	v_mul_f32_e32 v186, v117, v117
	v_mul_f32_e32 v187, v119, v119
	v_mul_f32_e32 v188, v185, v185
	v_mul_f32_e32 v189, v183, v183
	v_fmac_f32_e32 v125, v124, v124
	v_fmac_f32_e32 v127, v126, v126
	v_fmac_f32_e32 v121, v120, v120
	v_fmac_f32_e32 v123, v122, v122
	v_fmac_f32_e32 v186, v116, v116
	v_fmac_f32_e32 v187, v118, v118
	v_fmac_f32_e32 v188, v184, v184
	v_fmac_f32_e32 v189, v182, v182
	v_add_f32_e32 v120, v125, v127
	v_add_f32_e32 v121, v121, v123
	v_add_f32_e32 v122, v186, v187
	v_add_f32_e32 v123, v188, v189
	v_add_f32_e32 v120, v120, v121
	v_add_f32_e32 v121, v122, v123
	v_add_f32_e32 v122, v120, v121
	ds_bpermute_b32 v123, v245, v122
	v_lshl_add_u64 v[120:121], s[12:13], 0, v[190:191]
	v_lshl_add_u64 v[120:121], v[120:121], 0, v[162:163]
	global_store_dwordx4 v[120:121], v[112:115], off
	s_waitcnt lgkmcnt(0)
	s_nop 0
	v_add_f32_e32 v112, v122, v123
	ds_bpermute_b32 v113, v244, v112
	v_cvt_pk_bf16_f32 v114, v116, v117
	v_cvt_pk_bf16_f32 v115, v118, v119
	v_cvt_pk_bf16_f32 v116, v184, v185
	v_cvt_pk_bf16_f32 v117, v182, v183
	global_store_dwordx4 v[120:121], v[114:117], off offset:256
	s_and_saveexec_b64 s[42:43], s[6:7]
	s_cbranch_execz .LBB0_1584
	s_waitcnt lgkmcnt(0)
	v_add_f32_e32 v112, v112, v113
	v_fma_f32 v112, v112, s59, 0.5
	v_cvt_u32_f32_e32 v114, v112
	v_lshl_add_u64 v[112:113], v[170:171], 2, s[14:15]
	global_atomic_add v[112:113], v114, off

; #define PG8_BAR __builtin_amdgcn_s_barrier()
; template <class Epi>
; __device__ __forceinline__ void gemm_phase(LAS unsigned char* lds, const Gemm g, const StaticOrder& S, const Epi& E, int wv) {
;     ...
;         const bool has_next = S.next(ui + 1, nxt);
;         const char* nA = has_next ? (const char*)g.A + (size_t)nxt.pm * tstepA + ((g.adiag & 1) ? (size_t)(nxt.pn >> 1) * K * 2 : 0) + kbeg : cA;
;         const char* nB = has_next ? (const char*)g.Bt + (size_t)nxt.pn * tstepB + kbeg : cB;
;         for (int t = 0; t < nt; t += 2) {
;             const bool last = (t == nt - 2);
;             const char* a1 = cA + (ptrdiff_t)(t + 1) * kstep;
;             const char* a2 = last ? nA : cA + (ptrdiff_t)(t + 2) * kstep; const char* b2 = last ? nB : cB + (ptrdiff_t)(t + 2) * kstep;
;             const char* a3 = a2 + kstep; const char* b3 = b2 + kstep;
;             PG8_LDB(B0, 0, 0); PG8_SCHED; PG8_LDA(At, 0, 0); PG8_STAGE(PG8_SA(1, 1), a1 + hstepA, voffA);
;             PG8_WAIT_L(8); PG8_BAR; PG8_WAIT_L(0); PG8_MMA(0, 0, At, B0); PG8_BAR; PG8_SCHED;
;             PG8_LDB(B1, 0, 1); PG8_STAGE(PG8_SB(0, 0), b2, voffB);
;             PG8_BAR; PG8_WAIT_L(0); PG8_MMA(0, 1, At, B1); PG8_BAR;
;             PG8_LDA(At, 0, 1); PG8_STAGE(PG8_SA(0, 0), a2, voffA);
;             PG8_BAR; PG8_WAIT_L(0); PG8_MMA(1, 0, At, B0); PG8_BAR; PG8_SCHED;
;             PG8_STAGE(PG8_SB(0, 1), b2 + hstepB, voffB);
;             PG8_WAIT_V(6); PG8_BAR; PG8_MMA(1, 1, At, B1); PG8_BAR;
;             PG8_LDB(B0, 1, 0); PG8_SCHED; PG8_LDA(At, 1, 0); PG8_STAGE(PG8_SA(0, 1), a2 + hstepA, voffA);
;             PG8_WAIT_L(8); PG8_BAR; PG8_WAIT_L(0); PG8_MMA(0, 0, At, B0); PG8_BAR; PG8_SCHED;
;             PG8_LDB(B1, 1, 1); PG8_STAGE(PG8_SB(1, 0), b3, voffB);
;             PG8_BAR; PG8_WAIT_L(0); PG8_MMA(0, 1, At, B1); PG8_BAR;
;             PG8_LDA(At, 1, 1); PG8_STAGE(PG8_SA(1, 0), a3, voffA);
;             PG8_BAR; PG8_WAIT_L(0); PG8_MMA(1, 0, At, B0); PG8_BAR; PG8_SCHED;
;             PG8_STAGE(PG8_SB(1, 1), b3 + hstepB, voffB);
;             PG8_WAIT_V(6); PG8_BAR; PG8_MMA(1, 1, At, B1); PG8_BAR;
;         }
;         E(acc, cur, wr, wc, fr, fq);
;         if (!has_next) break;
; #pragma unroll
;         for (int a = 0; a < 2; ++a)
; #pragma unroll
;             for (int b = 0; b < 2; ++b)
; #pragma unroll
;                 for (int m = 0; m < 4; ++m)
; #pragma unroll
.LBB0_1667:
	s_ashr_i32 s37, s36, 31
	v_cmp_lt_i64_e32 vcc, s[38:39], v[140:141]
	s_lshl_b64 s[38:39], s[36:37], 20
	s_add_u32 s38, s5, s38
	s_addc_u32 s39, s22, s39
	s_and_b64 s[40:41], vcc, exec
	s_cselect_b32 s37, s39, s47
	s_cselect_b32 s62, s38, s46
	s_ashr_i32 s35, s34, 31
	s_lshl_b64 s[40:41], s[34:35], 20
	s_add_u32 s40, s23, s40
	s_addc_u32 s41, s24, s41
	s_and_b64 s[48:49], vcc, exec
	s_cselect_b32 s35, s41, s45
	s_cselect_b32 s63, s40, s44
	s_add_u32 s64, s44, 0x100
	s_addc_u32 s65, s45, 0
	s_add_u32 s44, s46, 0x80080
	v_mov_b32_e32 v0, 0
	s_addc_u32 s45, s47, 0
	s_mov_b32 s66, -2
	v_mov_b32_e32 v1, v0
	v_mov_b32_e32 v2, v0
	v_mov_b32_e32 v3, v0
	v_mov_b32_e32 v4, v0
	v_mov_b32_e32 v5, v0
	v_mov_b32_e32 v6, v0
	v_mov_b32_e32 v7, v0
	v_mov_b32_e32 v16, v0
	v_mov_b32_e32 v17, v0
	v_mov_b32_e32 v18, v0
	v_mov_b32_e32 v19, v0
	v_mov_b32_e32 v20, v0
	v_mov_b32_e32 v21, v0
	v_mov_b32_e32 v22, v0
	v_mov_b32_e32 v23, v0
	v_mov_b32_e32 v32, v0
	v_mov_b32_e32 v33, v0
	v_mov_b32_e32 v34, v0
	v_mov_b32_e32 v35, v0
	v_mov_b32_e32 v36, v0
	v_mov_b32_e32 v37, v0
	v_mov_b32_e32 v38, v0
	v_mov_b32_e32 v39, v0
	v_mov_b32_e32 v48, v0
	v_mov_b32_e32 v49, v0
	v_mov_b32_e32 v50, v0
	v_mov_b32_e32 v51, v0
	v_mov_b32_e32 v52, v0
	v_mov_b32_e32 v53, v0
	v_mov_b32_e32 v54, v0
	v_mov_b32_e32 v55, v0
	v_mov_b32_e32 v8, v0
	v_mov_b32_e32 v9, v0
	v_mov_b32_e32 v10, v0
	v_mov_b32_e32 v11, v0
	v_mov_b32_e32 v12, v0
	v_mov_b32_e32 v13, v0
	v_mov_b32_e32 v14, v0
	v_mov_b32_e32 v15, v0
	v_mov_b32_e32 v24, v0
	v_mov_b32_e32 v25, v0
	v_mov_b32_e32 v26, v0
	v_mov_b32_e32 v27, v0
	v_mov_b32_e32 v28, v0
	v_mov_b32_e32 v29, v0
	v_mov_b32_e32 v30, v0
	v_mov_b32_e32 v31, v0
	v_mov_b32_e32 v40, v0
	v_mov_b32_e32 v41, v0
	v_mov_b32_e32 v42, v0
	v_mov_b32_e32 v43, v0
	v_mov_b32_e32 v44, v0
	v_mov_b32_e32 v45, v0
	v_mov_b32_e32 v46, v0
	v_mov_b32_e32 v47, v0
	v_mov_b32_e32 v56, v0
	v_mov_b32_e32 v57, v0
	v_mov_b32_e32 v58, v0
	v_mov_b32_e32 v59, v0
	v_mov_b32_e32 v60, v0
	v_mov_b32_e32 v61, v0
	v_mov_b32_e32 v62, v0
	v_mov_b32_e32 v63, v0
	v_mov_b32_e32 v64, v0
	v_mov_b32_e32 v65, v0
	v_mov_b32_e32 v66, v0
	v_mov_b32_e32 v67, v0
	v_mov_b32_e32 v68, v0
	v_mov_b32_e32 v69, v0
	v_mov_b32_e32 v70, v0
	v_mov_b32_e32 v71, v0
	v_mov_b32_e32 v80, v0
	v_mov_b32_e32 v81, v0
	v_mov_b32_e32 v82, v0
	v_mov_b32_e32 v83, v0
	v_mov_b32_e32 v84, v0
	v_mov_b32_e32 v85, v0
	v_mov_b32_e32 v86, v0
	v_mov_b32_e32 v87, v0
	v_mov_b32_e32 v96, v0
	v_mov_b32_e32 v97, v0
	v_mov_b32_e32 v98, v0
	v_mov_b32_e32 v99, v0
	v_mov_b32_e32 v100, v0
	v_mov_b32_e32 v101, v0
	v_mov_b32_e32 v102, v0
	v_mov_b32_e32 v103, v0
	v_mov_b32_e32 v104, v0
	v_mov_b32_e32 v105, v0
	v_mov_b32_e32 v106, v0
	v_mov_b32_e32 v107, v0
	v_mov_b32_e32 v108, v0
	v_mov_b32_e32 v109, v0
	v_mov_b32_e32 v110, v0
	v_mov_b32_e32 v111, v0
	v_mov_b32_e32 v72, v0
	v_mov_b32_e32 v73, v0
	v_mov_b32_e32 v74, v0
	v_mov_b32_e32 v75, v0
	v_mov_b32_e32 v76, v0
	v_mov_b32_e32 v77, v0
	v_mov_b32_e32 v78, v0
	v_mov_b32_e32 v79, v0
	v_mov_b32_e32 v88, v0
	v_mov_b32_e32 v89, v0
	v_mov_b32_e32 v90, v0
	v_mov_b32_e32 v91, v0
	v_mov_b32_e32 v92, v0
	v_mov_b32_e32 v93, v0
	v_mov_b32_e32 v94, v0
	v_mov_b32_e32 v95, v0
	v_mov_b32_e32 v112, v0
	v_mov_b32_e32 v113, v0
	v_mov_b32_e32 v114, v0
	v_mov_b32_e32 v115, v0
	v_mov_b32_e32 v116, v0
	v_mov_b32_e32 v117, v0
	v_mov_b32_e32 v118, v0
	v_mov_b32_e32 v119, v0
	v_mov_b32_e32 v120, v0
	v_mov_b32_e32 v121, v0
	v_mov_b32_e32 v122, v0
	v_mov_b32_e32 v123, v0
	v_mov_b32_e32 v124, v0
	v_mov_b32_e32 v125, v0
	v_mov_b32_e32 v126, v0
	v_mov_b32_e32 v127, v0
	ds_read_b128 v[144:147], v153
	ds_read_b128 v[158:161], v153 offset:1024
	ds_read_b128 v[162:165], v153 offset:2048
	ds_read_b128 v[166:169], v153 offset:3072
	s_branch .Lrot_in_1668
.LBB0_1668:
	s_barrier
	v_mfma_f32_16x16x32_bf16 v[52:55], v[202:205], v[170:173], v[52:55]
	v_mfma_f32_16x16x32_bf16 v[48:51], v[210:213], v[170:173], v[48:51]
	v_mfma_f32_16x16x32_bf16 v[36:39], v[202:205], v[178:181], v[36:39]
	v_mfma_f32_16x16x32_bf16 v[32:35], v[210:213], v[178:181], v[32:35]
	v_mfma_f32_16x16x32_bf16 v[20:23], v[202:205], v[186:189], v[20:23]
	v_mfma_f32_16x16x32_bf16 v[16:19], v[210:213], v[186:189], v[16:19]
	v_mfma_f32_16x16x32_bf16 v[4:7], v[202:205], v[194:197], v[4:7]
	v_mfma_f32_16x16x32_bf16 v[0:3], v[210:213], v[194:197], v[0:3]
	v_mfma_f32_16x16x32_bf16 v[52:55], v[206:209], v[174:177], v[52:55]
	v_mfma_f32_16x16x32_bf16 v[48:51], v[214:217], v[174:177], v[48:51]
	v_mfma_f32_16x16x32_bf16 v[36:39], v[206:209], v[182:185], v[36:39]
	v_mfma_f32_16x16x32_bf16 v[32:35], v[214:217], v[182:185], v[32:35]
	v_mfma_f32_16x16x32_bf16 v[20:23], v[206:209], v[190:193], v[20:23]
	v_mfma_f32_16x16x32_bf16 v[16:19], v[214:217], v[190:193], v[16:19]
	v_mfma_f32_16x16x32_bf16 v[4:7], v[206:209], v[198:201], v[4:7]
	v_mfma_f32_16x16x32_bf16 v[0:3], v[214:217], v[198:201], v[0:3]
	s_waitcnt lgkmcnt(0)
	s_add_i32 s66, s66, 2
	s_add_u32 s64, s64, 0x100
	s_addc_u32 s65, s65, 0
	s_add_u32 s44, s44, 0x100
	s_addc_u32 s45, s45, 0
	s_cmp_gt_u32 s66, 29
	s_barrier
	s_cbranch_scc1 .Lrot_out_1668
; #define PG8_STAGE(bufoff, gbase, voff) do { _Pragma("unroll") for (int _i = 0; _i < 2; ++_i) \
;         __builtin_amdgcn_global_load_lds((const unsigned*)((const char*)(gbase) + (voff)[_i]), (LAS unsigned*)(lds + (bufoff) + ldsw + _i * 8192), 16, 0, 0); } while (0)
; #define PG8_LDA(dst, b, h) do { _Pragma("unroll") for (int m = 0; m < 4; ++m) _Pragma("unroll") for (int k = 0; k < 2; ++k) dst[m][k] = *(const LAS bf16x8*)(lds + PG8_SA(b, h) + aoff + m * 2048 + k * 1024); } while (0)
; #define PG8_LDB(dst, b, h) do { _Pragma("unroll") for (int n = 0; n < 2; ++n) _Pragma("unroll") for (int k = 0; k < 2; ++k) dst[n][k] = *(const LAS bf16x8*)(lds + PG8_SB(b, h) + boff + n * 2048 + k * 1024); } while (0)
; #define PG8_MMA(ai, bj, At, Bt) do { __builtin_amdgcn_s_setprio(1); _Pragma("unroll") for (int m = 0; m < 4; ++m) _Pragma("unroll") for (int n = 0; n < 2; ++n) _Pragma("unroll") for (int k = 0; k < 2; ++k) \
;         acc[ai][bj][m][n] = __builtin_amdgcn_mfma_f32_16x16x32_bf16(Bt[n][k], At[m][k], acc[ai][bj][m][n], 0, 0, 0); __builtin_amdgcn_s_setprio(0); } while (0)
; #define PG8_WAIT_V(n) asm volatile("s_waitcnt vmcnt(" #n ")" ::: "memory")
; #define PG8_WAIT_L(n) asm volatile("s_waitcnt lgkmcnt(" #n ")" ::: "memory")
; template <class Epi>
; __device__ __forceinline__ void gemm_phase(LAS unsigned char* lds, const Gemm g, const StaticOrder& S, const Epi& E, int wv) {
;     ...
;         for (int t = 0; t < nt; t += 2) {
;             const bool last = (t == nt - 2);
;             const char* a1 = cA + (ptrdiff_t)(t + 1) * kstep;
;             const char* a2 = last ? nA : cA + (ptrdiff_t)(t + 2) * kstep; const char* b2 = last ? nB : cB + (ptrdiff_t)(t + 2) * kstep;
;             const char* a3 = a2 + kstep; const char* b3 = b2 + kstep;
;             PG8_LDB(B0, 0, 0); PG8_SCHED; PG8_LDA(At, 0, 0); PG8_STAGE(PG8_SA(1, 1), a1 + hstepA, voffA);
;             PG8_WAIT_L(8); PG8_BAR; PG8_WAIT_L(0); PG8_MMA(0, 0, At, B0); PG8_BAR; PG8_SCHED;
;             PG8_LDB(B1, 0, 1); PG8_STAGE(PG8_SB(0, 0), b2, voffB);
;             PG8_BAR; PG8_WAIT_L(0); PG8_MMA(0, 1, At, B1); PG8_BAR;
;             PG8_LDA(At, 0, 1); PG8_STAGE(PG8_SA(0, 0), a2, voffA);
;             PG8_BAR; PG8_WAIT_L(0); PG8_MMA(1, 0, At, B0); PG8_BAR; PG8_SCHED;
;             PG8_STAGE(PG8_SB(0, 1), b2 + hstepB, voffB);
;             PG8_WAIT_V(6); PG8_BAR; PG8_MMA(1, 1, At, B1); PG8_BAR;
.Lrot_in_1668:
	s_add_u32 s46, s44, 0xfff80080
	s_addc_u32 s47, s45, -1
	s_cmp_eq_u32 s66, 28
	s_cselect_b32 s49, s37, s47
	s_cselect_b32 s48, s62, s46
	s_cselect_b32 s47, s35, s65
	s_cselect_b32 s46, s63, s64
	s_add_i32 m0, s33, 0xc000
	ds_read_b128 v[170:173], v154
	ds_read_b128 v[174:177], v154 offset:1024
	ds_read_b128 v[178:181], v154 offset:2048
	ds_read_b128 v[182:185], v154 offset:3072
	ds_read_b128 v[186:189], v154 offset:4096
	ds_read_b128 v[190:193], v154 offset:5120
	ds_read_b128 v[194:197], v154 offset:6144
	ds_read_b128 v[198:201], v154 offset:7168
	global_load_lds_dwordx4 v138, s[44:45]
	s_add_i32 m0, s33, 0xe000
	s_nop 0
	global_load_lds_dwordx4 v136, s[44:45]
	s_waitcnt lgkmcnt(8)
	s_barrier
	s_waitcnt lgkmcnt(0)
	s_waitcnt lgkmcnt(0)
	v_mfma_f32_16x16x32_bf16 v[124:127], v[144:147], v[170:173], v[124:127]
	v_mfma_f32_16x16x32_bf16 v[120:123], v[162:165], v[170:173], v[120:123]
	v_mfma_f32_16x16x32_bf16 v[116:119], v[144:147], v[178:181], v[116:119]
	v_mfma_f32_16x16x32_bf16 v[112:115], v[162:165], v[178:181], v[112:115]
	v_mfma_f32_16x16x32_bf16 v[92:95], v[144:147], v[186:189], v[92:95]
	v_mfma_f32_16x16x32_bf16 v[88:91], v[162:165], v[186:189], v[88:91]
	v_mfma_f32_16x16x32_bf16 v[76:79], v[144:147], v[194:197], v[76:79]
	v_mfma_f32_16x16x32_bf16 v[72:75], v[162:165], v[194:197], v[72:75]
	v_mfma_f32_16x16x32_bf16 v[124:127], v[158:161], v[174:177], v[124:127]
	v_mfma_f32_16x16x32_bf16 v[120:123], v[166:169], v[174:177], v[120:123]
	v_mfma_f32_16x16x32_bf16 v[116:119], v[158:161], v[182:185], v[116:119]
	v_mfma_f32_16x16x32_bf16 v[112:115], v[166:169], v[182:185], v[112:115]
	v_mfma_f32_16x16x32_bf16 v[92:95], v[158:161], v[190:193], v[92:95]
	v_mfma_f32_16x16x32_bf16 v[88:91], v[166:169], v[190:193], v[88:91]
	v_mfma_f32_16x16x32_bf16 v[76:79], v[158:161], v[198:201], v[76:79]
	v_mfma_f32_16x16x32_bf16 v[72:75], v[166:169], v[198:201], v[72:75]
	s_barrier
	s_add_i32 s67, s55, s25
	s_add_u32 s98, s46, s12
	s_addc_u32 s99, s47, s13
	s_mov_b32 m0, s67
	ds_read_b128 v[202:205], v155
	ds_read_b128 v[206:209], v155 offset:1024
	ds_read_b128 v[210:213], v155 offset:2048
	ds_read_b128 v[214:217], v155 offset:3072
	global_load_lds_dwordx4 v130, s[46:47]
	s_add_i32 m0, s67, 0x2000
	s_nop 0
	global_load_lds_dwordx4 v134, s[46:47]
	s_barrier
	s_waitcnt lgkmcnt(0)
	s_waitcnt lgkmcnt(0)
	v_mfma_f32_16x16x32_bf16 v[108:111], v[202:205], v[170:173], v[108:111]
	v_mfma_f32_16x16x32_bf16 v[104:107], v[210:213], v[170:173], v[104:107]
	v_mfma_f32_16x16x32_bf16 v[100:103], v[202:205], v[178:181], v[100:103]
	v_mfma_f32_16x16x32_bf16 v[96:99], v[210:213], v[178:181], v[96:99]
	v_mfma_f32_16x16x32_bf16 v[84:87], v[202:205], v[186:189], v[84:87]
	v_mfma_f32_16x16x32_bf16 v[80:83], v[210:213], v[186:189], v[80:83]
	v_mfma_f32_16x16x32_bf16 v[68:71], v[202:205], v[194:197], v[68:71]
	v_mfma_f32_16x16x32_bf16 v[64:67], v[210:213], v[194:197], v[64:67]
	v_mfma_f32_16x16x32_bf16 v[108:111], v[206:209], v[174:177], v[108:111]
	v_mfma_f32_16x16x32_bf16 v[104:107], v[214:217], v[174:177], v[104:107]
	v_mfma_f32_16x16x32_bf16 v[100:103], v[206:209], v[182:185], v[100:103]
	v_mfma_f32_16x16x32_bf16 v[96:99], v[214:217], v[182:185], v[96:99]
	v_mfma_f32_16x16x32_bf16 v[84:87], v[206:209], v[190:193], v[84:87]
	v_mfma_f32_16x16x32_bf16 v[80:83], v[214:217], v[190:193], v[80:83]
	v_mfma_f32_16x16x32_bf16 v[68:71], v[206:209], v[198:201], v[68:71]
	v_mfma_f32_16x16x32_bf16 v[64:67], v[214:217], v[198:201], v[64:67]
	s_mov_b32 m0, s33
	s_add_u32 s100, s48, s12
	s_addc_u32 s101, s49, s13
	s_barrier
	ds_read_b128 v[170:173], v154 offset:16384
	ds_read_b128 v[174:177], v154 offset:17408
	ds_read_b128 v[178:181], v154 offset:18432
	ds_read_b128 v[182:185], v154 offset:19456
	ds_read_b128 v[186:189], v154 offset:20480
	ds_read_b128 v[190:193], v154 offset:21504
	ds_read_b128 v[194:197], v154 offset:22528
	ds_read_b128 v[198:201], v154 offset:23552
	global_load_lds_dwordx4 v128, s[48:49]
	s_mov_b32 m0, s43
	s_nop 0
	global_load_lds_dwordx4 v132, s[48:49]
	s_waitcnt vmcnt(10)
	s_barrier
	s_waitcnt lgkmcnt(0)
	s_waitcnt lgkmcnt(0)
	v_mfma_f32_16x16x32_bf16 v[60:63], v[144:147], v[170:173], v[60:63]
	v_mfma_f32_16x16x32_bf16 v[56:59], v[162:165], v[170:173], v[56:59]
	v_mfma_f32_16x16x32_bf16 v[44:47], v[144:147], v[178:181], v[44:47]
	v_mfma_f32_16x16x32_bf16 v[40:43], v[162:165], v[178:181], v[40:43]
	v_mfma_f32_16x16x32_bf16 v[28:31], v[144:147], v[186:189], v[28:31]
	v_mfma_f32_16x16x32_bf16 v[24:27], v[162:165], v[186:189], v[24:27]
	v_mfma_f32_16x16x32_bf16 v[12:15], v[144:147], v[194:197], v[12:15]
	v_mfma_f32_16x16x32_bf16 v[8:11], v[162:165], v[194:197], v[8:11]
	v_mfma_f32_16x16x32_bf16 v[60:63], v[158:161], v[174:177], v[60:63]
	v_mfma_f32_16x16x32_bf16 v[56:59], v[166:169], v[174:177], v[56:59]
	v_mfma_f32_16x16x32_bf16 v[44:47], v[158:161], v[182:185], v[44:47]
	v_mfma_f32_16x16x32_bf16 v[40:43], v[166:169], v[182:185], v[40:43]
	v_mfma_f32_16x16x32_bf16 v[28:31], v[158:161], v[190:193], v[28:31]
	v_mfma_f32_16x16x32_bf16 v[24:27], v[166:169], v[190:193], v[24:27]
	v_mfma_f32_16x16x32_bf16 v[12:15], v[158:161], v[198:201], v[12:15]
	v_mfma_f32_16x16x32_bf16 v[8:11], v[166:169], v[198:201], v[8:11]
	s_barrier
	s_add_u32 s68, s46, 0x80000
	s_addc_u32 s69, s47, 0
	s_add_i32 s67, s56, s25
	s_mov_b32 m0, s67
	s_nop 0
	global_load_lds_dwordx4 v130, s[68:69]
	s_add_i32 m0, s67, 0x2000
	s_nop 0
	global_load_lds_dwordx4 v134, s[68:69]
	s_add_i32 s67, 0, 0x18000
	v_add_u32_e32 v157, s67, v151
	ds_read_b128 v[144:147], v157
	ds_read_b128 v[158:161], v157 offset:1024
	ds_read_b128 v[162:165], v157 offset:2048
	ds_read_b128 v[166:169], v157 offset:3072
	s_waitcnt vmcnt(6)
	s_barrier
; #define PG8_STAGE(bufoff, gbase, voff) do { _Pragma("unroll") for (int _i = 0; _i < 2; ++_i) \
;         __builtin_amdgcn_global_load_lds((const unsigned*)((const char*)(gbase) + (voff)[_i]), (LAS unsigned*)(lds + (bufoff) + ldsw + _i * 8192), 16, 0, 0); } while (0)
; #define PG8_LDA(dst, b, h) do { _Pragma("unroll") for (int m = 0; m < 4; ++m) _Pragma("unroll") for (int k = 0; k < 2; ++k) dst[m][k] = *(const LAS bf16x8*)(lds + PG8_SA(b, h) + aoff + m * 2048 + k * 1024); } while (0)
; #define PG8_LDB(dst, b, h) do { _Pragma("unroll") for (int n = 0; n < 2; ++n) _Pragma("unroll") for (int k = 0; k < 2; ++k) dst[n][k] = *(const LAS bf16x8*)(lds + PG8_SB(b, h) + boff + n * 2048 + k * 1024); } while (0)
; #define PG8_MMA(ai, bj, At, Bt) do { __builtin_amdgcn_s_setprio(1); _Pragma("unroll") for (int m = 0; m < 4; ++m) _Pragma("unroll") for (int n = 0; n < 2; ++n) _Pragma("unroll") for (int k = 0; k < 2; ++k) \
;         acc[ai][bj][m][n] = __builtin_amdgcn_mfma_f32_16x16x32_bf16(Bt[n][k], At[m][k], acc[ai][bj][m][n], 0, 0, 0); __builtin_amdgcn_s_setprio(0); } while (0)
; #define PG8_WAIT_V(n) asm volatile("s_waitcnt vmcnt(" #n ")" ::: "memory")
; #define PG8_WAIT_L(n) asm volatile("s_waitcnt lgkmcnt(" #n ")" ::: "memory")
; #define PG8_BAR __builtin_amdgcn_s_barrier()
; #define PG8_SCHED __builtin_amdgcn_sched_barrier(0)
; template <class Epi>
; __device__ __forceinline__ void gemm_phase(LAS unsigned char* lds, const Gemm g, const StaticOrder& S, const Epi& E, int wv) {
;     ...
;             PG8_WAIT_V(6); PG8_BAR; PG8_MMA(1, 1, At, B1); PG8_BAR;
;             PG8_LDB(B0, 1, 0); PG8_SCHED; PG8_LDA(At, 1, 0); PG8_STAGE(PG8_SA(0, 1), a2 + hstepA, voffA);
;             PG8_WAIT_L(8); PG8_BAR; PG8_WAIT_L(0); PG8_MMA(0, 0, At, B0); PG8_BAR; PG8_SCHED;
;             PG8_LDB(B1, 1, 1); PG8_STAGE(PG8_SB(1, 0), b3, voffB);
;             PG8_BAR; PG8_WAIT_L(0); PG8_MMA(0, 1, At, B1); PG8_BAR;
;             PG8_LDA(At, 1, 1); PG8_STAGE(PG8_SA(1, 0), a3, voffA);
;             PG8_BAR; PG8_WAIT_L(0); PG8_MMA(1, 0, At, B0); PG8_BAR; PG8_SCHED;
;             PG8_STAGE(PG8_SB(1, 1), b3 + hstepB, voffB);
;             PG8_WAIT_V(6); PG8_BAR; PG8_MMA(1, 1, At, B1); PG8_BAR;
	v_mfma_f32_16x16x32_bf16 v[52:55], v[202:205], v[170:173], v[52:55]
	v_mfma_f32_16x16x32_bf16 v[48:51], v[210:213], v[170:173], v[48:51]
	v_mfma_f32_16x16x32_bf16 v[36:39], v[202:205], v[178:181], v[36:39]
	v_mfma_f32_16x16x32_bf16 v[32:35], v[210:213], v[178:181], v[32:35]
	v_mfma_f32_16x16x32_bf16 v[20:23], v[202:205], v[186:189], v[20:23]
	v_mfma_f32_16x16x32_bf16 v[16:19], v[210:213], v[186:189], v[16:19]
	v_mfma_f32_16x16x32_bf16 v[4:7], v[202:205], v[194:197], v[4:7]
	v_mfma_f32_16x16x32_bf16 v[0:3], v[210:213], v[194:197], v[0:3]
	v_mfma_f32_16x16x32_bf16 v[52:55], v[206:209], v[174:177], v[52:55]
	v_mfma_f32_16x16x32_bf16 v[48:51], v[214:217], v[174:177], v[48:51]
	v_mfma_f32_16x16x32_bf16 v[36:39], v[206:209], v[182:185], v[36:39]
	v_mfma_f32_16x16x32_bf16 v[32:35], v[214:217], v[182:185], v[32:35]
	v_mfma_f32_16x16x32_bf16 v[20:23], v[206:209], v[190:193], v[20:23]
	v_mfma_f32_16x16x32_bf16 v[16:19], v[214:217], v[190:193], v[16:19]
	v_mfma_f32_16x16x32_bf16 v[4:7], v[206:209], v[198:201], v[4:7]
	v_mfma_f32_16x16x32_bf16 v[0:3], v[214:217], v[198:201], v[0:3]
	s_waitcnt lgkmcnt(0)
	s_barrier
	s_add_u32 s48, s48, 0x80000
	s_addc_u32 s49, s49, 0
	s_mov_b32 m0, s50
	ds_read_b128 v[170:173], v154 offset:32768
	ds_read_b128 v[174:177], v154 offset:33792
	ds_read_b128 v[178:181], v154 offset:34816
	ds_read_b128 v[182:185], v154 offset:35840
	ds_read_b128 v[186:189], v154 offset:36864
	ds_read_b128 v[190:193], v154 offset:37888
	ds_read_b128 v[194:197], v154 offset:38912
	ds_read_b128 v[198:201], v154 offset:39936
	global_load_lds_dwordx4 v128, s[48:49]
	s_mov_b32 m0, s51
	s_nop 0
	global_load_lds_dwordx4 v132, s[48:49]
	s_waitcnt lgkmcnt(8)
	s_barrier
	s_waitcnt lgkmcnt(0)
	s_waitcnt lgkmcnt(0)
	v_mfma_f32_16x16x32_bf16 v[124:127], v[144:147], v[170:173], v[124:127]
	v_mfma_f32_16x16x32_bf16 v[120:123], v[162:165], v[170:173], v[120:123]
	v_mfma_f32_16x16x32_bf16 v[116:119], v[144:147], v[178:181], v[116:119]
	v_mfma_f32_16x16x32_bf16 v[112:115], v[162:165], v[178:181], v[112:115]
	v_mfma_f32_16x16x32_bf16 v[92:95], v[144:147], v[186:189], v[92:95]
	v_mfma_f32_16x16x32_bf16 v[88:91], v[162:165], v[186:189], v[88:91]
	v_mfma_f32_16x16x32_bf16 v[76:79], v[144:147], v[194:197], v[76:79]
	v_mfma_f32_16x16x32_bf16 v[72:75], v[162:165], v[194:197], v[72:75]
	v_mfma_f32_16x16x32_bf16 v[124:127], v[158:161], v[174:177], v[124:127]
	v_mfma_f32_16x16x32_bf16 v[120:123], v[166:169], v[174:177], v[120:123]
	v_mfma_f32_16x16x32_bf16 v[116:119], v[158:161], v[182:185], v[116:119]
	v_mfma_f32_16x16x32_bf16 v[112:115], v[166:169], v[182:185], v[112:115]
	v_mfma_f32_16x16x32_bf16 v[92:95], v[158:161], v[190:193], v[92:95]
	v_mfma_f32_16x16x32_bf16 v[88:91], v[166:169], v[190:193], v[88:91]
	v_mfma_f32_16x16x32_bf16 v[76:79], v[158:161], v[198:201], v[76:79]
	v_mfma_f32_16x16x32_bf16 v[72:75], v[166:169], v[198:201], v[72:75]
	s_barrier
	s_add_i32 s48, 0, 0x1c000
	s_add_i32 s49, s67, s25
	v_add_u32_e32 v157, s48, v151
	s_mov_b32 m0, s49
	ds_read_b128 v[202:205], v157
	ds_read_b128 v[206:209], v157 offset:1024
	ds_read_b128 v[210:213], v157 offset:2048
	ds_read_b128 v[214:217], v157 offset:3072
	global_load_lds_dwordx4 v130, s[98:99]
	s_add_i32 m0, s49, 0x2000
	s_nop 0
	global_load_lds_dwordx4 v134, s[98:99]
	s_barrier
	s_waitcnt lgkmcnt(0)
	s_waitcnt lgkmcnt(0)
	v_mfma_f32_16x16x32_bf16 v[108:111], v[202:205], v[170:173], v[108:111]
	v_mfma_f32_16x16x32_bf16 v[104:107], v[210:213], v[170:173], v[104:107]
	v_mfma_f32_16x16x32_bf16 v[100:103], v[202:205], v[178:181], v[100:103]
	v_mfma_f32_16x16x32_bf16 v[96:99], v[210:213], v[178:181], v[96:99]
	v_mfma_f32_16x16x32_bf16 v[84:87], v[202:205], v[186:189], v[84:87]
	v_mfma_f32_16x16x32_bf16 v[80:83], v[210:213], v[186:189], v[80:83]
	v_mfma_f32_16x16x32_bf16 v[68:71], v[202:205], v[194:197], v[68:71]
	v_mfma_f32_16x16x32_bf16 v[64:67], v[210:213], v[194:197], v[64:67]
	v_mfma_f32_16x16x32_bf16 v[108:111], v[206:209], v[174:177], v[108:111]
	v_mfma_f32_16x16x32_bf16 v[104:107], v[214:217], v[174:177], v[104:107]
	v_mfma_f32_16x16x32_bf16 v[100:103], v[206:209], v[182:185], v[100:103]
	v_mfma_f32_16x16x32_bf16 v[96:99], v[214:217], v[182:185], v[96:99]
	v_mfma_f32_16x16x32_bf16 v[84:87], v[206:209], v[190:193], v[84:87]
	v_mfma_f32_16x16x32_bf16 v[80:83], v[214:217], v[190:193], v[80:83]
	v_mfma_f32_16x16x32_bf16 v[68:71], v[206:209], v[198:201], v[68:71]
	v_mfma_f32_16x16x32_bf16 v[64:67], v[214:217], v[198:201], v[64:67]
	s_mov_b32 m0, s53
	s_barrier
	ds_read_b128 v[170:173], v154 offset:49152
	ds_read_b128 v[174:177], v154 offset:50176
	ds_read_b128 v[178:181], v154 offset:51200
	ds_read_b128 v[182:185], v154 offset:52224
	ds_read_b128 v[186:189], v154 offset:53248
	ds_read_b128 v[190:193], v154 offset:54272
	ds_read_b128 v[194:197], v154 offset:55296
	ds_read_b128 v[198:201], v154 offset:56320
	global_load_lds_dwordx4 v128, s[100:101]
	s_mov_b32 m0, s54
	s_nop 0
	global_load_lds_dwordx4 v132, s[100:101]
	s_waitcnt vmcnt(10)
	s_barrier
	s_waitcnt lgkmcnt(0)
	s_waitcnt lgkmcnt(0)
	v_mfma_f32_16x16x32_bf16 v[60:63], v[144:147], v[170:173], v[60:63]
	v_mfma_f32_16x16x32_bf16 v[56:59], v[162:165], v[170:173], v[56:59]
	v_mfma_f32_16x16x32_bf16 v[44:47], v[144:147], v[178:181], v[44:47]
	v_mfma_f32_16x16x32_bf16 v[40:43], v[162:165], v[178:181], v[40:43]
	v_mfma_f32_16x16x32_bf16 v[28:31], v[144:147], v[186:189], v[28:31]
	v_mfma_f32_16x16x32_bf16 v[24:27], v[162:165], v[186:189], v[24:27]
	v_mfma_f32_16x16x32_bf16 v[12:15], v[144:147], v[194:197], v[12:15]
	v_mfma_f32_16x16x32_bf16 v[8:11], v[162:165], v[194:197], v[8:11]
	v_mfma_f32_16x16x32_bf16 v[60:63], v[158:161], v[174:177], v[60:63]
	v_mfma_f32_16x16x32_bf16 v[56:59], v[166:169], v[174:177], v[56:59]
	v_mfma_f32_16x16x32_bf16 v[44:47], v[158:161], v[182:185], v[44:47]
	v_mfma_f32_16x16x32_bf16 v[40:43], v[166:169], v[182:185], v[40:43]
	v_mfma_f32_16x16x32_bf16 v[28:31], v[158:161], v[190:193], v[28:31]
	v_mfma_f32_16x16x32_bf16 v[24:27], v[166:169], v[190:193], v[24:27]
	v_mfma_f32_16x16x32_bf16 v[12:15], v[158:161], v[198:201], v[12:15]
	v_mfma_f32_16x16x32_bf16 v[8:11], v[166:169], v[198:201], v[8:11]
	s_barrier
	s_add_u32 s46, s46, 0x80080
	s_addc_u32 s47, s47, 0
	s_add_i32 s48, s48, s25
	s_mov_b32 m0, s48
	s_nop 0
	global_load_lds_dwordx4 v130, s[46:47]
	s_add_i32 m0, s48, 0x2000
	s_nop 0
	global_load_lds_dwordx4 v134, s[46:47]
	ds_read_b128 v[144:147], v153
	ds_read_b128 v[158:161], v153 offset:1024
	ds_read_b128 v[162:165], v153 offset:2048
	ds_read_b128 v[166:169], v153 offset:3072
	s_waitcnt vmcnt(6)
	s_branch .LBB0_1668
; __device__ __forceinline__ float fast_sigmoid(float x) { return __builtin_amdgcn_rcpf(1.0f + __builtin_amdgcn_exp2f(-x * LOG2E)); }
; __device__ __forceinline__ float ss_fix(float raw) { return (float)__float_as_uint(raw) * (1.0f / 256.0f); }
;     __device__ __forceinline__ const CAS char* base() const { const CAS char* ka = (const CAS char*)__builtin_amdgcn_kernarg_segment_ptr(); asm volatile("" : "+s"(ka)); return ka; }
;     __device__ __forceinline__ void operator()(const f32x4 (&acc)[2][2][4][2], const Unit& u, int wr, int wc, int fr, int fq) const {
;     ...
;         float rsv[8];
; #pragma unroll
;         for (int it = 0; it < 8; ++it) rsv[it] = (SM == 1) ? ss[row0 + (it >> 2) * HALF + (it & 3) * 16] : 1.0f;
; #pragma unroll
;         for (int ai = 0; ai < 2; ++ai)
; #pragma unroll
;             for (int m = 0; m < 4; ++m) { const int row = row0 + ai * HALF + m * 16; float rs = 1.0f; if (SM == 1) rs = __builtin_amdgcn_rsqf(ss_fix(rsv[ai * 4 + m]) * (1.0f / DM) + EPS);
;                 bf16_t* rowp = base + (size_t)row * ldc + col0;
; #pragma unroll
;                 for (int bj = 0; bj < 2; ++bj) { f32x4 v0 = acc[ai][bj][m][0], v1 = acc[ai][bj][m][1];
;                     if (SM == 1) { v0 *= rs; v1 *= rs; }
;                     if (SM == 2) { v0 *= cs[bj][0]; v1 *= cs[bj][1]; }
;                     if (ACT == 1) {
; #pragma unroll
;                         for (int j = 0; j < 4; ++j) { const float a = fmaxf(v0[j], 0.f), b = fmaxf(v1[j], 0.f); v0[j] = a * a; v1[j] = b * b; } }
;                     if (ACT == 2) { if (tsel == 0) {
; #pragma unroll
;                         for (int j = 0; j < 4; ++j) { const float a = v0[j], b = v1[j];
;                             v0[j] = a * fast_sigmoid(1.5957691216057308f * (a + 0.044715f * a * a * a)); v1[j] = b * fast_sigmoid(1.5957691216057308f * (b + 0.044715f * b * b * b)); } } }
;                     u32x4 w; w.x = pk_bf16(v0[0], v0[1]); w.y = pk_bf16(v0[2], v0[3]); w.z = pk_bf16(v1[0], v1[1]); w.w = pk_bf16(v1[2], v1[3]);
;                     *(u32x4*)(rowp + bj * HALF) = w; } }
.Lrot_out_1668:
	v_lshl_add_u32 v146, s42, 8, v150
	v_ashrrev_i32_e32 v147, 31, v146
	v_lshl_add_u64 v[144:145], v[146:147], 2, s[10:11]
	global_load_dword v157, v[144:145], off
	global_load_dword v162, v[144:145], off offset:64
	v_lshlrev_b64 v[160:161], 14, v[146:147]
	global_load_dword v166, v[144:145], off offset:128
	global_load_dword v167, v[144:145], off offset:192
	global_load_dword v168, v[144:145], off offset:512
	global_load_dword v169, v[144:145], off offset:576
	global_load_dword v170, v[144:145], off offset:640
	global_load_dword v147, v[144:145], off offset:704
	v_lshl_or_b32 v148, s61, 8, v152
	v_ashrrev_i32_e32 v149, 31, v148
	v_lshl_add_u64 v[148:149], v[148:149], 1, s[8:9]
	v_lshl_add_u64 v[144:145], v[148:149], 0, v[160:161]
	v_or_b32_e32 v158, 16, v146
	v_ashrrev_i32_e32 v159, 31, v158
	v_lshlrev_b64 v[158:159], 14, v[158:159]
	v_lshl_add_u64 v[158:159], v[148:149], 0, v[158:159]
	s_mov_b32 s61, s34
	s_mov_b32 s42, s36
	s_mov_b64 s[44:45], s[40:41]
	s_mov_b64 s[46:47], s[38:39]
	s_waitcnt vmcnt(0)
	v_cvt_f32_u32_e32 v157, v157
	v_cvt_f32_u32_e32 v161, v162
	v_mul_f32_e32 v157, 0x3b800000, v157
	v_fmamk_f32 v157, v157, 0x3a000000, v156
	v_rsq_f32_e32 v160, v157
	v_mul_f32_e32 v157, 0x3b800000, v161
	v_fmamk_f32 v157, v157, 0x3a000000, v156
	v_rsq_f32_e32 v162, v157
	v_pk_mul_f32 v[126:127], v[126:127], v[160:161] op_sel_hi:[1,0]
	v_pk_mul_f32 v[124:125], v[124:125], v[160:161] op_sel_hi:[1,0]
	v_pk_mul_f32 v[122:123], v[122:123], v[160:161] op_sel_hi:[1,0]
	v_pk_mul_f32 v[120:121], v[120:121], v[160:161] op_sel_hi:[1,0]
	v_pk_mul_f32 v[110:111], v[110:111], v[160:161] op_sel_hi:[1,0]
	v_pk_mul_f32 v[108:109], v[108:109], v[160:161] op_sel_hi:[1,0]
	v_pk_mul_f32 v[106:107], v[106:107], v[160:161] op_sel_hi:[1,0]
	v_pk_mul_f32 v[104:105], v[104:105], v[160:161] op_sel_hi:[1,0]
	v_pk_mul_f32 v[118:119], v[118:119], v[162:163] op_sel_hi:[1,0]
	v_pk_mul_f32 v[116:117], v[116:117], v[162:163] op_sel_hi:[1,0]
	v_pk_mul_f32 v[114:115], v[114:115], v[162:163] op_sel_hi:[1,0]
	v_pk_mul_f32 v[112:113], v[112:113], v[162:163] op_sel_hi:[1,0]
	v_pk_mul_f32 v[160:161], v[102:103], v[162:163] op_sel_hi:[1,0]
	v_pk_mul_f32 v[100:101], v[100:101], v[162:163] op_sel_hi:[1,0]
	v_pk_mul_f32 v[164:165], v[98:99], v[162:163] op_sel_hi:[1,0]
	v_pk_mul_f32 v[162:163], v[96:97], v[162:163] op_sel_hi:[1,0]
	v_max_f32_e32 v96, 0, v124
	v_max_f32_e32 v98, 0, v120
	v_max_f32_e32 v97, 0, v125
	v_max_f32_e32 v99, 0, v121
	v_max_f32_e32 v102, 0, v126
	v_max_f32_e32 v120, 0, v122
	v_max_f32_e32 v103, 0, v127
	v_max_f32_e32 v121, 0, v123
	v_max_f32_e32 v108, 0, v108
	v_max_f32_e32 v109, 0, v109
	v_max_f32_e32 v110, 0, v110
	v_max_f32_e32 v111, 0, v111
	v_max_f32_e32 v104, 0, v104
	v_max_f32_e32 v105, 0, v105
	v_max_f32_e32 v106, 0, v106
	v_max_f32_e32 v107, 0, v107
	v_max_f32_e32 v116, 0, v116
	v_max_f32_e32 v112, 0, v112
	v_max_f32_e32 v117, 0, v117
	v_max_f32_e32 v113, 0, v113
	v_max_f32_e32 v118, 0, v118
	v_max_f32_e32 v114, 0, v114
	v_max_f32_e32 v119, 0, v119
	v_max_f32_e32 v115, 0, v115
	v_max_f32_e32 v122, 0, v100
	v_max_f32_e32 v123, 0, v101
	v_pk_mul_f32 v[96:97], v[96:97], v[96:97]
	v_pk_mul_f32 v[98:99], v[98:99], v[98:99]
	v_pk_mul_f32 v[100:101], v[102:103], v[102:103]
	v_pk_mul_f32 v[102:103], v[120:121], v[120:121]
	v_pk_mul_f32 v[108:109], v[108:109], v[108:109]
	v_pk_mul_f32 v[110:111], v[110:111], v[110:111]
	v_pk_mul_f32 v[104:105], v[104:105], v[104:105]
	v_pk_mul_f32 v[106:107], v[106:107], v[106:107]
	v_pk_mul_f32 v[116:117], v[116:117], v[116:117]
	v_pk_mul_f32 v[112:113], v[112:113], v[112:113]
	v_pk_mul_f32 v[118:119], v[118:119], v[118:119]
	v_pk_mul_f32 v[114:115], v[114:115], v[114:115]
	v_cvt_pk_bf16_f32 v96, v96, v97
	v_cvt_pk_bf16_f32 v97, v100, v101
	v_cvt_pk_bf16_f32 v98, v98, v99
	v_cvt_pk_bf16_f32 v99, v102, v103
	v_cvt_pk_bf16_f32 v100, v108, v109
	v_cvt_pk_bf16_f32 v101, v110, v111
	v_cvt_pk_bf16_f32 v102, v104, v105
	v_cvt_pk_bf16_f32 v103, v106, v107
	v_cvt_pk_bf16_f32 v104, v116, v117
	v_cvt_pk_bf16_f32 v105, v118, v119
	v_cvt_pk_bf16_f32 v106, v112, v113
	v_cvt_pk_bf16_f32 v107, v114, v115
	global_store_dwordx4 v[144:145], v[96:99], off
	global_store_dwordx4 v[144:145], v[100:103], off offset:256
	global_store_dwordx4 v[158:159], v[104:107], off
	v_pk_mul_f32 v[96:97], v[122:123], v[122:123]
	v_max_f32_e32 v100, 0, v160
	v_max_f32_e32 v101, 0, v161
	v_pk_mul_f32 v[100:101], v[100:101], v[100:101]
	v_cvt_pk_bf16_f32 v96, v96, v97
	v_cvt_pk_bf16_f32 v97, v100, v101
	v_cvt_f32_u32_e32 v100, v166
	v_max_f32_e32 v124, 0, v162
	v_max_f32_e32 v125, 0, v163
	v_max_f32_e32 v102, 0, v164
	v_max_f32_e32 v103, 0, v165
	v_pk_mul_f32 v[98:99], v[124:125], v[124:125]
	v_pk_mul_f32 v[102:103], v[102:103], v[102:103]
	v_cvt_pk_bf16_f32 v98, v98, v99
	v_cvt_pk_bf16_f32 v99, v102, v103
	global_store_dwordx4 v[158:159], v[96:99], off offset:256
	s_nop 1
	v_mul_f32_e32 v97, 0x3b800000, v100
	v_fmamk_f32 v97, v97, 0x3a000000, v156
	v_rsq_f32_e32 v98, v97
	v_or_b32_e32 v96, 32, v146
	v_ashrrev_i32_e32 v97, 31, v96
	v_lshlrev_b64 v[96:97], 14, v[96:97]
	v_pk_mul_f32 v[88:89], v[88:89], v[98:99] op_sel_hi:[1,0]
	v_pk_mul_f32 v[94:95], v[94:95], v[98:99] op_sel_hi:[1,0]
	v_pk_mul_f32 v[92:93], v[92:93], v[98:99] op_sel_hi:[1,0]
	v_pk_mul_f32 v[90:91], v[90:91], v[98:99] op_sel_hi:[1,0]
	v_max_f32_e32 v88, 0, v88
	v_max_f32_e32 v89, 0, v89
	v_max_f32_e32 v92, 0, v92
	v_max_f32_e32 v93, 0, v93
	v_pk_mul_f32 v[100:101], v[88:89], v[88:89]
	v_max_f32_e32 v88, 0, v94
	v_max_f32_e32 v90, 0, v90
	v_max_f32_e32 v89, 0, v95
	v_max_f32_e32 v91, 0, v91
	v_pk_mul_f32 v[92:93], v[92:93], v[92:93]
	v_pk_mul_f32 v[94:95], v[88:89], v[88:89]
; __device__ __forceinline__ float fast_sigmoid(float x) { return __builtin_amdgcn_rcpf(1.0f + __builtin_amdgcn_exp2f(-x * LOG2E)); }
; __device__ __forceinline__ float ss_fix(float raw) { return (float)__float_as_uint(raw) * (1.0f / 256.0f); }
;     __device__ __forceinline__ const CAS char* base() const { const CAS char* ka = (const CAS char*)__builtin_amdgcn_kernarg_segment_ptr(); asm volatile("" : "+s"(ka)); return ka; }
;     __device__ __forceinline__ void operator()(const f32x4 (&acc)[2][2][4][2], const Unit& u, int wr, int wc, int fr, int fq) const {
;     ...
; #pragma unroll
;         for (int ai = 0; ai < 2; ++ai)
; #pragma unroll
;             for (int m = 0; m < 4; ++m) { const int row = row0 + ai * HALF + m * 16; float rs = 1.0f; if (SM == 1) rs = __builtin_amdgcn_rsqf(ss_fix(rsv[ai * 4 + m]) * (1.0f / DM) + EPS);
;                 bf16_t* rowp = base + (size_t)row * ldc + col0;
; #pragma unroll
;                 for (int bj = 0; bj < 2; ++bj) { f32x4 v0 = acc[ai][bj][m][0], v1 = acc[ai][bj][m][1];
;                     if (SM == 1) { v0 *= rs; v1 *= rs; }
;                     if (SM == 2) { v0 *= cs[bj][0]; v1 *= cs[bj][1]; }
;                     if (ACT == 1) {
; #pragma unroll
;                         for (int j = 0; j < 4; ++j) { const float a = fmaxf(v0[j], 0.f), b = fmaxf(v1[j], 0.f); v0[j] = a * a; v1[j] = b * b; } }
;                     if (ACT == 2) { if (tsel == 0) {
; #pragma unroll
;                         for (int j = 0; j < 4; ++j) { const float a = v0[j], b = v1[j];
;                             v0[j] = a * fast_sigmoid(1.5957691216057308f * (a + 0.044715f * a * a * a)); v1[j] = b * fast_sigmoid(1.5957691216057308f * (b + 0.044715f * b * b * b)); } } }
;                     u32x4 w; w.x = pk_bf16(v0[0], v0[1]); w.y = pk_bf16(v0[2], v0[3]); w.z = pk_bf16(v1[0], v1[1]); w.w = pk_bf16(v1[2], v1[3]);
;                     *(u32x4*)(rowp + bj * HALF) = w; } }
	v_pk_mul_f32 v[102:103], v[90:91], v[90:91]
	v_pk_mul_f32 v[84:85], v[84:85], v[98:99] op_sel_hi:[1,0]
	v_pk_mul_f32 v[80:81], v[80:81], v[98:99] op_sel_hi:[1,0]
	v_lshl_add_u64 v[96:97], v[148:149], 0, v[96:97]
	v_cvt_pk_bf16_f32 v88, v92, v93
	v_cvt_pk_bf16_f32 v89, v94, v95
	v_cvt_pk_bf16_f32 v90, v100, v101
	v_cvt_pk_bf16_f32 v91, v102, v103
	v_pk_mul_f32 v[86:87], v[86:87], v[98:99] op_sel_hi:[1,0]
	v_max_f32_e32 v84, 0, v84
	v_max_f32_e32 v80, 0, v80
	v_max_f32_e32 v85, 0, v85
	v_max_f32_e32 v81, 0, v81
	global_store_dwordx4 v[96:97], v[88:91], off
	v_pk_mul_f32 v[84:85], v[84:85], v[84:85]
	v_pk_mul_f32 v[82:83], v[82:83], v[98:99] op_sel_hi:[1,0]
	v_pk_mul_f32 v[88:89], v[80:81], v[80:81]
	v_max_f32_e32 v80, 0, v86
	v_max_f32_e32 v81, 0, v87
	v_pk_mul_f32 v[86:87], v[80:81], v[80:81]
	v_cvt_pk_bf16_f32 v80, v84, v85
	v_cvt_f32_u32_e32 v84, v167
	v_max_f32_e32 v82, 0, v82
	v_max_f32_e32 v83, 0, v83
	v_pk_mul_f32 v[90:91], v[82:83], v[82:83]
	v_cvt_pk_bf16_f32 v81, v86, v87
	v_cvt_pk_bf16_f32 v82, v88, v89
	v_cvt_pk_bf16_f32 v83, v90, v91
	global_store_dwordx4 v[96:97], v[80:83], off offset:256
	s_nop 1
	v_mul_f32_e32 v81, 0x3b800000, v84
	v_fmamk_f32 v81, v81, 0x3a000000, v156
	v_rsq_f32_e32 v82, v81
	v_or_b32_e32 v80, 48, v146
	v_ashrrev_i32_e32 v81, 31, v80
	v_lshlrev_b64 v[80:81], 14, v[80:81]
	v_pk_mul_f32 v[72:73], v[72:73], v[82:83] op_sel_hi:[1,0]
	v_pk_mul_f32 v[78:79], v[78:79], v[82:83] op_sel_hi:[1,0]
	v_pk_mul_f32 v[76:77], v[76:77], v[82:83] op_sel_hi:[1,0]
	v_pk_mul_f32 v[74:75], v[74:75], v[82:83] op_sel_hi:[1,0]
	v_max_f32_e32 v72, 0, v72
	v_max_f32_e32 v73, 0, v73
	v_max_f32_e32 v76, 0, v76
	v_max_f32_e32 v77, 0, v77
	v_pk_mul_f32 v[84:85], v[72:73], v[72:73]
	v_max_f32_e32 v72, 0, v78
	v_max_f32_e32 v74, 0, v74
	v_max_f32_e32 v73, 0, v79
	v_max_f32_e32 v75, 0, v75
	v_pk_mul_f32 v[76:77], v[76:77], v[76:77]
	v_pk_mul_f32 v[78:79], v[72:73], v[72:73]
	v_pk_mul_f32 v[86:87], v[74:75], v[74:75]
	v_pk_mul_f32 v[66:67], v[66:67], v[82:83] op_sel_hi:[1,0]
	v_lshl_add_u64 v[80:81], v[148:149], 0, v[80:81]
	v_cvt_pk_bf16_f32 v72, v76, v77
	v_cvt_pk_bf16_f32 v73, v78, v79
	v_cvt_pk_bf16_f32 v74, v84, v85
	v_cvt_pk_bf16_f32 v75, v86, v87
	v_max_f32_e32 v66, 0, v66
	v_max_f32_e32 v67, 0, v67
	global_store_dwordx4 v[80:81], v[72:75], off
	v_pk_mul_f32 v[68:69], v[68:69], v[82:83] op_sel_hi:[1,0]
	v_pk_mul_f32 v[64:65], v[64:65], v[82:83] op_sel_hi:[1,0]
	v_pk_mul_f32 v[74:75], v[66:67], v[66:67]
	v_cvt_f32_u32_e32 v67, v168
	v_pk_mul_f32 v[70:71], v[70:71], v[82:83] op_sel_hi:[1,0]
	v_max_f32_e32 v68, 0, v68
	v_max_f32_e32 v64, 0, v64
	v_max_f32_e32 v69, 0, v69
	v_max_f32_e32 v65, 0, v65
	v_mul_f32_e32 v67, 0x3b800000, v67
	v_pk_mul_f32 v[68:69], v[68:69], v[68:69]
	v_pk_mul_f32 v[72:73], v[64:65], v[64:65]
	v_max_f32_e32 v64, 0, v70
	v_max_f32_e32 v65, 0, v71
	v_fmamk_f32 v67, v67, 0x3a000000, v156
	v_pk_mul_f32 v[70:71], v[64:65], v[64:65]
	v_cvt_pk_bf16_f32 v64, v68, v69
	v_rsq_f32_e32 v68, v67
	v_cvt_pk_bf16_f32 v65, v70, v71
	v_cvt_pk_bf16_f32 v66, v72, v73
	v_cvt_pk_bf16_f32 v67, v74, v75
	v_pk_mul_f32 v[60:61], v[60:61], v[68:69] op_sel_hi:[1,0]
	v_pk_mul_f32 v[56:57], v[56:57], v[68:69] op_sel_hi:[1,0]
	v_pk_mul_f32 v[62:63], v[62:63], v[68:69] op_sel_hi:[1,0]
	v_pk_mul_f32 v[58:59], v[58:59], v[68:69] op_sel_hi:[1,0]
	v_max_f32_e32 v60, 0, v60
	v_max_f32_e32 v56, 0, v56
	v_max_f32_e32 v61, 0, v61
	v_max_f32_e32 v57, 0, v57
	global_store_dwordx4 v[80:81], v[64:67], off offset:256
	v_pk_mul_f32 v[60:61], v[60:61], v[60:61]
	v_max_f32_e32 v58, 0, v58
	v_pk_mul_f32 v[66:67], v[56:57], v[56:57]
	v_max_f32_e32 v56, 0, v62
	v_max_f32_e32 v57, 0, v63
	v_max_f32_e32 v59, 0, v59
	v_pk_mul_f32 v[62:63], v[56:57], v[56:57]
	v_pk_mul_f32 v[70:71], v[58:59], v[58:59]
	v_cvt_pk_bf16_f32 v56, v60, v61
	v_add_co_u32_e32 v60, vcc, s57, v144
	v_pk_mul_f32 v[50:51], v[50:51], v[68:69] op_sel_hi:[1,0]
	v_cvt_pk_bf16_f32 v57, v62, v63
	v_cvt_pk_bf16_f32 v58, v66, v67
	v_cvt_pk_bf16_f32 v59, v70, v71
	v_addc_co_u32_e32 v61, vcc, 0, v145, vcc
	v_max_f32_e32 v50, 0, v50
	v_max_f32_e32 v51, 0, v51
	global_store_dwordx4 v[60:61], v[56:59], off
	v_pk_mul_f32 v[52:53], v[52:53], v[68:69] op_sel_hi:[1,0]
	v_pk_mul_f32 v[48:49], v[48:49], v[68:69] op_sel_hi:[1,0]
	v_pk_mul_f32 v[58:59], v[50:51], v[50:51]
	v_cvt_f32_u32_e32 v51, v169
	v_pk_mul_f32 v[54:55], v[54:55], v[68:69] op_sel_hi:[1,0]
	v_max_f32_e32 v52, 0, v52
	v_max_f32_e32 v48, 0, v48
	v_max_f32_e32 v53, 0, v53
	v_max_f32_e32 v49, 0, v49
	v_mul_f32_e32 v51, 0x3b800000, v51
	v_pk_mul_f32 v[52:53], v[52:53], v[52:53]
	v_pk_mul_f32 v[56:57], v[48:49], v[48:49]
	v_max_f32_e32 v48, 0, v54
	v_max_f32_e32 v49, 0, v55
	v_fmamk_f32 v51, v51, 0x3a000000, v156
	v_pk_mul_f32 v[54:55], v[48:49], v[48:49]
	v_cvt_pk_bf16_f32 v48, v52, v53
	v_rsq_f32_e32 v52, v51
	v_lshl_add_u64 v[64:65], v[144:145], 0, s[14:15]
	v_cvt_pk_bf16_f32 v49, v54, v55
	v_cvt_pk_bf16_f32 v50, v56, v57
	v_pk_mul_f32 v[44:45], v[44:45], v[52:53] op_sel_hi:[1,0]
	v_pk_mul_f32 v[40:41], v[40:41], v[52:53] op_sel_hi:[1,0]
	v_cvt_pk_bf16_f32 v51, v58, v59
	v_pk_mul_f32 v[46:47], v[46:47], v[52:53] op_sel_hi:[1,0]
	v_pk_mul_f32 v[42:43], v[42:43], v[52:53] op_sel_hi:[1,0]
	v_max_f32_e32 v44, 0, v44
	v_max_f32_e32 v40, 0, v40
	v_max_f32_e32 v45, 0, v45
	v_max_f32_e32 v41, 0, v41
; __device__ __forceinline__ float fast_sigmoid(float x) { return __builtin_amdgcn_rcpf(1.0f + __builtin_amdgcn_exp2f(-x * LOG2E)); }
; __device__ __forceinline__ float ss_fix(float raw) { return (float)__float_as_uint(raw) * (1.0f / 256.0f); }
; #define PG8_WAIT_V(n) asm volatile("s_waitcnt vmcnt(" #n ")" ::: "memory")
; template <class Epi>
; __device__ __forceinline__ void gemm_phase(LAS unsigned char* lds, const Gemm g, const StaticOrder& S, const Epi& E, int wv) {
;     ...
;         if (!has_next) break;
; #pragma unroll
;         for (int a = 0; a < 2; ++a)
; #pragma unroll
;             for (int b = 0; b < 2; ++b)
; #pragma unroll
;                 for (int m = 0; m < 4; ++m)
; #pragma unroll
;                     for (int n = 0; n < 2; ++n) acc[a][b][m][n] = (f32x4){0.f, 0.f, 0.f, 0.f};
;         cur = nxt; cA = nA; cB = nB; ++ui;
;     }
;     PG8_WAIT_V(0);
;     if (wr == 0) PG8_BAR;
;     __device__ __forceinline__ void operator()(const f32x4 (&acc)[2][2][4][2], const Unit& u, int wr, int wc, int fr, int fq) const {
;     ...
; #pragma unroll
;         for (int ai = 0; ai < 2; ++ai)
; #pragma unroll
;             for (int m = 0; m < 4; ++m) { const int row = row0 + ai * HALF + m * 16; float rs = 1.0f; if (SM == 1) rs = __builtin_amdgcn_rsqf(ss_fix(rsv[ai * 4 + m]) * (1.0f / DM) + EPS);
;                 bf16_t* rowp = base + (size_t)row * ldc + col0;
; #pragma unroll
;                 for (int bj = 0; bj < 2; ++bj) { f32x4 v0 = acc[ai][bj][m][0], v1 = acc[ai][bj][m][1];
;                     if (SM == 1) { v0 *= rs; v1 *= rs; }
;                     if (SM == 2) { v0 *= cs[bj][0]; v1 *= cs[bj][1]; }
;                     if (ACT == 1) {
; #pragma unroll
;                         for (int j = 0; j < 4; ++j) { const float a = fmaxf(v0[j], 0.f), b = fmaxf(v1[j], 0.f); v0[j] = a * a; v1[j] = b * b; } }
;                     if (ACT == 2) { if (tsel == 0) {
; #pragma unroll
;                         for (int j = 0; j < 4; ++j) { const float a = v0[j], b = v1[j];
;                             v0[j] = a * fast_sigmoid(1.5957691216057308f * (a + 0.044715f * a * a * a)); v1[j] = b * fast_sigmoid(1.5957691216057308f * (b + 0.044715f * b * b * b)); } } }
;                     u32x4 w; w.x = pk_bf16(v0[0], v0[1]); w.y = pk_bf16(v0[2], v0[3]); w.z = pk_bf16(v1[0], v1[1]); w.w = pk_bf16(v1[2], v1[3]);
;                     *(u32x4*)(rowp + bj * HALF) = w; } }
	global_store_dwordx4 v[64:65], v[48:51], off offset:256
	v_pk_mul_f32 v[44:45], v[44:45], v[44:45]
	v_max_f32_e32 v42, 0, v42
	v_pk_mul_f32 v[50:51], v[40:41], v[40:41]
	v_max_f32_e32 v40, 0, v46
	v_max_f32_e32 v41, 0, v47
	v_max_f32_e32 v43, 0, v43
	v_pk_mul_f32 v[46:47], v[40:41], v[40:41]
	v_pk_mul_f32 v[54:55], v[42:43], v[42:43]
	v_cvt_pk_bf16_f32 v40, v44, v45
	v_add_co_u32_e32 v44, vcc, s58, v144
	v_pk_mul_f32 v[34:35], v[34:35], v[52:53] op_sel_hi:[1,0]
	v_cvt_pk_bf16_f32 v41, v46, v47
	v_cvt_pk_bf16_f32 v42, v50, v51
	v_cvt_pk_bf16_f32 v43, v54, v55
	v_addc_co_u32_e32 v45, vcc, 0, v145, vcc
	v_max_f32_e32 v34, 0, v34
	v_max_f32_e32 v35, 0, v35
	global_store_dwordx4 v[44:45], v[40:43], off
	v_pk_mul_f32 v[36:37], v[36:37], v[52:53] op_sel_hi:[1,0]
	v_pk_mul_f32 v[32:33], v[32:33], v[52:53] op_sel_hi:[1,0]
	v_pk_mul_f32 v[42:43], v[34:35], v[34:35]
	v_cvt_f32_u32_e32 v35, v170
	v_pk_mul_f32 v[38:39], v[38:39], v[52:53] op_sel_hi:[1,0]
	v_max_f32_e32 v36, 0, v36
	v_max_f32_e32 v32, 0, v32
	v_max_f32_e32 v37, 0, v37
	v_max_f32_e32 v33, 0, v33
	v_mul_f32_e32 v35, 0x3b800000, v35
	v_pk_mul_f32 v[36:37], v[36:37], v[36:37]
	v_pk_mul_f32 v[40:41], v[32:33], v[32:33]
	v_max_f32_e32 v32, 0, v38
	v_max_f32_e32 v33, 0, v39
	v_fmamk_f32 v35, v35, 0x3a000000, v156
	v_pk_mul_f32 v[38:39], v[32:33], v[32:33]
	v_cvt_pk_bf16_f32 v32, v36, v37
	v_rsq_f32_e32 v36, v35
	v_lshl_add_u64 v[48:49], v[144:145], 0, s[16:17]
	v_cvt_pk_bf16_f32 v33, v38, v39
	v_cvt_pk_bf16_f32 v34, v40, v41
	v_pk_mul_f32 v[28:29], v[28:29], v[36:37] op_sel_hi:[1,0]
	v_pk_mul_f32 v[24:25], v[24:25], v[36:37] op_sel_hi:[1,0]
	v_cvt_pk_bf16_f32 v35, v42, v43
	v_pk_mul_f32 v[30:31], v[30:31], v[36:37] op_sel_hi:[1,0]
	v_pk_mul_f32 v[26:27], v[26:27], v[36:37] op_sel_hi:[1,0]
	v_max_f32_e32 v28, 0, v28
	v_max_f32_e32 v24, 0, v24
	v_max_f32_e32 v29, 0, v29
	v_max_f32_e32 v25, 0, v25
	global_store_dwordx4 v[48:49], v[32:35], off offset:256
	v_pk_mul_f32 v[28:29], v[28:29], v[28:29]
	v_max_f32_e32 v26, 0, v26
	v_pk_mul_f32 v[34:35], v[24:25], v[24:25]
	v_max_f32_e32 v24, 0, v30
	v_max_f32_e32 v25, 0, v31
	v_max_f32_e32 v27, 0, v27
	v_pk_mul_f32 v[30:31], v[24:25], v[24:25]
	v_pk_mul_f32 v[38:39], v[26:27], v[26:27]
	v_cvt_pk_bf16_f32 v24, v28, v29
	v_add_co_u32_e32 v28, vcc, s59, v144
	v_pk_mul_f32 v[18:19], v[18:19], v[36:37] op_sel_hi:[1,0]
	v_cvt_pk_bf16_f32 v25, v30, v31
	v_cvt_pk_bf16_f32 v26, v34, v35
	v_cvt_pk_bf16_f32 v27, v38, v39
	v_addc_co_u32_e32 v29, vcc, 0, v145, vcc
	v_max_f32_e32 v18, 0, v18
	v_max_f32_e32 v19, 0, v19
	global_store_dwordx4 v[28:29], v[24:27], off
	v_pk_mul_f32 v[20:21], v[20:21], v[36:37] op_sel_hi:[1,0]
	v_pk_mul_f32 v[16:17], v[16:17], v[36:37] op_sel_hi:[1,0]
	v_pk_mul_f32 v[26:27], v[18:19], v[18:19]
	v_cvt_f32_u32_e32 v19, v147
	v_pk_mul_f32 v[22:23], v[22:23], v[36:37] op_sel_hi:[1,0]
	v_max_f32_e32 v20, 0, v20
	v_max_f32_e32 v16, 0, v16
	v_max_f32_e32 v21, 0, v21
	v_max_f32_e32 v17, 0, v17
	v_mul_f32_e32 v19, 0x3b800000, v19
	v_pk_mul_f32 v[20:21], v[20:21], v[20:21]
	v_pk_mul_f32 v[24:25], v[16:17], v[16:17]
	v_max_f32_e32 v16, 0, v22
	v_max_f32_e32 v17, 0, v23
	v_fmamk_f32 v19, v19, 0x3a000000, v156
	v_pk_mul_f32 v[22:23], v[16:17], v[16:17]
	v_cvt_pk_bf16_f32 v16, v20, v21
	v_rsq_f32_e32 v20, v19
	v_lshl_add_u64 v[32:33], v[144:145], 0, s[18:19]
	v_cvt_pk_bf16_f32 v17, v22, v23
	v_cvt_pk_bf16_f32 v18, v24, v25
	v_pk_mul_f32 v[12:13], v[12:13], v[20:21] op_sel_hi:[1,0]
	v_pk_mul_f32 v[8:9], v[8:9], v[20:21] op_sel_hi:[1,0]
	v_cvt_pk_bf16_f32 v19, v26, v27
	v_pk_mul_f32 v[14:15], v[14:15], v[20:21] op_sel_hi:[1,0]
	v_pk_mul_f32 v[10:11], v[10:11], v[20:21] op_sel_hi:[1,0]
	v_max_f32_e32 v12, 0, v12
	v_max_f32_e32 v8, 0, v8
	v_max_f32_e32 v13, 0, v13
	v_max_f32_e32 v9, 0, v9
	global_store_dwordx4 v[32:33], v[16:19], off offset:256
	v_pk_mul_f32 v[12:13], v[12:13], v[12:13]
	v_max_f32_e32 v10, 0, v10
	v_pk_mul_f32 v[18:19], v[8:9], v[8:9]
	v_max_f32_e32 v8, 0, v14
	v_max_f32_e32 v9, 0, v15
	v_max_f32_e32 v11, 0, v11
	v_pk_mul_f32 v[14:15], v[8:9], v[8:9]
	v_pk_mul_f32 v[22:23], v[10:11], v[10:11]
	v_cvt_pk_bf16_f32 v8, v12, v13
	v_add_co_u32_e32 v12, vcc, s60, v144
	v_pk_mul_f32 v[0:1], v[0:1], v[20:21] op_sel_hi:[1,0]
	v_cvt_pk_bf16_f32 v9, v14, v15
	v_cvt_pk_bf16_f32 v10, v18, v19
	v_cvt_pk_bf16_f32 v11, v22, v23
	v_addc_co_u32_e32 v13, vcc, 0, v145, vcc
	v_pk_mul_f32 v[6:7], v[6:7], v[20:21] op_sel_hi:[1,0]
	v_pk_mul_f32 v[4:5], v[4:5], v[20:21] op_sel_hi:[1,0]
	v_pk_mul_f32 v[2:3], v[2:3], v[20:21] op_sel_hi:[1,0]
	v_max_f32_e32 v0, 0, v0
	v_max_f32_e32 v1, 0, v1
	global_store_dwordx4 v[12:13], v[8:11], off
	v_max_f32_e32 v4, 0, v4
	v_max_f32_e32 v5, 0, v5
	v_pk_mul_f32 v[8:9], v[0:1], v[0:1]
	v_max_f32_e32 v0, 0, v6
	v_max_f32_e32 v2, 0, v2
	v_max_f32_e32 v1, 0, v7
	v_max_f32_e32 v3, 0, v3
	v_pk_mul_f32 v[4:5], v[4:5], v[4:5]
	v_pk_mul_f32 v[6:7], v[0:1], v[0:1]
	v_pk_mul_f32 v[10:11], v[2:3], v[2:3]
	v_lshl_add_u64 v[16:17], v[144:145], 0, s[30:31]
	v_cvt_pk_bf16_f32 v0, v4, v5
	v_cvt_pk_bf16_f32 v1, v6, v7
	v_cvt_pk_bf16_f32 v2, v8, v9
	v_cvt_pk_bf16_f32 v3, v10, v11
	s_and_b64 vcc, exec, s[6:7]
	global_store_dwordx4 v[16:17], v[0:3], off offset:256
	s_cbranch_vccz .LBB0_1661
	s_waitcnt vmcnt(0)
	s_cmpk_gt_u32 s4, 0xff
	s_cbranch_scc1 .LBB0_1672
	s_barrier

; #define PG8_BAR __builtin_amdgcn_s_barrier()
; template <class Epi>
; __device__ __forceinline__ void gemm_phase(LAS unsigned char* lds, const Gemm g, const StaticOrder& S, const Epi& E, int wv) {
;     ...
;         const bool has_next = S.next(ui + 1, nxt);
;         const char* nA = has_next ? (const char*)g.A + (size_t)nxt.pm * tstepA + ((g.adiag & 1) ? (size_t)(nxt.pn >> 1) * K * 2 : 0) + kbeg : cA;
;         const char* nB = has_next ? (const char*)g.Bt + (size_t)nxt.pn * tstepB + kbeg : cB;
;         for (int t = 0; t < nt; t += 2) {
;             const bool last = (t == nt - 2);
;             const char* a1 = cA + (ptrdiff_t)(t + 1) * kstep;
;             const char* a2 = last ? nA : cA + (ptrdiff_t)(t + 2) * kstep; const char* b2 = last ? nB : cB + (ptrdiff_t)(t + 2) * kstep;
;             const char* a3 = a2 + kstep; const char* b3 = b2 + kstep;
;             PG8_LDB(B0, 0, 0); PG8_SCHED; PG8_LDA(At, 0, 0); PG8_STAGE(PG8_SA(1, 1), a1 + hstepA, voffA);
;             PG8_WAIT_L(8); PG8_BAR; PG8_WAIT_L(0); PG8_MMA(0, 0, At, B0); PG8_BAR; PG8_SCHED;
;             PG8_LDB(B1, 0, 1); PG8_STAGE(PG8_SB(0, 0), b2, voffB);
;             PG8_BAR; PG8_WAIT_L(0); PG8_MMA(0, 1, At, B1); PG8_BAR;
;             PG8_LDA(At, 0, 1); PG8_STAGE(PG8_SA(0, 0), a2, voffA);
;             PG8_BAR; PG8_WAIT_L(0); PG8_MMA(1, 0, At, B0); PG8_BAR; PG8_SCHED;
;             PG8_STAGE(PG8_SB(0, 1), b2 + hstepB, voffB);
;             PG8_WAIT_V(6); PG8_BAR; PG8_MMA(1, 1, At, B1); PG8_BAR;
;             PG8_LDB(B0, 1, 0); PG8_SCHED; PG8_LDA(At, 1, 0); PG8_STAGE(PG8_SA(0, 1), a2 + hstepA, voffA);
;             PG8_WAIT_L(8); PG8_BAR; PG8_WAIT_L(0); PG8_MMA(0, 0, At, B0); PG8_BAR; PG8_SCHED;
;             PG8_LDB(B1, 1, 1); PG8_STAGE(PG8_SB(1, 0), b3, voffB);
;             PG8_BAR; PG8_WAIT_L(0); PG8_MMA(0, 1, At, B1); PG8_BAR;
;             PG8_LDA(At, 1, 1); PG8_STAGE(PG8_SA(1, 0), a3, voffA);
;             PG8_BAR; PG8_WAIT_L(0); PG8_MMA(1, 0, At, B0); PG8_BAR; PG8_SCHED;
;             PG8_STAGE(PG8_SB(1, 1), b3 + hstepB, voffB);
;             PG8_WAIT_V(6); PG8_BAR; PG8_MMA(1, 1, At, B1); PG8_BAR;
;         }
;         E(acc, cur, wr, wc, fr, fq);
;         if (!has_next) break;
; #pragma unroll
;         for (int a = 0; a < 2; ++a)
; #pragma unroll
;             for (int b = 0; b < 2; ++b)
; #pragma unroll
;                 for (int m = 0; m < 4; ++m)
; #pragma unroll
.LBB0_1852:
	s_ashr_i32 s19, s18, 31
	v_cmp_lt_i64_e32 vcc, s[20:21], v[172:173]
	s_lshl_b64 s[20:21], s[18:19], 20
	s_add_u32 s20, s36, s20
	s_addc_u32 s21, s37, s21
	s_and_b64 s[22:23], vcc, exec
	s_cselect_b32 s19, s21, s31
	s_cselect_b32 s50, s20, s30
	s_ashr_i32 s17, s16, 31
	s_lshl_b64 s[22:23], s[16:17], 20
	s_add_u32 s22, s38, s22
	s_addc_u32 s23, s39, s23
	s_and_b64 s[34:35], vcc, exec
	s_cselect_b32 s17, s23, s29
	s_cselect_b32 s51, s22, s28
	s_add_u32 s52, s28, 0x100
	s_addc_u32 s53, s29, 0
	s_add_u32 s28, s30, 0x80080
	v_mov_b32_e32 v0, 0
	s_addc_u32 s29, s31, 0
	s_mov_b32 s54, -2
	v_mov_b32_e32 v1, v0
	v_mov_b32_e32 v2, v0
	v_mov_b32_e32 v3, v0
	v_mov_b32_e32 v4, v0
	v_mov_b32_e32 v5, v0
	v_mov_b32_e32 v6, v0
	v_mov_b32_e32 v7, v0
	v_mov_b32_e32 v16, v0
	v_mov_b32_e32 v17, v0
	v_mov_b32_e32 v18, v0
	v_mov_b32_e32 v19, v0
	v_mov_b32_e32 v20, v0
	v_mov_b32_e32 v21, v0
	v_mov_b32_e32 v22, v0
	v_mov_b32_e32 v23, v0
	v_mov_b32_e32 v32, v0
	v_mov_b32_e32 v33, v0
	v_mov_b32_e32 v34, v0
	v_mov_b32_e32 v35, v0
	v_mov_b32_e32 v36, v0
	v_mov_b32_e32 v37, v0
	v_mov_b32_e32 v38, v0
	v_mov_b32_e32 v39, v0
	v_mov_b32_e32 v48, v0
	v_mov_b32_e32 v49, v0
	v_mov_b32_e32 v50, v0
	v_mov_b32_e32 v51, v0
	v_mov_b32_e32 v52, v0
	v_mov_b32_e32 v53, v0
	v_mov_b32_e32 v54, v0
	v_mov_b32_e32 v55, v0
	v_mov_b32_e32 v8, v0
	v_mov_b32_e32 v9, v0
	v_mov_b32_e32 v10, v0
	v_mov_b32_e32 v11, v0
	v_mov_b32_e32 v12, v0
	v_mov_b32_e32 v13, v0
	v_mov_b32_e32 v14, v0
	v_mov_b32_e32 v15, v0
	v_mov_b32_e32 v24, v0
	v_mov_b32_e32 v25, v0
	v_mov_b32_e32 v26, v0
	v_mov_b32_e32 v27, v0
	v_mov_b32_e32 v28, v0
	v_mov_b32_e32 v29, v0
	v_mov_b32_e32 v30, v0
	v_mov_b32_e32 v31, v0
	v_mov_b32_e32 v40, v0
	v_mov_b32_e32 v41, v0
	v_mov_b32_e32 v42, v0
	v_mov_b32_e32 v43, v0
	v_mov_b32_e32 v44, v0
	v_mov_b32_e32 v45, v0
	v_mov_b32_e32 v46, v0
	v_mov_b32_e32 v47, v0
	v_mov_b32_e32 v56, v0
	v_mov_b32_e32 v57, v0
	v_mov_b32_e32 v58, v0
	v_mov_b32_e32 v59, v0
	v_mov_b32_e32 v60, v0
	v_mov_b32_e32 v61, v0
	v_mov_b32_e32 v62, v0
	v_mov_b32_e32 v63, v0
	v_mov_b32_e32 v64, v0
	v_mov_b32_e32 v65, v0
	v_mov_b32_e32 v66, v0
	v_mov_b32_e32 v67, v0
	v_mov_b32_e32 v68, v0
	v_mov_b32_e32 v69, v0
	v_mov_b32_e32 v70, v0
	v_mov_b32_e32 v71, v0
	v_mov_b32_e32 v80, v0
	v_mov_b32_e32 v81, v0
	v_mov_b32_e32 v82, v0
	v_mov_b32_e32 v83, v0
	v_mov_b32_e32 v84, v0
	v_mov_b32_e32 v85, v0
	v_mov_b32_e32 v86, v0
	v_mov_b32_e32 v87, v0
	v_mov_b32_e32 v96, v0
	v_mov_b32_e32 v97, v0
	v_mov_b32_e32 v98, v0
	v_mov_b32_e32 v99, v0
	v_mov_b32_e32 v100, v0
	v_mov_b32_e32 v101, v0
	v_mov_b32_e32 v102, v0
	v_mov_b32_e32 v103, v0
	v_mov_b32_e32 v112, v0
	v_mov_b32_e32 v113, v0
	v_mov_b32_e32 v114, v0
	v_mov_b32_e32 v115, v0
	v_mov_b32_e32 v116, v0
	v_mov_b32_e32 v117, v0
	v_mov_b32_e32 v118, v0
	v_mov_b32_e32 v119, v0
	v_mov_b32_e32 v72, v0
	v_mov_b32_e32 v73, v0
	v_mov_b32_e32 v74, v0
	v_mov_b32_e32 v75, v0
	v_mov_b32_e32 v76, v0
	v_mov_b32_e32 v77, v0
	v_mov_b32_e32 v78, v0
	v_mov_b32_e32 v79, v0
	v_mov_b32_e32 v88, v0
	v_mov_b32_e32 v89, v0
	v_mov_b32_e32 v90, v0
	v_mov_b32_e32 v91, v0
	v_mov_b32_e32 v92, v0
	v_mov_b32_e32 v93, v0
	v_mov_b32_e32 v94, v0
	v_mov_b32_e32 v95, v0
	v_mov_b32_e32 v104, v0
	v_mov_b32_e32 v105, v0
	v_mov_b32_e32 v106, v0
	v_mov_b32_e32 v107, v0
	v_mov_b32_e32 v108, v0
	v_mov_b32_e32 v109, v0
	v_mov_b32_e32 v110, v0
	v_mov_b32_e32 v111, v0
	v_mov_b32_e32 v120, v0
	v_mov_b32_e32 v121, v0
	v_mov_b32_e32 v122, v0
	v_mov_b32_e32 v123, v0
	v_mov_b32_e32 v124, v0
	v_mov_b32_e32 v125, v0
	v_mov_b32_e32 v126, v0
	v_mov_b32_e32 v127, v0
	ds_read_b128 v[128:131], v193
	ds_read_b128 v[132:135], v193 offset:1024
	ds_read_b128 v[136:139], v193 offset:2048
	ds_read_b128 v[140:143], v193 offset:3072
	s_branch .Lrot_in_1853
.LBB0_1853:
	s_barrier
	v_mfma_f32_16x16x32_bf16 v[52:55], v[202:205], v[144:147], v[52:55]
	v_mfma_f32_16x16x32_bf16 v[48:51], v[210:213], v[144:147], v[48:51]
	v_mfma_f32_16x16x32_bf16 v[36:39], v[202:205], v[152:155], v[36:39]
	v_mfma_f32_16x16x32_bf16 v[32:35], v[210:213], v[152:155], v[32:35]
	v_mfma_f32_16x16x32_bf16 v[20:23], v[202:205], v[176:179], v[20:23]
	v_mfma_f32_16x16x32_bf16 v[16:19], v[210:213], v[176:179], v[16:19]
	v_mfma_f32_16x16x32_bf16 v[4:7], v[202:205], v[184:187], v[4:7]
	v_mfma_f32_16x16x32_bf16 v[0:3], v[210:213], v[184:187], v[0:3]
	v_mfma_f32_16x16x32_bf16 v[52:55], v[206:209], v[148:151], v[52:55]
	v_mfma_f32_16x16x32_bf16 v[48:51], v[214:217], v[148:151], v[48:51]
	v_mfma_f32_16x16x32_bf16 v[36:39], v[206:209], v[156:159], v[36:39]
	v_mfma_f32_16x16x32_bf16 v[32:35], v[214:217], v[156:159], v[32:35]
	v_mfma_f32_16x16x32_bf16 v[20:23], v[206:209], v[180:183], v[20:23]
	v_mfma_f32_16x16x32_bf16 v[16:19], v[214:217], v[180:183], v[16:19]
	v_mfma_f32_16x16x32_bf16 v[4:7], v[206:209], v[198:201], v[4:7]
	v_mfma_f32_16x16x32_bf16 v[0:3], v[214:217], v[198:201], v[0:3]
	s_waitcnt lgkmcnt(0)
	s_add_i32 s54, s54, 2
	s_add_u32 s52, s52, 0x100
	s_addc_u32 s53, s53, 0
	s_add_u32 s28, s28, 0x100
	s_addc_u32 s29, s29, 0
	s_cmp_gt_u32 s54, 29
	s_barrier
	s_cbranch_scc1 .Lrot_out_1853
; #define PG8_STAGE(bufoff, gbase, voff) do { _Pragma("unroll") for (int _i = 0; _i < 2; ++_i) \
;         __builtin_amdgcn_global_load_lds((const unsigned*)((const char*)(gbase) + (voff)[_i]), (LAS unsigned*)(lds + (bufoff) + ldsw + _i * 8192), 16, 0, 0); } while (0)
; #define PG8_LDA(dst, b, h) do { _Pragma("unroll") for (int m = 0; m < 4; ++m) _Pragma("unroll") for (int k = 0; k < 2; ++k) dst[m][k] = *(const LAS bf16x8*)(lds + PG8_SA(b, h) + aoff + m * 2048 + k * 1024); } while (0)
; #define PG8_LDB(dst, b, h) do { _Pragma("unroll") for (int n = 0; n < 2; ++n) _Pragma("unroll") for (int k = 0; k < 2; ++k) dst[n][k] = *(const LAS bf16x8*)(lds + PG8_SB(b, h) + boff + n * 2048 + k * 1024); } while (0)
; #define PG8_MMA(ai, bj, At, Bt) do { __builtin_amdgcn_s_setprio(1); _Pragma("unroll") for (int m = 0; m < 4; ++m) _Pragma("unroll") for (int n = 0; n < 2; ++n) _Pragma("unroll") for (int k = 0; k < 2; ++k) \
;         acc[ai][bj][m][n] = __builtin_amdgcn_mfma_f32_16x16x32_bf16(Bt[n][k], At[m][k], acc[ai][bj][m][n], 0, 0, 0); __builtin_amdgcn_s_setprio(0); } while (0)
; #define PG8_WAIT_V(n) asm volatile("s_waitcnt vmcnt(" #n ")" ::: "memory")
; #define PG8_WAIT_L(n) asm volatile("s_waitcnt lgkmcnt(" #n ")" ::: "memory")
; template <class Epi>
; __device__ __forceinline__ void gemm_phase(LAS unsigned char* lds, const Gemm g, const StaticOrder& S, const Epi& E, int wv) {
;     ...
;         for (int t = 0; t < nt; t += 2) {
;             const bool last = (t == nt - 2);
;             const char* a1 = cA + (ptrdiff_t)(t + 1) * kstep;
;             const char* a2 = last ? nA : cA + (ptrdiff_t)(t + 2) * kstep; const char* b2 = last ? nB : cB + (ptrdiff_t)(t + 2) * kstep;
;             const char* a3 = a2 + kstep; const char* b3 = b2 + kstep;
;             PG8_LDB(B0, 0, 0); PG8_SCHED; PG8_LDA(At, 0, 0); PG8_STAGE(PG8_SA(1, 1), a1 + hstepA, voffA);
;             PG8_WAIT_L(8); PG8_BAR; PG8_WAIT_L(0); PG8_MMA(0, 0, At, B0); PG8_BAR; PG8_SCHED;
;             PG8_LDB(B1, 0, 1); PG8_STAGE(PG8_SB(0, 0), b2, voffB);
;             PG8_BAR; PG8_WAIT_L(0); PG8_MMA(0, 1, At, B1); PG8_BAR;
;             PG8_LDA(At, 0, 1); PG8_STAGE(PG8_SA(0, 0), a2, voffA);
;             PG8_BAR; PG8_WAIT_L(0); PG8_MMA(1, 0, At, B0); PG8_BAR; PG8_SCHED;
;             PG8_STAGE(PG8_SB(0, 1), b2 + hstepB, voffB);
;             PG8_WAIT_V(6); PG8_BAR; PG8_MMA(1, 1, At, B1); PG8_BAR;
.Lrot_in_1853:
	s_add_u32 s30, s28, 0xfff80080
	s_addc_u32 s31, s29, -1
	s_cmp_eq_u32 s54, 28
	s_cselect_b32 s35, s19, s31
	s_cselect_b32 s34, s50, s30
	s_cselect_b32 s31, s17, s53
	s_cselect_b32 s30, s51, s52
	s_add_i32 m0, s25, 0xc000
	ds_read_b128 v[144:147], v194
	ds_read_b128 v[148:151], v194 offset:1024
	ds_read_b128 v[152:155], v194 offset:2048
	ds_read_b128 v[156:159], v194 offset:3072
	ds_read_b128 v[176:179], v194 offset:4096
	ds_read_b128 v[180:183], v194 offset:5120
	ds_read_b128 v[184:187], v194 offset:6144
	ds_read_b128 v[198:201], v194 offset:7168
	global_load_lds_dwordx4 v170, s[28:29]
	s_add_i32 m0, s25, 0xe000
	s_nop 0
	global_load_lds_dwordx4 v168, s[28:29]
	s_waitcnt lgkmcnt(8)
	s_barrier
	s_waitcnt lgkmcnt(0)
	s_waitcnt lgkmcnt(0)
	v_mfma_f32_16x16x32_bf16 v[124:127], v[128:131], v[144:147], v[124:127]
	v_mfma_f32_16x16x32_bf16 v[120:123], v[136:139], v[144:147], v[120:123]
	v_mfma_f32_16x16x32_bf16 v[108:111], v[128:131], v[152:155], v[108:111]
	v_mfma_f32_16x16x32_bf16 v[104:107], v[136:139], v[152:155], v[104:107]
	v_mfma_f32_16x16x32_bf16 v[92:95], v[128:131], v[176:179], v[92:95]
	v_mfma_f32_16x16x32_bf16 v[88:91], v[136:139], v[176:179], v[88:91]
	v_mfma_f32_16x16x32_bf16 v[76:79], v[128:131], v[184:187], v[76:79]
	v_mfma_f32_16x16x32_bf16 v[72:75], v[136:139], v[184:187], v[72:75]
	v_mfma_f32_16x16x32_bf16 v[124:127], v[132:135], v[148:151], v[124:127]
	v_mfma_f32_16x16x32_bf16 v[120:123], v[140:143], v[148:151], v[120:123]
	v_mfma_f32_16x16x32_bf16 v[108:111], v[132:135], v[156:159], v[108:111]
	v_mfma_f32_16x16x32_bf16 v[104:107], v[140:143], v[156:159], v[104:107]
	v_mfma_f32_16x16x32_bf16 v[92:95], v[132:135], v[180:183], v[92:95]
	v_mfma_f32_16x16x32_bf16 v[88:91], v[140:143], v[180:183], v[88:91]
	v_mfma_f32_16x16x32_bf16 v[76:79], v[132:135], v[198:201], v[76:79]
	v_mfma_f32_16x16x32_bf16 v[72:75], v[140:143], v[198:201], v[72:75]
	s_barrier
	s_add_i32 s55, s47, s40
	s_add_u32 s98, s30, s12
	s_addc_u32 s99, s31, s13
	s_mov_b32 m0, s55
	ds_read_b128 v[202:205], v195
	ds_read_b128 v[206:209], v195 offset:1024
	ds_read_b128 v[210:213], v195 offset:2048
	ds_read_b128 v[214:217], v195 offset:3072
	global_load_lds_dwordx4 v162, s[30:31]
	s_add_i32 m0, s55, 0x2000
	s_nop 0
	global_load_lds_dwordx4 v166, s[30:31]
	s_barrier
	s_waitcnt lgkmcnt(0)
	s_waitcnt lgkmcnt(0)
	v_mfma_f32_16x16x32_bf16 v[116:119], v[202:205], v[144:147], v[116:119]
	v_mfma_f32_16x16x32_bf16 v[112:115], v[210:213], v[144:147], v[112:115]
	v_mfma_f32_16x16x32_bf16 v[100:103], v[202:205], v[152:155], v[100:103]
	v_mfma_f32_16x16x32_bf16 v[96:99], v[210:213], v[152:155], v[96:99]
	v_mfma_f32_16x16x32_bf16 v[84:87], v[202:205], v[176:179], v[84:87]
	v_mfma_f32_16x16x32_bf16 v[80:83], v[210:213], v[176:179], v[80:83]
	v_mfma_f32_16x16x32_bf16 v[68:71], v[202:205], v[184:187], v[68:71]
	v_mfma_f32_16x16x32_bf16 v[64:67], v[210:213], v[184:187], v[64:67]
	v_mfma_f32_16x16x32_bf16 v[116:119], v[206:209], v[148:151], v[116:119]
	v_mfma_f32_16x16x32_bf16 v[112:115], v[214:217], v[148:151], v[112:115]
	v_mfma_f32_16x16x32_bf16 v[100:103], v[206:209], v[156:159], v[100:103]
	v_mfma_f32_16x16x32_bf16 v[96:99], v[214:217], v[156:159], v[96:99]
	v_mfma_f32_16x16x32_bf16 v[84:87], v[206:209], v[180:183], v[84:87]
	v_mfma_f32_16x16x32_bf16 v[80:83], v[214:217], v[180:183], v[80:83]
	v_mfma_f32_16x16x32_bf16 v[68:71], v[206:209], v[198:201], v[68:71]
	v_mfma_f32_16x16x32_bf16 v[64:67], v[214:217], v[198:201], v[64:67]
	s_mov_b32 m0, s25
	s_add_u32 s100, s34, s12
	s_addc_u32 s101, s35, s13
	s_barrier
	ds_read_b128 v[144:147], v194 offset:16384
	ds_read_b128 v[148:151], v194 offset:17408
	ds_read_b128 v[152:155], v194 offset:18432
	ds_read_b128 v[156:159], v194 offset:19456
	ds_read_b128 v[176:179], v194 offset:20480
	ds_read_b128 v[180:183], v194 offset:21504
	ds_read_b128 v[184:187], v194 offset:22528
	ds_read_b128 v[198:201], v194 offset:23552
	global_load_lds_dwordx4 v160, s[34:35]
	s_mov_b32 m0, s41
	s_nop 0
	global_load_lds_dwordx4 v164, s[34:35]
	s_waitcnt vmcnt(10)
	s_barrier
	s_waitcnt lgkmcnt(0)
	s_waitcnt lgkmcnt(0)
	v_mfma_f32_16x16x32_bf16 v[60:63], v[128:131], v[144:147], v[60:63]
	v_mfma_f32_16x16x32_bf16 v[56:59], v[136:139], v[144:147], v[56:59]
	v_mfma_f32_16x16x32_bf16 v[44:47], v[128:131], v[152:155], v[44:47]
	v_mfma_f32_16x16x32_bf16 v[40:43], v[136:139], v[152:155], v[40:43]
	v_mfma_f32_16x16x32_bf16 v[28:31], v[128:131], v[176:179], v[28:31]
	v_mfma_f32_16x16x32_bf16 v[24:27], v[136:139], v[176:179], v[24:27]
	v_mfma_f32_16x16x32_bf16 v[12:15], v[128:131], v[184:187], v[12:15]
	v_mfma_f32_16x16x32_bf16 v[8:11], v[136:139], v[184:187], v[8:11]
	v_mfma_f32_16x16x32_bf16 v[60:63], v[132:135], v[148:151], v[60:63]
	v_mfma_f32_16x16x32_bf16 v[56:59], v[140:143], v[148:151], v[56:59]
	v_mfma_f32_16x16x32_bf16 v[44:47], v[132:135], v[156:159], v[44:47]
	v_mfma_f32_16x16x32_bf16 v[40:43], v[140:143], v[156:159], v[40:43]
	v_mfma_f32_16x16x32_bf16 v[28:31], v[132:135], v[180:183], v[28:31]
	v_mfma_f32_16x16x32_bf16 v[24:27], v[140:143], v[180:183], v[24:27]
	v_mfma_f32_16x16x32_bf16 v[12:15], v[132:135], v[198:201], v[12:15]
	v_mfma_f32_16x16x32_bf16 v[8:11], v[140:143], v[198:201], v[8:11]
	s_barrier
	s_add_u32 s56, s30, 0x80000
	s_addc_u32 s57, s31, 0
	s_add_i32 s55, s48, s40
	s_mov_b32 m0, s55
	s_nop 0
	global_load_lds_dwordx4 v162, s[56:57]
	s_add_i32 m0, s55, 0x2000
	s_nop 0
	global_load_lds_dwordx4 v166, s[56:57]
	s_add_i32 s55, 0, 0x18000
	v_add_u32_e32 v140, s55, v191
	ds_read_b128 v[128:131], v140
	ds_read_b128 v[132:135], v140 offset:1024
	ds_read_b128 v[136:139], v140 offset:2048
	ds_read_b128 v[140:143], v140 offset:3072
	s_waitcnt vmcnt(6)
	s_barrier
; #define PG8_STAGE(bufoff, gbase, voff) do { _Pragma("unroll") for (int _i = 0; _i < 2; ++_i) \
;         __builtin_amdgcn_global_load_lds((const unsigned*)((const char*)(gbase) + (voff)[_i]), (LAS unsigned*)(lds + (bufoff) + ldsw + _i * 8192), 16, 0, 0); } while (0)
; #define PG8_LDA(dst, b, h) do { _Pragma("unroll") for (int m = 0; m < 4; ++m) _Pragma("unroll") for (int k = 0; k < 2; ++k) dst[m][k] = *(const LAS bf16x8*)(lds + PG8_SA(b, h) + aoff + m * 2048 + k * 1024); } while (0)
; #define PG8_LDB(dst, b, h) do { _Pragma("unroll") for (int n = 0; n < 2; ++n) _Pragma("unroll") for (int k = 0; k < 2; ++k) dst[n][k] = *(const LAS bf16x8*)(lds + PG8_SB(b, h) + boff + n * 2048 + k * 1024); } while (0)
; #define PG8_MMA(ai, bj, At, Bt) do { __builtin_amdgcn_s_setprio(1); _Pragma("unroll") for (int m = 0; m < 4; ++m) _Pragma("unroll") for (int n = 0; n < 2; ++n) _Pragma("unroll") for (int k = 0; k < 2; ++k) \
;         acc[ai][bj][m][n] = __builtin_amdgcn_mfma_f32_16x16x32_bf16(Bt[n][k], At[m][k], acc[ai][bj][m][n], 0, 0, 0); __builtin_amdgcn_s_setprio(0); } while (0)
; #define PG8_WAIT_V(n) asm volatile("s_waitcnt vmcnt(" #n ")" ::: "memory")
; #define PG8_WAIT_L(n) asm volatile("s_waitcnt lgkmcnt(" #n ")" ::: "memory")
; #define PG8_BAR __builtin_amdgcn_s_barrier()
; #define PG8_SCHED __builtin_amdgcn_sched_barrier(0)
; template <class Epi>
; __device__ __forceinline__ void gemm_phase(LAS unsigned char* lds, const Gemm g, const StaticOrder& S, const Epi& E, int wv) {
;     ...
;             PG8_WAIT_V(6); PG8_BAR; PG8_MMA(1, 1, At, B1); PG8_BAR;
;             PG8_LDB(B0, 1, 0); PG8_SCHED; PG8_LDA(At, 1, 0); PG8_STAGE(PG8_SA(0, 1), a2 + hstepA, voffA);
;             PG8_WAIT_L(8); PG8_BAR; PG8_WAIT_L(0); PG8_MMA(0, 0, At, B0); PG8_BAR; PG8_SCHED;
;             PG8_LDB(B1, 1, 1); PG8_STAGE(PG8_SB(1, 0), b3, voffB);
;             PG8_BAR; PG8_WAIT_L(0); PG8_MMA(0, 1, At, B1); PG8_BAR;
;             PG8_LDA(At, 1, 1); PG8_STAGE(PG8_SA(1, 0), a3, voffA);
;             PG8_BAR; PG8_WAIT_L(0); PG8_MMA(1, 0, At, B0); PG8_BAR; PG8_SCHED;
;             PG8_STAGE(PG8_SB(1, 1), b3 + hstepB, voffB);
;             PG8_WAIT_V(6); PG8_BAR; PG8_MMA(1, 1, At, B1); PG8_BAR;
	v_mfma_f32_16x16x32_bf16 v[52:55], v[202:205], v[144:147], v[52:55]
	v_mfma_f32_16x16x32_bf16 v[48:51], v[210:213], v[144:147], v[48:51]
	v_mfma_f32_16x16x32_bf16 v[36:39], v[202:205], v[152:155], v[36:39]
	v_mfma_f32_16x16x32_bf16 v[32:35], v[210:213], v[152:155], v[32:35]
	v_mfma_f32_16x16x32_bf16 v[20:23], v[202:205], v[176:179], v[20:23]
	v_mfma_f32_16x16x32_bf16 v[16:19], v[210:213], v[176:179], v[16:19]
	v_mfma_f32_16x16x32_bf16 v[4:7], v[202:205], v[184:187], v[4:7]
	v_mfma_f32_16x16x32_bf16 v[0:3], v[210:213], v[184:187], v[0:3]
	v_mfma_f32_16x16x32_bf16 v[52:55], v[206:209], v[148:151], v[52:55]
	v_mfma_f32_16x16x32_bf16 v[48:51], v[214:217], v[148:151], v[48:51]
	v_mfma_f32_16x16x32_bf16 v[36:39], v[206:209], v[156:159], v[36:39]
	v_mfma_f32_16x16x32_bf16 v[32:35], v[214:217], v[156:159], v[32:35]
	v_mfma_f32_16x16x32_bf16 v[20:23], v[206:209], v[180:183], v[20:23]
	v_mfma_f32_16x16x32_bf16 v[16:19], v[214:217], v[180:183], v[16:19]
	v_mfma_f32_16x16x32_bf16 v[4:7], v[206:209], v[198:201], v[4:7]
	v_mfma_f32_16x16x32_bf16 v[0:3], v[214:217], v[198:201], v[0:3]
	s_waitcnt lgkmcnt(0)
	s_barrier
	s_add_u32 s34, s34, 0x80000
	s_addc_u32 s35, s35, 0
	s_mov_b32 m0, s42
	ds_read_b128 v[144:147], v194 offset:32768
	ds_read_b128 v[148:151], v194 offset:33792
	ds_read_b128 v[152:155], v194 offset:34816
	ds_read_b128 v[156:159], v194 offset:35840
	ds_read_b128 v[176:179], v194 offset:36864
	ds_read_b128 v[180:183], v194 offset:37888
	ds_read_b128 v[184:187], v194 offset:38912
	ds_read_b128 v[198:201], v194 offset:39936
	global_load_lds_dwordx4 v160, s[34:35]
	s_mov_b32 m0, s43
	s_nop 0
	global_load_lds_dwordx4 v164, s[34:35]
	s_waitcnt lgkmcnt(8)
	s_barrier
	s_waitcnt lgkmcnt(0)
	s_waitcnt lgkmcnt(0)
	v_mfma_f32_16x16x32_bf16 v[124:127], v[128:131], v[144:147], v[124:127]
	v_mfma_f32_16x16x32_bf16 v[120:123], v[136:139], v[144:147], v[120:123]
	v_mfma_f32_16x16x32_bf16 v[108:111], v[128:131], v[152:155], v[108:111]
	v_mfma_f32_16x16x32_bf16 v[104:107], v[136:139], v[152:155], v[104:107]
	v_mfma_f32_16x16x32_bf16 v[92:95], v[128:131], v[176:179], v[92:95]
	v_mfma_f32_16x16x32_bf16 v[88:91], v[136:139], v[176:179], v[88:91]
	v_mfma_f32_16x16x32_bf16 v[76:79], v[128:131], v[184:187], v[76:79]
	v_mfma_f32_16x16x32_bf16 v[72:75], v[136:139], v[184:187], v[72:75]
	v_mfma_f32_16x16x32_bf16 v[124:127], v[132:135], v[148:151], v[124:127]
	v_mfma_f32_16x16x32_bf16 v[120:123], v[140:143], v[148:151], v[120:123]
	v_mfma_f32_16x16x32_bf16 v[108:111], v[132:135], v[156:159], v[108:111]
	v_mfma_f32_16x16x32_bf16 v[104:107], v[140:143], v[156:159], v[104:107]
	v_mfma_f32_16x16x32_bf16 v[92:95], v[132:135], v[180:183], v[92:95]
	v_mfma_f32_16x16x32_bf16 v[88:91], v[140:143], v[180:183], v[88:91]
	v_mfma_f32_16x16x32_bf16 v[76:79], v[132:135], v[198:201], v[76:79]
	v_mfma_f32_16x16x32_bf16 v[72:75], v[140:143], v[198:201], v[72:75]
	s_barrier
	s_add_i32 s34, 0, 0x1c000
	s_add_i32 s35, s55, s40
	v_add_u32_e32 v197, s34, v191
	s_mov_b32 m0, s35
	ds_read_b128 v[202:205], v197
	ds_read_b128 v[206:209], v197 offset:1024
	ds_read_b128 v[210:213], v197 offset:2048
	ds_read_b128 v[214:217], v197 offset:3072
	global_load_lds_dwordx4 v162, s[98:99]
	s_add_i32 m0, s35, 0x2000
	s_nop 0
	global_load_lds_dwordx4 v166, s[98:99]
	s_barrier
	s_waitcnt lgkmcnt(0)
	s_waitcnt lgkmcnt(0)
	v_mfma_f32_16x16x32_bf16 v[116:119], v[202:205], v[144:147], v[116:119]
	v_mfma_f32_16x16x32_bf16 v[112:115], v[210:213], v[144:147], v[112:115]
	v_mfma_f32_16x16x32_bf16 v[100:103], v[202:205], v[152:155], v[100:103]
	v_mfma_f32_16x16x32_bf16 v[96:99], v[210:213], v[152:155], v[96:99]
	v_mfma_f32_16x16x32_bf16 v[84:87], v[202:205], v[176:179], v[84:87]
	v_mfma_f32_16x16x32_bf16 v[80:83], v[210:213], v[176:179], v[80:83]
	v_mfma_f32_16x16x32_bf16 v[68:71], v[202:205], v[184:187], v[68:71]
	v_mfma_f32_16x16x32_bf16 v[64:67], v[210:213], v[184:187], v[64:67]
	v_mfma_f32_16x16x32_bf16 v[116:119], v[206:209], v[148:151], v[116:119]
	v_mfma_f32_16x16x32_bf16 v[112:115], v[214:217], v[148:151], v[112:115]
	v_mfma_f32_16x16x32_bf16 v[100:103], v[206:209], v[156:159], v[100:103]
	v_mfma_f32_16x16x32_bf16 v[96:99], v[214:217], v[156:159], v[96:99]
	v_mfma_f32_16x16x32_bf16 v[84:87], v[206:209], v[180:183], v[84:87]
	v_mfma_f32_16x16x32_bf16 v[80:83], v[214:217], v[180:183], v[80:83]
	v_mfma_f32_16x16x32_bf16 v[68:71], v[206:209], v[198:201], v[68:71]
	v_mfma_f32_16x16x32_bf16 v[64:67], v[214:217], v[198:201], v[64:67]
	s_mov_b32 m0, s45
	s_barrier
	ds_read_b128 v[144:147], v194 offset:49152
	ds_read_b128 v[148:151], v194 offset:50176
	ds_read_b128 v[152:155], v194 offset:51200
	ds_read_b128 v[156:159], v194 offset:52224
	ds_read_b128 v[176:179], v194 offset:53248
	ds_read_b128 v[180:183], v194 offset:54272
	ds_read_b128 v[184:187], v194 offset:55296
	ds_read_b128 v[198:201], v194 offset:56320
	global_load_lds_dwordx4 v160, s[100:101]
	s_mov_b32 m0, s46
	s_nop 0
	global_load_lds_dwordx4 v164, s[100:101]
	s_waitcnt vmcnt(10)
	s_barrier
	s_waitcnt lgkmcnt(0)
	s_waitcnt lgkmcnt(0)
	v_mfma_f32_16x16x32_bf16 v[60:63], v[128:131], v[144:147], v[60:63]
	v_mfma_f32_16x16x32_bf16 v[56:59], v[136:139], v[144:147], v[56:59]
	v_mfma_f32_16x16x32_bf16 v[44:47], v[128:131], v[152:155], v[44:47]
	v_mfma_f32_16x16x32_bf16 v[40:43], v[136:139], v[152:155], v[40:43]
	v_mfma_f32_16x16x32_bf16 v[28:31], v[128:131], v[176:179], v[28:31]
	v_mfma_f32_16x16x32_bf16 v[24:27], v[136:139], v[176:179], v[24:27]
	v_mfma_f32_16x16x32_bf16 v[12:15], v[128:131], v[184:187], v[12:15]
	v_mfma_f32_16x16x32_bf16 v[8:11], v[136:139], v[184:187], v[8:11]
	v_mfma_f32_16x16x32_bf16 v[60:63], v[132:135], v[148:151], v[60:63]
	v_mfma_f32_16x16x32_bf16 v[56:59], v[140:143], v[148:151], v[56:59]
	v_mfma_f32_16x16x32_bf16 v[44:47], v[132:135], v[156:159], v[44:47]
	v_mfma_f32_16x16x32_bf16 v[40:43], v[140:143], v[156:159], v[40:43]
	v_mfma_f32_16x16x32_bf16 v[28:31], v[132:135], v[180:183], v[28:31]
	v_mfma_f32_16x16x32_bf16 v[24:27], v[140:143], v[180:183], v[24:27]
	v_mfma_f32_16x16x32_bf16 v[12:15], v[132:135], v[198:201], v[12:15]
	v_mfma_f32_16x16x32_bf16 v[8:11], v[140:143], v[198:201], v[8:11]
	s_barrier
	s_add_u32 s30, s30, 0x80080
	s_addc_u32 s31, s31, 0
	s_add_i32 s34, s34, s40
	s_mov_b32 m0, s34
	s_nop 0
	global_load_lds_dwordx4 v162, s[30:31]
	s_add_i32 m0, s34, 0x2000
	s_nop 0
	global_load_lds_dwordx4 v166, s[30:31]
	ds_read_b128 v[128:131], v193
	ds_read_b128 v[132:135], v193 offset:1024
	ds_read_b128 v[136:139], v193 offset:2048
	ds_read_b128 v[140:143], v193 offset:3072
	s_waitcnt vmcnt(6)
	s_branch .LBB0_1853
; __device__ __forceinline__ float bf_lo(unsigned w) { return __uint_as_float(w << 16); }
; __device__ __forceinline__ float bf_hi(unsigned w) { return __uint_as_float(w & 0xffff0000u); }
; __device__ __forceinline__ float fast_sigmoid(float x) { return __builtin_amdgcn_rcpf(1.0f + __builtin_amdgcn_exp2f(-x * LOG2E)); }
;     __device__ __forceinline__ void operator()(const f32x4 (&acc)[2][2][4][2], const Unit& u, int wr, int wc, int fr, int fq) const {
;         const int row0 = u.pm * BM + wr * 64 + fr, col0 = u.pn * BM + wc * 32 + 8 * fq;
;         constexpr int RD = 3;
;         f32x4 hbuf[RD][4]; u32x4 hraw[RD][2]; u32x4 pbuf[RD][2]; float rsb[RD];
;     ...
;         RES_LOAD(0, 0); RES_LOAD(1, 1);
; #pragma unroll
;         for (int it = 0; it < 8; ++it) { const int ai = it >> 2, m = it & 3, sc = it % RD;
;             if (it + RD - 1 < 8) RES_LOAD((it + RD - 1) % RD, it + RD - 1);
;             asm volatile("" ::: "memory");
;             const int row = row0 + ai * HALF + m * 16; const size_t ro = (size_t)row * DM + col0;
;             float rs = 1.0f; if (MODE == 1) rs = __builtin_amdgcn_rsqf(ss_fix(rsb[sc]) * (1.0f / DM) + EPS);
;             float sq = 0.f;
; #pragma unroll
;             for (int bj = 0; bj < 2; ++bj) { const size_t off = ro + bj * HALF;
;                 f32x4 v0 = acc[ai][bj][m][0], v1 = acc[ai][bj][m][1];
;                 if (MODE == 1) { const u32x4 pw = pbuf[sc][bj];
;                     v0[0] = fast_sigmoid(rs * v0[0]) * bf_lo(pw.x); v0[1] = fast_sigmoid(rs * v0[1]) * bf_hi(pw.x); v0[2] = fast_sigmoid(rs * v0[2]) * bf_lo(pw.y); v0[3] = fast_sigmoid(rs * v0[3]) * bf_hi(pw.y);
;                     v1[0] = fast_sigmoid(rs * v1[0]) * bf_lo(pw.z); v1[1] = fast_sigmoid(rs * v1[1]) * bf_hi(pw.z); v1[2] = fast_sigmoid(rs * v1[2]) * bf_lo(pw.w); v1[3] = fast_sigmoid(rs * v1[3]) * bf_hi(pw.w); }
;                 f32x4 h0, h1;
;                 if (IN16) { const u32x4 hw = hraw[sc][bj]; h0 = (f32x4){bf_lo(hw.x), bf_hi(hw.x), bf_lo(hw.y), bf_hi(hw.y)}; h1 = (f32x4){bf_lo(hw.z), bf_hi(hw.z), bf_lo(hw.w), bf_hi(hw.w)}; }
;                 else { h0 = hbuf[sc][2 * bj]; h1 = hbuf[sc][2 * bj + 1]; }
;                 const f32x4 o0 = h0 + v0, o1 = h1 + v1;
;                 if (OUT32) { *(f32x4*)(hout + off) = o0; *(f32x4*)(hout + off + 4) = o1; }
.Lrot_out_1853:
	v_lshl_add_u32 v178, s24, 8, v190
	v_lshl_or_b32 v176, s49, 8, v192
	v_ashrrev_i32_e32 v179, 31, v178
	v_lshlrev_b64 v[128:129], 11, v[178:179]
	v_ashrrev_i32_e32 v177, 31, v176
	v_lshl_add_u64 v[186:187], v[128:129], 0, v[176:177]
	v_lshlrev_b64 v[128:129], 1, v[186:187]
	v_lshl_add_u64 v[180:181], v[178:179], 2, s[8:9]
	v_lshl_add_u64 v[130:131], s[10:11], 0, v[128:129]
	global_load_dword v184, v[180:181], off
	global_load_dwordx4 v[198:201], v[130:131], off
	v_or_b32_e32 v130, 32, v178
	v_ashrrev_i32_e32 v131, 31, v130
	v_lshl_add_u64 v[132:133], v[130:131], 2, s[8:9]
	global_load_dword v179, v[132:133], off
	v_or_b32_e32 v132, 16, v178
	v_ashrrev_i32_e32 v133, 31, v132
	v_lshlrev_b64 v[134:135], 11, v[132:133]
	v_lshl_add_u64 v[132:133], v[132:133], 2, s[8:9]
	global_load_dword v197, v[132:133], off
	v_lshl_add_u64 v[132:133], s[6:7], 0, v[128:129]
	global_load_dwordx4 v[202:205], v[132:133], off
	v_lshlrev_b64 v[130:131], 11, v[130:131]
	v_lshl_add_u64 v[188:189], v[134:135], 0, v[176:177]
	v_or_b32_e32 v128, 0x100, v128
	v_lshl_add_u64 v[182:183], v[130:131], 0, v[176:177]
	v_lshlrev_b64 v[130:131], 1, v[188:189]
	v_lshl_add_u64 v[134:135], s[6:7], 0, v[128:129]
	v_lshl_add_u64 v[128:129], s[10:11], 0, v[128:129]
	v_lshl_add_u64 v[136:137], s[6:7], 0, v[130:131]
	v_lshl_add_u64 v[138:139], s[10:11], 0, v[130:131]
	global_load_dwordx4 v[206:209], v[134:135], off
	global_load_dwordx4 v[210:213], v[128:129], off
	global_load_dwordx4 v[152:155], v[136:137], off
	global_load_dwordx4 v[156:159], v[138:139], off
	v_lshlrev_b64 v[132:133], 1, v[182:183]
	v_or_b32_e32 v130, 0x100, v130
	v_lshl_add_u64 v[140:141], s[6:7], 0, v[132:133]
	v_lshl_add_u64 v[142:143], s[10:11], 0, v[132:133]
	v_or_b32_e32 v132, 0x100, v132
	v_lshl_add_u64 v[128:129], s[6:7], 0, v[130:131]
	v_lshl_add_u64 v[130:131], s[10:11], 0, v[130:131]
	v_lshl_add_u64 v[134:135], s[6:7], 0, v[132:133]
	v_lshl_add_u64 v[132:133], s[10:11], 0, v[132:133]
	global_load_dwordx4 v[136:139], v[140:141], off
	s_nop 0
	global_load_dwordx4 v[140:143], v[142:143], off
	s_nop 0
	global_load_dwordx4 v[144:147], v[128:129], off
	global_load_dwordx4 v[148:151], v[130:131], off
	s_nop 0
	global_load_dwordx4 v[128:131], v[134:135], off
	s_nop 0
	global_load_dwordx4 v[132:135], v[132:133], off
	s_and_b64 vcc, exec, s[0:1]
	s_mov_b32 s49, s16
	s_mov_b32 s24, s18
	s_mov_b64 s[28:29], s[22:23]
	s_mov_b64 s[30:31], s[20:21]
	s_waitcnt vmcnt(0)
	v_cvt_f32_u32_e32 v214, v184
	v_lshlrev_b32_e32 v184, 16, v198
	v_and_b32_e32 v185, 0xffff0000, v198
	v_and_b32_e32 v215, 0xffff0000, v200
	v_mul_f32_e32 v214, 0x3b800000, v214
	v_fmamk_f32 v214, v214, 0x3a000000, v196
	v_rsq_f32_e32 v220, v214
	v_lshlrev_b32_e32 v214, 16, v200
	v_lshlrev_b32_e32 v200, 16, v201
	v_and_b32_e32 v201, 0xffff0000, v201
	v_mul_f32_e32 v124, v124, v220
	v_mul_f32_e32 v125, v125, v220
	v_mul_f32_e32 v126, v126, v220
	v_mul_f32_e32 v127, v127, v220
	v_mul_f32_e32 v120, v120, v220
	v_mul_f32_e32 v121, v121, v220
	v_mul_f32_e32 v122, v122, v220
	v_mul_f32_e32 v123, v123, v220
	v_mul_f32_e32 v124, 0xbfb8aa3b, v124
	v_mul_f32_e32 v125, 0xbfb8aa3b, v125
	v_mul_f32_e32 v126, 0xbfb8aa3b, v126
	v_mul_f32_e32 v127, 0xbfb8aa3b, v127
	v_mul_f32_e32 v120, 0xbfb8aa3b, v120
	v_mul_f32_e32 v121, 0xbfb8aa3b, v121
	v_mul_f32_e32 v122, 0xbfb8aa3b, v122
	v_mul_f32_e32 v123, 0xbfb8aa3b, v123
	v_exp_f32_e32 v124, v124
	v_exp_f32_e32 v125, v125
	v_exp_f32_e32 v126, v126
	v_exp_f32_e32 v127, v127
	v_exp_f32_e32 v120, v120
	v_exp_f32_e32 v121, v121
	v_exp_f32_e32 v122, v122
	v_exp_f32_e32 v123, v123
	v_mul_f32_e32 v112, v112, v220
	v_add_f32_e32 v124, 1.0, v124
	v_add_f32_e32 v125, 1.0, v125
	v_add_f32_e32 v126, 1.0, v126
	v_add_f32_e32 v127, 1.0, v127
	v_add_f32_e32 v216, 1.0, v120
	v_add_f32_e32 v217, 1.0, v121
	v_add_f32_e32 v218, 1.0, v122
	v_add_f32_e32 v219, 1.0, v123
	v_mul_f32_e32 v112, 0xbfb8aa3b, v112
	v_mul_f32_e32 v113, v113, v220
	v_rcp_f32_e32 v120, v124
	v_rcp_f32_e32 v121, v125
	v_rcp_f32_e32 v122, v126
	v_rcp_f32_e32 v123, v127
	v_rcp_f32_e32 v124, v216
	v_rcp_f32_e32 v125, v217
	v_rcp_f32_e32 v126, v218
	v_rcp_f32_e32 v127, v219
	v_exp_f32_e32 v112, v112
	v_mul_f32_e32 v113, 0xbfb8aa3b, v113
	v_exp_f32_e32 v113, v113
	v_lshlrev_b32_e32 v216, 16, v202
	v_and_b32_e32 v217, 0xffff0000, v202
	v_lshlrev_b32_e32 v218, 16, v204
	v_and_b32_e32 v219, 0xffff0000, v204
	v_lshlrev_b32_e32 v204, 16, v205
	v_and_b32_e32 v205, 0xffff0000, v205
	v_pk_fma_f32 v[120:121], v[120:121], v[184:185], v[216:217]
	v_pk_fma_f32 v[126:127], v[126:127], v[200:201], v[204:205]
	v_pk_fma_f32 v[124:125], v[124:125], v[214:215], v[218:219]
	v_lshl_add_u64 v[184:185], v[186:187], 2, s[4:5]
	v_add_f32_e32 v112, 1.0, v112
	global_store_dwordx4 v[184:185], v[124:127], off offset:16
	v_mul_f32_e32 v116, v116, v220
	v_mul_f32_e32 v117, v117, v220
	v_rcp_f32_e32 v124, v112
	v_add_f32_e32 v112, 1.0, v113
	v_rcp_f32_e32 v125, v112
	v_mul_f32_e32 v112, v114, v220
	v_mul_f32_e32 v118, v118, v220
	v_mul_f32_e32 v119, v119, v220
	v_mul_f32_e32 v112, 0xbfb8aa3b, v112
	v_mul_f32_e32 v113, v115, v220
	v_mul_f32_e32 v116, 0xbfb8aa3b, v116
	v_mul_f32_e32 v117, 0xbfb8aa3b, v117
	v_mul_f32_e32 v118, 0xbfb8aa3b, v118
	v_mul_f32_e32 v119, 0xbfb8aa3b, v119
	v_exp_f32_e32 v112, v112
	v_mul_f32_e32 v113, 0xbfb8aa3b, v113
	v_exp_f32_e32 v116, v116
	v_exp_f32_e32 v117, v117
	v_exp_f32_e32 v118, v118
	v_exp_f32_e32 v119, v119
	v_exp_f32_e32 v113, v113
	v_lshlrev_b32_e32 v198, 16, v199
	v_and_b32_e32 v199, 0xffff0000, v199
	v_lshlrev_b32_e32 v202, 16, v203
	v_and_b32_e32 v203, 0xffff0000, v203
	v_add_f32_e32 v112, 1.0, v112
	v_pk_fma_f32 v[122:123], v[122:123], v[198:199], v[202:203]
; __device__ __forceinline__ float bf_lo(unsigned w) { return __uint_as_float(w << 16); }
; __device__ __forceinline__ float bf_hi(unsigned w) { return __uint_as_float(w & 0xffff0000u); }
; __device__ __forceinline__ float fast_sigmoid(float x) { return __builtin_amdgcn_rcpf(1.0f + __builtin_amdgcn_exp2f(-x * LOG2E)); }
; __device__ __forceinline__ float ss_fix(float raw) { return (float)__float_as_uint(raw) * (1.0f / 256.0f); }
;     __device__ __forceinline__ void operator()(const f32x4 (&acc)[2][2][4][2], const Unit& u, int wr, int wc, int fr, int fq) const {
;     ...
;         for (int it = 0; it < 8; ++it) { const int ai = it >> 2, m = it & 3, sc = it % RD;
;             if (it + RD - 1 < 8) RES_LOAD((it + RD - 1) % RD, it + RD - 1);
;             asm volatile("" ::: "memory");
;             const int row = row0 + ai * HALF + m * 16; const size_t ro = (size_t)row * DM + col0;
;             float rs = 1.0f; if (MODE == 1) rs = __builtin_amdgcn_rsqf(ss_fix(rsb[sc]) * (1.0f / DM) + EPS);
;             float sq = 0.f;
; #pragma unroll
;             for (int bj = 0; bj < 2; ++bj) { const size_t off = ro + bj * HALF;
;                 f32x4 v0 = acc[ai][bj][m][0], v1 = acc[ai][bj][m][1];
;                 if (MODE == 1) { const u32x4 pw = pbuf[sc][bj];
;                     v0[0] = fast_sigmoid(rs * v0[0]) * bf_lo(pw.x); v0[1] = fast_sigmoid(rs * v0[1]) * bf_hi(pw.x); v0[2] = fast_sigmoid(rs * v0[2]) * bf_lo(pw.y); v0[3] = fast_sigmoid(rs * v0[3]) * bf_hi(pw.y);
;                     v1[0] = fast_sigmoid(rs * v1[0]) * bf_lo(pw.z); v1[1] = fast_sigmoid(rs * v1[1]) * bf_hi(pw.z); v1[2] = fast_sigmoid(rs * v1[2]) * bf_lo(pw.w); v1[3] = fast_sigmoid(rs * v1[3]) * bf_hi(pw.w); }
;                 f32x4 h0, h1;
;                 if (IN16) { const u32x4 hw = hraw[sc][bj]; h0 = (f32x4){bf_lo(hw.x), bf_hi(hw.x), bf_lo(hw.y), bf_hi(hw.y)}; h1 = (f32x4){bf_lo(hw.z), bf_hi(hw.z), bf_lo(hw.w), bf_hi(hw.w)}; }
;                 else { h0 = hbuf[sc][2 * bj]; h1 = hbuf[sc][2 * bj + 1]; }
;                 const f32x4 o0 = h0 + v0, o1 = h1 + v1;
;                 if (OUT32) { *(f32x4*)(hout + off) = o0; *(f32x4*)(hout + off + 4) = o1; }
	v_add_f32_e32 v116, 1.0, v116
	v_add_f32_e32 v117, 1.0, v117
	v_add_f32_e32 v118, 1.0, v118
	v_add_f32_e32 v119, 1.0, v119
	v_rcp_f32_e32 v198, v112
	v_add_f32_e32 v112, 1.0, v113
	v_rcp_f32_e32 v116, v116
	v_rcp_f32_e32 v117, v117
	v_rcp_f32_e32 v118, v118
	v_rcp_f32_e32 v119, v119
	v_rcp_f32_e32 v199, v112
	global_store_dwordx4 v[184:185], v[120:123], off
	v_lshlrev_b32_e32 v200, 16, v213
	v_and_b32_e32 v201, 0xffff0000, v213
	v_lshlrev_b32_e32 v120, 16, v210
	v_and_b32_e32 v121, 0xffff0000, v210
	v_lshlrev_b32_e32 v122, 16, v211
	v_and_b32_e32 v123, 0xffff0000, v211
	v_lshlrev_b32_e32 v112, 16, v206
	v_and_b32_e32 v113, 0xffff0000, v206
	v_lshlrev_b32_e32 v114, 16, v207
	v_and_b32_e32 v115, 0xffff0000, v207
	v_lshlrev_b32_e32 v204, 16, v209
	v_and_b32_e32 v205, 0xffff0000, v209
	v_lshlrev_b32_e32 v126, 16, v212
	v_and_b32_e32 v127, 0xffff0000, v212
	v_lshlrev_b32_e32 v202, 16, v208
	v_and_b32_e32 v203, 0xffff0000, v208
	v_pk_fma_f32 v[114:115], v[118:119], v[122:123], v[114:115]
	v_pk_fma_f32 v[112:113], v[116:117], v[120:121], v[112:113]
	v_pk_fma_f32 v[118:119], v[198:199], v[200:201], v[204:205]
	v_pk_fma_f32 v[116:117], v[124:125], v[126:127], v[202:203]
	global_store_dwordx4 v[184:185], v[112:115], off offset:512
	global_store_dwordx4 v[184:185], v[116:119], off offset:528
	v_or_b32_e32 v198, 48, v178
	v_ashrrev_i32_e32 v199, 31, v198
	v_cvt_f32_u32_e32 v118, v197
	v_lshlrev_b64 v[112:113], 11, v[198:199]
	v_lshl_add_u64 v[198:199], v[198:199], 2, s[8:9]
	v_mul_f32_e32 v118, 0x3b800000, v118
	v_fmamk_f32 v118, v118, 0x3a000000, v196
	v_rsq_f32_e32 v197, v118
	global_load_dword v206, v[198:199], off
	v_lshl_add_u64 v[184:185], v[112:113], 0, v[176:177]
	v_lshlrev_b64 v[116:117], 1, v[184:185]
	v_mul_f32_e32 v104, v104, v197
	v_mul_f32_e32 v104, 0xbfb8aa3b, v104
	v_mul_f32_e32 v105, v105, v197
	v_exp_f32_e32 v104, v104
	v_mul_f32_e32 v105, 0xbfb8aa3b, v105
	v_exp_f32_e32 v105, v105
	v_mul_f32_e32 v108, v108, v197
	v_add_f32_e32 v104, 1.0, v104
	v_rcp_f32_e32 v200, v104
	v_add_f32_e32 v104, 1.0, v105
	v_rcp_f32_e32 v201, v104
	v_mul_f32_e32 v104, v106, v197
	v_mul_f32_e32 v109, v109, v197
	v_mul_f32_e32 v110, v110, v197
	v_mul_f32_e32 v111, v111, v197
	v_mul_f32_e32 v104, 0xbfb8aa3b, v104
	v_mul_f32_e32 v105, v107, v197
	v_mul_f32_e32 v108, 0xbfb8aa3b, v108
	v_mul_f32_e32 v109, 0xbfb8aa3b, v109
	v_mul_f32_e32 v110, 0xbfb8aa3b, v110
	v_mul_f32_e32 v111, 0xbfb8aa3b, v111
	v_exp_f32_e32 v104, v104
	v_mul_f32_e32 v105, 0xbfb8aa3b, v105
	v_exp_f32_e32 v108, v108
	v_exp_f32_e32 v109, v109
	v_exp_f32_e32 v110, v110
	v_exp_f32_e32 v111, v111
	v_exp_f32_e32 v105, v105
	v_add_f32_e32 v104, 1.0, v104
	v_mul_f32_e32 v96, v96, v197
	v_add_f32_e32 v108, 1.0, v108
	v_add_f32_e32 v109, 1.0, v109
	v_add_f32_e32 v110, 1.0, v110
	v_add_f32_e32 v111, 1.0, v111
	v_rcp_f32_e32 v204, v104
	v_add_f32_e32 v104, 1.0, v105
	v_mul_f32_e32 v96, 0xbfb8aa3b, v96
	v_mul_f32_e32 v97, v97, v197
	v_rcp_f32_e32 v108, v108
	v_rcp_f32_e32 v109, v109
	v_rcp_f32_e32 v110, v110
	v_rcp_f32_e32 v111, v111
	v_rcp_f32_e32 v205, v104
	v_exp_f32_e32 v96, v96
	v_mul_f32_e32 v97, 0xbfb8aa3b, v97
	v_exp_f32_e32 v97, v97
	v_lshl_add_u64 v[112:113], s[6:7], 0, v[116:117]
	global_load_dwordx4 v[120:123], v[112:113], off
	v_lshl_add_u64 v[112:113], s[10:11], 0, v[116:117]
	v_or_b32_e32 v116, 0x100, v116
	v_lshlrev_b32_e32 v198, 16, v156
	v_and_b32_e32 v199, 0xffff0000, v156
	v_lshlrev_b32_e32 v156, 16, v157
	v_and_b32_e32 v157, 0xffff0000, v157
	v_lshlrev_b32_e32 v202, 16, v158
	v_and_b32_e32 v203, 0xffff0000, v158
	v_lshlrev_b32_e32 v158, 16, v159
	v_and_b32_e32 v159, 0xffff0000, v159
	v_lshlrev_b32_e32 v104, 16, v152
	v_and_b32_e32 v105, 0xffff0000, v152
	v_lshlrev_b32_e32 v106, 16, v153
	v_and_b32_e32 v107, 0xffff0000, v153
	v_lshlrev_b32_e32 v152, 16, v154
	v_and_b32_e32 v153, 0xffff0000, v154
	v_lshlrev_b32_e32 v154, 16, v155
	v_and_b32_e32 v155, 0xffff0000, v155
	global_load_dwordx4 v[124:127], v[112:113], off
	v_lshl_add_u64 v[112:113], s[6:7], 0, v[116:117]
	v_lshl_add_u64 v[116:117], s[10:11], 0, v[116:117]
	v_pk_fma_f32 v[106:107], v[110:111], v[156:157], v[106:107]
	v_pk_fma_f32 v[104:105], v[108:109], v[198:199], v[104:105]
	v_pk_fma_f32 v[110:111], v[204:205], v[158:159], v[154:155]
	v_pk_fma_f32 v[108:109], v[200:201], v[202:203], v[152:153]
	v_lshl_add_u64 v[152:153], v[188:189], 2, s[4:5]
	v_add_f32_e32 v96, 1.0, v96
	global_load_dwordx4 v[112:115], v[112:113], off
	v_mul_f32_e32 v100, v100, v197
	global_load_dwordx4 v[116:119], v[116:117], off
	global_store_dwordx4 v[152:153], v[108:111], off offset:16
	v_mul_f32_e32 v101, v101, v197
	v_mul_f32_e32 v102, v102, v197
	v_rcp_f32_e32 v108, v96
	v_add_f32_e32 v96, 1.0, v97
	v_rcp_f32_e32 v109, v96
	v_mul_f32_e32 v96, v98, v197
	v_mul_f32_e32 v103, v103, v197
	v_mul_f32_e32 v96, 0xbfb8aa3b, v96
	v_mul_f32_e32 v97, v99, v197
	v_mul_f32_e32 v100, 0xbfb8aa3b, v100
	v_mul_f32_e32 v101, 0xbfb8aa3b, v101
	v_mul_f32_e32 v102, 0xbfb8aa3b, v102
	v_mul_f32_e32 v103, 0xbfb8aa3b, v103
	v_exp_f32_e32 v96, v96
	v_mul_f32_e32 v97, 0xbfb8aa3b, v97
	v_exp_f32_e32 v100, v100
	v_exp_f32_e32 v101, v101
	v_exp_f32_e32 v102, v102
	v_exp_f32_e32 v103, v103
	v_exp_f32_e32 v97, v97
	v_add_f32_e32 v96, 1.0, v96
	global_store_dwordx4 v[152:153], v[104:107], off
	v_add_f32_e32 v100, 1.0, v100
	v_add_f32_e32 v101, 1.0, v101
	v_lshlrev_b32_e32 v104, 16, v148
	v_and_b32_e32 v105, 0xffff0000, v148
	v_add_f32_e32 v102, 1.0, v102
	v_add_f32_e32 v103, 1.0, v103
	v_rcp_f32_e32 v148, v96
	v_add_f32_e32 v96, 1.0, v97
	v_rcp_f32_e32 v100, v100
	v_rcp_f32_e32 v101, v101
	v_rcp_f32_e32 v102, v102
	v_rcp_f32_e32 v103, v103
	v_lshlrev_b32_e32 v106, 16, v149
; __device__ __forceinline__ float bf_lo(unsigned w) { return __uint_as_float(w << 16); }
; __device__ __forceinline__ float bf_hi(unsigned w) { return __uint_as_float(w & 0xffff0000u); }
; __device__ __forceinline__ float fast_sigmoid(float x) { return __builtin_amdgcn_rcpf(1.0f + __builtin_amdgcn_exp2f(-x * LOG2E)); }
; __device__ __forceinline__ float ss_fix(float raw) { return (float)__float_as_uint(raw) * (1.0f / 256.0f); }
;     __device__ __forceinline__ void operator()(const f32x4 (&acc)[2][2][4][2], const Unit& u, int wr, int wc, int fr, int fq) const {
;     ...
;         for (int it = 0; it < 8; ++it) { const int ai = it >> 2, m = it & 3, sc = it % RD;
;             if (it + RD - 1 < 8) RES_LOAD((it + RD - 1) % RD, it + RD - 1);
;             asm volatile("" ::: "memory");
;             const int row = row0 + ai * HALF + m * 16; const size_t ro = (size_t)row * DM + col0;
;             float rs = 1.0f; if (MODE == 1) rs = __builtin_amdgcn_rsqf(ss_fix(rsb[sc]) * (1.0f / DM) + EPS);
;             float sq = 0.f;
; #pragma unroll
;             for (int bj = 0; bj < 2; ++bj) { const size_t off = ro + bj * HALF;
;                 f32x4 v0 = acc[ai][bj][m][0], v1 = acc[ai][bj][m][1];
;                 if (MODE == 1) { const u32x4 pw = pbuf[sc][bj];
;                     v0[0] = fast_sigmoid(rs * v0[0]) * bf_lo(pw.x); v0[1] = fast_sigmoid(rs * v0[1]) * bf_hi(pw.x); v0[2] = fast_sigmoid(rs * v0[2]) * bf_lo(pw.y); v0[3] = fast_sigmoid(rs * v0[3]) * bf_hi(pw.y);
;                     v1[0] = fast_sigmoid(rs * v1[0]) * bf_lo(pw.z); v1[1] = fast_sigmoid(rs * v1[1]) * bf_hi(pw.z); v1[2] = fast_sigmoid(rs * v1[2]) * bf_lo(pw.w); v1[3] = fast_sigmoid(rs * v1[3]) * bf_hi(pw.w); }
;                 f32x4 h0, h1;
;                 if (IN16) { const u32x4 hw = hraw[sc][bj]; h0 = (f32x4){bf_lo(hw.x), bf_hi(hw.x), bf_lo(hw.y), bf_hi(hw.y)}; h1 = (f32x4){bf_lo(hw.z), bf_hi(hw.z), bf_lo(hw.w), bf_hi(hw.w)}; }
;                 else { h0 = hbuf[sc][2 * bj]; h1 = hbuf[sc][2 * bj + 1]; }
;                 const f32x4 o0 = h0 + v0, o1 = h1 + v1;
;                 if (OUT32) { *(f32x4*)(hout + off) = o0; *(f32x4*)(hout + off + 4) = o1; }
	v_and_b32_e32 v107, 0xffff0000, v149
	v_rcp_f32_e32 v149, v96
	v_lshlrev_b32_e32 v110, 16, v150
	v_and_b32_e32 v111, 0xffff0000, v150
	v_lshlrev_b32_e32 v150, 16, v151
	v_and_b32_e32 v151, 0xffff0000, v151
	v_lshlrev_b32_e32 v96, 16, v144
	v_and_b32_e32 v97, 0xffff0000, v144
	v_lshlrev_b32_e32 v98, 16, v145
	v_and_b32_e32 v99, 0xffff0000, v145
	v_lshlrev_b32_e32 v144, 16, v146
	v_and_b32_e32 v145, 0xffff0000, v146
	v_lshlrev_b32_e32 v146, 16, v147
	v_and_b32_e32 v147, 0xffff0000, v147
	v_pk_fma_f32 v[98:99], v[102:103], v[106:107], v[98:99]
	v_pk_fma_f32 v[96:97], v[100:101], v[104:105], v[96:97]
	v_pk_fma_f32 v[102:103], v[148:149], v[150:151], v[146:147]
	v_pk_fma_f32 v[100:101], v[108:109], v[110:111], v[144:145]
	global_store_dwordx4 v[152:153], v[96:99], off offset:512
	global_store_dwordx4 v[152:153], v[100:103], off offset:528
	v_lshl_add_u64 v[144:145], v[186:187], 0, s[14:15]
	v_lshlrev_b32_e32 v146, 16, v140
	v_cvt_f32_u32_e32 v102, v179
	v_lshlrev_b64 v[100:101], 1, v[144:145]
	v_lshl_add_u64 v[96:97], s[6:7], 0, v[100:101]
	global_load_dwordx4 v[104:107], v[96:97], off
	v_mul_f32_e32 v102, 0x3b800000, v102
	v_fmamk_f32 v102, v102, 0x3a000000, v196
	v_rsq_f32_e32 v154, v102
	v_lshl_add_u64 v[96:97], s[10:11], 0, v[100:101]
	v_or_b32_e32 v100, 0x100, v100
	global_load_dwordx4 v[108:111], v[96:97], off
	v_lshl_add_u64 v[96:97], s[6:7], 0, v[100:101]
	v_lshl_add_u64 v[100:101], s[10:11], 0, v[100:101]
	global_load_dwordx4 v[96:99], v[96:97], off
	s_nop 0
	global_load_dwordx4 v[100:103], v[100:101], off
	s_nop 0
	global_load_dword v155, v[180:181], off offset:512
	v_mul_f32_e32 v88, v88, v154
	v_mul_f32_e32 v88, 0xbfb8aa3b, v88
	v_mul_f32_e32 v89, v89, v154
	v_exp_f32_e32 v88, v88
	v_mul_f32_e32 v89, 0xbfb8aa3b, v89
	v_exp_f32_e32 v89, v89
	v_mul_f32_e32 v92, v92, v154
	v_add_f32_e32 v88, 1.0, v88
	v_rcp_f32_e32 v148, v88
	v_add_f32_e32 v88, 1.0, v89
	v_rcp_f32_e32 v149, v88
	v_mul_f32_e32 v88, v90, v154
	v_mul_f32_e32 v93, v93, v154
	v_mul_f32_e32 v94, v94, v154
	v_mul_f32_e32 v95, v95, v154
	v_mul_f32_e32 v88, 0xbfb8aa3b, v88
	v_mul_f32_e32 v89, v91, v154
	v_mul_f32_e32 v92, 0xbfb8aa3b, v92
	v_mul_f32_e32 v93, 0xbfb8aa3b, v93
	v_mul_f32_e32 v94, 0xbfb8aa3b, v94
	v_mul_f32_e32 v95, 0xbfb8aa3b, v95
	v_exp_f32_e32 v88, v88
	v_mul_f32_e32 v89, 0xbfb8aa3b, v89
	v_exp_f32_e32 v92, v92
	v_exp_f32_e32 v93, v93
	v_exp_f32_e32 v94, v94
	v_exp_f32_e32 v95, v95
	v_exp_f32_e32 v89, v89
	v_add_f32_e32 v88, 1.0, v88
	v_mul_f32_e32 v80, v80, v154
	v_add_f32_e32 v92, 1.0, v92
	v_add_f32_e32 v93, 1.0, v93
	v_add_f32_e32 v94, 1.0, v94
	v_add_f32_e32 v95, 1.0, v95
	v_rcp_f32_e32 v152, v88
	v_add_f32_e32 v88, 1.0, v89
	v_mul_f32_e32 v80, 0xbfb8aa3b, v80
	v_mul_f32_e32 v81, v81, v154
	v_rcp_f32_e32 v92, v92
	v_rcp_f32_e32 v93, v93
	v_rcp_f32_e32 v94, v94
	v_rcp_f32_e32 v95, v95
	v_rcp_f32_e32 v153, v88
	v_exp_f32_e32 v80, v80
	v_mul_f32_e32 v81, 0xbfb8aa3b, v81
	v_exp_f32_e32 v81, v81
	v_and_b32_e32 v147, 0xffff0000, v140
	v_lshlrev_b32_e32 v140, 16, v141
	v_and_b32_e32 v141, 0xffff0000, v141
	v_lshlrev_b32_e32 v150, 16, v142
	v_and_b32_e32 v151, 0xffff0000, v142
	v_lshlrev_b32_e32 v142, 16, v143
	v_and_b32_e32 v143, 0xffff0000, v143
	v_lshlrev_b32_e32 v88, 16, v136
	v_and_b32_e32 v89, 0xffff0000, v136
	v_lshlrev_b32_e32 v90, 16, v137
	v_and_b32_e32 v91, 0xffff0000, v137
	v_lshlrev_b32_e32 v136, 16, v138
	v_and_b32_e32 v137, 0xffff0000, v138
	v_lshlrev_b32_e32 v138, 16, v139
	v_and_b32_e32 v139, 0xffff0000, v139
	v_pk_fma_f32 v[90:91], v[94:95], v[140:141], v[90:91]
	v_pk_fma_f32 v[88:89], v[92:93], v[146:147], v[88:89]
	v_pk_fma_f32 v[94:95], v[152:153], v[142:143], v[138:139]
	v_pk_fma_f32 v[92:93], v[148:149], v[150:151], v[136:137]
	v_lshl_add_u64 v[136:137], v[182:183], 2, s[4:5]
	v_add_f32_e32 v80, 1.0, v80
	global_store_dwordx4 v[136:137], v[92:95], off offset:16
	v_mul_f32_e32 v84, v84, v154
	v_mul_f32_e32 v85, v85, v154
	v_rcp_f32_e32 v92, v80
	v_add_f32_e32 v80, 1.0, v81
	v_rcp_f32_e32 v93, v80
	v_mul_f32_e32 v80, v82, v154
	v_mul_f32_e32 v86, v86, v154
	v_mul_f32_e32 v87, v87, v154
	v_mul_f32_e32 v80, 0xbfb8aa3b, v80
	v_mul_f32_e32 v81, v83, v154
	v_mul_f32_e32 v84, 0xbfb8aa3b, v84
	v_mul_f32_e32 v85, 0xbfb8aa3b, v85
	v_mul_f32_e32 v86, 0xbfb8aa3b, v86
	v_mul_f32_e32 v87, 0xbfb8aa3b, v87
	v_exp_f32_e32 v80, v80
	v_mul_f32_e32 v81, 0xbfb8aa3b, v81
	v_exp_f32_e32 v84, v84
	v_exp_f32_e32 v85, v85
	v_exp_f32_e32 v86, v86
	v_exp_f32_e32 v87, v87
	v_exp_f32_e32 v81, v81
	v_add_f32_e32 v80, 1.0, v80
	global_store_dwordx4 v[136:137], v[88:91], off
	v_add_f32_e32 v84, 1.0, v84
	v_add_f32_e32 v85, 1.0, v85
	v_lshlrev_b32_e32 v88, 16, v132
	v_and_b32_e32 v89, 0xffff0000, v132
	v_add_f32_e32 v86, 1.0, v86
	v_add_f32_e32 v87, 1.0, v87
	v_rcp_f32_e32 v132, v80
	v_add_f32_e32 v80, 1.0, v81
	v_rcp_f32_e32 v84, v84
	v_rcp_f32_e32 v85, v85
	v_rcp_f32_e32 v86, v86
	v_rcp_f32_e32 v87, v87
	v_lshlrev_b32_e32 v90, 16, v133
	v_and_b32_e32 v91, 0xffff0000, v133
	v_rcp_f32_e32 v133, v80
	v_lshlrev_b32_e32 v94, 16, v134
	v_and_b32_e32 v95, 0xffff0000, v134
	v_lshlrev_b32_e32 v134, 16, v135
	v_and_b32_e32 v135, 0xffff0000, v135
	v_lshlrev_b32_e32 v80, 16, v128
	v_and_b32_e32 v81, 0xffff0000, v128
	v_lshlrev_b32_e32 v82, 16, v129
	v_and_b32_e32 v83, 0xffff0000, v129
	v_lshlrev_b32_e32 v128, 16, v130
	v_and_b32_e32 v129, 0xffff0000, v130
	v_lshlrev_b32_e32 v130, 16, v131
	v_and_b32_e32 v131, 0xffff0000, v131
	v_pk_fma_f32 v[82:83], v[86:87], v[90:91], v[82:83]
	v_pk_fma_f32 v[80:81], v[84:85], v[88:89], v[80:81]
	v_pk_fma_f32 v[86:87], v[132:133], v[134:135], v[130:131]
	v_pk_fma_f32 v[84:85], v[92:93], v[94:95], v[128:129]
	global_store_dwordx4 v[136:137], v[80:83], off offset:512
	global_store_dwordx4 v[136:137], v[84:87], off offset:528
	v_add_u32_e32 v128, 0x90, v178
	v_ashrrev_i32_e32 v129, 31, v128
	s_waitcnt vmcnt(0)
; __device__ __forceinline__ float bf_lo(unsigned w) { return __uint_as_float(w << 16); }
; __device__ __forceinline__ float bf_hi(unsigned w) { return __uint_as_float(w & 0xffff0000u); }
; __device__ __forceinline__ float fast_sigmoid(float x) { return __builtin_amdgcn_rcpf(1.0f + __builtin_amdgcn_exp2f(-x * LOG2E)); }
; __device__ __forceinline__ float ss_fix(float raw) { return (float)__float_as_uint(raw) * (1.0f / 256.0f); }
;     __device__ __forceinline__ void operator()(const f32x4 (&acc)[2][2][4][2], const Unit& u, int wr, int wc, int fr, int fq) const {
;     ...
;         for (int it = 0; it < 8; ++it) { const int ai = it >> 2, m = it & 3, sc = it % RD;
;             if (it + RD - 1 < 8) RES_LOAD((it + RD - 1) % RD, it + RD - 1);
;             asm volatile("" ::: "memory");
;             const int row = row0 + ai * HALF + m * 16; const size_t ro = (size_t)row * DM + col0;
;             float rs = 1.0f; if (MODE == 1) rs = __builtin_amdgcn_rsqf(ss_fix(rsb[sc]) * (1.0f / DM) + EPS);
;             float sq = 0.f;
; #pragma unroll
;             for (int bj = 0; bj < 2; ++bj) { const size_t off = ro + bj * HALF;
;                 f32x4 v0 = acc[ai][bj][m][0], v1 = acc[ai][bj][m][1];
;                 if (MODE == 1) { const u32x4 pw = pbuf[sc][bj];
;                     v0[0] = fast_sigmoid(rs * v0[0]) * bf_lo(pw.x); v0[1] = fast_sigmoid(rs * v0[1]) * bf_hi(pw.x); v0[2] = fast_sigmoid(rs * v0[2]) * bf_lo(pw.y); v0[3] = fast_sigmoid(rs * v0[3]) * bf_hi(pw.y);
;                     v1[0] = fast_sigmoid(rs * v1[0]) * bf_lo(pw.z); v1[1] = fast_sigmoid(rs * v1[1]) * bf_hi(pw.z); v1[2] = fast_sigmoid(rs * v1[2]) * bf_lo(pw.w); v1[3] = fast_sigmoid(rs * v1[3]) * bf_hi(pw.w); }
;                 f32x4 h0, h1;
;                 if (IN16) { const u32x4 hw = hraw[sc][bj]; h0 = (f32x4){bf_lo(hw.x), bf_hi(hw.x), bf_lo(hw.y), bf_hi(hw.y)}; h1 = (f32x4){bf_lo(hw.z), bf_hi(hw.z), bf_lo(hw.w), bf_hi(hw.w)}; }
;                 else { h0 = hbuf[sc][2 * bj]; h1 = hbuf[sc][2 * bj + 1]; }
;                 const f32x4 o0 = h0 + v0, o1 = h1 + v1;
;                 if (OUT32) { *(f32x4*)(hout + off) = o0; *(f32x4*)(hout + off + 4) = o1; }
	v_cvt_f32_u32_e32 v86, v206
	v_lshlrev_b64 v[80:81], 11, v[128:129]
	v_lshl_add_u64 v[80:81], v[80:81], 0, v[176:177]
	v_lshlrev_b64 v[84:85], 1, v[80:81]
	v_mul_f32_e32 v86, 0x3b800000, v86
	v_fmamk_f32 v86, v86, 0x3a000000, v196
	v_rsq_f32_e32 v138, v86
	v_lshl_add_u64 v[80:81], s[6:7], 0, v[84:85]
	global_load_dwordx4 v[88:91], v[80:81], off
	v_mul_f32_e32 v72, v72, v138
	v_mul_f32_e32 v72, 0xbfb8aa3b, v72
	v_mul_f32_e32 v73, v73, v138
	v_exp_f32_e32 v72, v72
	v_mul_f32_e32 v73, 0xbfb8aa3b, v73
	v_exp_f32_e32 v73, v73
	v_lshl_add_u64 v[80:81], s[10:11], 0, v[84:85]
	v_or_b32_e32 v84, 0x100, v84
	global_load_dwordx4 v[92:95], v[80:81], off
	v_lshl_add_u64 v[80:81], s[6:7], 0, v[84:85]
	v_lshl_add_u64 v[84:85], s[10:11], 0, v[84:85]
	v_add_f32_e32 v72, 1.0, v72
	global_load_dwordx4 v[80:83], v[80:81], off
	s_nop 0
	global_load_dwordx4 v[84:87], v[84:85], off
	s_nop 0
	global_load_dword v139, v[180:181], off offset:576
	v_rcp_f32_e32 v132, v72
	v_add_f32_e32 v72, 1.0, v73
	v_rcp_f32_e32 v133, v72
	v_mul_f32_e32 v72, v74, v138
	v_mul_f32_e32 v76, v76, v138
	v_mul_f32_e32 v77, v77, v138
	v_mul_f32_e32 v78, v78, v138
	v_mul_f32_e32 v79, v79, v138
	v_mul_f32_e32 v72, 0xbfb8aa3b, v72
	v_mul_f32_e32 v73, v75, v138
	v_mul_f32_e32 v76, 0xbfb8aa3b, v76
	v_mul_f32_e32 v77, 0xbfb8aa3b, v77
	v_mul_f32_e32 v78, 0xbfb8aa3b, v78
	v_mul_f32_e32 v79, 0xbfb8aa3b, v79
	v_exp_f32_e32 v72, v72
	v_mul_f32_e32 v73, 0xbfb8aa3b, v73
	v_exp_f32_e32 v76, v76
	v_exp_f32_e32 v77, v77
	v_exp_f32_e32 v78, v78
	v_exp_f32_e32 v79, v79
	v_exp_f32_e32 v73, v73
	v_add_f32_e32 v72, 1.0, v72
	v_mul_f32_e32 v64, v64, v138
	v_add_f32_e32 v76, 1.0, v76
	v_add_f32_e32 v77, 1.0, v77
	v_add_f32_e32 v78, 1.0, v78
	v_add_f32_e32 v79, 1.0, v79
	v_rcp_f32_e32 v136, v72
	v_add_f32_e32 v72, 1.0, v73
	v_mul_f32_e32 v64, 0xbfb8aa3b, v64
	v_mul_f32_e32 v65, v65, v138
	v_rcp_f32_e32 v76, v76
	v_rcp_f32_e32 v77, v77
	v_rcp_f32_e32 v78, v78
	v_rcp_f32_e32 v79, v79
	v_rcp_f32_e32 v137, v72
	v_exp_f32_e32 v64, v64
	v_mul_f32_e32 v65, 0xbfb8aa3b, v65
	v_exp_f32_e32 v65, v65
	v_lshlrev_b32_e32 v130, 16, v124
	v_and_b32_e32 v131, 0xffff0000, v124
	v_lshlrev_b32_e32 v124, 16, v125
	v_and_b32_e32 v125, 0xffff0000, v125
	v_lshlrev_b32_e32 v134, 16, v126
	v_and_b32_e32 v135, 0xffff0000, v126
	v_lshlrev_b32_e32 v126, 16, v127
	v_and_b32_e32 v127, 0xffff0000, v127
	v_lshlrev_b32_e32 v72, 16, v120
	v_and_b32_e32 v73, 0xffff0000, v120
	v_lshlrev_b32_e32 v74, 16, v121
	v_and_b32_e32 v75, 0xffff0000, v121
	v_lshlrev_b32_e32 v120, 16, v122
	v_and_b32_e32 v121, 0xffff0000, v122
	v_lshlrev_b32_e32 v122, 16, v123
	v_and_b32_e32 v123, 0xffff0000, v123
	v_pk_fma_f32 v[74:75], v[78:79], v[124:125], v[74:75]
	v_pk_fma_f32 v[72:73], v[76:77], v[130:131], v[72:73]
	v_pk_fma_f32 v[78:79], v[136:137], v[126:127], v[122:123]
	v_pk_fma_f32 v[76:77], v[132:133], v[134:135], v[120:121]
	v_lshl_add_u64 v[120:121], v[184:185], 2, s[4:5]
	v_add_f32_e32 v64, 1.0, v64
	global_store_dwordx4 v[120:121], v[76:79], off offset:16
	v_mul_f32_e32 v68, v68, v138
	v_mul_f32_e32 v69, v69, v138
	v_rcp_f32_e32 v76, v64
	v_add_f32_e32 v64, 1.0, v65
	v_rcp_f32_e32 v77, v64
	v_mul_f32_e32 v64, v66, v138
	v_mul_f32_e32 v70, v70, v138
	v_mul_f32_e32 v71, v71, v138
	v_mul_f32_e32 v64, 0xbfb8aa3b, v64
	v_mul_f32_e32 v65, v67, v138
	v_mul_f32_e32 v68, 0xbfb8aa3b, v68
	v_mul_f32_e32 v69, 0xbfb8aa3b, v69
	v_mul_f32_e32 v70, 0xbfb8aa3b, v70
	v_mul_f32_e32 v71, 0xbfb8aa3b, v71
	v_exp_f32_e32 v64, v64
	v_mul_f32_e32 v65, 0xbfb8aa3b, v65
	v_exp_f32_e32 v68, v68
	v_exp_f32_e32 v69, v69
	v_exp_f32_e32 v70, v70
	v_exp_f32_e32 v71, v71
	v_exp_f32_e32 v65, v65
	v_add_f32_e32 v64, 1.0, v64
	global_store_dwordx4 v[120:121], v[72:75], off
	v_add_f32_e32 v68, 1.0, v68
	v_add_f32_e32 v69, 1.0, v69
	v_lshlrev_b32_e32 v72, 16, v116
	v_and_b32_e32 v73, 0xffff0000, v116
	v_add_f32_e32 v70, 1.0, v70
	v_add_f32_e32 v71, 1.0, v71
	v_rcp_f32_e32 v116, v64
	v_add_f32_e32 v64, 1.0, v65
	v_rcp_f32_e32 v68, v68
	v_rcp_f32_e32 v69, v69
	v_rcp_f32_e32 v70, v70
	v_rcp_f32_e32 v71, v71
	v_lshlrev_b32_e32 v74, 16, v117
	v_and_b32_e32 v75, 0xffff0000, v117
	v_rcp_f32_e32 v117, v64
	v_lshlrev_b32_e32 v78, 16, v118
	v_and_b32_e32 v79, 0xffff0000, v118
	v_lshlrev_b32_e32 v118, 16, v119
	v_and_b32_e32 v119, 0xffff0000, v119
	v_lshlrev_b32_e32 v64, 16, v112
	v_and_b32_e32 v65, 0xffff0000, v112
	v_lshlrev_b32_e32 v66, 16, v113
	v_and_b32_e32 v67, 0xffff0000, v113
	v_lshlrev_b32_e32 v112, 16, v114
	v_and_b32_e32 v113, 0xffff0000, v114
	v_lshlrev_b32_e32 v114, 16, v115
	v_and_b32_e32 v115, 0xffff0000, v115
	v_pk_fma_f32 v[66:67], v[70:71], v[74:75], v[66:67]
	v_pk_fma_f32 v[64:65], v[68:69], v[72:73], v[64:65]
	v_pk_fma_f32 v[70:71], v[116:117], v[118:119], v[114:115]
	v_pk_fma_f32 v[68:69], v[76:77], v[78:79], v[112:113]
	global_store_dwordx4 v[120:121], v[64:67], off offset:512
	global_store_dwordx4 v[120:121], v[68:71], off offset:528
	v_add_u32_e32 v114, 0xa0, v178
	v_ashrrev_i32_e32 v115, 31, v114
	v_cvt_f32_u32_e32 v70, v155
	v_lshlrev_b64 v[64:65], 11, v[114:115]
	v_lshl_add_u64 v[114:115], v[114:115], 2, s[8:9]
	v_mul_f32_e32 v70, 0x3b800000, v70
	v_fmamk_f32 v70, v70, 0x3a000000, v196
	v_rsq_f32_e32 v122, v70
	global_load_dword v123, v[114:115], off
	v_lshl_add_u64 v[112:113], v[64:65], 0, v[176:177]
	v_lshlrev_b64 v[68:69], 1, v[112:113]
	v_mul_f32_e32 v56, v56, v122
	v_mul_f32_e32 v56, 0xbfb8aa3b, v56
	v_mul_f32_e32 v57, v57, v122
	v_exp_f32_e32 v56, v56
	v_mul_f32_e32 v57, 0xbfb8aa3b, v57
	v_exp_f32_e32 v57, v57
	v_mul_f32_e32 v60, v60, v122
	v_add_f32_e32 v56, 1.0, v56
	v_rcp_f32_e32 v116, v56
	v_add_f32_e32 v56, 1.0, v57
	v_rcp_f32_e32 v117, v56
	v_mul_f32_e32 v56, v58, v122
; __device__ __forceinline__ float bf_lo(unsigned w) { return __uint_as_float(w << 16); }
; __device__ __forceinline__ float bf_hi(unsigned w) { return __uint_as_float(w & 0xffff0000u); }
; __device__ __forceinline__ float fast_sigmoid(float x) { return __builtin_amdgcn_rcpf(1.0f + __builtin_amdgcn_exp2f(-x * LOG2E)); }
; __device__ __forceinline__ float ss_fix(float raw) { return (float)__float_as_uint(raw) * (1.0f / 256.0f); }
;     __device__ __forceinline__ void operator()(const f32x4 (&acc)[2][2][4][2], const Unit& u, int wr, int wc, int fr, int fq) const {
;     ...
;         for (int it = 0; it < 8; ++it) { const int ai = it >> 2, m = it & 3, sc = it % RD;
;             if (it + RD - 1 < 8) RES_LOAD((it + RD - 1) % RD, it + RD - 1);
;             asm volatile("" ::: "memory");
;             const int row = row0 + ai * HALF + m * 16; const size_t ro = (size_t)row * DM + col0;
;             float rs = 1.0f; if (MODE == 1) rs = __builtin_amdgcn_rsqf(ss_fix(rsb[sc]) * (1.0f / DM) + EPS);
;             float sq = 0.f;
; #pragma unroll
;             for (int bj = 0; bj < 2; ++bj) { const size_t off = ro + bj * HALF;
;                 f32x4 v0 = acc[ai][bj][m][0], v1 = acc[ai][bj][m][1];
;                 if (MODE == 1) { const u32x4 pw = pbuf[sc][bj];
;                     v0[0] = fast_sigmoid(rs * v0[0]) * bf_lo(pw.x); v0[1] = fast_sigmoid(rs * v0[1]) * bf_hi(pw.x); v0[2] = fast_sigmoid(rs * v0[2]) * bf_lo(pw.y); v0[3] = fast_sigmoid(rs * v0[3]) * bf_hi(pw.y);
;                     v1[0] = fast_sigmoid(rs * v1[0]) * bf_lo(pw.z); v1[1] = fast_sigmoid(rs * v1[1]) * bf_hi(pw.z); v1[2] = fast_sigmoid(rs * v1[2]) * bf_lo(pw.w); v1[3] = fast_sigmoid(rs * v1[3]) * bf_hi(pw.w); }
;                 f32x4 h0, h1;
;                 if (IN16) { const u32x4 hw = hraw[sc][bj]; h0 = (f32x4){bf_lo(hw.x), bf_hi(hw.x), bf_lo(hw.y), bf_hi(hw.y)}; h1 = (f32x4){bf_lo(hw.z), bf_hi(hw.z), bf_lo(hw.w), bf_hi(hw.w)}; }
;                 else { h0 = hbuf[sc][2 * bj]; h1 = hbuf[sc][2 * bj + 1]; }
;                 const f32x4 o0 = h0 + v0, o1 = h1 + v1;
;                 if (OUT32) { *(f32x4*)(hout + off) = o0; *(f32x4*)(hout + off + 4) = o1; }
	v_mul_f32_e32 v61, v61, v122
	v_mul_f32_e32 v62, v62, v122
	v_mul_f32_e32 v63, v63, v122
	v_mul_f32_e32 v56, 0xbfb8aa3b, v56
	v_mul_f32_e32 v57, v59, v122
	v_mul_f32_e32 v60, 0xbfb8aa3b, v60
	v_mul_f32_e32 v61, 0xbfb8aa3b, v61
	v_mul_f32_e32 v62, 0xbfb8aa3b, v62
	v_mul_f32_e32 v63, 0xbfb8aa3b, v63
	v_exp_f32_e32 v56, v56
	v_mul_f32_e32 v57, 0xbfb8aa3b, v57
	v_exp_f32_e32 v60, v60
	v_exp_f32_e32 v61, v61
	v_exp_f32_e32 v62, v62
	v_exp_f32_e32 v63, v63
	v_exp_f32_e32 v57, v57
	v_add_f32_e32 v56, 1.0, v56
	v_mul_f32_e32 v48, v48, v122
	v_add_f32_e32 v60, 1.0, v60
	v_add_f32_e32 v61, 1.0, v61
	v_add_f32_e32 v62, 1.0, v62
	v_add_f32_e32 v63, 1.0, v63
	v_rcp_f32_e32 v120, v56
	v_add_f32_e32 v56, 1.0, v57
	v_mul_f32_e32 v48, 0xbfb8aa3b, v48
	v_mul_f32_e32 v49, v49, v122
	v_rcp_f32_e32 v60, v60
	v_rcp_f32_e32 v61, v61
	v_rcp_f32_e32 v62, v62
	v_rcp_f32_e32 v63, v63
	v_rcp_f32_e32 v121, v56
	v_exp_f32_e32 v48, v48
	v_mul_f32_e32 v49, 0xbfb8aa3b, v49
	v_exp_f32_e32 v49, v49
	v_lshl_add_u64 v[64:65], s[6:7], 0, v[68:69]
	global_load_dwordx4 v[72:75], v[64:65], off
	v_lshl_add_u64 v[64:65], s[10:11], 0, v[68:69]
	v_or_b32_e32 v68, 0x100, v68
	v_lshlrev_b32_e32 v114, 16, v108
	v_and_b32_e32 v115, 0xffff0000, v108
	v_lshlrev_b32_e32 v108, 16, v109
	v_and_b32_e32 v109, 0xffff0000, v109
	v_lshlrev_b32_e32 v118, 16, v110
	v_and_b32_e32 v119, 0xffff0000, v110
	v_lshlrev_b32_e32 v110, 16, v111
	v_and_b32_e32 v111, 0xffff0000, v111
	v_lshlrev_b32_e32 v56, 16, v104
	v_and_b32_e32 v57, 0xffff0000, v104
	v_lshlrev_b32_e32 v58, 16, v105
	v_and_b32_e32 v59, 0xffff0000, v105
	v_lshlrev_b32_e32 v104, 16, v106
	v_and_b32_e32 v105, 0xffff0000, v106
	v_lshlrev_b32_e32 v106, 16, v107
	v_and_b32_e32 v107, 0xffff0000, v107
	global_load_dwordx4 v[76:79], v[64:65], off
	v_lshl_add_u64 v[64:65], s[6:7], 0, v[68:69]
	v_lshl_add_u64 v[68:69], s[10:11], 0, v[68:69]
	v_pk_fma_f32 v[58:59], v[62:63], v[108:109], v[58:59]
	v_pk_fma_f32 v[56:57], v[60:61], v[114:115], v[56:57]
	v_pk_fma_f32 v[62:63], v[120:121], v[110:111], v[106:107]
	v_pk_fma_f32 v[60:61], v[116:117], v[118:119], v[104:105]
	v_lshl_add_u64 v[104:105], v[144:145], 2, s[4:5]
	v_add_f32_e32 v48, 1.0, v48
	global_load_dwordx4 v[64:67], v[64:65], off
	v_mul_f32_e32 v52, v52, v122
	global_load_dwordx4 v[68:71], v[68:69], off
	global_store_dwordx4 v[104:105], v[60:63], off offset:16
	v_mul_f32_e32 v53, v53, v122
	v_mul_f32_e32 v54, v54, v122
	v_rcp_f32_e32 v60, v48
	v_add_f32_e32 v48, 1.0, v49
	v_rcp_f32_e32 v61, v48
	v_mul_f32_e32 v48, v50, v122
	v_mul_f32_e32 v55, v55, v122
	v_mul_f32_e32 v48, 0xbfb8aa3b, v48
	v_mul_f32_e32 v49, v51, v122
	v_mul_f32_e32 v52, 0xbfb8aa3b, v52
	v_mul_f32_e32 v53, 0xbfb8aa3b, v53
	v_mul_f32_e32 v54, 0xbfb8aa3b, v54
	v_mul_f32_e32 v55, 0xbfb8aa3b, v55
	v_exp_f32_e32 v48, v48
	v_mul_f32_e32 v49, 0xbfb8aa3b, v49
	v_exp_f32_e32 v52, v52
	v_exp_f32_e32 v53, v53
	v_exp_f32_e32 v54, v54
	v_exp_f32_e32 v55, v55
	v_exp_f32_e32 v49, v49
	v_add_f32_e32 v48, 1.0, v48
	global_store_dwordx4 v[104:105], v[56:59], off
	v_add_f32_e32 v52, 1.0, v52
	v_add_f32_e32 v53, 1.0, v53
	v_lshlrev_b32_e32 v56, 16, v100
	v_and_b32_e32 v57, 0xffff0000, v100
	v_add_f32_e32 v54, 1.0, v54
	v_add_f32_e32 v55, 1.0, v55
	v_rcp_f32_e32 v100, v48
	v_add_f32_e32 v48, 1.0, v49
	v_rcp_f32_e32 v52, v52
	v_rcp_f32_e32 v53, v53
	v_rcp_f32_e32 v54, v54
	v_rcp_f32_e32 v55, v55
	v_lshlrev_b32_e32 v58, 16, v101
	v_and_b32_e32 v59, 0xffff0000, v101
	v_rcp_f32_e32 v101, v48
	v_lshlrev_b32_e32 v62, 16, v102
	v_and_b32_e32 v63, 0xffff0000, v102
	v_lshlrev_b32_e32 v102, 16, v103
	v_and_b32_e32 v103, 0xffff0000, v103
	v_lshlrev_b32_e32 v48, 16, v96
	v_and_b32_e32 v49, 0xffff0000, v96
	v_lshlrev_b32_e32 v50, 16, v97
	v_and_b32_e32 v51, 0xffff0000, v97
	v_lshlrev_b32_e32 v96, 16, v98
	v_and_b32_e32 v97, 0xffff0000, v98
	v_lshlrev_b32_e32 v98, 16, v99
	v_and_b32_e32 v99, 0xffff0000, v99
	v_pk_fma_f32 v[50:51], v[54:55], v[58:59], v[50:51]
	v_pk_fma_f32 v[48:49], v[52:53], v[56:57], v[48:49]
	v_pk_fma_f32 v[54:55], v[100:101], v[102:103], v[98:99]
	v_add_u32_e32 v98, 0xb0, v178
	v_pk_fma_f32 v[52:53], v[60:61], v[62:63], v[96:97]
	global_store_dwordx4 v[104:105], v[48:51], off offset:512
	global_store_dwordx4 v[104:105], v[52:55], off offset:528
	v_ashrrev_i32_e32 v99, 31, v98
	v_lshlrev_b64 v[48:49], 11, v[98:99]
	v_lshl_add_u64 v[98:99], v[98:99], 2, s[8:9]
	global_load_dword v107, v[98:99], off
	s_waitcnt vmcnt(0)
; __device__ __forceinline__ float bf_lo(unsigned w) { return __uint_as_float(w << 16); }
; __device__ __forceinline__ float bf_hi(unsigned w) { return __uint_as_float(w & 0xffff0000u); }
; __device__ __forceinline__ float fast_sigmoid(float x) { return __builtin_amdgcn_rcpf(1.0f + __builtin_amdgcn_exp2f(-x * LOG2E)); }
; __device__ __forceinline__ float ss_fix(float raw) { return (float)__float_as_uint(raw) * (1.0f / 256.0f); }
;     __device__ __forceinline__ void operator()(const f32x4 (&acc)[2][2][4][2], const Unit& u, int wr, int wc, int fr, int fq) const {
;     ...
;         for (int it = 0; it < 8; ++it) { const int ai = it >> 2, m = it & 3, sc = it % RD;
;             if (it + RD - 1 < 8) RES_LOAD((it + RD - 1) % RD, it + RD - 1);
;             asm volatile("" ::: "memory");
;             const int row = row0 + ai * HALF + m * 16; const size_t ro = (size_t)row * DM + col0;
;             float rs = 1.0f; if (MODE == 1) rs = __builtin_amdgcn_rsqf(ss_fix(rsb[sc]) * (1.0f / DM) + EPS);
;             float sq = 0.f;
; #pragma unroll
;             for (int bj = 0; bj < 2; ++bj) { const size_t off = ro + bj * HALF;
;                 f32x4 v0 = acc[ai][bj][m][0], v1 = acc[ai][bj][m][1];
;                 if (MODE == 1) { const u32x4 pw = pbuf[sc][bj];
;                     v0[0] = fast_sigmoid(rs * v0[0]) * bf_lo(pw.x); v0[1] = fast_sigmoid(rs * v0[1]) * bf_hi(pw.x); v0[2] = fast_sigmoid(rs * v0[2]) * bf_lo(pw.y); v0[3] = fast_sigmoid(rs * v0[3]) * bf_hi(pw.y);
;                     v1[0] = fast_sigmoid(rs * v1[0]) * bf_lo(pw.z); v1[1] = fast_sigmoid(rs * v1[1]) * bf_hi(pw.z); v1[2] = fast_sigmoid(rs * v1[2]) * bf_lo(pw.w); v1[3] = fast_sigmoid(rs * v1[3]) * bf_hi(pw.w); }
;                 f32x4 h0, h1;
;                 if (IN16) { const u32x4 hw = hraw[sc][bj]; h0 = (f32x4){bf_lo(hw.x), bf_hi(hw.x), bf_lo(hw.y), bf_hi(hw.y)}; h1 = (f32x4){bf_lo(hw.z), bf_hi(hw.z), bf_lo(hw.w), bf_hi(hw.w)}; }
;                 else { h0 = hbuf[sc][2 * bj]; h1 = hbuf[sc][2 * bj + 1]; }
;                 const f32x4 o0 = h0 + v0, o1 = h1 + v1;
;                 if (OUT32) { *(f32x4*)(hout + off) = o0; *(f32x4*)(hout + off + 4) = o1; }
	v_cvt_f32_u32_e32 v54, v139
	v_lshl_add_u64 v[96:97], v[48:49], 0, v[176:177]
	v_lshlrev_b64 v[52:53], 1, v[96:97]
	v_lshl_add_u64 v[48:49], s[6:7], 0, v[52:53]
	v_mul_f32_e32 v54, 0x3b800000, v54
	v_fmamk_f32 v54, v54, 0x3a000000, v196
	v_rsq_f32_e32 v106, v54
	global_load_dwordx4 v[56:59], v[48:49], off
	v_lshl_add_u64 v[48:49], s[10:11], 0, v[52:53]
	global_load_dwordx4 v[60:63], v[48:49], off
	v_mul_f32_e32 v40, v40, v106
	v_mul_f32_e32 v40, 0xbfb8aa3b, v40
	v_mul_f32_e32 v41, v41, v106
	v_exp_f32_e32 v40, v40
	v_mul_f32_e32 v41, 0xbfb8aa3b, v41
	v_exp_f32_e32 v41, v41
	v_mul_f32_e32 v44, v44, v106
	v_add_f32_e32 v40, 1.0, v40
	v_mul_f32_e32 v45, v45, v106
	v_rcp_f32_e32 v100, v40
	v_add_f32_e32 v40, 1.0, v41
	v_mul_f32_e32 v44, 0xbfb8aa3b, v44
	v_mul_f32_e32 v45, 0xbfb8aa3b, v45
	v_rcp_f32_e32 v101, v40
	v_mul_f32_e32 v40, v42, v106
	v_exp_f32_e32 v44, v44
	v_exp_f32_e32 v45, v45
	v_mul_f32_e32 v46, v46, v106
	v_mul_f32_e32 v47, v47, v106
	v_mul_f32_e32 v40, 0xbfb8aa3b, v40
	v_mul_f32_e32 v41, v43, v106
	v_mul_f32_e32 v46, 0xbfb8aa3b, v46
	v_mul_f32_e32 v47, 0xbfb8aa3b, v47
	v_exp_f32_e32 v40, v40
	v_mul_f32_e32 v41, 0xbfb8aa3b, v41
	v_exp_f32_e32 v46, v46
	v_exp_f32_e32 v47, v47
	v_exp_f32_e32 v41, v41
	v_add_f32_e32 v44, 1.0, v44
	v_add_f32_e32 v45, 1.0, v45
	v_rcp_f32_e32 v44, v44
	v_rcp_f32_e32 v45, v45
	v_add_f32_e32 v40, 1.0, v40
	v_mul_f32_e32 v32, v32, v106
	v_add_f32_e32 v46, 1.0, v46
	v_add_f32_e32 v47, 1.0, v47
	v_rcp_f32_e32 v104, v40
	v_add_f32_e32 v40, 1.0, v41
	v_mul_f32_e32 v32, 0xbfb8aa3b, v32
	v_mul_f32_e32 v33, v33, v106
	v_rcp_f32_e32 v46, v46
	v_rcp_f32_e32 v47, v47
	v_rcp_f32_e32 v105, v40
	v_mul_f32_e32 v38, v38, v106
	v_mul_f32_e32 v39, v39, v106
	v_exp_f32_e32 v32, v32
	v_mul_f32_e32 v33, 0xbfb8aa3b, v33
	v_lshlrev_b32_e32 v98, 16, v92
	v_and_b32_e32 v99, 0xffff0000, v92
	v_lshlrev_b32_e32 v102, 16, v94
	v_and_b32_e32 v103, 0xffff0000, v94
	v_lshlrev_b32_e32 v40, 16, v88
	v_and_b32_e32 v41, 0xffff0000, v88
	v_lshlrev_b32_e32 v42, 16, v89
	v_and_b32_e32 v43, 0xffff0000, v89
	v_lshlrev_b32_e32 v88, 16, v90
	v_and_b32_e32 v89, 0xffff0000, v90
	v_mul_f32_e32 v38, 0xbfb8aa3b, v38
	v_mul_f32_e32 v39, 0xbfb8aa3b, v39
	v_exp_f32_e32 v33, v33
	v_pk_fma_f32 v[40:41], v[44:45], v[98:99], v[40:41]
	v_pk_fma_f32 v[44:45], v[100:101], v[102:103], v[88:89]
	v_lshlrev_b64 v[88:89], 13, v[128:129]
	v_exp_f32_e32 v38, v38
	v_exp_f32_e32 v39, v39
	v_or_b32_e32 v52, 0x100, v52
	v_lshlrev_b32_e32 v92, 16, v93
	v_and_b32_e32 v93, 0xffff0000, v93
	v_lshlrev_b32_e32 v94, 16, v95
	v_and_b32_e32 v95, 0xffff0000, v95
	v_lshlrev_b32_e32 v90, 16, v91
	v_and_b32_e32 v91, 0xffff0000, v91
	v_lshl_add_u64 v[88:89], s[4:5], 0, v[88:89]
	v_lshl_add_u64 v[48:49], s[6:7], 0, v[52:53]
	v_lshl_add_u64 v[52:53], s[10:11], 0, v[52:53]
	v_pk_fma_f32 v[42:43], v[46:47], v[92:93], v[42:43]
	v_pk_fma_f32 v[46:47], v[104:105], v[94:95], v[90:91]
	v_lshl_add_u64 v[88:89], v[176:177], 2, v[88:89]
	v_mul_f32_e32 v36, v36, v106
	v_mul_f32_e32 v37, v37, v106
	v_add_f32_e32 v32, 1.0, v32
	global_load_dwordx4 v[48:51], v[48:49], off
	v_mul_f32_e32 v36, 0xbfb8aa3b, v36
	global_load_dwordx4 v[52:55], v[52:53], off
	v_mul_f32_e32 v37, 0xbfb8aa3b, v37
	global_store_dwordx4 v[88:89], v[44:47], off offset:16
	v_exp_f32_e32 v36, v36
	v_exp_f32_e32 v37, v37
	v_rcp_f32_e32 v44, v32
	v_add_f32_e32 v32, 1.0, v33
	v_add_f32_e32 v38, 1.0, v38
	v_add_f32_e32 v39, 1.0, v39
	v_rcp_f32_e32 v45, v32
	v_mul_f32_e32 v32, v34, v106
	v_rcp_f32_e32 v38, v38
	v_rcp_f32_e32 v39, v39
	v_mul_f32_e32 v32, 0xbfb8aa3b, v32
	v_mul_f32_e32 v33, v35, v106
	v_exp_f32_e32 v32, v32
	v_mul_f32_e32 v33, 0xbfb8aa3b, v33
	v_exp_f32_e32 v33, v33
	global_store_dwordx4 v[88:89], v[40:43], off
	v_add_f32_e32 v36, 1.0, v36
	v_add_f32_e32 v37, 1.0, v37
	v_lshlrev_b32_e32 v42, 16, v85
	v_and_b32_e32 v43, 0xffff0000, v85
	v_lshlrev_b32_e32 v34, 16, v81
	v_and_b32_e32 v35, 0xffff0000, v81
	v_rcp_f32_e32 v36, v36
	v_rcp_f32_e32 v37, v37
	v_pk_fma_f32 v[34:35], v[38:39], v[42:43], v[34:35]
	v_cvt_f32_u32_e32 v42, v123
	v_add_f32_e32 v32, 1.0, v32
	v_lshlrev_b32_e32 v40, 16, v84
	v_and_b32_e32 v41, 0xffff0000, v84
	v_rcp_f32_e32 v84, v32
	v_add_f32_e32 v32, 1.0, v33
	v_rcp_f32_e32 v85, v32
	v_lshlrev_b32_e32 v32, 16, v80
	v_and_b32_e32 v33, 0xffff0000, v80
	v_pk_fma_f32 v[32:33], v[36:37], v[40:41], v[32:33]
	v_mul_f32_e32 v40, 0x3b800000, v42
	v_lshlrev_b32_e32 v46, 16, v86
	v_and_b32_e32 v47, 0xffff0000, v86
	v_lshlrev_b32_e32 v80, 16, v82
	v_and_b32_e32 v81, 0xffff0000, v82
	v_fmamk_f32 v40, v40, 0x3a000000, v196
	v_pk_fma_f32 v[36:37], v[44:45], v[46:47], v[80:81]
	v_rsq_f32_e32 v80, v40
	v_lshlrev_b32_e32 v86, 16, v87
	v_and_b32_e32 v87, 0xffff0000, v87
	v_lshlrev_b32_e32 v82, 16, v83
	v_mul_f32_e32 v24, v24, v80
	v_mul_f32_e32 v24, 0xbfb8aa3b, v24
	v_mul_f32_e32 v25, v25, v80
	v_exp_f32_e32 v24, v24
	v_mul_f32_e32 v25, 0xbfb8aa3b, v25
	v_exp_f32_e32 v25, v25
	v_and_b32_e32 v83, 0xffff0000, v83
	v_add_f32_e32 v24, 1.0, v24
	v_pk_fma_f32 v[38:39], v[84:85], v[86:87], v[82:83]
	global_store_dwordx4 v[88:89], v[32:35], off offset:512
	global_store_dwordx4 v[88:89], v[36:39], off offset:528
	v_mul_f32_e32 v28, v28, v80
	v_mul_f32_e32 v29, v29, v80
	v_rcp_f32_e32 v36, v24
	v_add_f32_e32 v24, 1.0, v25
	v_rcp_f32_e32 v37, v24
	v_mul_f32_e32 v24, v26, v80
	v_mul_f32_e32 v30, v30, v80
	v_mul_f32_e32 v31, v31, v80
	v_mul_f32_e32 v24, 0xbfb8aa3b, v24
	v_mul_f32_e32 v25, v27, v80
	v_mul_f32_e32 v28, 0xbfb8aa3b, v28
	v_mul_f32_e32 v29, 0xbfb8aa3b, v29
	v_mul_f32_e32 v30, 0xbfb8aa3b, v30
	v_mul_f32_e32 v31, 0xbfb8aa3b, v31
	v_exp_f32_e32 v24, v24
	v_mul_f32_e32 v25, 0xbfb8aa3b, v25
	v_exp_f32_e32 v28, v28
; __device__ __forceinline__ float bf_lo(unsigned w) { return __uint_as_float(w << 16); }
;     __device__ __forceinline__ void operator()(const f32x4 (&acc)[2][2][4][2], const Unit& u, int wr, int wc, int fr, int fq) const {
;     ...
;         for (int it = 0; it < 8; ++it) { const int ai = it >> 2, m = it & 3, sc = it % RD;
;             if (it + RD - 1 < 8) RES_LOAD((it + RD - 1) % RD, it + RD - 1);
;             asm volatile("" ::: "memory");
;             const int row = row0 + ai * HALF + m * 16; const size_t ro = (size_t)row * DM + col0;
;             float rs = 1.0f; if (MODE == 1) rs = __builtin_amdgcn_rsqf(ss_fix(rsb[sc]) * (1.0f / DM) + EPS);
;             float sq = 0.f;
; #pragma unroll
;             for (int bj = 0; bj < 2; ++bj) { const size_t off = ro + bj * HALF;
;                 f32x4 v0 = acc[ai][bj][m][0], v1 = acc[ai][bj][m][1];
;                 if (MODE == 1) { const u32x4 pw = pbuf[sc][bj];
;                     v0[0] = fast_sigmoid(rs * v0[0]) * bf_lo(pw.x); v0[1] = fast_sigmoid(rs * v0[1]) * bf_hi(pw.x); v0[2] = fast_sigmoid(rs * v0[2]) * bf_lo(pw.y); v0[3] = fast_sigmoid(rs * v0[3]) * bf_hi(pw.y);
;                     v1[0] = fast_sigmoid(rs * v1[0]) * bf_lo(pw.z); v1[1] = fast_sigmoid(rs * v1[1]) * bf_hi(pw.z); v1[2] = fast_sigmoid(rs * v1[2]) * bf_lo(pw.w); v1[3] = fast_sigmoid(rs * v1[3]) * bf_hi(pw.w); }
;                 f32x4 h0, h1;
;                 if (IN16) { const u32x4 hw = hraw[sc][bj]; h0 = (f32x4){bf_lo(hw.x), bf_hi(hw.x), bf_lo(hw.y), bf_hi(hw.y)}; h1 = (f32x4){bf_lo(hw.z), bf_hi(hw.z), bf_lo(hw.w), bf_hi(hw.w)}; }
;                 else { h0 = hbuf[sc][2 * bj]; h1 = hbuf[sc][2 * bj + 1]; }
;                 const f32x4 o0 = h0 + v0, o1 = h1 + v1;
;                 if (OUT32) { *(f32x4*)(hout + off) = o0; *(f32x4*)(hout + off + 4) = o1; }
;                 if (hb) { u32x4 w; w.x = pk_bf16(o0[0], o0[1]); w.y = pk_bf16(o0[2], o0[3]); w.z = pk_bf16(o1[0], o1[1]); w.w = pk_bf16(o1[2], o1[3]); *(u32x4*)(hb + off) = w; }
;                 sq += ((o0[0] * o0[0] + o0[1] * o0[1]) + (o0[2] * o0[2] + o0[3] * o0[3])) + ((o1[0] * o1[0] + o1[1] * o1[1]) + (o1[2] * o1[2] + o1[3] * o1[3])); }
;             if (ss_out) { sq += __shfl_xor(sq, 16); sq += __shfl_xor(sq, 32); if (fq == 0) atomicAdd((unsigned*)(ss_out + row), ss_enc(sq)); }
;             asm volatile("" ::: "memory"); }
	v_exp_f32_e32 v29, v29
	v_exp_f32_e32 v30, v30
	v_exp_f32_e32 v31, v31
	v_exp_f32_e32 v25, v25
	v_add_f32_e32 v24, 1.0, v24
	v_mul_f32_e32 v16, v16, v80
	v_add_f32_e32 v28, 1.0, v28
	v_add_f32_e32 v29, 1.0, v29
	v_add_f32_e32 v30, 1.0, v30
	v_add_f32_e32 v31, 1.0, v31
	v_rcp_f32_e32 v40, v24
	v_add_f32_e32 v24, 1.0, v25
	v_mul_f32_e32 v16, 0xbfb8aa3b, v16
	v_mul_f32_e32 v17, v17, v80
	v_rcp_f32_e32 v28, v28
	v_rcp_f32_e32 v29, v29
	v_rcp_f32_e32 v30, v30
	v_rcp_f32_e32 v31, v31
	v_rcp_f32_e32 v41, v24
	v_exp_f32_e32 v16, v16
	v_mul_f32_e32 v17, 0xbfb8aa3b, v17
	v_mul_f32_e32 v22, v22, v80
	v_mul_f32_e32 v23, v23, v80
	v_exp_f32_e32 v17, v17
	v_mul_f32_e32 v22, 0xbfb8aa3b, v22
	v_mul_f32_e32 v23, 0xbfb8aa3b, v23
	v_lshlrev_b32_e32 v32, 16, v76
	v_and_b32_e32 v33, 0xffff0000, v76
	v_lshlrev_b32_e32 v34, 16, v77
	v_and_b32_e32 v35, 0xffff0000, v77
	v_lshlrev_b32_e32 v38, 16, v78
	v_and_b32_e32 v39, 0xffff0000, v78
	v_lshlrev_b32_e32 v42, 16, v79
	v_and_b32_e32 v43, 0xffff0000, v79
	v_lshlrev_b32_e32 v24, 16, v72
	v_and_b32_e32 v25, 0xffff0000, v72
	v_lshlrev_b32_e32 v26, 16, v73
	v_and_b32_e32 v27, 0xffff0000, v73
	v_lshlrev_b32_e32 v44, 16, v74
	v_and_b32_e32 v45, 0xffff0000, v74
	v_lshlrev_b32_e32 v46, 16, v75
	v_and_b32_e32 v47, 0xffff0000, v75
	v_exp_f32_e32 v22, v22
	v_exp_f32_e32 v23, v23
	v_pk_fma_f32 v[26:27], v[30:31], v[34:35], v[26:27]
	v_pk_fma_f32 v[24:25], v[28:29], v[32:33], v[24:25]
	v_pk_fma_f32 v[30:31], v[40:41], v[42:43], v[46:47]
	v_pk_fma_f32 v[28:29], v[36:37], v[38:39], v[44:45]
	v_lshl_add_u64 v[32:33], v[112:113], 2, s[4:5]
	v_add_f32_e32 v16, 1.0, v16
	v_mul_f32_e32 v20, v20, v80
	v_mul_f32_e32 v21, v21, v80
	global_store_dwordx4 v[32:33], v[28:31], off offset:16
	v_mul_f32_e32 v20, 0xbfb8aa3b, v20
	v_mul_f32_e32 v21, 0xbfb8aa3b, v21
	v_rcp_f32_e32 v28, v16
	v_add_f32_e32 v16, 1.0, v17
	v_rcp_f32_e32 v29, v16
	v_mul_f32_e32 v16, v18, v80
	v_exp_f32_e32 v20, v20
	v_exp_f32_e32 v21, v21
	v_add_f32_e32 v22, 1.0, v22
	v_add_f32_e32 v23, 1.0, v23
	v_mul_f32_e32 v16, 0xbfb8aa3b, v16
	v_mul_f32_e32 v17, v19, v80
	v_rcp_f32_e32 v22, v22
	v_rcp_f32_e32 v23, v23
	v_exp_f32_e32 v16, v16
	v_mul_f32_e32 v17, 0xbfb8aa3b, v17
	v_exp_f32_e32 v17, v17
	global_store_dwordx4 v[32:33], v[24:27], off
	v_add_f32_e32 v20, 1.0, v20
	v_add_f32_e32 v21, 1.0, v21
	v_lshlrev_b32_e32 v26, 16, v69
	v_and_b32_e32 v27, 0xffff0000, v69
	v_lshlrev_b32_e32 v18, 16, v65
	v_and_b32_e32 v19, 0xffff0000, v65
	v_rcp_f32_e32 v20, v20
	v_rcp_f32_e32 v21, v21
	v_add_f32_e32 v16, 1.0, v16
	v_pk_fma_f32 v[18:19], v[22:23], v[26:27], v[18:19]
	v_cvt_f32_u32_e32 v26, v107
	v_rcp_f32_e32 v34, v16
	v_add_f32_e32 v16, 1.0, v17
	v_rcp_f32_e32 v35, v16
	v_lshlrev_b32_e32 v24, 16, v68
	v_and_b32_e32 v25, 0xffff0000, v68
	v_lshlrev_b32_e32 v16, 16, v64
	v_and_b32_e32 v17, 0xffff0000, v64
	v_pk_fma_f32 v[16:17], v[20:21], v[24:25], v[16:17]
	v_mul_f32_e32 v24, 0x3b800000, v26
	v_lshlrev_b32_e32 v36, 16, v71
	v_and_b32_e32 v37, 0xffff0000, v71
	v_lshlrev_b32_e32 v40, 16, v67
	v_and_b32_e32 v41, 0xffff0000, v67
	v_fmamk_f32 v24, v24, 0x3a000000, v196
	v_pk_fma_f32 v[22:23], v[34:35], v[36:37], v[40:41]
	v_rsq_f32_e32 v34, v24
	v_lshlrev_b32_e32 v30, 16, v70
	v_and_b32_e32 v31, 0xffff0000, v70
	v_lshlrev_b32_e32 v38, 16, v66
	v_mul_f32_e32 v8, v8, v34
	v_mul_f32_e32 v8, 0xbfb8aa3b, v8
	v_mul_f32_e32 v9, v9, v34
	v_exp_f32_e32 v8, v8
	v_mul_f32_e32 v9, 0xbfb8aa3b, v9
	v_exp_f32_e32 v9, v9
	v_and_b32_e32 v39, 0xffff0000, v66
	v_pk_fma_f32 v[20:21], v[28:29], v[30:31], v[38:39]
	v_add_f32_e32 v8, 1.0, v8
	global_store_dwordx4 v[32:33], v[16:19], off offset:512
	global_store_dwordx4 v[32:33], v[20:23], off offset:528
	v_mul_f32_e32 v12, v12, v34
	v_mul_f32_e32 v13, v13, v34
	v_rcp_f32_e32 v20, v8
	v_add_f32_e32 v8, 1.0, v9
	v_rcp_f32_e32 v21, v8
	v_mul_f32_e32 v8, v10, v34
	v_mul_f32_e32 v14, v14, v34
	v_mul_f32_e32 v15, v15, v34
	v_mul_f32_e32 v8, 0xbfb8aa3b, v8
	v_mul_f32_e32 v9, v11, v34
	v_mul_f32_e32 v12, 0xbfb8aa3b, v12
	v_mul_f32_e32 v13, 0xbfb8aa3b, v13
	v_mul_f32_e32 v14, 0xbfb8aa3b, v14
	v_mul_f32_e32 v15, 0xbfb8aa3b, v15
	v_exp_f32_e32 v8, v8
	v_mul_f32_e32 v9, 0xbfb8aa3b, v9
	v_exp_f32_e32 v12, v12
	v_exp_f32_e32 v13, v13
	v_exp_f32_e32 v14, v14
	v_exp_f32_e32 v15, v15
	v_exp_f32_e32 v9, v9
	v_add_f32_e32 v8, 1.0, v8
	v_mul_f32_e32 v0, v0, v34
	v_add_f32_e32 v12, 1.0, v12
	v_add_f32_e32 v13, 1.0, v13
	v_add_f32_e32 v14, 1.0, v14
	v_add_f32_e32 v15, 1.0, v15
	v_rcp_f32_e32 v24, v8
	v_add_f32_e32 v8, 1.0, v9
	v_mul_f32_e32 v0, 0xbfb8aa3b, v0
	v_mul_f32_e32 v1, v1, v34
	v_rcp_f32_e32 v12, v12
	v_rcp_f32_e32 v13, v13
	v_rcp_f32_e32 v14, v14
	v_rcp_f32_e32 v15, v15
	v_rcp_f32_e32 v25, v8
	v_exp_f32_e32 v0, v0
	v_mul_f32_e32 v1, 0xbfb8aa3b, v1
	v_exp_f32_e32 v1, v1
	s_waitcnt vmcnt(0)
; __device__ __forceinline__ float bf_lo(unsigned w) { return __uint_as_float(w << 16); }
; __device__ __forceinline__ float bf_hi(unsigned w) { return __uint_as_float(w & 0xffff0000u); }
; __device__ __forceinline__ float fast_sigmoid(float x) { return __builtin_amdgcn_rcpf(1.0f + __builtin_amdgcn_exp2f(-x * LOG2E)); }
; #define PG8_WAIT_V(n) asm volatile("s_waitcnt vmcnt(" #n ")" ::: "memory")
; template <class Epi>
; __device__ __forceinline__ void gemm_phase(LAS unsigned char* lds, const Gemm g, const StaticOrder& S, const Epi& E, int wv) {
;     ...
;     PG8_WAIT_V(0);
;     if (wr == 0) PG8_BAR;
;     PG8_BAR;
;     __device__ __forceinline__ void operator()(const f32x4 (&acc)[2][2][4][2], const Unit& u, int wr, int wc, int fr, int fq) const {
;     ...
;             for (int bj = 0; bj < 2; ++bj) { const size_t off = ro + bj * HALF;
;                 f32x4 v0 = acc[ai][bj][m][0], v1 = acc[ai][bj][m][1];
;                 if (MODE == 1) { const u32x4 pw = pbuf[sc][bj];
;                     v0[0] = fast_sigmoid(rs * v0[0]) * bf_lo(pw.x); v0[1] = fast_sigmoid(rs * v0[1]) * bf_hi(pw.x); v0[2] = fast_sigmoid(rs * v0[2]) * bf_lo(pw.y); v0[3] = fast_sigmoid(rs * v0[3]) * bf_hi(pw.y);
;                     v1[0] = fast_sigmoid(rs * v1[0]) * bf_lo(pw.z); v1[1] = fast_sigmoid(rs * v1[1]) * bf_hi(pw.z); v1[2] = fast_sigmoid(rs * v1[2]) * bf_lo(pw.w); v1[3] = fast_sigmoid(rs * v1[3]) * bf_hi(pw.w); }
;                 f32x4 h0, h1;
;                 if (IN16) { const u32x4 hw = hraw[sc][bj]; h0 = (f32x4){bf_lo(hw.x), bf_hi(hw.x), bf_lo(hw.y), bf_hi(hw.y)}; h1 = (f32x4){bf_lo(hw.z), bf_hi(hw.z), bf_lo(hw.w), bf_hi(hw.w)}; }
;                 else { h0 = hbuf[sc][2 * bj]; h1 = hbuf[sc][2 * bj + 1]; }
;                 const f32x4 o0 = h0 + v0, o1 = h1 + v1;
;                 if (OUT32) { *(f32x4*)(hout + off) = o0; *(f32x4*)(hout + off + 4) = o1; }
;                 if (hb) { u32x4 w; w.x = pk_bf16(o0[0], o0[1]); w.y = pk_bf16(o0[2], o0[3]); w.z = pk_bf16(o1[0], o1[1]); w.w = pk_bf16(o1[2], o1[3]); *(u32x4*)(hb + off) = w; }
;                 sq += ((o0[0] * o0[0] + o0[1] * o0[1]) + (o0[2] * o0[2] + o0[3] * o0[3])) + ((o1[0] * o1[0] + o1[1] * o1[1]) + (o1[2] * o1[2] + o1[3] * o1[3])); }
;             if (ss_out) { sq += __shfl_xor(sq, 16); sq += __shfl_xor(sq, 32); if (fq == 0) atomicAdd((unsigned*)(ss_out + row), ss_enc(sq)); }
;             asm volatile("" ::: "memory"); }
	v_lshlrev_b32_e32 v16, 16, v60
	v_and_b32_e32 v17, 0xffff0000, v60
	v_lshlrev_b32_e32 v18, 16, v61
	v_and_b32_e32 v19, 0xffff0000, v61
	v_lshlrev_b32_e32 v22, 16, v62
	v_and_b32_e32 v23, 0xffff0000, v62
	v_lshlrev_b32_e32 v26, 16, v63
	v_and_b32_e32 v27, 0xffff0000, v63
	v_lshlrev_b32_e32 v8, 16, v56
	v_and_b32_e32 v9, 0xffff0000, v56
	v_lshlrev_b32_e32 v10, 16, v57
	v_and_b32_e32 v11, 0xffff0000, v57
	v_lshlrev_b32_e32 v28, 16, v58
	v_and_b32_e32 v29, 0xffff0000, v58
	v_lshlrev_b32_e32 v30, 16, v59
	v_and_b32_e32 v31, 0xffff0000, v59
	v_pk_fma_f32 v[10:11], v[14:15], v[18:19], v[10:11]
	v_pk_fma_f32 v[8:9], v[12:13], v[16:17], v[8:9]
	v_pk_fma_f32 v[14:15], v[24:25], v[26:27], v[30:31]
	v_pk_fma_f32 v[12:13], v[20:21], v[22:23], v[28:29]
	v_lshl_add_u64 v[16:17], v[96:97], 2, s[4:5]
	v_add_f32_e32 v0, 1.0, v0
	global_store_dwordx4 v[16:17], v[12:15], off offset:16
	v_mul_f32_e32 v4, v4, v34
	v_mul_f32_e32 v5, v5, v34
	v_rcp_f32_e32 v12, v0
	v_add_f32_e32 v0, 1.0, v1
	v_mul_f32_e32 v6, v6, v34
	v_mul_f32_e32 v7, v7, v34
	v_rcp_f32_e32 v13, v0
	v_mul_f32_e32 v0, v2, v34
	v_mul_f32_e32 v4, 0xbfb8aa3b, v4
	v_mul_f32_e32 v5, 0xbfb8aa3b, v5
	v_mul_f32_e32 v6, 0xbfb8aa3b, v6
	v_mul_f32_e32 v7, 0xbfb8aa3b, v7
	v_mul_f32_e32 v0, 0xbfb8aa3b, v0
	v_mul_f32_e32 v1, v3, v34
	v_exp_f32_e32 v4, v4
	v_exp_f32_e32 v5, v5
	v_exp_f32_e32 v6, v6
	v_exp_f32_e32 v7, v7
	v_exp_f32_e32 v0, v0
	v_mul_f32_e32 v1, 0xbfb8aa3b, v1
	v_exp_f32_e32 v1, v1
	v_add_f32_e32 v4, 1.0, v4
	v_add_f32_e32 v5, 1.0, v5
	v_add_f32_e32 v6, 1.0, v6
	v_add_f32_e32 v7, 1.0, v7
	v_add_f32_e32 v0, 1.0, v0
	v_rcp_f32_e32 v4, v4
	v_rcp_f32_e32 v5, v5
	v_rcp_f32_e32 v6, v6
	v_rcp_f32_e32 v7, v7
	v_rcp_f32_e32 v18, v0
	v_add_f32_e32 v0, 1.0, v1
	v_rcp_f32_e32 v19, v0
	global_store_dwordx4 v[16:17], v[8:11], off
	v_lshlrev_b32_e32 v0, 16, v48
	v_and_b32_e32 v1, 0xffff0000, v48
	v_lshlrev_b32_e32 v8, 16, v52
	v_and_b32_e32 v9, 0xffff0000, v52
	v_lshlrev_b32_e32 v10, 16, v53
	v_and_b32_e32 v11, 0xffff0000, v53
	v_lshlrev_b32_e32 v2, 16, v49
	v_and_b32_e32 v3, 0xffff0000, v49
	v_lshlrev_b32_e32 v14, 16, v54
	v_and_b32_e32 v15, 0xffff0000, v54
	v_lshlrev_b32_e32 v20, 16, v55
	v_and_b32_e32 v21, 0xffff0000, v55
	v_lshlrev_b32_e32 v22, 16, v50
	v_and_b32_e32 v23, 0xffff0000, v50
	v_lshlrev_b32_e32 v24, 16, v51
	v_and_b32_e32 v25, 0xffff0000, v51
	v_pk_fma_f32 v[2:3], v[6:7], v[10:11], v[2:3]
	v_pk_fma_f32 v[0:1], v[4:5], v[8:9], v[0:1]
	v_pk_fma_f32 v[6:7], v[18:19], v[20:21], v[24:25]
	v_pk_fma_f32 v[4:5], v[12:13], v[14:15], v[22:23]
	global_store_dwordx4 v[16:17], v[0:3], off offset:512
	global_store_dwordx4 v[16:17], v[4:7], off offset:528
	s_cbranch_vccz .LBB0_1846
	s_waitcnt vmcnt(0)
	s_cmpk_gt_u32 s33, 0xff
	s_cbranch_scc1 .LBB0_1857
	s_barrier
